# GEMM K-loops: priority drop moved behind the burst-closing barrier (on top of segment-head slimming)
# baseline (speedup 1.0000x reference)
; #define PG8_STAGE(bufoff, gbase, voff) do { _Pragma("unroll") for (int _i = 0; _i < 2; ++_i) \
;         __builtin_amdgcn_global_load_lds((const unsigned*)((const char*)(gbase) + (voff)[_i]), (PG8_LAS unsigned*)(lds + (bufoff) + ldsw + _i * 8192), 16, 0, 0); } while (0)
; #define PG8_LDA(dst, b, h) do { _Pragma("unroll") for (int m = 0; m < 4; ++m) _Pragma("unroll") for (int k = 0; k < 2; ++k) dst[m][k] = *(const PG8_LAS bf16x8*)(lds + PG8_SA(b, h) + aoff + m * 2048 + k * 1024); } while (0)
; template <class Epi, class Sched, bool ALIGN_EPI = false, bool SP2 = false>
; __device__ __forceinline__ void gemm_phase(PG8_LAS unsigned char* lds, const Gemm g, const Sched& S, const Epi& E, const int wid) {
;     ...
;         const bool has_next = S.next(ui + 1, nxt);
;         const char* nA = has_next ? (const char*)g.A + (size_t)nxt.pm * tstep : cA; const char* nB = has_next ? (const char*)g.Bt + (size_t)nxt.pn * tstep : cB;
;         for (int t = 0; t < nt; t += 2) {
;             const bool last = (t == nt - 2);
;             const char* a1 = cA + (size_t)(t + 1) * kstep;
;             const char* a2 = last ? nA : cA + (size_t)(t + 2) * kstep; const char* b2 = last ? nB : cB + (size_t)(t + 2) * kstep;
;             const char* a3 = a2 + kstep; const char* b3 = b2 + kstep;
;             if (last && has_next) S.a_ready(nxt);
;             if constexpr (SP2) {
;             PG8_LDB(B0, 0, 0); PG8_LDB(B1, 0, 1); PG8_SCHED; PG8_LDA(At, 0, 0); PG8_STAGE(PG8_SA(1, 1), a1 + hstep, voffA);
;             PG8_WAIT_V(8); PG8_WAIT_L(0); PG8_BAR; PG8_MMA(0, 0, At, B0); PG8_MMA(0, 1, At, B1); PG8_BAR; PG8_SCHED;
;             PG8_LDA(At, 0, 1); PG8_STAGE(PG8_SB(0, 0), b2, voffB); PG8_STAGE(PG8_SB(0, 1), b2 + hstep, voffB); PG8_STAGE(PG8_SA(0, 0), a2, voffA);
;             PG8_WAIT_V(8); PG8_WAIT_L(0); PG8_BAR; PG8_MMA(1, 0, At, B0); PG8_MMA(1, 1, At, B1); PG8_BAR; PG8_SCHED;
;             PG8_LDB(B0, 1, 0); PG8_LDB(B1, 1, 1); PG8_SCHED; PG8_LDA(At, 1, 0); PG8_STAGE(PG8_SA(0, 1), a2 + hstep, voffA);
;             PG8_WAIT_V(8); PG8_WAIT_L(0); PG8_BAR; PG8_MMA(0, 0, At, B0); PG8_MMA(0, 1, At, B1); PG8_BAR; PG8_SCHED;
;             PG8_LDA(At, 1, 1); PG8_STAGE(PG8_SB(1, 0), b3, voffB); PG8_STAGE(PG8_SB(1, 1), b3 + hstep, voffB); PG8_STAGE(PG8_SA(1, 0), a3, voffA);
;             PG8_WAIT_V(8); PG8_WAIT_L(0); PG8_BAR; PG8_MMA(1, 0, At, B0); PG8_MMA(1, 1, At, B1); PG8_BAR; PG8_SCHED;
.LBB0_18:
	s_andn2_b64 vcc, exec, s[24:25]
	s_cbranch_vccnz .Lz_G1A
	s_add_u32 s4, s38, 0x80
	s_addc_u32 s5, s39, 0
	s_add_u32 s0, s36, 0x100
	s_addc_u32 s1, s37, 0
	s_mov_b32 s36, 0
	ds_read_b128 v[128:131], v165
	ds_read_b128 v[146:149], v165 offset:1024
	ds_read_b128 v[150:153], v165 offset:2048
	ds_read_b128 v[154:157], v165 offset:3072
	ds_read_b128 v[158:161], v166
	ds_read_b128 v[172:175], v166 offset:1024
	ds_read_b128 v[176:179], v166 offset:2048
	ds_read_b128 v[180:183], v166 offset:3072
	s_add_i32 s38, s36, 2
	s_add_u32 s33, s4, 0x80
	s_addc_u32 s37, s5, 0
	s_cmp_eq_u32 s57, s36
	s_cselect_b32 s36, s30, s33
	s_cselect_b32 s37, s31, s37
	s_cselect_b32 s71, s35, s1
	s_cselect_b32 s70, s34, s0
	v_lshl_add_u64 v[216:217], s[4:5], 0, v[140:141]
	s_add_i32 m0, s47, 0xc000
	ds_read_b128 v[184:187], v167
	ds_read_b128 v[188:191], v167 offset:1024
	ds_read_b128 v[192:195], v167 offset:2048
	ds_read_b128 v[196:199], v167 offset:3072
	ds_read_b128 v[200:203], v167 offset:4096
	ds_read_b128 v[204:207], v167 offset:5120
	ds_read_b128 v[208:211], v167 offset:6144
	ds_read_b128 v[212:215], v167 offset:7168
	global_load_lds_dwordx4 v[216:217], off
	v_lshl_add_u64 v[216:217], s[4:5], 0, v[142:143]
	s_add_i32 m0, s47, 0xe000
	s_nop 0
	global_load_lds_dwordx4 v[216:217], off
	s_waitcnt vmcnt(8)
	s_waitcnt lgkmcnt(0)
	s_setprio 1
	s_barrier
	v_mfma_f32_16x16x32_bf16 v[124:127], v[128:131], v[184:187], 0
	v_mfma_f32_16x16x32_bf16 v[120:123], v[150:153], v[184:187], 0
	v_mfma_f32_16x16x32_bf16 v[108:111], v[128:131], v[192:195], 0
	v_mfma_f32_16x16x32_bf16 v[104:107], v[150:153], v[192:195], 0
	v_mfma_f32_16x16x32_bf16 v[92:95], v[128:131], v[200:203], 0
	v_mfma_f32_16x16x32_bf16 v[88:91], v[150:153], v[200:203], 0
	v_mfma_f32_16x16x32_bf16 v[76:79], v[128:131], v[208:211], 0
	v_mfma_f32_16x16x32_bf16 v[72:75], v[150:153], v[208:211], 0
	v_mfma_f32_16x16x32_bf16 v[124:127], v[146:149], v[188:191], v[124:127]
	v_mfma_f32_16x16x32_bf16 v[120:123], v[154:157], v[188:191], v[120:123]
	v_mfma_f32_16x16x32_bf16 v[108:111], v[146:149], v[196:199], v[108:111]
	v_mfma_f32_16x16x32_bf16 v[104:107], v[154:157], v[196:199], v[104:107]
	v_mfma_f32_16x16x32_bf16 v[92:95], v[146:149], v[204:207], v[92:95]
	v_mfma_f32_16x16x32_bf16 v[88:91], v[154:157], v[204:207], v[88:91]
	v_mfma_f32_16x16x32_bf16 v[76:79], v[146:149], v[212:215], v[76:79]
	v_mfma_f32_16x16x32_bf16 v[72:75], v[154:157], v[212:215], v[72:75]
	v_mfma_f32_16x16x32_bf16 v[116:119], v[158:161], v[184:187], 0
	v_mfma_f32_16x16x32_bf16 v[112:115], v[176:179], v[184:187], 0
	v_mfma_f32_16x16x32_bf16 v[100:103], v[158:161], v[192:195], 0
	v_mfma_f32_16x16x32_bf16 v[96:99], v[176:179], v[192:195], 0
	v_mfma_f32_16x16x32_bf16 v[84:87], v[158:161], v[200:203], 0
	v_mfma_f32_16x16x32_bf16 v[80:83], v[176:179], v[200:203], 0
	v_mfma_f32_16x16x32_bf16 v[68:71], v[158:161], v[208:211], 0
	v_mfma_f32_16x16x32_bf16 v[64:67], v[176:179], v[208:211], 0
	v_mfma_f32_16x16x32_bf16 v[116:119], v[172:175], v[188:191], v[116:119]
	v_mfma_f32_16x16x32_bf16 v[112:115], v[180:183], v[188:191], v[112:115]
	v_mfma_f32_16x16x32_bf16 v[100:103], v[172:175], v[196:199], v[100:103]
	v_mfma_f32_16x16x32_bf16 v[96:99], v[180:183], v[196:199], v[96:99]
	v_mfma_f32_16x16x32_bf16 v[84:87], v[172:175], v[204:207], v[84:87]
	v_mfma_f32_16x16x32_bf16 v[80:83], v[180:183], v[204:207], v[80:83]
	v_mfma_f32_16x16x32_bf16 v[68:71], v[172:175], v[212:215], v[68:71]
	v_mfma_f32_16x16x32_bf16 v[64:67], v[180:183], v[212:215], v[64:67]
	s_barrier
	s_setprio 0
	s_add_i32 s33, s60, s40
	v_lshl_add_u64 v[216:217], s[70:71], 0, v[136:137]
	s_mov_b32 m0, s33
	ds_read_b128 v[184:187], v167 offset:16384
	ds_read_b128 v[188:191], v167 offset:17408
	ds_read_b128 v[192:195], v167 offset:18432
	ds_read_b128 v[196:199], v167 offset:19456
	ds_read_b128 v[200:203], v167 offset:20480
	ds_read_b128 v[204:207], v167 offset:21504
	ds_read_b128 v[208:211], v167 offset:22528
	ds_read_b128 v[212:215], v167 offset:23552
	global_load_lds_dwordx4 v[216:217], off
	s_add_i32 m0, s33, 0x2000
	v_lshl_add_u64 v[218:219], s[70:71], 0, v[132:133]
	s_add_u32 s70, s70, s6
	s_addc_u32 s71, s71, s7
	s_add_i32 s33, s61, s40
	global_load_lds_dwordx4 v[218:219], off
	v_lshl_add_u64 v[220:221], s[70:71], 0, v[136:137]
	s_mov_b32 m0, s33
	v_lshl_add_u64 v[222:223], s[70:71], 0, v[132:133]
	global_load_lds_dwordx4 v[220:221], off
	s_add_i32 m0, s33, 0x2000
	v_lshl_add_u64 v[224:225], s[36:37], 0, v[138:139]
	global_load_lds_dwordx4 v[222:223], off
	s_mov_b32 m0, s47
	v_lshl_add_u64 v[226:227], s[36:37], 0, v[134:135]
	global_load_lds_dwordx4 v[224:225], off
	s_mov_b32 m0, s49
	s_nop 0
	global_load_lds_dwordx4 v[226:227], off
	s_waitcnt vmcnt(8)
	s_waitcnt lgkmcnt(0)
	s_setprio 1
	s_barrier
; #define PG8_STAGE(bufoff, gbase, voff) do { _Pragma("unroll") for (int _i = 0; _i < 2; ++_i) \
;         __builtin_amdgcn_global_load_lds((const unsigned*)((const char*)(gbase) + (voff)[_i]), (PG8_LAS unsigned*)(lds + (bufoff) + ldsw + _i * 8192), 16, 0, 0); } while (0)
; #define PG8_LDA(dst, b, h) do { _Pragma("unroll") for (int m = 0; m < 4; ++m) _Pragma("unroll") for (int k = 0; k < 2; ++k) dst[m][k] = *(const PG8_LAS bf16x8*)(lds + PG8_SA(b, h) + aoff + m * 2048 + k * 1024); } while (0)
; #define PG8_LDB(dst, b, h) do { _Pragma("unroll") for (int n = 0; n < 2; ++n) _Pragma("unroll") for (int k = 0; k < 2; ++k) dst[n][k] = *(const PG8_LAS bf16x8*)(lds + PG8_SB(b, h) + boff + n * 2048 + k * 1024); } while (0)
; #define PG8_MMA(ai, bj, At, Bt) do { __builtin_amdgcn_s_setprio(1); _Pragma("unroll") for (int m = 0; m < 4; ++m) _Pragma("unroll") for (int n = 0; n < 2; ++n) _Pragma("unroll") for (int k = 0; k < 2; ++k) \
;         acc[ai][bj][m][n] = __builtin_amdgcn_mfma_f32_16x16x32_bf16(Bt[n][k], At[m][k], acc[ai][bj][m][n], 0, 0, 0); __builtin_amdgcn_s_setprio(0); } while (0)
; #define PG8_BAR __builtin_amdgcn_s_barrier()
; template <class Epi, class Sched, bool ALIGN_EPI = false, bool SP2 = false>
; __device__ __forceinline__ void gemm_phase(PG8_LAS unsigned char* lds, const Gemm g, const Sched& S, const Epi& E, const int wid) {
;     ...
;             PG8_LDB(B0, 0, 0); PG8_LDB(B1, 0, 1); PG8_SCHED; PG8_LDA(At, 0, 0); PG8_STAGE(PG8_SA(1, 1), a1 + hstep, voffA);
;             PG8_WAIT_V(8); PG8_WAIT_L(0); PG8_BAR; PG8_MMA(0, 0, At, B0); PG8_MMA(0, 1, At, B1); PG8_BAR; PG8_SCHED;
;             PG8_LDA(At, 0, 1); PG8_STAGE(PG8_SB(0, 0), b2, voffB); PG8_STAGE(PG8_SB(0, 1), b2 + hstep, voffB); PG8_STAGE(PG8_SA(0, 0), a2, voffA);
;             PG8_WAIT_V(8); PG8_WAIT_L(0); PG8_BAR; PG8_MMA(1, 0, At, B0); PG8_MMA(1, 1, At, B1); PG8_BAR; PG8_SCHED;
;             PG8_LDB(B0, 1, 0); PG8_LDB(B1, 1, 1); PG8_SCHED; PG8_LDA(At, 1, 0); PG8_STAGE(PG8_SA(0, 1), a2 + hstep, voffA);
;             PG8_WAIT_V(8); PG8_WAIT_L(0); PG8_BAR; PG8_MMA(0, 0, At, B0); PG8_MMA(0, 1, At, B1); PG8_BAR; PG8_SCHED;
;             PG8_LDA(At, 1, 1); PG8_STAGE(PG8_SB(1, 0), b3, voffB); PG8_STAGE(PG8_SB(1, 1), b3 + hstep, voffB); PG8_STAGE(PG8_SA(1, 0), a3, voffA);
;             PG8_WAIT_V(8); PG8_WAIT_L(0); PG8_BAR; PG8_MMA(1, 0, At, B0); PG8_MMA(1, 1, At, B1); PG8_BAR; PG8_SCHED;
	v_mfma_f32_16x16x32_bf16 v[60:63], v[128:131], v[184:187], 0
	v_mfma_f32_16x16x32_bf16 v[56:59], v[150:153], v[184:187], 0
	v_mfma_f32_16x16x32_bf16 v[44:47], v[128:131], v[192:195], 0
	v_mfma_f32_16x16x32_bf16 v[40:43], v[150:153], v[192:195], 0
	v_mfma_f32_16x16x32_bf16 v[28:31], v[128:131], v[200:203], 0
	v_mfma_f32_16x16x32_bf16 v[24:27], v[150:153], v[200:203], 0
	v_mfma_f32_16x16x32_bf16 v[12:15], v[128:131], v[208:211], 0
	v_mfma_f32_16x16x32_bf16 v[8:11], v[150:153], v[208:211], 0
	v_mfma_f32_16x16x32_bf16 v[60:63], v[146:149], v[188:191], v[60:63]
	v_mfma_f32_16x16x32_bf16 v[56:59], v[154:157], v[188:191], v[56:59]
	v_mfma_f32_16x16x32_bf16 v[44:47], v[146:149], v[196:199], v[44:47]
	v_mfma_f32_16x16x32_bf16 v[40:43], v[154:157], v[196:199], v[40:43]
	v_mfma_f32_16x16x32_bf16 v[28:31], v[146:149], v[204:207], v[28:31]
	v_mfma_f32_16x16x32_bf16 v[24:27], v[154:157], v[204:207], v[24:27]
	v_mfma_f32_16x16x32_bf16 v[12:15], v[146:149], v[212:215], v[12:15]
	v_mfma_f32_16x16x32_bf16 v[8:11], v[154:157], v[212:215], v[8:11]
	v_mfma_f32_16x16x32_bf16 v[52:55], v[158:161], v[184:187], 0
	v_mfma_f32_16x16x32_bf16 v[48:51], v[176:179], v[184:187], 0
	v_mfma_f32_16x16x32_bf16 v[36:39], v[158:161], v[192:195], 0
	v_mfma_f32_16x16x32_bf16 v[32:35], v[176:179], v[192:195], 0
	v_mfma_f32_16x16x32_bf16 v[20:23], v[158:161], v[200:203], 0
	v_mfma_f32_16x16x32_bf16 v[16:19], v[176:179], v[200:203], 0
	v_mfma_f32_16x16x32_bf16 v[4:7], v[158:161], v[208:211], 0
	v_mfma_f32_16x16x32_bf16 v[0:3], v[176:179], v[208:211], 0
	v_mfma_f32_16x16x32_bf16 v[52:55], v[172:175], v[188:191], v[52:55]
	v_mfma_f32_16x16x32_bf16 v[48:51], v[180:183], v[188:191], v[48:51]
	v_mfma_f32_16x16x32_bf16 v[36:39], v[172:175], v[196:199], v[36:39]
	v_mfma_f32_16x16x32_bf16 v[32:35], v[180:183], v[196:199], v[32:35]
	v_mfma_f32_16x16x32_bf16 v[20:23], v[172:175], v[204:207], v[20:23]
	v_mfma_f32_16x16x32_bf16 v[16:19], v[180:183], v[204:207], v[16:19]
	v_mfma_f32_16x16x32_bf16 v[4:7], v[172:175], v[212:215], v[4:7]
	v_mfma_f32_16x16x32_bf16 v[0:3], v[180:183], v[212:215], v[0:3]
	s_barrier
	s_setprio 0
	s_add_i32 s33, 0, 0x18000
	s_add_i32 s39, 0, 0x1c000
	v_add_u32_e32 v154, s33, v164
	v_add_u32_e32 v180, s39, v164
	ds_read_b128 v[128:131], v154
	ds_read_b128 v[146:149], v154 offset:1024
	ds_read_b128 v[150:153], v154 offset:2048
	ds_read_b128 v[154:157], v154 offset:3072
	ds_read_b128 v[158:161], v180
	ds_read_b128 v[172:175], v180 offset:1024
	ds_read_b128 v[176:179], v180 offset:2048
	ds_read_b128 v[180:183], v180 offset:3072
	s_add_u32 s36, s36, s6
	s_addc_u32 s37, s37, s7
	s_mov_b32 m0, s50
	v_lshl_add_u64 v[228:229], s[36:37], 0, v[138:139]
	ds_read_b128 v[184:187], v167 offset:32768
	ds_read_b128 v[188:191], v167 offset:33792
	ds_read_b128 v[192:195], v167 offset:34816
	ds_read_b128 v[196:199], v167 offset:35840
	ds_read_b128 v[200:203], v167 offset:36864
	ds_read_b128 v[204:207], v167 offset:37888
	ds_read_b128 v[208:211], v167 offset:38912
	ds_read_b128 v[212:215], v167 offset:39936
	global_load_lds_dwordx4 v[228:229], off
	v_lshl_add_u64 v[228:229], s[36:37], 0, v[134:135]
	s_mov_b32 m0, s51
	s_nop 0
	global_load_lds_dwordx4 v[228:229], off
	s_waitcnt vmcnt(8)
	s_waitcnt lgkmcnt(0)
	s_setprio 1
	s_barrier
	v_mfma_f32_16x16x32_bf16 v[124:127], v[128:131], v[184:187], v[124:127]
	v_mfma_f32_16x16x32_bf16 v[120:123], v[150:153], v[184:187], v[120:123]
	v_mfma_f32_16x16x32_bf16 v[108:111], v[128:131], v[192:195], v[108:111]
	v_mfma_f32_16x16x32_bf16 v[104:107], v[150:153], v[192:195], v[104:107]
	v_mfma_f32_16x16x32_bf16 v[92:95], v[128:131], v[200:203], v[92:95]
	v_mfma_f32_16x16x32_bf16 v[88:91], v[150:153], v[200:203], v[88:91]
	v_mfma_f32_16x16x32_bf16 v[76:79], v[128:131], v[208:211], v[76:79]
	v_mfma_f32_16x16x32_bf16 v[72:75], v[150:153], v[208:211], v[72:75]
	v_mfma_f32_16x16x32_bf16 v[124:127], v[146:149], v[188:191], v[124:127]
	v_mfma_f32_16x16x32_bf16 v[120:123], v[154:157], v[188:191], v[120:123]
	v_mfma_f32_16x16x32_bf16 v[108:111], v[146:149], v[196:199], v[108:111]
	v_mfma_f32_16x16x32_bf16 v[104:107], v[154:157], v[196:199], v[104:107]
	v_mfma_f32_16x16x32_bf16 v[92:95], v[146:149], v[204:207], v[92:95]
	v_mfma_f32_16x16x32_bf16 v[88:91], v[154:157], v[204:207], v[88:91]
	v_mfma_f32_16x16x32_bf16 v[76:79], v[146:149], v[212:215], v[76:79]
	v_mfma_f32_16x16x32_bf16 v[72:75], v[154:157], v[212:215], v[72:75]
	v_mfma_f32_16x16x32_bf16 v[116:119], v[158:161], v[184:187], v[116:119]
	v_mfma_f32_16x16x32_bf16 v[112:115], v[176:179], v[184:187], v[112:115]
	v_mfma_f32_16x16x32_bf16 v[100:103], v[158:161], v[192:195], v[100:103]
	v_mfma_f32_16x16x32_bf16 v[96:99], v[176:179], v[192:195], v[96:99]
	v_mfma_f32_16x16x32_bf16 v[84:87], v[158:161], v[200:203], v[84:87]
	v_mfma_f32_16x16x32_bf16 v[80:83], v[176:179], v[200:203], v[80:83]
	v_mfma_f32_16x16x32_bf16 v[68:71], v[158:161], v[208:211], v[68:71]
	v_mfma_f32_16x16x32_bf16 v[64:67], v[176:179], v[208:211], v[64:67]
	v_mfma_f32_16x16x32_bf16 v[116:119], v[172:175], v[188:191], v[116:119]
	v_mfma_f32_16x16x32_bf16 v[112:115], v[180:183], v[188:191], v[112:115]
	v_mfma_f32_16x16x32_bf16 v[100:103], v[172:175], v[196:199], v[100:103]
	v_mfma_f32_16x16x32_bf16 v[96:99], v[180:183], v[196:199], v[96:99]
	v_mfma_f32_16x16x32_bf16 v[84:87], v[172:175], v[204:207], v[84:87]
	v_mfma_f32_16x16x32_bf16 v[80:83], v[180:183], v[204:207], v[80:83]
	v_mfma_f32_16x16x32_bf16 v[68:71], v[172:175], v[212:215], v[68:71]
	v_mfma_f32_16x16x32_bf16 v[64:67], v[180:183], v[212:215], v[64:67]
	s_barrier
; #define PG8_STAGE(bufoff, gbase, voff) do { _Pragma("unroll") for (int _i = 0; _i < 2; ++_i) \
;         __builtin_amdgcn_global_load_lds((const unsigned*)((const char*)(gbase) + (voff)[_i]), (PG8_LAS unsigned*)(lds + (bufoff) + ldsw + _i * 8192), 16, 0, 0); } while (0)
; #define PG8_LDA(dst, b, h) do { _Pragma("unroll") for (int m = 0; m < 4; ++m) _Pragma("unroll") for (int k = 0; k < 2; ++k) dst[m][k] = *(const PG8_LAS bf16x8*)(lds + PG8_SA(b, h) + aoff + m * 2048 + k * 1024); } while (0)
; #define PG8_WAIT_V(n) asm volatile("s_waitcnt vmcnt(" #n ")" ::: "memory")
; #define PG8_WAIT_L(n) asm volatile("s_waitcnt lgkmcnt(" #n ")" ::: "memory")
; #define PG8_BAR __builtin_amdgcn_s_barrier()
; template <class Epi, class Sched, bool ALIGN_EPI = false, bool SP2 = false>
; __device__ __forceinline__ void gemm_phase(PG8_LAS unsigned char* lds, const Gemm g, const Sched& S, const Epi& E, const int wid) {
;     ...
;         for (int t = 0; t < nt; t += 2) {
;             const bool last = (t == nt - 2);
;             const char* a1 = cA + (size_t)(t + 1) * kstep;
;             const char* a2 = last ? nA : cA + (size_t)(t + 2) * kstep; const char* b2 = last ? nB : cB + (size_t)(t + 2) * kstep;
;             const char* a3 = a2 + kstep; const char* b3 = b2 + kstep;
;             if (last && has_next) S.a_ready(nxt);
;             if constexpr (SP2) {
;             PG8_LDB(B0, 0, 0); PG8_LDB(B1, 0, 1); PG8_SCHED; PG8_LDA(At, 0, 0); PG8_STAGE(PG8_SA(1, 1), a1 + hstep, voffA);
;             PG8_WAIT_V(8); PG8_WAIT_L(0); PG8_BAR; PG8_MMA(0, 0, At, B0); PG8_MMA(0, 1, At, B1); PG8_BAR; PG8_SCHED;
;             PG8_LDA(At, 0, 1); PG8_STAGE(PG8_SB(0, 0), b2, voffB); PG8_STAGE(PG8_SB(0, 1), b2 + hstep, voffB); PG8_STAGE(PG8_SA(0, 0), a2, voffA);
;             PG8_WAIT_V(8); PG8_WAIT_L(0); PG8_BAR; PG8_MMA(1, 0, At, B0); PG8_MMA(1, 1, At, B1); PG8_BAR; PG8_SCHED;
;             PG8_LDB(B0, 1, 0); PG8_LDB(B1, 1, 1); PG8_SCHED; PG8_LDA(At, 1, 0); PG8_STAGE(PG8_SA(0, 1), a2 + hstep, voffA);
;             PG8_WAIT_V(8); PG8_WAIT_L(0); PG8_BAR; PG8_MMA(0, 0, At, B0); PG8_MMA(0, 1, At, B1); PG8_BAR; PG8_SCHED;
;             PG8_LDA(At, 1, 1); PG8_STAGE(PG8_SB(1, 0), b3, voffB); PG8_STAGE(PG8_SB(1, 1), b3 + hstep, voffB); PG8_STAGE(PG8_SA(1, 0), a3, voffA);
;             PG8_WAIT_V(8); PG8_WAIT_L(0); PG8_BAR; PG8_MMA(1, 0, At, B0); PG8_MMA(1, 1, At, B1); PG8_BAR; PG8_SCHED;
	s_setprio 0
	s_add_i32 s33, s33, s40
	v_lshl_add_u64 v[216:217], v[216:217], 0, s[22:23]
	s_mov_b32 m0, s33
	ds_read_b128 v[184:187], v167 offset:49152
	ds_read_b128 v[188:191], v167 offset:50176
	ds_read_b128 v[192:195], v167 offset:51200
	ds_read_b128 v[196:199], v167 offset:52224
	ds_read_b128 v[200:203], v167 offset:53248
	ds_read_b128 v[204:207], v167 offset:54272
	ds_read_b128 v[208:211], v167 offset:55296
	ds_read_b128 v[212:215], v167 offset:56320
	global_load_lds_dwordx4 v[216:217], off
	v_lshl_add_u64 v[216:217], v[218:219], 0, s[22:23]
	s_add_i32 m0, s33, 0x2000
	s_add_i32 s33, s39, s40
	global_load_lds_dwordx4 v[216:217], off
	v_lshl_add_u64 v[216:217], v[220:221], 0, s[22:23]
	s_mov_b32 m0, s33
	s_nop 0
	global_load_lds_dwordx4 v[216:217], off
	v_lshl_add_u64 v[216:217], v[222:223], 0, s[22:23]
	s_add_i32 m0, s33, 0x2000
	s_nop 0
	global_load_lds_dwordx4 v[216:217], off
	v_lshl_add_u64 v[216:217], v[224:225], 0, s[22:23]
	s_mov_b32 m0, s53
	s_nop 0
	global_load_lds_dwordx4 v[216:217], off
	v_lshl_add_u64 v[216:217], v[226:227], 0, s[22:23]
	s_mov_b32 m0, s54
	s_nop 0
	global_load_lds_dwordx4 v[216:217], off
	s_waitcnt vmcnt(8)
	s_waitcnt lgkmcnt(0)
	s_setprio 1
	s_barrier
	v_mfma_f32_16x16x32_bf16 v[60:63], v[128:131], v[184:187], v[60:63]
	v_mfma_f32_16x16x32_bf16 v[56:59], v[150:153], v[184:187], v[56:59]
	v_mfma_f32_16x16x32_bf16 v[44:47], v[128:131], v[192:195], v[44:47]
	v_mfma_f32_16x16x32_bf16 v[40:43], v[150:153], v[192:195], v[40:43]
	v_mfma_f32_16x16x32_bf16 v[28:31], v[128:131], v[200:203], v[28:31]
	v_mfma_f32_16x16x32_bf16 v[24:27], v[150:153], v[200:203], v[24:27]
	v_mfma_f32_16x16x32_bf16 v[12:15], v[128:131], v[208:211], v[12:15]
	v_mfma_f32_16x16x32_bf16 v[8:11], v[150:153], v[208:211], v[8:11]
	v_mfma_f32_16x16x32_bf16 v[60:63], v[146:149], v[188:191], v[60:63]
	v_mfma_f32_16x16x32_bf16 v[56:59], v[154:157], v[188:191], v[56:59]
	v_mfma_f32_16x16x32_bf16 v[44:47], v[146:149], v[196:199], v[44:47]
	v_mfma_f32_16x16x32_bf16 v[40:43], v[154:157], v[196:199], v[40:43]
	v_mfma_f32_16x16x32_bf16 v[28:31], v[146:149], v[204:207], v[28:31]
	v_mfma_f32_16x16x32_bf16 v[24:27], v[154:157], v[204:207], v[24:27]
	v_mfma_f32_16x16x32_bf16 v[12:15], v[146:149], v[212:215], v[12:15]
	v_mfma_f32_16x16x32_bf16 v[8:11], v[154:157], v[212:215], v[8:11]
	v_mfma_f32_16x16x32_bf16 v[52:55], v[158:161], v[184:187], v[52:55]
	v_mfma_f32_16x16x32_bf16 v[48:51], v[176:179], v[184:187], v[48:51]
	v_mfma_f32_16x16x32_bf16 v[36:39], v[158:161], v[192:195], v[36:39]
	v_mfma_f32_16x16x32_bf16 v[32:35], v[176:179], v[192:195], v[32:35]
	v_mfma_f32_16x16x32_bf16 v[20:23], v[158:161], v[200:203], v[20:23]
	v_mfma_f32_16x16x32_bf16 v[16:19], v[176:179], v[200:203], v[16:19]
	v_mfma_f32_16x16x32_bf16 v[4:7], v[158:161], v[208:211], v[4:7]
	v_mfma_f32_16x16x32_bf16 v[0:3], v[176:179], v[208:211], v[0:3]
	v_mfma_f32_16x16x32_bf16 v[52:55], v[172:175], v[188:191], v[52:55]
	v_mfma_f32_16x16x32_bf16 v[48:51], v[180:183], v[188:191], v[48:51]
	v_mfma_f32_16x16x32_bf16 v[36:39], v[172:175], v[196:199], v[36:39]
	v_mfma_f32_16x16x32_bf16 v[32:35], v[180:183], v[196:199], v[32:35]
	v_mfma_f32_16x16x32_bf16 v[20:23], v[172:175], v[204:207], v[20:23]
	v_mfma_f32_16x16x32_bf16 v[16:19], v[180:183], v[204:207], v[16:19]
	v_mfma_f32_16x16x32_bf16 v[4:7], v[172:175], v[212:215], v[4:7]
	v_mfma_f32_16x16x32_bf16 v[0:3], v[180:183], v[212:215], v[0:3]
	s_barrier
	s_setprio 0
	s_add_u32 s4, s4, 0x100
	s_addc_u32 s5, s5, 0
	s_add_u32 s0, s0, 0x100
	s_addc_u32 s1, s1, 0
	s_cmp_ge_i32 s38, s55
	s_mov_b32 s36, s38
	s_cbranch_scc1 .LBB0_21
.LBB0_20:
	ds_read_b128 v[128:131], v165
	ds_read_b128 v[146:149], v165 offset:1024
	ds_read_b128 v[150:153], v165 offset:2048
	ds_read_b128 v[154:157], v165 offset:3072
	ds_read_b128 v[158:161], v166
	ds_read_b128 v[172:175], v166 offset:1024
	ds_read_b128 v[176:179], v166 offset:2048
	ds_read_b128 v[180:183], v166 offset:3072
	s_add_i32 s38, s36, 2
	s_add_u32 s33, s4, 0x80
	s_addc_u32 s37, s5, 0
	s_cmp_eq_u32 s57, s36
	s_cselect_b32 s36, s30, s33
	s_cselect_b32 s37, s31, s37
	s_cselect_b32 s71, s35, s1
	s_cselect_b32 s70, s34, s0
	v_lshl_add_u64 v[216:217], s[4:5], 0, v[140:141]
	s_add_i32 m0, s47, 0xc000
	ds_read_b128 v[184:187], v167
	ds_read_b128 v[188:191], v167 offset:1024
	ds_read_b128 v[192:195], v167 offset:2048
	ds_read_b128 v[196:199], v167 offset:3072
	ds_read_b128 v[200:203], v167 offset:4096
	ds_read_b128 v[204:207], v167 offset:5120
	ds_read_b128 v[208:211], v167 offset:6144
	ds_read_b128 v[212:215], v167 offset:7168
	global_load_lds_dwordx4 v[216:217], off
	v_lshl_add_u64 v[216:217], s[4:5], 0, v[142:143]
	s_add_i32 m0, s47, 0xe000
	s_nop 0
	global_load_lds_dwordx4 v[216:217], off
	s_waitcnt vmcnt(8)
	s_waitcnt lgkmcnt(0)
	s_setprio 1
	s_barrier
; #define PG8_STAGE(bufoff, gbase, voff) do { _Pragma("unroll") for (int _i = 0; _i < 2; ++_i) \
;         __builtin_amdgcn_global_load_lds((const unsigned*)((const char*)(gbase) + (voff)[_i]), (PG8_LAS unsigned*)(lds + (bufoff) + ldsw + _i * 8192), 16, 0, 0); } while (0)
; #define PG8_LDA(dst, b, h) do { _Pragma("unroll") for (int m = 0; m < 4; ++m) _Pragma("unroll") for (int k = 0; k < 2; ++k) dst[m][k] = *(const PG8_LAS bf16x8*)(lds + PG8_SA(b, h) + aoff + m * 2048 + k * 1024); } while (0)
; #define PG8_LDB(dst, b, h) do { _Pragma("unroll") for (int n = 0; n < 2; ++n) _Pragma("unroll") for (int k = 0; k < 2; ++k) dst[n][k] = *(const PG8_LAS bf16x8*)(lds + PG8_SB(b, h) + boff + n * 2048 + k * 1024); } while (0)
; #define PG8_MMA(ai, bj, At, Bt) do { __builtin_amdgcn_s_setprio(1); _Pragma("unroll") for (int m = 0; m < 4; ++m) _Pragma("unroll") for (int n = 0; n < 2; ++n) _Pragma("unroll") for (int k = 0; k < 2; ++k) \
;         acc[ai][bj][m][n] = __builtin_amdgcn_mfma_f32_16x16x32_bf16(Bt[n][k], At[m][k], acc[ai][bj][m][n], 0, 0, 0); __builtin_amdgcn_s_setprio(0); } while (0)
; #define PG8_BAR __builtin_amdgcn_s_barrier()
; template <class Epi, class Sched, bool ALIGN_EPI = false, bool SP2 = false>
; __device__ __forceinline__ void gemm_phase(PG8_LAS unsigned char* lds, const Gemm g, const Sched& S, const Epi& E, const int wid) {
;     ...
;             PG8_LDB(B0, 0, 0); PG8_LDB(B1, 0, 1); PG8_SCHED; PG8_LDA(At, 0, 0); PG8_STAGE(PG8_SA(1, 1), a1 + hstep, voffA);
;             PG8_WAIT_V(8); PG8_WAIT_L(0); PG8_BAR; PG8_MMA(0, 0, At, B0); PG8_MMA(0, 1, At, B1); PG8_BAR; PG8_SCHED;
;             PG8_LDA(At, 0, 1); PG8_STAGE(PG8_SB(0, 0), b2, voffB); PG8_STAGE(PG8_SB(0, 1), b2 + hstep, voffB); PG8_STAGE(PG8_SA(0, 0), a2, voffA);
;             PG8_WAIT_V(8); PG8_WAIT_L(0); PG8_BAR; PG8_MMA(1, 0, At, B0); PG8_MMA(1, 1, At, B1); PG8_BAR; PG8_SCHED;
;             PG8_LDB(B0, 1, 0); PG8_LDB(B1, 1, 1); PG8_SCHED; PG8_LDA(At, 1, 0); PG8_STAGE(PG8_SA(0, 1), a2 + hstep, voffA);
;             PG8_WAIT_V(8); PG8_WAIT_L(0); PG8_BAR; PG8_MMA(0, 0, At, B0); PG8_MMA(0, 1, At, B1); PG8_BAR; PG8_SCHED;
;             PG8_LDA(At, 1, 1); PG8_STAGE(PG8_SB(1, 0), b3, voffB); PG8_STAGE(PG8_SB(1, 1), b3 + hstep, voffB); PG8_STAGE(PG8_SA(1, 0), a3, voffA);
;             PG8_WAIT_V(8); PG8_WAIT_L(0); PG8_BAR; PG8_MMA(1, 0, At, B0); PG8_MMA(1, 1, At, B1); PG8_BAR; PG8_SCHED;
	v_mfma_f32_16x16x32_bf16 v[124:127], v[128:131], v[184:187], v[124:127]
	v_mfma_f32_16x16x32_bf16 v[120:123], v[150:153], v[184:187], v[120:123]
	v_mfma_f32_16x16x32_bf16 v[108:111], v[128:131], v[192:195], v[108:111]
	v_mfma_f32_16x16x32_bf16 v[104:107], v[150:153], v[192:195], v[104:107]
	v_mfma_f32_16x16x32_bf16 v[92:95], v[128:131], v[200:203], v[92:95]
	v_mfma_f32_16x16x32_bf16 v[88:91], v[150:153], v[200:203], v[88:91]
	v_mfma_f32_16x16x32_bf16 v[76:79], v[128:131], v[208:211], v[76:79]
	v_mfma_f32_16x16x32_bf16 v[72:75], v[150:153], v[208:211], v[72:75]
	v_mfma_f32_16x16x32_bf16 v[124:127], v[146:149], v[188:191], v[124:127]
	v_mfma_f32_16x16x32_bf16 v[120:123], v[154:157], v[188:191], v[120:123]
	v_mfma_f32_16x16x32_bf16 v[108:111], v[146:149], v[196:199], v[108:111]
	v_mfma_f32_16x16x32_bf16 v[104:107], v[154:157], v[196:199], v[104:107]
	v_mfma_f32_16x16x32_bf16 v[92:95], v[146:149], v[204:207], v[92:95]
	v_mfma_f32_16x16x32_bf16 v[88:91], v[154:157], v[204:207], v[88:91]
	v_mfma_f32_16x16x32_bf16 v[76:79], v[146:149], v[212:215], v[76:79]
	v_mfma_f32_16x16x32_bf16 v[72:75], v[154:157], v[212:215], v[72:75]
	v_mfma_f32_16x16x32_bf16 v[116:119], v[158:161], v[184:187], v[116:119]
	v_mfma_f32_16x16x32_bf16 v[112:115], v[176:179], v[184:187], v[112:115]
	v_mfma_f32_16x16x32_bf16 v[100:103], v[158:161], v[192:195], v[100:103]
	v_mfma_f32_16x16x32_bf16 v[96:99], v[176:179], v[192:195], v[96:99]
	v_mfma_f32_16x16x32_bf16 v[84:87], v[158:161], v[200:203], v[84:87]
	v_mfma_f32_16x16x32_bf16 v[80:83], v[176:179], v[200:203], v[80:83]
	v_mfma_f32_16x16x32_bf16 v[68:71], v[158:161], v[208:211], v[68:71]
	v_mfma_f32_16x16x32_bf16 v[64:67], v[176:179], v[208:211], v[64:67]
	v_mfma_f32_16x16x32_bf16 v[116:119], v[172:175], v[188:191], v[116:119]
	v_mfma_f32_16x16x32_bf16 v[112:115], v[180:183], v[188:191], v[112:115]
	v_mfma_f32_16x16x32_bf16 v[100:103], v[172:175], v[196:199], v[100:103]
	v_mfma_f32_16x16x32_bf16 v[96:99], v[180:183], v[196:199], v[96:99]
	v_mfma_f32_16x16x32_bf16 v[84:87], v[172:175], v[204:207], v[84:87]
	v_mfma_f32_16x16x32_bf16 v[80:83], v[180:183], v[204:207], v[80:83]
	v_mfma_f32_16x16x32_bf16 v[68:71], v[172:175], v[212:215], v[68:71]
	v_mfma_f32_16x16x32_bf16 v[64:67], v[180:183], v[212:215], v[64:67]
	s_barrier
	s_setprio 0
	s_add_i32 s33, s60, s40
	v_lshl_add_u64 v[216:217], s[70:71], 0, v[136:137]
	s_mov_b32 m0, s33
	ds_read_b128 v[184:187], v167 offset:16384
	ds_read_b128 v[188:191], v167 offset:17408
	ds_read_b128 v[192:195], v167 offset:18432
	ds_read_b128 v[196:199], v167 offset:19456
	ds_read_b128 v[200:203], v167 offset:20480
	ds_read_b128 v[204:207], v167 offset:21504
	ds_read_b128 v[208:211], v167 offset:22528
	ds_read_b128 v[212:215], v167 offset:23552
	global_load_lds_dwordx4 v[216:217], off
	s_add_i32 m0, s33, 0x2000
	v_lshl_add_u64 v[218:219], s[70:71], 0, v[132:133]
	s_add_u32 s70, s70, s6
	s_addc_u32 s71, s71, s7
	s_add_i32 s33, s61, s40
	global_load_lds_dwordx4 v[218:219], off
	v_lshl_add_u64 v[220:221], s[70:71], 0, v[136:137]
	s_mov_b32 m0, s33
	v_lshl_add_u64 v[222:223], s[70:71], 0, v[132:133]
	global_load_lds_dwordx4 v[220:221], off
	s_add_i32 m0, s33, 0x2000
	v_lshl_add_u64 v[224:225], s[36:37], 0, v[138:139]
	global_load_lds_dwordx4 v[222:223], off
	s_mov_b32 m0, s47
	v_lshl_add_u64 v[226:227], s[36:37], 0, v[134:135]
	global_load_lds_dwordx4 v[224:225], off
	s_mov_b32 m0, s49
	s_nop 0
	global_load_lds_dwordx4 v[226:227], off
	s_waitcnt vmcnt(8)
	s_waitcnt lgkmcnt(0)
	s_setprio 1
	s_barrier
	v_mfma_f32_16x16x32_bf16 v[60:63], v[128:131], v[184:187], v[60:63]
	v_mfma_f32_16x16x32_bf16 v[56:59], v[150:153], v[184:187], v[56:59]
	v_mfma_f32_16x16x32_bf16 v[44:47], v[128:131], v[192:195], v[44:47]
	v_mfma_f32_16x16x32_bf16 v[40:43], v[150:153], v[192:195], v[40:43]
	v_mfma_f32_16x16x32_bf16 v[28:31], v[128:131], v[200:203], v[28:31]
	v_mfma_f32_16x16x32_bf16 v[24:27], v[150:153], v[200:203], v[24:27]
	v_mfma_f32_16x16x32_bf16 v[12:15], v[128:131], v[208:211], v[12:15]
	v_mfma_f32_16x16x32_bf16 v[8:11], v[150:153], v[208:211], v[8:11]
	v_mfma_f32_16x16x32_bf16 v[60:63], v[146:149], v[188:191], v[60:63]
	v_mfma_f32_16x16x32_bf16 v[56:59], v[154:157], v[188:191], v[56:59]
	v_mfma_f32_16x16x32_bf16 v[44:47], v[146:149], v[196:199], v[44:47]
	v_mfma_f32_16x16x32_bf16 v[40:43], v[154:157], v[196:199], v[40:43]
	v_mfma_f32_16x16x32_bf16 v[28:31], v[146:149], v[204:207], v[28:31]
	v_mfma_f32_16x16x32_bf16 v[24:27], v[154:157], v[204:207], v[24:27]
	v_mfma_f32_16x16x32_bf16 v[12:15], v[146:149], v[212:215], v[12:15]
	v_mfma_f32_16x16x32_bf16 v[8:11], v[154:157], v[212:215], v[8:11]
	v_mfma_f32_16x16x32_bf16 v[52:55], v[158:161], v[184:187], v[52:55]
	v_mfma_f32_16x16x32_bf16 v[48:51], v[176:179], v[184:187], v[48:51]
	v_mfma_f32_16x16x32_bf16 v[36:39], v[158:161], v[192:195], v[36:39]
	v_mfma_f32_16x16x32_bf16 v[32:35], v[176:179], v[192:195], v[32:35]
	v_mfma_f32_16x16x32_bf16 v[20:23], v[158:161], v[200:203], v[20:23]
	v_mfma_f32_16x16x32_bf16 v[16:19], v[176:179], v[200:203], v[16:19]
	v_mfma_f32_16x16x32_bf16 v[4:7], v[158:161], v[208:211], v[4:7]
	v_mfma_f32_16x16x32_bf16 v[0:3], v[176:179], v[208:211], v[0:3]
	v_mfma_f32_16x16x32_bf16 v[52:55], v[172:175], v[188:191], v[52:55]
	v_mfma_f32_16x16x32_bf16 v[48:51], v[180:183], v[188:191], v[48:51]
	v_mfma_f32_16x16x32_bf16 v[36:39], v[172:175], v[196:199], v[36:39]
	v_mfma_f32_16x16x32_bf16 v[32:35], v[180:183], v[196:199], v[32:35]
	v_mfma_f32_16x16x32_bf16 v[20:23], v[172:175], v[204:207], v[20:23]
	v_mfma_f32_16x16x32_bf16 v[16:19], v[180:183], v[204:207], v[16:19]
	v_mfma_f32_16x16x32_bf16 v[4:7], v[172:175], v[212:215], v[4:7]
	v_mfma_f32_16x16x32_bf16 v[0:3], v[180:183], v[212:215], v[0:3]
	s_barrier
; #define PG8_STAGE(bufoff, gbase, voff) do { _Pragma("unroll") for (int _i = 0; _i < 2; ++_i) \
;         __builtin_amdgcn_global_load_lds((const unsigned*)((const char*)(gbase) + (voff)[_i]), (PG8_LAS unsigned*)(lds + (bufoff) + ldsw + _i * 8192), 16, 0, 0); } while (0)
; #define PG8_LDA(dst, b, h) do { _Pragma("unroll") for (int m = 0; m < 4; ++m) _Pragma("unroll") for (int k = 0; k < 2; ++k) dst[m][k] = *(const PG8_LAS bf16x8*)(lds + PG8_SA(b, h) + aoff + m * 2048 + k * 1024); } while (0)
; #define PG8_LDB(dst, b, h) do { _Pragma("unroll") for (int n = 0; n < 2; ++n) _Pragma("unroll") for (int k = 0; k < 2; ++k) dst[n][k] = *(const PG8_LAS bf16x8*)(lds + PG8_SB(b, h) + boff + n * 2048 + k * 1024); } while (0)
; template <class Epi, class Sched, bool ALIGN_EPI = false, bool SP2 = false>
; __device__ __forceinline__ void gemm_phase(PG8_LAS unsigned char* lds, const Gemm g, const Sched& S, const Epi& E, const int wid) {
;     ...
;         for (int t = 0; t < nt; t += 2) {
;             const bool last = (t == nt - 2);
;             const char* a1 = cA + (size_t)(t + 1) * kstep;
;             const char* a2 = last ? nA : cA + (size_t)(t + 2) * kstep; const char* b2 = last ? nB : cB + (size_t)(t + 2) * kstep;
;             const char* a3 = a2 + kstep; const char* b3 = b2 + kstep;
;             if (last && has_next) S.a_ready(nxt);
;     ...
;             PG8_LDB(B0, 0, 0); PG8_LDB(B1, 0, 1); PG8_SCHED; PG8_LDA(At, 0, 0); PG8_STAGE(PG8_SA(1, 1), a1 + hstep, voffA);
;             PG8_WAIT_V(8); PG8_WAIT_L(0); PG8_BAR; PG8_MMA(0, 0, At, B0); PG8_MMA(0, 1, At, B1); PG8_BAR; PG8_SCHED;
;             PG8_LDA(At, 0, 1); PG8_STAGE(PG8_SB(0, 0), b2, voffB); PG8_STAGE(PG8_SB(0, 1), b2 + hstep, voffB); PG8_STAGE(PG8_SA(0, 0), a2, voffA);
;             PG8_WAIT_V(8); PG8_WAIT_L(0); PG8_BAR; PG8_MMA(1, 0, At, B0); PG8_MMA(1, 1, At, B1); PG8_BAR; PG8_SCHED;
;             PG8_LDB(B0, 1, 0); PG8_LDB(B1, 1, 1); PG8_SCHED; PG8_LDA(At, 1, 0); PG8_STAGE(PG8_SA(0, 1), a2 + hstep, voffA);
;             PG8_WAIT_V(8); PG8_WAIT_L(0); PG8_BAR; PG8_MMA(0, 0, At, B0); PG8_MMA(0, 1, At, B1); PG8_BAR; PG8_SCHED;
;             PG8_LDA(At, 1, 1); PG8_STAGE(PG8_SB(1, 0), b3, voffB); PG8_STAGE(PG8_SB(1, 1), b3 + hstep, voffB); PG8_STAGE(PG8_SA(1, 0), a3, voffA);
;             PG8_WAIT_V(8); PG8_WAIT_L(0); PG8_BAR; PG8_MMA(1, 0, At, B0); PG8_MMA(1, 1, At, B1); PG8_BAR; PG8_SCHED;
	s_setprio 0
	s_add_i32 s33, 0, 0x18000
	s_add_i32 s39, 0, 0x1c000
	v_add_u32_e32 v154, s33, v164
	v_add_u32_e32 v180, s39, v164
	ds_read_b128 v[128:131], v154
	ds_read_b128 v[146:149], v154 offset:1024
	ds_read_b128 v[150:153], v154 offset:2048
	ds_read_b128 v[154:157], v154 offset:3072
	ds_read_b128 v[158:161], v180
	ds_read_b128 v[172:175], v180 offset:1024
	ds_read_b128 v[176:179], v180 offset:2048
	ds_read_b128 v[180:183], v180 offset:3072
	s_add_u32 s36, s36, s6
	s_addc_u32 s37, s37, s7
	s_mov_b32 m0, s50
	v_lshl_add_u64 v[228:229], s[36:37], 0, v[138:139]
	ds_read_b128 v[184:187], v167 offset:32768
	ds_read_b128 v[188:191], v167 offset:33792
	ds_read_b128 v[192:195], v167 offset:34816
	ds_read_b128 v[196:199], v167 offset:35840
	ds_read_b128 v[200:203], v167 offset:36864
	ds_read_b128 v[204:207], v167 offset:37888
	ds_read_b128 v[208:211], v167 offset:38912
	ds_read_b128 v[212:215], v167 offset:39936
	global_load_lds_dwordx4 v[228:229], off
	v_lshl_add_u64 v[228:229], s[36:37], 0, v[134:135]
	s_mov_b32 m0, s51
	s_nop 0
	global_load_lds_dwordx4 v[228:229], off
	s_waitcnt vmcnt(8)
	s_waitcnt lgkmcnt(0)
	s_setprio 1
	s_barrier
	v_mfma_f32_16x16x32_bf16 v[124:127], v[128:131], v[184:187], v[124:127]
	v_mfma_f32_16x16x32_bf16 v[120:123], v[150:153], v[184:187], v[120:123]
	v_mfma_f32_16x16x32_bf16 v[108:111], v[128:131], v[192:195], v[108:111]
	v_mfma_f32_16x16x32_bf16 v[104:107], v[150:153], v[192:195], v[104:107]
	v_mfma_f32_16x16x32_bf16 v[92:95], v[128:131], v[200:203], v[92:95]
	v_mfma_f32_16x16x32_bf16 v[88:91], v[150:153], v[200:203], v[88:91]
	v_mfma_f32_16x16x32_bf16 v[76:79], v[128:131], v[208:211], v[76:79]
	v_mfma_f32_16x16x32_bf16 v[72:75], v[150:153], v[208:211], v[72:75]
	v_mfma_f32_16x16x32_bf16 v[124:127], v[146:149], v[188:191], v[124:127]
	v_mfma_f32_16x16x32_bf16 v[120:123], v[154:157], v[188:191], v[120:123]
	v_mfma_f32_16x16x32_bf16 v[108:111], v[146:149], v[196:199], v[108:111]
	v_mfma_f32_16x16x32_bf16 v[104:107], v[154:157], v[196:199], v[104:107]
	v_mfma_f32_16x16x32_bf16 v[92:95], v[146:149], v[204:207], v[92:95]
	v_mfma_f32_16x16x32_bf16 v[88:91], v[154:157], v[204:207], v[88:91]
	v_mfma_f32_16x16x32_bf16 v[76:79], v[146:149], v[212:215], v[76:79]
	v_mfma_f32_16x16x32_bf16 v[72:75], v[154:157], v[212:215], v[72:75]
	v_mfma_f32_16x16x32_bf16 v[116:119], v[158:161], v[184:187], v[116:119]
	v_mfma_f32_16x16x32_bf16 v[112:115], v[176:179], v[184:187], v[112:115]
	v_mfma_f32_16x16x32_bf16 v[100:103], v[158:161], v[192:195], v[100:103]
	v_mfma_f32_16x16x32_bf16 v[96:99], v[176:179], v[192:195], v[96:99]
	v_mfma_f32_16x16x32_bf16 v[84:87], v[158:161], v[200:203], v[84:87]
	v_mfma_f32_16x16x32_bf16 v[80:83], v[176:179], v[200:203], v[80:83]
	v_mfma_f32_16x16x32_bf16 v[68:71], v[158:161], v[208:211], v[68:71]
	v_mfma_f32_16x16x32_bf16 v[64:67], v[176:179], v[208:211], v[64:67]
	v_mfma_f32_16x16x32_bf16 v[116:119], v[172:175], v[188:191], v[116:119]
	v_mfma_f32_16x16x32_bf16 v[112:115], v[180:183], v[188:191], v[112:115]
	v_mfma_f32_16x16x32_bf16 v[100:103], v[172:175], v[196:199], v[100:103]
	v_mfma_f32_16x16x32_bf16 v[96:99], v[180:183], v[196:199], v[96:99]
	v_mfma_f32_16x16x32_bf16 v[84:87], v[172:175], v[204:207], v[84:87]
	v_mfma_f32_16x16x32_bf16 v[80:83], v[180:183], v[204:207], v[80:83]
	v_mfma_f32_16x16x32_bf16 v[68:71], v[172:175], v[212:215], v[68:71]
	v_mfma_f32_16x16x32_bf16 v[64:67], v[180:183], v[212:215], v[64:67]
	s_barrier
	s_setprio 0
	s_add_i32 s33, s33, s40
	v_lshl_add_u64 v[216:217], v[216:217], 0, s[22:23]
	s_mov_b32 m0, s33
	ds_read_b128 v[184:187], v167 offset:49152
	ds_read_b128 v[188:191], v167 offset:50176
	ds_read_b128 v[192:195], v167 offset:51200
	ds_read_b128 v[196:199], v167 offset:52224
	ds_read_b128 v[200:203], v167 offset:53248
	ds_read_b128 v[204:207], v167 offset:54272
	ds_read_b128 v[208:211], v167 offset:55296
	ds_read_b128 v[212:215], v167 offset:56320
	global_load_lds_dwordx4 v[216:217], off
	v_lshl_add_u64 v[216:217], v[218:219], 0, s[22:23]
	s_add_i32 m0, s33, 0x2000
	s_add_i32 s33, s39, s40
	global_load_lds_dwordx4 v[216:217], off
	v_lshl_add_u64 v[216:217], v[220:221], 0, s[22:23]
	s_mov_b32 m0, s33
	s_nop 0
	global_load_lds_dwordx4 v[216:217], off
	v_lshl_add_u64 v[216:217], v[222:223], 0, s[22:23]
	s_add_i32 m0, s33, 0x2000
	s_nop 0
	global_load_lds_dwordx4 v[216:217], off
	v_lshl_add_u64 v[216:217], v[224:225], 0, s[22:23]
	s_mov_b32 m0, s53
	s_nop 0
	global_load_lds_dwordx4 v[216:217], off
	v_lshl_add_u64 v[216:217], v[226:227], 0, s[22:23]
	s_mov_b32 m0, s54
	s_nop 0
	global_load_lds_dwordx4 v[216:217], off
	s_waitcnt vmcnt(8)
	s_waitcnt lgkmcnt(0)
	s_setprio 1
	s_barrier
	v_mfma_f32_16x16x32_bf16 v[60:63], v[128:131], v[184:187], v[60:63]
	v_mfma_f32_16x16x32_bf16 v[56:59], v[150:153], v[184:187], v[56:59]
	v_mfma_f32_16x16x32_bf16 v[44:47], v[128:131], v[192:195], v[44:47]
	v_mfma_f32_16x16x32_bf16 v[40:43], v[150:153], v[192:195], v[40:43]
	v_mfma_f32_16x16x32_bf16 v[28:31], v[128:131], v[200:203], v[28:31]
	v_mfma_f32_16x16x32_bf16 v[24:27], v[150:153], v[200:203], v[24:27]
	v_mfma_f32_16x16x32_bf16 v[12:15], v[128:131], v[208:211], v[12:15]
	v_mfma_f32_16x16x32_bf16 v[8:11], v[150:153], v[208:211], v[8:11]
	v_mfma_f32_16x16x32_bf16 v[60:63], v[146:149], v[188:191], v[60:63]
	v_mfma_f32_16x16x32_bf16 v[56:59], v[154:157], v[188:191], v[56:59]
	v_mfma_f32_16x16x32_bf16 v[44:47], v[146:149], v[196:199], v[44:47]
	v_mfma_f32_16x16x32_bf16 v[40:43], v[154:157], v[196:199], v[40:43]
	v_mfma_f32_16x16x32_bf16 v[28:31], v[146:149], v[204:207], v[28:31]
	v_mfma_f32_16x16x32_bf16 v[24:27], v[154:157], v[204:207], v[24:27]
	v_mfma_f32_16x16x32_bf16 v[12:15], v[146:149], v[212:215], v[12:15]
	v_mfma_f32_16x16x32_bf16 v[8:11], v[154:157], v[212:215], v[8:11]
	v_mfma_f32_16x16x32_bf16 v[52:55], v[158:161], v[184:187], v[52:55]
	v_mfma_f32_16x16x32_bf16 v[48:51], v[176:179], v[184:187], v[48:51]
	v_mfma_f32_16x16x32_bf16 v[36:39], v[158:161], v[192:195], v[36:39]
	v_mfma_f32_16x16x32_bf16 v[32:35], v[176:179], v[192:195], v[32:35]
	v_mfma_f32_16x16x32_bf16 v[20:23], v[158:161], v[200:203], v[20:23]
	v_mfma_f32_16x16x32_bf16 v[16:19], v[176:179], v[200:203], v[16:19]
	v_mfma_f32_16x16x32_bf16 v[4:7], v[158:161], v[208:211], v[4:7]
	v_mfma_f32_16x16x32_bf16 v[0:3], v[176:179], v[208:211], v[0:3]
	v_mfma_f32_16x16x32_bf16 v[52:55], v[172:175], v[188:191], v[52:55]
	v_mfma_f32_16x16x32_bf16 v[48:51], v[180:183], v[188:191], v[48:51]
	v_mfma_f32_16x16x32_bf16 v[36:39], v[172:175], v[196:199], v[36:39]
	v_mfma_f32_16x16x32_bf16 v[32:35], v[180:183], v[196:199], v[32:35]
	v_mfma_f32_16x16x32_bf16 v[20:23], v[172:175], v[204:207], v[20:23]
	v_mfma_f32_16x16x32_bf16 v[16:19], v[180:183], v[204:207], v[16:19]
	v_mfma_f32_16x16x32_bf16 v[4:7], v[172:175], v[212:215], v[4:7]
	v_mfma_f32_16x16x32_bf16 v[0:3], v[180:183], v[212:215], v[0:3]
	s_barrier
	s_setprio 0
	s_add_u32 s4, s4, 0x100
	s_addc_u32 s5, s5, 0
	s_add_u32 s0, s0, 0x100
	s_addc_u32 s1, s1, 0
	s_cmp_ge_i32 s38, s55
	s_mov_b32 s36, s38
	s_cbranch_scc0 .LBB0_20

; #define PG8_STAGE(bufoff, gbase, voff) do { _Pragma("unroll") for (int _i = 0; _i < 2; ++_i) \
;         __builtin_amdgcn_global_load_lds((const unsigned*)((const char*)(gbase) + (voff)[_i]), (PG8_LAS unsigned*)(lds + (bufoff) + ldsw + _i * 8192), 16, 0, 0); } while (0)
; #define PG8_LDA(dst, b, h) do { _Pragma("unroll") for (int m = 0; m < 4; ++m) _Pragma("unroll") for (int k = 0; k < 2; ++k) dst[m][k] = *(const PG8_LAS bf16x8*)(lds + PG8_SA(b, h) + aoff + m * 2048 + k * 1024); } while (0)
; template <class Epi, class Sched, bool ALIGN_EPI = false, bool SP2 = false>
; __device__ __forceinline__ void gemm_phase(PG8_LAS unsigned char* lds, const Gemm g, const Sched& S, const Epi& E, const int wid) {
;     ...
;         const bool has_next = S.next(ui + 1, nxt);
;         const char* nA = has_next ? (const char*)g.A + (size_t)nxt.pm * tstep : cA; const char* nB = has_next ? (const char*)g.Bt + (size_t)nxt.pn * tstep : cB;
;         for (int t = 0; t < nt; t += 2) {
;             const bool last = (t == nt - 2);
;             const char* a1 = cA + (size_t)(t + 1) * kstep;
;             const char* a2 = last ? nA : cA + (size_t)(t + 2) * kstep; const char* b2 = last ? nB : cB + (size_t)(t + 2) * kstep;
;             const char* a3 = a2 + kstep; const char* b3 = b2 + kstep;
;             if (last && has_next) S.a_ready(nxt);
;             if constexpr (SP2) {
;             PG8_LDB(B0, 0, 0); PG8_LDB(B1, 0, 1); PG8_SCHED; PG8_LDA(At, 0, 0); PG8_STAGE(PG8_SA(1, 1), a1 + hstep, voffA);
;             PG8_WAIT_V(8); PG8_WAIT_L(0); PG8_BAR; PG8_MMA(0, 0, At, B0); PG8_MMA(0, 1, At, B1); PG8_BAR; PG8_SCHED;
;             PG8_LDA(At, 0, 1); PG8_STAGE(PG8_SB(0, 0), b2, voffB); PG8_STAGE(PG8_SB(0, 1), b2 + hstep, voffB); PG8_STAGE(PG8_SA(0, 0), a2, voffA);
;             PG8_WAIT_V(8); PG8_WAIT_L(0); PG8_BAR; PG8_MMA(1, 0, At, B0); PG8_MMA(1, 1, At, B1); PG8_BAR; PG8_SCHED;
;             PG8_LDB(B0, 1, 0); PG8_LDB(B1, 1, 1); PG8_SCHED; PG8_LDA(At, 1, 0); PG8_STAGE(PG8_SA(0, 1), a2 + hstep, voffA);
;             PG8_WAIT_V(8); PG8_WAIT_L(0); PG8_BAR; PG8_MMA(0, 0, At, B0); PG8_MMA(0, 1, At, B1); PG8_BAR; PG8_SCHED;
;             PG8_LDA(At, 1, 1); PG8_STAGE(PG8_SB(1, 0), b3, voffB); PG8_STAGE(PG8_SB(1, 1), b3 + hstep, voffB); PG8_STAGE(PG8_SA(1, 0), a3, voffA);
;             PG8_WAIT_V(8); PG8_WAIT_L(0); PG8_BAR; PG8_MMA(1, 0, At, B0); PG8_MMA(1, 1, At, B1); PG8_BAR; PG8_SCHED;
.LBB0_1098:
	s_andn2_b64 vcc, exec, s[28:29]
	s_cbranch_vccnz .Lz_G1B
	s_add_u32 s4, s8, 0x80
	s_addc_u32 s5, s9, 0
	s_add_u32 s0, s6, 0x100
	s_addc_u32 s1, s7, 0
	s_mov_b32 s6, 0
	ds_read_b128 v[44:47], v163
	ds_read_b128 v[52:55], v163 offset:1024
	ds_read_b128 v[60:63], v163 offset:2048
	ds_read_b128 v[68:71], v163 offset:3072
	ds_read_b128 v[166:169], v164
	ds_read_b128 v[170:173], v164 offset:1024
	ds_read_b128 v[174:177], v164 offset:2048
	ds_read_b128 v[178:181], v164 offset:3072
	s_add_i32 s8, s6, 2
	s_add_u32 s9, s4, 0x80
	s_addc_u32 s7, s5, 0
	s_cmp_eq_u32 s72, s6
	s_cselect_b32 s6, s48, s9
	s_cselect_b32 s7, s49, s7
	s_cselect_b32 s77, s51, s1
	s_cselect_b32 s76, s50, s0
	v_lshl_add_u64 v[158:159], s[4:5], 0, v[152:153]
	s_add_i32 m0, s63, 0xc000
	ds_read_b128 v[182:185], v165
	ds_read_b128 v[186:189], v165 offset:1024
	ds_read_b128 v[190:193], v165 offset:2048
	ds_read_b128 v[194:197], v165 offset:3072
	ds_read_b128 v[198:201], v165 offset:4096
	ds_read_b128 v[202:205], v165 offset:5120
	ds_read_b128 v[206:209], v165 offset:6144
	ds_read_b128 v[210:213], v165 offset:7168
	global_load_lds_dwordx4 v[158:159], off
	v_lshl_add_u64 v[158:159], s[4:5], 0, v[154:155]
	s_add_i32 m0, s63, 0xe000
	s_nop 0
	global_load_lds_dwordx4 v[158:159], off
	s_waitcnt vmcnt(8)
	s_waitcnt lgkmcnt(0)
	s_setprio 1
	s_barrier
	v_mfma_f32_16x16x32_bf16 v[140:143], v[44:47], v[182:185], 0
	v_mfma_f32_16x16x32_bf16 v[136:139], v[60:63], v[182:185], 0
	v_mfma_f32_16x16x32_bf16 v[124:127], v[44:47], v[190:193], 0
	v_mfma_f32_16x16x32_bf16 v[120:123], v[60:63], v[190:193], 0
	v_mfma_f32_16x16x32_bf16 v[108:111], v[44:47], v[198:201], 0
	v_mfma_f32_16x16x32_bf16 v[104:107], v[60:63], v[198:201], 0
	v_mfma_f32_16x16x32_bf16 v[92:95], v[44:47], v[206:209], 0
	v_mfma_f32_16x16x32_bf16 v[88:91], v[60:63], v[206:209], 0
	v_mfma_f32_16x16x32_bf16 v[140:143], v[52:55], v[186:189], v[140:143]
	v_mfma_f32_16x16x32_bf16 v[136:139], v[68:71], v[186:189], v[136:139]
	v_mfma_f32_16x16x32_bf16 v[124:127], v[52:55], v[194:197], v[124:127]
	v_mfma_f32_16x16x32_bf16 v[120:123], v[68:71], v[194:197], v[120:123]
	v_mfma_f32_16x16x32_bf16 v[108:111], v[52:55], v[202:205], v[108:111]
	v_mfma_f32_16x16x32_bf16 v[104:107], v[68:71], v[202:205], v[104:107]
	v_mfma_f32_16x16x32_bf16 v[92:95], v[52:55], v[210:213], v[92:95]
	v_mfma_f32_16x16x32_bf16 v[88:91], v[68:71], v[210:213], v[88:91]
	v_mfma_f32_16x16x32_bf16 v[132:135], v[166:169], v[182:185], 0
	v_mfma_f32_16x16x32_bf16 v[128:131], v[174:177], v[182:185], 0
	v_mfma_f32_16x16x32_bf16 v[116:119], v[166:169], v[190:193], 0
	v_mfma_f32_16x16x32_bf16 v[112:115], v[174:177], v[190:193], 0
	v_mfma_f32_16x16x32_bf16 v[100:103], v[166:169], v[198:201], 0
	v_mfma_f32_16x16x32_bf16 v[96:99], v[174:177], v[198:201], 0
	v_mfma_f32_16x16x32_bf16 v[84:87], v[166:169], v[206:209], 0
	v_mfma_f32_16x16x32_bf16 v[80:83], v[174:177], v[206:209], 0
	v_mfma_f32_16x16x32_bf16 v[132:135], v[170:173], v[186:189], v[132:135]
	v_mfma_f32_16x16x32_bf16 v[128:131], v[178:181], v[186:189], v[128:131]
	v_mfma_f32_16x16x32_bf16 v[116:119], v[170:173], v[194:197], v[116:119]
	v_mfma_f32_16x16x32_bf16 v[112:115], v[178:181], v[194:197], v[112:115]
	v_mfma_f32_16x16x32_bf16 v[100:103], v[170:173], v[202:205], v[100:103]
	v_mfma_f32_16x16x32_bf16 v[96:99], v[178:181], v[202:205], v[96:99]
	v_mfma_f32_16x16x32_bf16 v[84:87], v[170:173], v[210:213], v[84:87]
	v_mfma_f32_16x16x32_bf16 v[80:83], v[178:181], v[210:213], v[80:83]
	s_barrier
	s_setprio 0
	s_add_i32 s9, s75, s55
	v_lshl_add_u64 v[158:159], s[76:77], 0, v[148:149]
	s_mov_b32 m0, s9
	ds_read_b128 v[182:185], v165 offset:16384
	ds_read_b128 v[186:189], v165 offset:17408
	ds_read_b128 v[190:193], v165 offset:18432
	ds_read_b128 v[194:197], v165 offset:19456
	ds_read_b128 v[198:201], v165 offset:20480
	ds_read_b128 v[202:205], v165 offset:21504
	ds_read_b128 v[206:209], v165 offset:22528
	ds_read_b128 v[210:213], v165 offset:23552
	global_load_lds_dwordx4 v[158:159], off
	s_add_i32 m0, s9, 0x2000
	v_lshl_add_u64 v[214:215], s[76:77], 0, v[144:145]
	s_add_u32 s76, s76, s12
	s_addc_u32 s77, s77, s13
	s_add_i32 s9, s78, s55
	global_load_lds_dwordx4 v[214:215], off
	v_lshl_add_u64 v[216:217], s[76:77], 0, v[148:149]
	s_mov_b32 m0, s9
	v_lshl_add_u64 v[218:219], s[76:77], 0, v[144:145]
	global_load_lds_dwordx4 v[216:217], off
	s_add_i32 m0, s9, 0x2000
	v_lshl_add_u64 v[220:221], s[6:7], 0, v[150:151]
	global_load_lds_dwordx4 v[218:219], off
	s_mov_b32 m0, s63
	v_lshl_add_u64 v[222:223], s[6:7], 0, v[146:147]
	global_load_lds_dwordx4 v[220:221], off
	s_mov_b32 m0, s64
	s_nop 0
	global_load_lds_dwordx4 v[222:223], off
	s_waitcnt vmcnt(8)
	s_waitcnt lgkmcnt(0)
	s_setprio 1
	s_barrier
; #define PG8_STAGE(bufoff, gbase, voff) do { _Pragma("unroll") for (int _i = 0; _i < 2; ++_i) \
;         __builtin_amdgcn_global_load_lds((const unsigned*)((const char*)(gbase) + (voff)[_i]), (PG8_LAS unsigned*)(lds + (bufoff) + ldsw + _i * 8192), 16, 0, 0); } while (0)
; #define PG8_LDA(dst, b, h) do { _Pragma("unroll") for (int m = 0; m < 4; ++m) _Pragma("unroll") for (int k = 0; k < 2; ++k) dst[m][k] = *(const PG8_LAS bf16x8*)(lds + PG8_SA(b, h) + aoff + m * 2048 + k * 1024); } while (0)
; #define PG8_LDB(dst, b, h) do { _Pragma("unroll") for (int n = 0; n < 2; ++n) _Pragma("unroll") for (int k = 0; k < 2; ++k) dst[n][k] = *(const PG8_LAS bf16x8*)(lds + PG8_SB(b, h) + boff + n * 2048 + k * 1024); } while (0)
; #define PG8_MMA(ai, bj, At, Bt) do { __builtin_amdgcn_s_setprio(1); _Pragma("unroll") for (int m = 0; m < 4; ++m) _Pragma("unroll") for (int n = 0; n < 2; ++n) _Pragma("unroll") for (int k = 0; k < 2; ++k) \
;         acc[ai][bj][m][n] = __builtin_amdgcn_mfma_f32_16x16x32_bf16(Bt[n][k], At[m][k], acc[ai][bj][m][n], 0, 0, 0); __builtin_amdgcn_s_setprio(0); } while (0)
; #define PG8_BAR __builtin_amdgcn_s_barrier()
; template <class Epi, class Sched, bool ALIGN_EPI = false, bool SP2 = false>
; __device__ __forceinline__ void gemm_phase(PG8_LAS unsigned char* lds, const Gemm g, const Sched& S, const Epi& E, const int wid) {
;     ...
;             PG8_LDB(B0, 0, 0); PG8_LDB(B1, 0, 1); PG8_SCHED; PG8_LDA(At, 0, 0); PG8_STAGE(PG8_SA(1, 1), a1 + hstep, voffA);
;             PG8_WAIT_V(8); PG8_WAIT_L(0); PG8_BAR; PG8_MMA(0, 0, At, B0); PG8_MMA(0, 1, At, B1); PG8_BAR; PG8_SCHED;
;             PG8_LDA(At, 0, 1); PG8_STAGE(PG8_SB(0, 0), b2, voffB); PG8_STAGE(PG8_SB(0, 1), b2 + hstep, voffB); PG8_STAGE(PG8_SA(0, 0), a2, voffA);
;             PG8_WAIT_V(8); PG8_WAIT_L(0); PG8_BAR; PG8_MMA(1, 0, At, B0); PG8_MMA(1, 1, At, B1); PG8_BAR; PG8_SCHED;
;             PG8_LDB(B0, 1, 0); PG8_LDB(B1, 1, 1); PG8_SCHED; PG8_LDA(At, 1, 0); PG8_STAGE(PG8_SA(0, 1), a2 + hstep, voffA);
;             PG8_WAIT_V(8); PG8_WAIT_L(0); PG8_BAR; PG8_MMA(0, 0, At, B0); PG8_MMA(0, 1, At, B1); PG8_BAR; PG8_SCHED;
;             PG8_LDA(At, 1, 1); PG8_STAGE(PG8_SB(1, 0), b3, voffB); PG8_STAGE(PG8_SB(1, 1), b3 + hstep, voffB); PG8_STAGE(PG8_SA(1, 0), a3, voffA);
;             PG8_WAIT_V(8); PG8_WAIT_L(0); PG8_BAR; PG8_MMA(1, 0, At, B0); PG8_MMA(1, 1, At, B1); PG8_BAR; PG8_SCHED;
	v_mfma_f32_16x16x32_bf16 v[76:79], v[44:47], v[182:185], 0
	v_mfma_f32_16x16x32_bf16 v[72:75], v[60:63], v[182:185], 0
	v_mfma_f32_16x16x32_bf16 v[48:51], v[44:47], v[190:193], 0
	v_mfma_f32_16x16x32_bf16 v[40:43], v[60:63], v[190:193], 0
	v_mfma_f32_16x16x32_bf16 v[28:31], v[44:47], v[198:201], 0
	v_mfma_f32_16x16x32_bf16 v[24:27], v[60:63], v[198:201], 0
	v_mfma_f32_16x16x32_bf16 v[12:15], v[44:47], v[206:209], 0
	v_mfma_f32_16x16x32_bf16 v[8:11], v[60:63], v[206:209], 0
	v_mfma_f32_16x16x32_bf16 v[76:79], v[52:55], v[186:189], v[76:79]
	v_mfma_f32_16x16x32_bf16 v[72:75], v[68:71], v[186:189], v[72:75]
	v_mfma_f32_16x16x32_bf16 v[48:51], v[52:55], v[194:197], v[48:51]
	v_mfma_f32_16x16x32_bf16 v[40:43], v[68:71], v[194:197], v[40:43]
	v_mfma_f32_16x16x32_bf16 v[28:31], v[52:55], v[202:205], v[28:31]
	v_mfma_f32_16x16x32_bf16 v[24:27], v[68:71], v[202:205], v[24:27]
	v_mfma_f32_16x16x32_bf16 v[12:15], v[52:55], v[210:213], v[12:15]
	v_mfma_f32_16x16x32_bf16 v[8:11], v[68:71], v[210:213], v[8:11]
	v_mfma_f32_16x16x32_bf16 v[36:39], v[166:169], v[190:193], 0
	v_mfma_f32_16x16x32_bf16 v[32:35], v[174:177], v[190:193], 0
	v_mfma_f32_16x16x32_bf16 v[20:23], v[166:169], v[198:201], 0
	v_mfma_f32_16x16x32_bf16 v[16:19], v[174:177], v[198:201], 0
	v_mfma_f32_16x16x32_bf16 v[4:7], v[166:169], v[206:209], 0
	v_mfma_f32_16x16x32_bf16 v[0:3], v[174:177], v[206:209], 0
	v_mfma_f32_16x16x32_bf16 v[44:47], v[166:169], v[182:185], 0
	v_mfma_f32_16x16x32_bf16 v[52:55], v[174:177], v[182:185], 0
	v_mfma_f32_16x16x32_bf16 v[36:39], v[170:173], v[194:197], v[36:39]
	v_mfma_f32_16x16x32_bf16 v[32:35], v[178:181], v[194:197], v[32:35]
	v_mfma_f32_16x16x32_bf16 v[20:23], v[170:173], v[202:205], v[20:23]
	v_mfma_f32_16x16x32_bf16 v[16:19], v[178:181], v[202:205], v[16:19]
	v_mfma_f32_16x16x32_bf16 v[4:7], v[170:173], v[210:213], v[4:7]
	v_mfma_f32_16x16x32_bf16 v[0:3], v[178:181], v[210:213], v[0:3]
	v_mfma_f32_16x16x32_bf16 v[44:47], v[170:173], v[186:189], v[44:47]
	v_mfma_f32_16x16x32_bf16 v[52:55], v[178:181], v[186:189], v[52:55]
	s_barrier
	s_setprio 0
	s_add_i32 s9, 0, 0x18000
	s_add_i32 s33, 0, 0x1c000
	v_add_u32_e32 v68, s9, v162
	v_add_u32_e32 v178, s33, v162
	ds_read_b128 v[56:59], v68
	ds_read_b128 v[60:63], v68 offset:1024
	ds_read_b128 v[64:67], v68 offset:2048
	ds_read_b128 v[68:71], v68 offset:3072
	ds_read_b128 v[166:169], v178
	ds_read_b128 v[170:173], v178 offset:1024
	ds_read_b128 v[174:177], v178 offset:2048
	ds_read_b128 v[178:181], v178 offset:3072
	s_add_u32 s6, s6, s12
	s_addc_u32 s7, s7, s13
	s_mov_b32 m0, s65
	v_lshl_add_u64 v[224:225], s[6:7], 0, v[150:151]
	ds_read_b128 v[182:185], v165 offset:32768
	ds_read_b128 v[186:189], v165 offset:33792
	ds_read_b128 v[190:193], v165 offset:34816
	ds_read_b128 v[194:197], v165 offset:35840
	ds_read_b128 v[198:201], v165 offset:36864
	ds_read_b128 v[202:205], v165 offset:37888
	ds_read_b128 v[206:209], v165 offset:38912
	ds_read_b128 v[210:213], v165 offset:39936
	global_load_lds_dwordx4 v[224:225], off
	v_lshl_add_u64 v[224:225], s[6:7], 0, v[146:147]
	s_mov_b32 m0, s66
	s_nop 0
	global_load_lds_dwordx4 v[224:225], off
	s_waitcnt vmcnt(8)
	s_waitcnt lgkmcnt(0)
	s_setprio 1
	s_barrier
	v_mfma_f32_16x16x32_bf16 v[140:143], v[56:59], v[182:185], v[140:143]
	v_mfma_f32_16x16x32_bf16 v[136:139], v[64:67], v[182:185], v[136:139]
	v_mfma_f32_16x16x32_bf16 v[124:127], v[56:59], v[190:193], v[124:127]
	v_mfma_f32_16x16x32_bf16 v[120:123], v[64:67], v[190:193], v[120:123]
	v_mfma_f32_16x16x32_bf16 v[108:111], v[56:59], v[198:201], v[108:111]
	v_mfma_f32_16x16x32_bf16 v[104:107], v[64:67], v[198:201], v[104:107]
	v_mfma_f32_16x16x32_bf16 v[92:95], v[56:59], v[206:209], v[92:95]
	v_mfma_f32_16x16x32_bf16 v[88:91], v[64:67], v[206:209], v[88:91]
	v_mfma_f32_16x16x32_bf16 v[140:143], v[60:63], v[186:189], v[140:143]
	v_mfma_f32_16x16x32_bf16 v[136:139], v[68:71], v[186:189], v[136:139]
	v_mfma_f32_16x16x32_bf16 v[124:127], v[60:63], v[194:197], v[124:127]
	v_mfma_f32_16x16x32_bf16 v[120:123], v[68:71], v[194:197], v[120:123]
	v_mfma_f32_16x16x32_bf16 v[108:111], v[60:63], v[202:205], v[108:111]
	v_mfma_f32_16x16x32_bf16 v[104:107], v[68:71], v[202:205], v[104:107]
	v_mfma_f32_16x16x32_bf16 v[92:95], v[60:63], v[210:213], v[92:95]
	v_mfma_f32_16x16x32_bf16 v[88:91], v[68:71], v[210:213], v[88:91]
	v_mfma_f32_16x16x32_bf16 v[132:135], v[166:169], v[182:185], v[132:135]
	v_mfma_f32_16x16x32_bf16 v[128:131], v[174:177], v[182:185], v[128:131]
	v_mfma_f32_16x16x32_bf16 v[116:119], v[166:169], v[190:193], v[116:119]
	v_mfma_f32_16x16x32_bf16 v[112:115], v[174:177], v[190:193], v[112:115]
	v_mfma_f32_16x16x32_bf16 v[100:103], v[166:169], v[198:201], v[100:103]
	v_mfma_f32_16x16x32_bf16 v[96:99], v[174:177], v[198:201], v[96:99]
	v_mfma_f32_16x16x32_bf16 v[84:87], v[166:169], v[206:209], v[84:87]
	v_mfma_f32_16x16x32_bf16 v[80:83], v[174:177], v[206:209], v[80:83]
	v_mfma_f32_16x16x32_bf16 v[132:135], v[170:173], v[186:189], v[132:135]
	v_mfma_f32_16x16x32_bf16 v[128:131], v[178:181], v[186:189], v[128:131]
	v_mfma_f32_16x16x32_bf16 v[116:119], v[170:173], v[194:197], v[116:119]
	v_mfma_f32_16x16x32_bf16 v[112:115], v[178:181], v[194:197], v[112:115]
	v_mfma_f32_16x16x32_bf16 v[100:103], v[170:173], v[202:205], v[100:103]
	v_mfma_f32_16x16x32_bf16 v[96:99], v[178:181], v[202:205], v[96:99]
	v_mfma_f32_16x16x32_bf16 v[84:87], v[170:173], v[210:213], v[84:87]
	v_mfma_f32_16x16x32_bf16 v[80:83], v[178:181], v[210:213], v[80:83]
	s_barrier
; #define PG8_STAGE(bufoff, gbase, voff) do { _Pragma("unroll") for (int _i = 0; _i < 2; ++_i) \
;         __builtin_amdgcn_global_load_lds((const unsigned*)((const char*)(gbase) + (voff)[_i]), (PG8_LAS unsigned*)(lds + (bufoff) + ldsw + _i * 8192), 16, 0, 0); } while (0)
; #define PG8_LDA(dst, b, h) do { _Pragma("unroll") for (int m = 0; m < 4; ++m) _Pragma("unroll") for (int k = 0; k < 2; ++k) dst[m][k] = *(const PG8_LAS bf16x8*)(lds + PG8_SA(b, h) + aoff + m * 2048 + k * 1024); } while (0)
; #define PG8_WAIT_V(n) asm volatile("s_waitcnt vmcnt(" #n ")" ::: "memory")
; #define PG8_WAIT_L(n) asm volatile("s_waitcnt lgkmcnt(" #n ")" ::: "memory")
; #define PG8_BAR __builtin_amdgcn_s_barrier()
; template <class Epi, class Sched, bool ALIGN_EPI = false, bool SP2 = false>
; __device__ __forceinline__ void gemm_phase(PG8_LAS unsigned char* lds, const Gemm g, const Sched& S, const Epi& E, const int wid) {
;     ...
;         for (int t = 0; t < nt; t += 2) {
;             const bool last = (t == nt - 2);
;             const char* a1 = cA + (size_t)(t + 1) * kstep;
;             const char* a2 = last ? nA : cA + (size_t)(t + 2) * kstep; const char* b2 = last ? nB : cB + (size_t)(t + 2) * kstep;
;             const char* a3 = a2 + kstep; const char* b3 = b2 + kstep;
;             if (last && has_next) S.a_ready(nxt);
;             if constexpr (SP2) {
;             PG8_LDB(B0, 0, 0); PG8_LDB(B1, 0, 1); PG8_SCHED; PG8_LDA(At, 0, 0); PG8_STAGE(PG8_SA(1, 1), a1 + hstep, voffA);
;             PG8_WAIT_V(8); PG8_WAIT_L(0); PG8_BAR; PG8_MMA(0, 0, At, B0); PG8_MMA(0, 1, At, B1); PG8_BAR; PG8_SCHED;
;             PG8_LDA(At, 0, 1); PG8_STAGE(PG8_SB(0, 0), b2, voffB); PG8_STAGE(PG8_SB(0, 1), b2 + hstep, voffB); PG8_STAGE(PG8_SA(0, 0), a2, voffA);
;             PG8_WAIT_V(8); PG8_WAIT_L(0); PG8_BAR; PG8_MMA(1, 0, At, B0); PG8_MMA(1, 1, At, B1); PG8_BAR; PG8_SCHED;
;             PG8_LDB(B0, 1, 0); PG8_LDB(B1, 1, 1); PG8_SCHED; PG8_LDA(At, 1, 0); PG8_STAGE(PG8_SA(0, 1), a2 + hstep, voffA);
;             PG8_WAIT_V(8); PG8_WAIT_L(0); PG8_BAR; PG8_MMA(0, 0, At, B0); PG8_MMA(0, 1, At, B1); PG8_BAR; PG8_SCHED;
;             PG8_LDA(At, 1, 1); PG8_STAGE(PG8_SB(1, 0), b3, voffB); PG8_STAGE(PG8_SB(1, 1), b3 + hstep, voffB); PG8_STAGE(PG8_SA(1, 0), a3, voffA);
;             PG8_WAIT_V(8); PG8_WAIT_L(0); PG8_BAR; PG8_MMA(1, 0, At, B0); PG8_MMA(1, 1, At, B1); PG8_BAR; PG8_SCHED;
	s_setprio 0
	s_add_i32 s6, s9, s55
	v_lshl_add_u64 v[158:159], v[158:159], 0, s[26:27]
	s_mov_b32 m0, s6
	ds_read_b128 v[182:185], v165 offset:49152
	ds_read_b128 v[186:189], v165 offset:50176
	ds_read_b128 v[190:193], v165 offset:51200
	ds_read_b128 v[194:197], v165 offset:52224
	ds_read_b128 v[198:201], v165 offset:53248
	ds_read_b128 v[202:205], v165 offset:54272
	ds_read_b128 v[206:209], v165 offset:55296
	ds_read_b128 v[210:213], v165 offset:56320
	global_load_lds_dwordx4 v[158:159], off
	v_lshl_add_u64 v[158:159], v[214:215], 0, s[26:27]
	s_add_i32 m0, s6, 0x2000
	s_add_i32 s6, s33, s55
	global_load_lds_dwordx4 v[158:159], off
	v_lshl_add_u64 v[158:159], v[216:217], 0, s[26:27]
	s_mov_b32 m0, s6
	s_nop 0
	global_load_lds_dwordx4 v[158:159], off
	v_lshl_add_u64 v[158:159], v[218:219], 0, s[26:27]
	s_add_i32 m0, s6, 0x2000
	s_nop 0
	global_load_lds_dwordx4 v[158:159], off
	v_lshl_add_u64 v[158:159], v[220:221], 0, s[26:27]
	s_mov_b32 m0, s68
	s_nop 0
	global_load_lds_dwordx4 v[158:159], off
	v_lshl_add_u64 v[158:159], v[222:223], 0, s[26:27]
	s_mov_b32 m0, s69
	s_nop 0
	global_load_lds_dwordx4 v[158:159], off
	s_waitcnt vmcnt(8)
	s_waitcnt lgkmcnt(0)
	s_setprio 1
	s_barrier
	v_mfma_f32_16x16x32_bf16 v[76:79], v[56:59], v[182:185], v[76:79]
	v_mfma_f32_16x16x32_bf16 v[72:75], v[64:67], v[182:185], v[72:75]
	v_mfma_f32_16x16x32_bf16 v[48:51], v[56:59], v[190:193], v[48:51]
	v_mfma_f32_16x16x32_bf16 v[40:43], v[64:67], v[190:193], v[40:43]
	v_mfma_f32_16x16x32_bf16 v[28:31], v[56:59], v[198:201], v[28:31]
	v_mfma_f32_16x16x32_bf16 v[24:27], v[64:67], v[198:201], v[24:27]
	v_mfma_f32_16x16x32_bf16 v[12:15], v[56:59], v[206:209], v[12:15]
	v_mfma_f32_16x16x32_bf16 v[8:11], v[64:67], v[206:209], v[8:11]
	v_mfma_f32_16x16x32_bf16 v[76:79], v[60:63], v[186:189], v[76:79]
	v_mfma_f32_16x16x32_bf16 v[72:75], v[68:71], v[186:189], v[72:75]
	v_mfma_f32_16x16x32_bf16 v[48:51], v[60:63], v[194:197], v[48:51]
	v_mfma_f32_16x16x32_bf16 v[40:43], v[68:71], v[194:197], v[40:43]
	v_mfma_f32_16x16x32_bf16 v[28:31], v[60:63], v[202:205], v[28:31]
	v_mfma_f32_16x16x32_bf16 v[24:27], v[68:71], v[202:205], v[24:27]
	v_mfma_f32_16x16x32_bf16 v[12:15], v[60:63], v[210:213], v[12:15]
	v_mfma_f32_16x16x32_bf16 v[8:11], v[68:71], v[210:213], v[8:11]
	v_mfma_f32_16x16x32_bf16 v[44:47], v[166:169], v[182:185], v[44:47]
	v_mfma_f32_16x16x32_bf16 v[64:67], v[170:173], v[186:189], v[44:47]
	v_mfma_f32_16x16x32_bf16 v[44:47], v[174:177], v[182:185], v[52:55]
	v_mfma_f32_16x16x32_bf16 v[36:39], v[166:169], v[190:193], v[36:39]
	v_mfma_f32_16x16x32_bf16 v[32:35], v[174:177], v[190:193], v[32:35]
	v_mfma_f32_16x16x32_bf16 v[20:23], v[166:169], v[198:201], v[20:23]
	v_mfma_f32_16x16x32_bf16 v[16:19], v[174:177], v[198:201], v[16:19]
	v_mfma_f32_16x16x32_bf16 v[4:7], v[166:169], v[206:209], v[4:7]
	v_mfma_f32_16x16x32_bf16 v[0:3], v[174:177], v[206:209], v[0:3]
	v_mfma_f32_16x16x32_bf16 v[56:59], v[178:181], v[186:189], v[44:47]
	v_mfma_f32_16x16x32_bf16 v[36:39], v[170:173], v[194:197], v[36:39]
	v_mfma_f32_16x16x32_bf16 v[32:35], v[178:181], v[194:197], v[32:35]
	v_mfma_f32_16x16x32_bf16 v[20:23], v[170:173], v[202:205], v[20:23]
	v_mfma_f32_16x16x32_bf16 v[16:19], v[178:181], v[202:205], v[16:19]
	v_mfma_f32_16x16x32_bf16 v[4:7], v[170:173], v[210:213], v[4:7]
	v_mfma_f32_16x16x32_bf16 v[0:3], v[178:181], v[210:213], v[0:3]
	s_barrier
	s_setprio 0
	s_add_u32 s4, s4, 0x100
	s_addc_u32 s5, s5, 0
	s_add_u32 s0, s0, 0x100
	s_addc_u32 s1, s1, 0
	s_cmp_ge_i32 s8, s70
	s_mov_b32 s6, s8
	s_cbranch_scc1 .LBB0_1101
.LBB0_1100:
	ds_read_b128 v[44:47], v163
	ds_read_b128 v[52:55], v163 offset:1024
	ds_read_b128 v[60:63], v163 offset:2048
	ds_read_b128 v[68:71], v163 offset:3072
	ds_read_b128 v[166:169], v164
	ds_read_b128 v[170:173], v164 offset:1024
	ds_read_b128 v[174:177], v164 offset:2048
	ds_read_b128 v[178:181], v164 offset:3072
	s_add_i32 s8, s6, 2
	s_add_u32 s9, s4, 0x80
	s_addc_u32 s7, s5, 0
	s_cmp_eq_u32 s72, s6
	s_cselect_b32 s6, s48, s9
	s_cselect_b32 s7, s49, s7
	s_cselect_b32 s77, s51, s1
	s_cselect_b32 s76, s50, s0
	v_lshl_add_u64 v[158:159], s[4:5], 0, v[152:153]
	s_add_i32 m0, s63, 0xc000
	ds_read_b128 v[182:185], v165
	ds_read_b128 v[186:189], v165 offset:1024
	ds_read_b128 v[190:193], v165 offset:2048
	ds_read_b128 v[194:197], v165 offset:3072
	ds_read_b128 v[198:201], v165 offset:4096
	ds_read_b128 v[202:205], v165 offset:5120
	ds_read_b128 v[206:209], v165 offset:6144
	ds_read_b128 v[210:213], v165 offset:7168
	global_load_lds_dwordx4 v[158:159], off
	v_lshl_add_u64 v[158:159], s[4:5], 0, v[154:155]
	s_add_i32 m0, s63, 0xe000
	s_nop 0
	global_load_lds_dwordx4 v[158:159], off
	s_waitcnt vmcnt(8)
	s_waitcnt lgkmcnt(0)
	s_setprio 1
	s_barrier
; #define PG8_STAGE(bufoff, gbase, voff) do { _Pragma("unroll") for (int _i = 0; _i < 2; ++_i) \
;         __builtin_amdgcn_global_load_lds((const unsigned*)((const char*)(gbase) + (voff)[_i]), (PG8_LAS unsigned*)(lds + (bufoff) + ldsw + _i * 8192), 16, 0, 0); } while (0)
; #define PG8_LDA(dst, b, h) do { _Pragma("unroll") for (int m = 0; m < 4; ++m) _Pragma("unroll") for (int k = 0; k < 2; ++k) dst[m][k] = *(const PG8_LAS bf16x8*)(lds + PG8_SA(b, h) + aoff + m * 2048 + k * 1024); } while (0)
; #define PG8_LDB(dst, b, h) do { _Pragma("unroll") for (int n = 0; n < 2; ++n) _Pragma("unroll") for (int k = 0; k < 2; ++k) dst[n][k] = *(const PG8_LAS bf16x8*)(lds + PG8_SB(b, h) + boff + n * 2048 + k * 1024); } while (0)
; #define PG8_MMA(ai, bj, At, Bt) do { __builtin_amdgcn_s_setprio(1); _Pragma("unroll") for (int m = 0; m < 4; ++m) _Pragma("unroll") for (int n = 0; n < 2; ++n) _Pragma("unroll") for (int k = 0; k < 2; ++k) \
;         acc[ai][bj][m][n] = __builtin_amdgcn_mfma_f32_16x16x32_bf16(Bt[n][k], At[m][k], acc[ai][bj][m][n], 0, 0, 0); __builtin_amdgcn_s_setprio(0); } while (0)
; #define PG8_BAR __builtin_amdgcn_s_barrier()
; template <class Epi, class Sched, bool ALIGN_EPI = false, bool SP2 = false>
; __device__ __forceinline__ void gemm_phase(PG8_LAS unsigned char* lds, const Gemm g, const Sched& S, const Epi& E, const int wid) {
;     ...
;             PG8_LDB(B0, 0, 0); PG8_LDB(B1, 0, 1); PG8_SCHED; PG8_LDA(At, 0, 0); PG8_STAGE(PG8_SA(1, 1), a1 + hstep, voffA);
;             PG8_WAIT_V(8); PG8_WAIT_L(0); PG8_BAR; PG8_MMA(0, 0, At, B0); PG8_MMA(0, 1, At, B1); PG8_BAR; PG8_SCHED;
;             PG8_LDA(At, 0, 1); PG8_STAGE(PG8_SB(0, 0), b2, voffB); PG8_STAGE(PG8_SB(0, 1), b2 + hstep, voffB); PG8_STAGE(PG8_SA(0, 0), a2, voffA);
;             PG8_WAIT_V(8); PG8_WAIT_L(0); PG8_BAR; PG8_MMA(1, 0, At, B0); PG8_MMA(1, 1, At, B1); PG8_BAR; PG8_SCHED;
;             PG8_LDB(B0, 1, 0); PG8_LDB(B1, 1, 1); PG8_SCHED; PG8_LDA(At, 1, 0); PG8_STAGE(PG8_SA(0, 1), a2 + hstep, voffA);
;             PG8_WAIT_V(8); PG8_WAIT_L(0); PG8_BAR; PG8_MMA(0, 0, At, B0); PG8_MMA(0, 1, At, B1); PG8_BAR; PG8_SCHED;
;             PG8_LDA(At, 1, 1); PG8_STAGE(PG8_SB(1, 0), b3, voffB); PG8_STAGE(PG8_SB(1, 1), b3 + hstep, voffB); PG8_STAGE(PG8_SA(1, 0), a3, voffA);
;             PG8_WAIT_V(8); PG8_WAIT_L(0); PG8_BAR; PG8_MMA(1, 0, At, B0); PG8_MMA(1, 1, At, B1); PG8_BAR; PG8_SCHED;
	v_mfma_f32_16x16x32_bf16 v[140:143], v[44:47], v[182:185], v[140:143]
	v_mfma_f32_16x16x32_bf16 v[136:139], v[60:63], v[182:185], v[136:139]
	v_mfma_f32_16x16x32_bf16 v[124:127], v[44:47], v[190:193], v[124:127]
	v_mfma_f32_16x16x32_bf16 v[120:123], v[60:63], v[190:193], v[120:123]
	v_mfma_f32_16x16x32_bf16 v[108:111], v[44:47], v[198:201], v[108:111]
	v_mfma_f32_16x16x32_bf16 v[104:107], v[60:63], v[198:201], v[104:107]
	v_mfma_f32_16x16x32_bf16 v[92:95], v[44:47], v[206:209], v[92:95]
	v_mfma_f32_16x16x32_bf16 v[88:91], v[60:63], v[206:209], v[88:91]
	v_mfma_f32_16x16x32_bf16 v[140:143], v[52:55], v[186:189], v[140:143]
	v_mfma_f32_16x16x32_bf16 v[136:139], v[68:71], v[186:189], v[136:139]
	v_mfma_f32_16x16x32_bf16 v[124:127], v[52:55], v[194:197], v[124:127]
	v_mfma_f32_16x16x32_bf16 v[120:123], v[68:71], v[194:197], v[120:123]
	v_mfma_f32_16x16x32_bf16 v[108:111], v[52:55], v[202:205], v[108:111]
	v_mfma_f32_16x16x32_bf16 v[104:107], v[68:71], v[202:205], v[104:107]
	v_mfma_f32_16x16x32_bf16 v[92:95], v[52:55], v[210:213], v[92:95]
	v_mfma_f32_16x16x32_bf16 v[88:91], v[68:71], v[210:213], v[88:91]
	v_mfma_f32_16x16x32_bf16 v[132:135], v[166:169], v[182:185], v[132:135]
	v_mfma_f32_16x16x32_bf16 v[128:131], v[174:177], v[182:185], v[128:131]
	v_mfma_f32_16x16x32_bf16 v[116:119], v[166:169], v[190:193], v[116:119]
	v_mfma_f32_16x16x32_bf16 v[112:115], v[174:177], v[190:193], v[112:115]
	v_mfma_f32_16x16x32_bf16 v[100:103], v[166:169], v[198:201], v[100:103]
	v_mfma_f32_16x16x32_bf16 v[96:99], v[174:177], v[198:201], v[96:99]
	v_mfma_f32_16x16x32_bf16 v[84:87], v[166:169], v[206:209], v[84:87]
	v_mfma_f32_16x16x32_bf16 v[80:83], v[174:177], v[206:209], v[80:83]
	v_mfma_f32_16x16x32_bf16 v[132:135], v[170:173], v[186:189], v[132:135]
	v_mfma_f32_16x16x32_bf16 v[128:131], v[178:181], v[186:189], v[128:131]
	v_mfma_f32_16x16x32_bf16 v[116:119], v[170:173], v[194:197], v[116:119]
	v_mfma_f32_16x16x32_bf16 v[112:115], v[178:181], v[194:197], v[112:115]
	v_mfma_f32_16x16x32_bf16 v[100:103], v[170:173], v[202:205], v[100:103]
	v_mfma_f32_16x16x32_bf16 v[96:99], v[178:181], v[202:205], v[96:99]
	v_mfma_f32_16x16x32_bf16 v[84:87], v[170:173], v[210:213], v[84:87]
	v_mfma_f32_16x16x32_bf16 v[80:83], v[178:181], v[210:213], v[80:83]
	s_barrier
	s_setprio 0
	s_add_i32 s9, s75, s55
	v_lshl_add_u64 v[158:159], s[76:77], 0, v[148:149]
	s_mov_b32 m0, s9
	ds_read_b128 v[182:185], v165 offset:16384
	ds_read_b128 v[186:189], v165 offset:17408
	ds_read_b128 v[190:193], v165 offset:18432
	ds_read_b128 v[194:197], v165 offset:19456
	ds_read_b128 v[198:201], v165 offset:20480
	ds_read_b128 v[202:205], v165 offset:21504
	ds_read_b128 v[206:209], v165 offset:22528
	ds_read_b128 v[210:213], v165 offset:23552
	global_load_lds_dwordx4 v[158:159], off
	s_add_i32 m0, s9, 0x2000
	v_lshl_add_u64 v[214:215], s[76:77], 0, v[144:145]
	s_add_u32 s76, s76, s12
	s_addc_u32 s77, s77, s13
	s_add_i32 s9, s78, s55
	global_load_lds_dwordx4 v[214:215], off
	v_lshl_add_u64 v[216:217], s[76:77], 0, v[148:149]
	s_mov_b32 m0, s9
	v_lshl_add_u64 v[218:219], s[76:77], 0, v[144:145]
	global_load_lds_dwordx4 v[216:217], off
	s_add_i32 m0, s9, 0x2000
	v_lshl_add_u64 v[220:221], s[6:7], 0, v[150:151]
	global_load_lds_dwordx4 v[218:219], off
	s_mov_b32 m0, s63
	v_lshl_add_u64 v[222:223], s[6:7], 0, v[146:147]
	global_load_lds_dwordx4 v[220:221], off
	s_mov_b32 m0, s64
	s_nop 0
	global_load_lds_dwordx4 v[222:223], off
	s_waitcnt vmcnt(8)
	s_waitcnt lgkmcnt(0)
	s_setprio 1
	s_barrier
	v_mfma_f32_16x16x32_bf16 v[76:79], v[44:47], v[182:185], v[76:79]
	v_mfma_f32_16x16x32_bf16 v[72:75], v[60:63], v[182:185], v[72:75]
	v_mfma_f32_16x16x32_bf16 v[48:51], v[44:47], v[190:193], v[48:51]
	v_mfma_f32_16x16x32_bf16 v[40:43], v[60:63], v[190:193], v[40:43]
	v_mfma_f32_16x16x32_bf16 v[28:31], v[44:47], v[198:201], v[28:31]
	v_mfma_f32_16x16x32_bf16 v[24:27], v[60:63], v[198:201], v[24:27]
	v_mfma_f32_16x16x32_bf16 v[12:15], v[44:47], v[206:209], v[12:15]
	v_mfma_f32_16x16x32_bf16 v[8:11], v[60:63], v[206:209], v[8:11]
	v_mfma_f32_16x16x32_bf16 v[76:79], v[52:55], v[186:189], v[76:79]
	v_mfma_f32_16x16x32_bf16 v[72:75], v[68:71], v[186:189], v[72:75]
	v_mfma_f32_16x16x32_bf16 v[48:51], v[52:55], v[194:197], v[48:51]
	v_mfma_f32_16x16x32_bf16 v[40:43], v[68:71], v[194:197], v[40:43]
	v_mfma_f32_16x16x32_bf16 v[28:31], v[52:55], v[202:205], v[28:31]
	v_mfma_f32_16x16x32_bf16 v[24:27], v[68:71], v[202:205], v[24:27]
	v_mfma_f32_16x16x32_bf16 v[12:15], v[52:55], v[210:213], v[12:15]
	v_mfma_f32_16x16x32_bf16 v[8:11], v[68:71], v[210:213], v[8:11]
	v_mfma_f32_16x16x32_bf16 v[36:39], v[166:169], v[190:193], v[36:39]
	v_mfma_f32_16x16x32_bf16 v[32:35], v[174:177], v[190:193], v[32:35]
	v_mfma_f32_16x16x32_bf16 v[20:23], v[166:169], v[198:201], v[20:23]
	v_mfma_f32_16x16x32_bf16 v[16:19], v[174:177], v[198:201], v[16:19]
	v_mfma_f32_16x16x32_bf16 v[4:7], v[166:169], v[206:209], v[4:7]
	v_mfma_f32_16x16x32_bf16 v[0:3], v[174:177], v[206:209], v[0:3]
	v_mfma_f32_16x16x32_bf16 v[44:47], v[166:169], v[182:185], v[64:67]
	v_mfma_f32_16x16x32_bf16 v[52:55], v[174:177], v[182:185], v[56:59]
	v_mfma_f32_16x16x32_bf16 v[36:39], v[170:173], v[194:197], v[36:39]
	v_mfma_f32_16x16x32_bf16 v[32:35], v[178:181], v[194:197], v[32:35]
	v_mfma_f32_16x16x32_bf16 v[20:23], v[170:173], v[202:205], v[20:23]
	v_mfma_f32_16x16x32_bf16 v[16:19], v[178:181], v[202:205], v[16:19]
	v_mfma_f32_16x16x32_bf16 v[4:7], v[170:173], v[210:213], v[4:7]
	v_mfma_f32_16x16x32_bf16 v[0:3], v[178:181], v[210:213], v[0:3]
	v_mfma_f32_16x16x32_bf16 v[44:47], v[170:173], v[186:189], v[44:47]
	v_mfma_f32_16x16x32_bf16 v[52:55], v[178:181], v[186:189], v[52:55]
	s_barrier
; #define PG8_STAGE(bufoff, gbase, voff) do { _Pragma("unroll") for (int _i = 0; _i < 2; ++_i) \
;         __builtin_amdgcn_global_load_lds((const unsigned*)((const char*)(gbase) + (voff)[_i]), (PG8_LAS unsigned*)(lds + (bufoff) + ldsw + _i * 8192), 16, 0, 0); } while (0)
; #define PG8_LDA(dst, b, h) do { _Pragma("unroll") for (int m = 0; m < 4; ++m) _Pragma("unroll") for (int k = 0; k < 2; ++k) dst[m][k] = *(const PG8_LAS bf16x8*)(lds + PG8_SA(b, h) + aoff + m * 2048 + k * 1024); } while (0)
; #define PG8_LDB(dst, b, h) do { _Pragma("unroll") for (int n = 0; n < 2; ++n) _Pragma("unroll") for (int k = 0; k < 2; ++k) dst[n][k] = *(const PG8_LAS bf16x8*)(lds + PG8_SB(b, h) + boff + n * 2048 + k * 1024); } while (0)
; template <class Epi, class Sched, bool ALIGN_EPI = false, bool SP2 = false>
; __device__ __forceinline__ void gemm_phase(PG8_LAS unsigned char* lds, const Gemm g, const Sched& S, const Epi& E, const int wid) {
;     ...
;         for (int t = 0; t < nt; t += 2) {
;             const bool last = (t == nt - 2);
;             const char* a1 = cA + (size_t)(t + 1) * kstep;
;             const char* a2 = last ? nA : cA + (size_t)(t + 2) * kstep; const char* b2 = last ? nB : cB + (size_t)(t + 2) * kstep;
;             const char* a3 = a2 + kstep; const char* b3 = b2 + kstep;
;             if (last && has_next) S.a_ready(nxt);
;     ...
;             PG8_LDB(B0, 0, 0); PG8_LDB(B1, 0, 1); PG8_SCHED; PG8_LDA(At, 0, 0); PG8_STAGE(PG8_SA(1, 1), a1 + hstep, voffA);
;             PG8_WAIT_V(8); PG8_WAIT_L(0); PG8_BAR; PG8_MMA(0, 0, At, B0); PG8_MMA(0, 1, At, B1); PG8_BAR; PG8_SCHED;
;             PG8_LDA(At, 0, 1); PG8_STAGE(PG8_SB(0, 0), b2, voffB); PG8_STAGE(PG8_SB(0, 1), b2 + hstep, voffB); PG8_STAGE(PG8_SA(0, 0), a2, voffA);
;             PG8_WAIT_V(8); PG8_WAIT_L(0); PG8_BAR; PG8_MMA(1, 0, At, B0); PG8_MMA(1, 1, At, B1); PG8_BAR; PG8_SCHED;
;             PG8_LDB(B0, 1, 0); PG8_LDB(B1, 1, 1); PG8_SCHED; PG8_LDA(At, 1, 0); PG8_STAGE(PG8_SA(0, 1), a2 + hstep, voffA);
;             PG8_WAIT_V(8); PG8_WAIT_L(0); PG8_BAR; PG8_MMA(0, 0, At, B0); PG8_MMA(0, 1, At, B1); PG8_BAR; PG8_SCHED;
;             PG8_LDA(At, 1, 1); PG8_STAGE(PG8_SB(1, 0), b3, voffB); PG8_STAGE(PG8_SB(1, 1), b3 + hstep, voffB); PG8_STAGE(PG8_SA(1, 0), a3, voffA);
;             PG8_WAIT_V(8); PG8_WAIT_L(0); PG8_BAR; PG8_MMA(1, 0, At, B0); PG8_MMA(1, 1, At, B1); PG8_BAR; PG8_SCHED;
	s_setprio 0
	s_add_i32 s9, 0, 0x18000
	s_add_i32 s33, 0, 0x1c000
	v_add_u32_e32 v68, s9, v162
	v_add_u32_e32 v178, s33, v162
	ds_read_b128 v[56:59], v68
	ds_read_b128 v[60:63], v68 offset:1024
	ds_read_b128 v[64:67], v68 offset:2048
	ds_read_b128 v[68:71], v68 offset:3072
	ds_read_b128 v[166:169], v178
	ds_read_b128 v[170:173], v178 offset:1024
	ds_read_b128 v[174:177], v178 offset:2048
	ds_read_b128 v[178:181], v178 offset:3072
	s_add_u32 s6, s6, s12
	s_addc_u32 s7, s7, s13
	s_mov_b32 m0, s65
	v_lshl_add_u64 v[224:225], s[6:7], 0, v[150:151]
	ds_read_b128 v[182:185], v165 offset:32768
	ds_read_b128 v[186:189], v165 offset:33792
	ds_read_b128 v[190:193], v165 offset:34816
	ds_read_b128 v[194:197], v165 offset:35840
	ds_read_b128 v[198:201], v165 offset:36864
	ds_read_b128 v[202:205], v165 offset:37888
	ds_read_b128 v[206:209], v165 offset:38912
	ds_read_b128 v[210:213], v165 offset:39936
	global_load_lds_dwordx4 v[224:225], off
	v_lshl_add_u64 v[224:225], s[6:7], 0, v[146:147]
	s_mov_b32 m0, s66
	s_nop 0
	global_load_lds_dwordx4 v[224:225], off
	s_waitcnt vmcnt(8)
	s_waitcnt lgkmcnt(0)
	s_setprio 1
	s_barrier
	v_mfma_f32_16x16x32_bf16 v[140:143], v[56:59], v[182:185], v[140:143]
	v_mfma_f32_16x16x32_bf16 v[136:139], v[64:67], v[182:185], v[136:139]
	v_mfma_f32_16x16x32_bf16 v[124:127], v[56:59], v[190:193], v[124:127]
	v_mfma_f32_16x16x32_bf16 v[120:123], v[64:67], v[190:193], v[120:123]
	v_mfma_f32_16x16x32_bf16 v[108:111], v[56:59], v[198:201], v[108:111]
	v_mfma_f32_16x16x32_bf16 v[104:107], v[64:67], v[198:201], v[104:107]
	v_mfma_f32_16x16x32_bf16 v[92:95], v[56:59], v[206:209], v[92:95]
	v_mfma_f32_16x16x32_bf16 v[88:91], v[64:67], v[206:209], v[88:91]
	v_mfma_f32_16x16x32_bf16 v[140:143], v[60:63], v[186:189], v[140:143]
	v_mfma_f32_16x16x32_bf16 v[136:139], v[68:71], v[186:189], v[136:139]
	v_mfma_f32_16x16x32_bf16 v[124:127], v[60:63], v[194:197], v[124:127]
	v_mfma_f32_16x16x32_bf16 v[120:123], v[68:71], v[194:197], v[120:123]
	v_mfma_f32_16x16x32_bf16 v[108:111], v[60:63], v[202:205], v[108:111]
	v_mfma_f32_16x16x32_bf16 v[104:107], v[68:71], v[202:205], v[104:107]
	v_mfma_f32_16x16x32_bf16 v[92:95], v[60:63], v[210:213], v[92:95]
	v_mfma_f32_16x16x32_bf16 v[88:91], v[68:71], v[210:213], v[88:91]
	v_mfma_f32_16x16x32_bf16 v[132:135], v[166:169], v[182:185], v[132:135]
	v_mfma_f32_16x16x32_bf16 v[128:131], v[174:177], v[182:185], v[128:131]
	v_mfma_f32_16x16x32_bf16 v[116:119], v[166:169], v[190:193], v[116:119]
	v_mfma_f32_16x16x32_bf16 v[112:115], v[174:177], v[190:193], v[112:115]
	v_mfma_f32_16x16x32_bf16 v[100:103], v[166:169], v[198:201], v[100:103]
	v_mfma_f32_16x16x32_bf16 v[96:99], v[174:177], v[198:201], v[96:99]
	v_mfma_f32_16x16x32_bf16 v[84:87], v[166:169], v[206:209], v[84:87]
	v_mfma_f32_16x16x32_bf16 v[80:83], v[174:177], v[206:209], v[80:83]
	v_mfma_f32_16x16x32_bf16 v[132:135], v[170:173], v[186:189], v[132:135]
	v_mfma_f32_16x16x32_bf16 v[128:131], v[178:181], v[186:189], v[128:131]
	v_mfma_f32_16x16x32_bf16 v[116:119], v[170:173], v[194:197], v[116:119]
	v_mfma_f32_16x16x32_bf16 v[112:115], v[178:181], v[194:197], v[112:115]
	v_mfma_f32_16x16x32_bf16 v[100:103], v[170:173], v[202:205], v[100:103]
	v_mfma_f32_16x16x32_bf16 v[96:99], v[178:181], v[202:205], v[96:99]
	v_mfma_f32_16x16x32_bf16 v[84:87], v[170:173], v[210:213], v[84:87]
	v_mfma_f32_16x16x32_bf16 v[80:83], v[178:181], v[210:213], v[80:83]
	s_barrier
	s_setprio 0
	s_add_i32 s6, s9, s55
	v_lshl_add_u64 v[158:159], v[158:159], 0, s[26:27]
	s_mov_b32 m0, s6
	ds_read_b128 v[182:185], v165 offset:49152
	ds_read_b128 v[186:189], v165 offset:50176
	ds_read_b128 v[190:193], v165 offset:51200
	ds_read_b128 v[194:197], v165 offset:52224
	ds_read_b128 v[198:201], v165 offset:53248
	ds_read_b128 v[202:205], v165 offset:54272
	ds_read_b128 v[206:209], v165 offset:55296
	ds_read_b128 v[210:213], v165 offset:56320
	global_load_lds_dwordx4 v[158:159], off
	v_lshl_add_u64 v[158:159], v[214:215], 0, s[26:27]
	s_add_i32 m0, s6, 0x2000
	s_add_i32 s6, s33, s55
	global_load_lds_dwordx4 v[158:159], off
	v_lshl_add_u64 v[158:159], v[216:217], 0, s[26:27]
	s_mov_b32 m0, s6
	s_nop 0
	global_load_lds_dwordx4 v[158:159], off
	v_lshl_add_u64 v[158:159], v[218:219], 0, s[26:27]
	s_add_i32 m0, s6, 0x2000
	s_nop 0
	global_load_lds_dwordx4 v[158:159], off
	v_lshl_add_u64 v[158:159], v[220:221], 0, s[26:27]
	s_mov_b32 m0, s68
	s_nop 0
	global_load_lds_dwordx4 v[158:159], off
	v_lshl_add_u64 v[158:159], v[222:223], 0, s[26:27]
	s_mov_b32 m0, s69
	s_nop 0
	global_load_lds_dwordx4 v[158:159], off
	s_waitcnt vmcnt(8)
	s_waitcnt lgkmcnt(0)
	s_setprio 1
	s_barrier
	v_mfma_f32_16x16x32_bf16 v[76:79], v[56:59], v[182:185], v[76:79]
	v_mfma_f32_16x16x32_bf16 v[72:75], v[64:67], v[182:185], v[72:75]
	v_mfma_f32_16x16x32_bf16 v[48:51], v[56:59], v[190:193], v[48:51]
	v_mfma_f32_16x16x32_bf16 v[40:43], v[64:67], v[190:193], v[40:43]
	v_mfma_f32_16x16x32_bf16 v[28:31], v[56:59], v[198:201], v[28:31]
	v_mfma_f32_16x16x32_bf16 v[24:27], v[64:67], v[198:201], v[24:27]
	v_mfma_f32_16x16x32_bf16 v[12:15], v[56:59], v[206:209], v[12:15]
	v_mfma_f32_16x16x32_bf16 v[8:11], v[64:67], v[206:209], v[8:11]
	v_mfma_f32_16x16x32_bf16 v[76:79], v[60:63], v[186:189], v[76:79]
	v_mfma_f32_16x16x32_bf16 v[72:75], v[68:71], v[186:189], v[72:75]
	v_mfma_f32_16x16x32_bf16 v[48:51], v[60:63], v[194:197], v[48:51]
	v_mfma_f32_16x16x32_bf16 v[40:43], v[68:71], v[194:197], v[40:43]
	v_mfma_f32_16x16x32_bf16 v[28:31], v[60:63], v[202:205], v[28:31]
	v_mfma_f32_16x16x32_bf16 v[24:27], v[68:71], v[202:205], v[24:27]
	v_mfma_f32_16x16x32_bf16 v[12:15], v[60:63], v[210:213], v[12:15]
	v_mfma_f32_16x16x32_bf16 v[8:11], v[68:71], v[210:213], v[8:11]
	v_mfma_f32_16x16x32_bf16 v[44:47], v[166:169], v[182:185], v[44:47]
	v_mfma_f32_16x16x32_bf16 v[64:67], v[170:173], v[186:189], v[44:47]
	v_mfma_f32_16x16x32_bf16 v[44:47], v[174:177], v[182:185], v[52:55]
	v_mfma_f32_16x16x32_bf16 v[36:39], v[166:169], v[190:193], v[36:39]
	v_mfma_f32_16x16x32_bf16 v[32:35], v[174:177], v[190:193], v[32:35]
	v_mfma_f32_16x16x32_bf16 v[20:23], v[166:169], v[198:201], v[20:23]
	v_mfma_f32_16x16x32_bf16 v[16:19], v[174:177], v[198:201], v[16:19]
	v_mfma_f32_16x16x32_bf16 v[4:7], v[166:169], v[206:209], v[4:7]
	v_mfma_f32_16x16x32_bf16 v[0:3], v[174:177], v[206:209], v[0:3]
	v_mfma_f32_16x16x32_bf16 v[56:59], v[178:181], v[186:189], v[44:47]
	v_mfma_f32_16x16x32_bf16 v[36:39], v[170:173], v[194:197], v[36:39]
	v_mfma_f32_16x16x32_bf16 v[32:35], v[178:181], v[194:197], v[32:35]
	v_mfma_f32_16x16x32_bf16 v[20:23], v[170:173], v[202:205], v[20:23]
	v_mfma_f32_16x16x32_bf16 v[16:19], v[178:181], v[202:205], v[16:19]
	v_mfma_f32_16x16x32_bf16 v[4:7], v[170:173], v[210:213], v[4:7]
	v_mfma_f32_16x16x32_bf16 v[0:3], v[178:181], v[210:213], v[0:3]
	s_barrier
	s_setprio 0
	s_add_u32 s4, s4, 0x100
	s_addc_u32 s5, s5, 0
	s_add_u32 s0, s0, 0x100
	s_addc_u32 s1, s1, 0
	s_cmp_ge_i32 s8, s70
	s_mov_b32 s6, s8
	s_cbranch_scc0 .LBB0_1100

; #define PG8_STAGE(bufoff, gbase, voff) do { _Pragma("unroll") for (int _i = 0; _i < 2; ++_i) \
;         __builtin_amdgcn_global_load_lds((const unsigned*)((const char*)(gbase) + (voff)[_i]), (PG8_LAS unsigned*)(lds + (bufoff) + ldsw + _i * 8192), 16, 0, 0); } while (0)
; #define PG8_LDA(dst, b, h) do { _Pragma("unroll") for (int m = 0; m < 4; ++m) _Pragma("unroll") for (int k = 0; k < 2; ++k) dst[m][k] = *(const PG8_LAS bf16x8*)(lds + PG8_SA(b, h) + aoff + m * 2048 + k * 1024); } while (0)
; template <class Epi, class Sched, bool ALIGN_EPI = false, bool SP2 = false>
; __device__ __forceinline__ void gemm_phase(PG8_LAS unsigned char* lds, const Gemm g, const Sched& S, const Epi& E, const int wid) {
;     ...
;         const bool has_next = S.next(ui + 1, nxt);
;         const char* nA = has_next ? (const char*)g.A + (size_t)nxt.pm * tstep : cA; const char* nB = has_next ? (const char*)g.Bt + (size_t)nxt.pn * tstep : cB;
;         for (int t = 0; t < nt; t += 2) {
;             const bool last = (t == nt - 2);
;             const char* a1 = cA + (size_t)(t + 1) * kstep;
;             const char* a2 = last ? nA : cA + (size_t)(t + 2) * kstep; const char* b2 = last ? nB : cB + (size_t)(t + 2) * kstep;
;             const char* a3 = a2 + kstep; const char* b3 = b2 + kstep;
;             if (last && has_next) S.a_ready(nxt);
;             if constexpr (SP2) {
;             PG8_LDB(B0, 0, 0); PG8_LDB(B1, 0, 1); PG8_SCHED; PG8_LDA(At, 0, 0); PG8_STAGE(PG8_SA(1, 1), a1 + hstep, voffA);
;             PG8_WAIT_V(8); PG8_WAIT_L(0); PG8_BAR; PG8_MMA(0, 0, At, B0); PG8_MMA(0, 1, At, B1); PG8_BAR; PG8_SCHED;
;             PG8_LDA(At, 0, 1); PG8_STAGE(PG8_SB(0, 0), b2, voffB); PG8_STAGE(PG8_SB(0, 1), b2 + hstep, voffB); PG8_STAGE(PG8_SA(0, 0), a2, voffA);
;             PG8_WAIT_V(8); PG8_WAIT_L(0); PG8_BAR; PG8_MMA(1, 0, At, B0); PG8_MMA(1, 1, At, B1); PG8_BAR; PG8_SCHED;
;             PG8_LDB(B0, 1, 0); PG8_LDB(B1, 1, 1); PG8_SCHED; PG8_LDA(At, 1, 0); PG8_STAGE(PG8_SA(0, 1), a2 + hstep, voffA);
;             PG8_WAIT_V(8); PG8_WAIT_L(0); PG8_BAR; PG8_MMA(0, 0, At, B0); PG8_MMA(0, 1, At, B1); PG8_BAR; PG8_SCHED;
;             PG8_LDA(At, 1, 1); PG8_STAGE(PG8_SB(1, 0), b3, voffB); PG8_STAGE(PG8_SB(1, 1), b3 + hstep, voffB); PG8_STAGE(PG8_SA(1, 0), a3, voffA);
;             PG8_WAIT_V(8); PG8_WAIT_L(0); PG8_BAR; PG8_MMA(1, 0, At, B0); PG8_MMA(1, 1, At, B1); PG8_BAR; PG8_SCHED;
.LBB0_1177:
	s_andn2_b64 vcc, exec, s[20:21]
	s_cbranch_vccnz .Lz_GMA
	s_add_u32 s26, s26, 0x80
	s_addc_u32 s27, s27, 0
	s_add_u32 s0, s28, 0x100
	s_addc_u32 s1, s29, 0
	s_mov_b32 s28, 0
	ds_read_b128 v[142:145], v149
	ds_read_b128 v[152:155], v149 offset:1024
	ds_read_b128 v[156:159], v149 offset:2048
	ds_read_b128 v[160:163], v149 offset:3072
	ds_read_b128 v[164:167], v150
	ds_read_b128 v[168:171], v150 offset:1024
	ds_read_b128 v[172:175], v150 offset:2048
	ds_read_b128 v[176:179], v150 offset:3072
	s_add_i32 s61, s28, 2
	s_add_u32 s33, s26, 0x80
	s_addc_u32 s29, s27, 0
	s_cmp_eq_u32 s53, s28
	s_cselect_b32 s28, s4, s33
	s_cselect_b32 s29, s5, s29
	s_cselect_b32 s63, s25, s1
	s_cselect_b32 s62, s24, s0
	v_lshl_add_u64 v[212:213], s[26:27], 0, v[136:137]
	s_add_i32 m0, s42, 0xc000
	ds_read_b128 v[180:183], v151
	ds_read_b128 v[184:187], v151 offset:1024
	ds_read_b128 v[188:191], v151 offset:2048
	ds_read_b128 v[192:195], v151 offset:3072
	ds_read_b128 v[196:199], v151 offset:4096
	ds_read_b128 v[200:203], v151 offset:5120
	ds_read_b128 v[204:207], v151 offset:6144
	ds_read_b128 v[208:211], v151 offset:7168
	global_load_lds_dwordx4 v[212:213], off
	v_lshl_add_u64 v[212:213], s[26:27], 0, v[138:139]
	s_add_i32 m0, s42, 0xe000
	s_nop 0
	global_load_lds_dwordx4 v[212:213], off
	s_waitcnt vmcnt(8)
	s_waitcnt lgkmcnt(0)
	s_setprio 1
	s_barrier
	v_mfma_f32_16x16x32_bf16 v[124:127], v[142:145], v[180:183], 0
	v_mfma_f32_16x16x32_bf16 v[120:123], v[156:159], v[180:183], 0
	v_mfma_f32_16x16x32_bf16 v[108:111], v[142:145], v[188:191], 0
	v_mfma_f32_16x16x32_bf16 v[104:107], v[156:159], v[188:191], 0
	v_mfma_f32_16x16x32_bf16 v[92:95], v[142:145], v[196:199], 0
	v_mfma_f32_16x16x32_bf16 v[88:91], v[156:159], v[196:199], 0
	v_mfma_f32_16x16x32_bf16 v[76:79], v[142:145], v[204:207], 0
	v_mfma_f32_16x16x32_bf16 v[72:75], v[156:159], v[204:207], 0
	v_mfma_f32_16x16x32_bf16 v[124:127], v[152:155], v[184:187], v[124:127]
	v_mfma_f32_16x16x32_bf16 v[120:123], v[160:163], v[184:187], v[120:123]
	v_mfma_f32_16x16x32_bf16 v[108:111], v[152:155], v[192:195], v[108:111]
	v_mfma_f32_16x16x32_bf16 v[104:107], v[160:163], v[192:195], v[104:107]
	v_mfma_f32_16x16x32_bf16 v[92:95], v[152:155], v[200:203], v[92:95]
	v_mfma_f32_16x16x32_bf16 v[88:91], v[160:163], v[200:203], v[88:91]
	v_mfma_f32_16x16x32_bf16 v[76:79], v[152:155], v[208:211], v[76:79]
	v_mfma_f32_16x16x32_bf16 v[72:75], v[160:163], v[208:211], v[72:75]
	v_mfma_f32_16x16x32_bf16 v[116:119], v[164:167], v[180:183], 0
	v_mfma_f32_16x16x32_bf16 v[112:115], v[172:175], v[180:183], 0
	v_mfma_f32_16x16x32_bf16 v[100:103], v[164:167], v[188:191], 0
	v_mfma_f32_16x16x32_bf16 v[96:99], v[172:175], v[188:191], 0
	v_mfma_f32_16x16x32_bf16 v[84:87], v[164:167], v[196:199], 0
	v_mfma_f32_16x16x32_bf16 v[80:83], v[172:175], v[196:199], 0
	v_mfma_f32_16x16x32_bf16 v[68:71], v[164:167], v[204:207], 0
	v_mfma_f32_16x16x32_bf16 v[64:67], v[172:175], v[204:207], 0
	v_mfma_f32_16x16x32_bf16 v[116:119], v[168:171], v[184:187], v[116:119]
	v_mfma_f32_16x16x32_bf16 v[112:115], v[176:179], v[184:187], v[112:115]
	v_mfma_f32_16x16x32_bf16 v[100:103], v[168:171], v[192:195], v[100:103]
	v_mfma_f32_16x16x32_bf16 v[96:99], v[176:179], v[192:195], v[96:99]
	v_mfma_f32_16x16x32_bf16 v[84:87], v[168:171], v[200:203], v[84:87]
	v_mfma_f32_16x16x32_bf16 v[80:83], v[176:179], v[200:203], v[80:83]
	v_mfma_f32_16x16x32_bf16 v[68:71], v[168:171], v[208:211], v[68:71]
	v_mfma_f32_16x16x32_bf16 v[64:67], v[176:179], v[208:211], v[64:67]
	s_barrier
	s_setprio 0
	s_add_i32 s33, s55, s34
	v_lshl_add_u64 v[212:213], s[62:63], 0, v[132:133]
	s_mov_b32 m0, s33
	ds_read_b128 v[180:183], v151 offset:16384
	ds_read_b128 v[184:187], v151 offset:17408
	ds_read_b128 v[188:191], v151 offset:18432
	ds_read_b128 v[192:195], v151 offset:19456
	ds_read_b128 v[196:199], v151 offset:20480
	ds_read_b128 v[200:203], v151 offset:21504
	ds_read_b128 v[204:207], v151 offset:22528
	ds_read_b128 v[208:211], v151 offset:23552
	global_load_lds_dwordx4 v[212:213], off
	s_add_i32 m0, s33, 0x2000
	v_lshl_add_u64 v[214:215], s[62:63], 0, v[128:129]
	s_add_u32 s62, s62, s8
	s_addc_u32 s63, s63, s9
	s_add_i32 s33, s56, s34
	global_load_lds_dwordx4 v[214:215], off
	v_lshl_add_u64 v[216:217], s[62:63], 0, v[132:133]
	s_mov_b32 m0, s33
	v_lshl_add_u64 v[218:219], s[62:63], 0, v[128:129]
	global_load_lds_dwordx4 v[216:217], off
	s_add_i32 m0, s33, 0x2000
	v_lshl_add_u64 v[220:221], s[28:29], 0, v[134:135]
	global_load_lds_dwordx4 v[218:219], off
	s_mov_b32 m0, s42
	v_lshl_add_u64 v[222:223], s[28:29], 0, v[130:131]
	global_load_lds_dwordx4 v[220:221], off
	s_mov_b32 m0, s43
	s_nop 0
	global_load_lds_dwordx4 v[222:223], off
	s_waitcnt vmcnt(8)
	s_waitcnt lgkmcnt(0)
	s_setprio 1
	s_barrier
; #define PG8_STAGE(bufoff, gbase, voff) do { _Pragma("unroll") for (int _i = 0; _i < 2; ++_i) \
;         __builtin_amdgcn_global_load_lds((const unsigned*)((const char*)(gbase) + (voff)[_i]), (PG8_LAS unsigned*)(lds + (bufoff) + ldsw + _i * 8192), 16, 0, 0); } while (0)
; #define PG8_LDA(dst, b, h) do { _Pragma("unroll") for (int m = 0; m < 4; ++m) _Pragma("unroll") for (int k = 0; k < 2; ++k) dst[m][k] = *(const PG8_LAS bf16x8*)(lds + PG8_SA(b, h) + aoff + m * 2048 + k * 1024); } while (0)
; #define PG8_LDB(dst, b, h) do { _Pragma("unroll") for (int n = 0; n < 2; ++n) _Pragma("unroll") for (int k = 0; k < 2; ++k) dst[n][k] = *(const PG8_LAS bf16x8*)(lds + PG8_SB(b, h) + boff + n * 2048 + k * 1024); } while (0)
; #define PG8_MMA(ai, bj, At, Bt) do { __builtin_amdgcn_s_setprio(1); _Pragma("unroll") for (int m = 0; m < 4; ++m) _Pragma("unroll") for (int n = 0; n < 2; ++n) _Pragma("unroll") for (int k = 0; k < 2; ++k) \
;         acc[ai][bj][m][n] = __builtin_amdgcn_mfma_f32_16x16x32_bf16(Bt[n][k], At[m][k], acc[ai][bj][m][n], 0, 0, 0); __builtin_amdgcn_s_setprio(0); } while (0)
; #define PG8_BAR __builtin_amdgcn_s_barrier()
; template <class Epi, class Sched, bool ALIGN_EPI = false, bool SP2 = false>
; __device__ __forceinline__ void gemm_phase(PG8_LAS unsigned char* lds, const Gemm g, const Sched& S, const Epi& E, const int wid) {
;     ...
;             PG8_LDB(B0, 0, 0); PG8_LDB(B1, 0, 1); PG8_SCHED; PG8_LDA(At, 0, 0); PG8_STAGE(PG8_SA(1, 1), a1 + hstep, voffA);
;             PG8_WAIT_V(8); PG8_WAIT_L(0); PG8_BAR; PG8_MMA(0, 0, At, B0); PG8_MMA(0, 1, At, B1); PG8_BAR; PG8_SCHED;
;             PG8_LDA(At, 0, 1); PG8_STAGE(PG8_SB(0, 0), b2, voffB); PG8_STAGE(PG8_SB(0, 1), b2 + hstep, voffB); PG8_STAGE(PG8_SA(0, 0), a2, voffA);
;             PG8_WAIT_V(8); PG8_WAIT_L(0); PG8_BAR; PG8_MMA(1, 0, At, B0); PG8_MMA(1, 1, At, B1); PG8_BAR; PG8_SCHED;
;             PG8_LDB(B0, 1, 0); PG8_LDB(B1, 1, 1); PG8_SCHED; PG8_LDA(At, 1, 0); PG8_STAGE(PG8_SA(0, 1), a2 + hstep, voffA);
;             PG8_WAIT_V(8); PG8_WAIT_L(0); PG8_BAR; PG8_MMA(0, 0, At, B0); PG8_MMA(0, 1, At, B1); PG8_BAR; PG8_SCHED;
;             PG8_LDA(At, 1, 1); PG8_STAGE(PG8_SB(1, 0), b3, voffB); PG8_STAGE(PG8_SB(1, 1), b3 + hstep, voffB); PG8_STAGE(PG8_SA(1, 0), a3, voffA);
;             PG8_WAIT_V(8); PG8_WAIT_L(0); PG8_BAR; PG8_MMA(1, 0, At, B0); PG8_MMA(1, 1, At, B1); PG8_BAR; PG8_SCHED;
	v_mfma_f32_16x16x32_bf16 v[60:63], v[142:145], v[180:183], 0
	v_mfma_f32_16x16x32_bf16 v[56:59], v[156:159], v[180:183], 0
	v_mfma_f32_16x16x32_bf16 v[44:47], v[142:145], v[188:191], 0
	v_mfma_f32_16x16x32_bf16 v[40:43], v[156:159], v[188:191], 0
	v_mfma_f32_16x16x32_bf16 v[28:31], v[142:145], v[196:199], 0
	v_mfma_f32_16x16x32_bf16 v[24:27], v[156:159], v[196:199], 0
	v_mfma_f32_16x16x32_bf16 v[12:15], v[142:145], v[204:207], 0
	v_mfma_f32_16x16x32_bf16 v[8:11], v[156:159], v[204:207], 0
	v_mfma_f32_16x16x32_bf16 v[60:63], v[152:155], v[184:187], v[60:63]
	v_mfma_f32_16x16x32_bf16 v[56:59], v[160:163], v[184:187], v[56:59]
	v_mfma_f32_16x16x32_bf16 v[44:47], v[152:155], v[192:195], v[44:47]
	v_mfma_f32_16x16x32_bf16 v[40:43], v[160:163], v[192:195], v[40:43]
	v_mfma_f32_16x16x32_bf16 v[28:31], v[152:155], v[200:203], v[28:31]
	v_mfma_f32_16x16x32_bf16 v[24:27], v[160:163], v[200:203], v[24:27]
	v_mfma_f32_16x16x32_bf16 v[12:15], v[152:155], v[208:211], v[12:15]
	v_mfma_f32_16x16x32_bf16 v[8:11], v[160:163], v[208:211], v[8:11]
	v_mfma_f32_16x16x32_bf16 v[52:55], v[164:167], v[180:183], 0
	v_mfma_f32_16x16x32_bf16 v[48:51], v[172:175], v[180:183], 0
	v_mfma_f32_16x16x32_bf16 v[36:39], v[164:167], v[188:191], 0
	v_mfma_f32_16x16x32_bf16 v[32:35], v[172:175], v[188:191], 0
	v_mfma_f32_16x16x32_bf16 v[20:23], v[164:167], v[196:199], 0
	v_mfma_f32_16x16x32_bf16 v[16:19], v[172:175], v[196:199], 0
	v_mfma_f32_16x16x32_bf16 v[4:7], v[164:167], v[204:207], 0
	v_mfma_f32_16x16x32_bf16 v[0:3], v[172:175], v[204:207], 0
	v_mfma_f32_16x16x32_bf16 v[52:55], v[168:171], v[184:187], v[52:55]
	v_mfma_f32_16x16x32_bf16 v[48:51], v[176:179], v[184:187], v[48:51]
	v_mfma_f32_16x16x32_bf16 v[36:39], v[168:171], v[192:195], v[36:39]
	v_mfma_f32_16x16x32_bf16 v[32:35], v[176:179], v[192:195], v[32:35]
	v_mfma_f32_16x16x32_bf16 v[20:23], v[168:171], v[200:203], v[20:23]
	v_mfma_f32_16x16x32_bf16 v[16:19], v[176:179], v[200:203], v[16:19]
	v_mfma_f32_16x16x32_bf16 v[4:7], v[168:171], v[208:211], v[4:7]
	v_mfma_f32_16x16x32_bf16 v[0:3], v[176:179], v[208:211], v[0:3]
	s_barrier
	s_setprio 0
	s_add_i32 s33, 0, 0x18000
	s_add_i32 s62, 0, 0x1c000
	v_add_u32_e32 v160, s33, v148
	v_add_u32_e32 v176, s62, v148
	ds_read_b128 v[142:145], v160
	ds_read_b128 v[152:155], v160 offset:1024
	ds_read_b128 v[156:159], v160 offset:2048
	ds_read_b128 v[160:163], v160 offset:3072
	ds_read_b128 v[164:167], v176
	ds_read_b128 v[168:171], v176 offset:1024
	ds_read_b128 v[172:175], v176 offset:2048
	ds_read_b128 v[176:179], v176 offset:3072
	s_add_u32 s28, s28, s8
	s_addc_u32 s29, s29, s9
	s_mov_b32 m0, s44
	v_lshl_add_u64 v[224:225], s[28:29], 0, v[134:135]
	ds_read_b128 v[180:183], v151 offset:32768
	ds_read_b128 v[184:187], v151 offset:33792
	ds_read_b128 v[188:191], v151 offset:34816
	ds_read_b128 v[192:195], v151 offset:35840
	ds_read_b128 v[196:199], v151 offset:36864
	ds_read_b128 v[200:203], v151 offset:37888
	ds_read_b128 v[204:207], v151 offset:38912
	ds_read_b128 v[208:211], v151 offset:39936
	global_load_lds_dwordx4 v[224:225], off
	v_lshl_add_u64 v[224:225], s[28:29], 0, v[130:131]
	s_mov_b32 m0, s45
	s_nop 0
	global_load_lds_dwordx4 v[224:225], off
	s_waitcnt vmcnt(8)
	s_waitcnt lgkmcnt(0)
	s_setprio 1
	s_barrier
	v_mfma_f32_16x16x32_bf16 v[124:127], v[142:145], v[180:183], v[124:127]
	v_mfma_f32_16x16x32_bf16 v[120:123], v[156:159], v[180:183], v[120:123]
	v_mfma_f32_16x16x32_bf16 v[108:111], v[142:145], v[188:191], v[108:111]
	v_mfma_f32_16x16x32_bf16 v[104:107], v[156:159], v[188:191], v[104:107]
	v_mfma_f32_16x16x32_bf16 v[92:95], v[142:145], v[196:199], v[92:95]
	v_mfma_f32_16x16x32_bf16 v[88:91], v[156:159], v[196:199], v[88:91]
	v_mfma_f32_16x16x32_bf16 v[76:79], v[142:145], v[204:207], v[76:79]
	v_mfma_f32_16x16x32_bf16 v[72:75], v[156:159], v[204:207], v[72:75]
	v_mfma_f32_16x16x32_bf16 v[124:127], v[152:155], v[184:187], v[124:127]
	v_mfma_f32_16x16x32_bf16 v[120:123], v[160:163], v[184:187], v[120:123]
	v_mfma_f32_16x16x32_bf16 v[108:111], v[152:155], v[192:195], v[108:111]
	v_mfma_f32_16x16x32_bf16 v[104:107], v[160:163], v[192:195], v[104:107]
	v_mfma_f32_16x16x32_bf16 v[92:95], v[152:155], v[200:203], v[92:95]
	v_mfma_f32_16x16x32_bf16 v[88:91], v[160:163], v[200:203], v[88:91]
	v_mfma_f32_16x16x32_bf16 v[76:79], v[152:155], v[208:211], v[76:79]
	v_mfma_f32_16x16x32_bf16 v[72:75], v[160:163], v[208:211], v[72:75]
	v_mfma_f32_16x16x32_bf16 v[116:119], v[164:167], v[180:183], v[116:119]
	v_mfma_f32_16x16x32_bf16 v[112:115], v[172:175], v[180:183], v[112:115]
	v_mfma_f32_16x16x32_bf16 v[100:103], v[164:167], v[188:191], v[100:103]
	v_mfma_f32_16x16x32_bf16 v[96:99], v[172:175], v[188:191], v[96:99]
	v_mfma_f32_16x16x32_bf16 v[84:87], v[164:167], v[196:199], v[84:87]
	v_mfma_f32_16x16x32_bf16 v[80:83], v[172:175], v[196:199], v[80:83]
	v_mfma_f32_16x16x32_bf16 v[68:71], v[164:167], v[204:207], v[68:71]
	v_mfma_f32_16x16x32_bf16 v[64:67], v[172:175], v[204:207], v[64:67]
	v_mfma_f32_16x16x32_bf16 v[116:119], v[168:171], v[184:187], v[116:119]
	v_mfma_f32_16x16x32_bf16 v[112:115], v[176:179], v[184:187], v[112:115]
	v_mfma_f32_16x16x32_bf16 v[100:103], v[168:171], v[192:195], v[100:103]
	v_mfma_f32_16x16x32_bf16 v[96:99], v[176:179], v[192:195], v[96:99]
	v_mfma_f32_16x16x32_bf16 v[84:87], v[168:171], v[200:203], v[84:87]
	v_mfma_f32_16x16x32_bf16 v[80:83], v[176:179], v[200:203], v[80:83]
	v_mfma_f32_16x16x32_bf16 v[68:71], v[168:171], v[208:211], v[68:71]
	v_mfma_f32_16x16x32_bf16 v[64:67], v[176:179], v[208:211], v[64:67]
	s_barrier
; #define PG8_STAGE(bufoff, gbase, voff) do { _Pragma("unroll") for (int _i = 0; _i < 2; ++_i) \
;         __builtin_amdgcn_global_load_lds((const unsigned*)((const char*)(gbase) + (voff)[_i]), (PG8_LAS unsigned*)(lds + (bufoff) + ldsw + _i * 8192), 16, 0, 0); } while (0)
; #define PG8_LDA(dst, b, h) do { _Pragma("unroll") for (int m = 0; m < 4; ++m) _Pragma("unroll") for (int k = 0; k < 2; ++k) dst[m][k] = *(const PG8_LAS bf16x8*)(lds + PG8_SA(b, h) + aoff + m * 2048 + k * 1024); } while (0)
; #define PG8_WAIT_V(n) asm volatile("s_waitcnt vmcnt(" #n ")" ::: "memory")
; #define PG8_WAIT_L(n) asm volatile("s_waitcnt lgkmcnt(" #n ")" ::: "memory")
; #define PG8_BAR __builtin_amdgcn_s_barrier()
; template <class Epi, class Sched, bool ALIGN_EPI = false, bool SP2 = false>
; __device__ __forceinline__ void gemm_phase(PG8_LAS unsigned char* lds, const Gemm g, const Sched& S, const Epi& E, const int wid) {
;     ...
;         for (int t = 0; t < nt; t += 2) {
;             const bool last = (t == nt - 2);
;             const char* a1 = cA + (size_t)(t + 1) * kstep;
;             const char* a2 = last ? nA : cA + (size_t)(t + 2) * kstep; const char* b2 = last ? nB : cB + (size_t)(t + 2) * kstep;
;             const char* a3 = a2 + kstep; const char* b3 = b2 + kstep;
;             if (last && has_next) S.a_ready(nxt);
;             if constexpr (SP2) {
;             PG8_LDB(B0, 0, 0); PG8_LDB(B1, 0, 1); PG8_SCHED; PG8_LDA(At, 0, 0); PG8_STAGE(PG8_SA(1, 1), a1 + hstep, voffA);
;             PG8_WAIT_V(8); PG8_WAIT_L(0); PG8_BAR; PG8_MMA(0, 0, At, B0); PG8_MMA(0, 1, At, B1); PG8_BAR; PG8_SCHED;
;             PG8_LDA(At, 0, 1); PG8_STAGE(PG8_SB(0, 0), b2, voffB); PG8_STAGE(PG8_SB(0, 1), b2 + hstep, voffB); PG8_STAGE(PG8_SA(0, 0), a2, voffA);
;             PG8_WAIT_V(8); PG8_WAIT_L(0); PG8_BAR; PG8_MMA(1, 0, At, B0); PG8_MMA(1, 1, At, B1); PG8_BAR; PG8_SCHED;
;             PG8_LDB(B0, 1, 0); PG8_LDB(B1, 1, 1); PG8_SCHED; PG8_LDA(At, 1, 0); PG8_STAGE(PG8_SA(0, 1), a2 + hstep, voffA);
;             PG8_WAIT_V(8); PG8_WAIT_L(0); PG8_BAR; PG8_MMA(0, 0, At, B0); PG8_MMA(0, 1, At, B1); PG8_BAR; PG8_SCHED;
;             PG8_LDA(At, 1, 1); PG8_STAGE(PG8_SB(1, 0), b3, voffB); PG8_STAGE(PG8_SB(1, 1), b3 + hstep, voffB); PG8_STAGE(PG8_SA(1, 0), a3, voffA);
;             PG8_WAIT_V(8); PG8_WAIT_L(0); PG8_BAR; PG8_MMA(1, 0, At, B0); PG8_MMA(1, 1, At, B1); PG8_BAR; PG8_SCHED;
	s_setprio 0
	s_add_i32 s28, s33, s34
	v_lshl_add_u64 v[212:213], v[212:213], 0, s[18:19]
	s_mov_b32 m0, s28
	ds_read_b128 v[180:183], v151 offset:49152
	ds_read_b128 v[184:187], v151 offset:50176
	ds_read_b128 v[188:191], v151 offset:51200
	ds_read_b128 v[192:195], v151 offset:52224
	ds_read_b128 v[196:199], v151 offset:53248
	ds_read_b128 v[200:203], v151 offset:54272
	ds_read_b128 v[204:207], v151 offset:55296
	ds_read_b128 v[208:211], v151 offset:56320
	global_load_lds_dwordx4 v[212:213], off
	v_lshl_add_u64 v[212:213], v[214:215], 0, s[18:19]
	s_add_i32 m0, s28, 0x2000
	s_add_i32 s28, s62, s34
	global_load_lds_dwordx4 v[212:213], off
	v_lshl_add_u64 v[212:213], v[216:217], 0, s[18:19]
	s_mov_b32 m0, s28
	s_nop 0
	global_load_lds_dwordx4 v[212:213], off
	v_lshl_add_u64 v[212:213], v[218:219], 0, s[18:19]
	s_add_i32 m0, s28, 0x2000
	s_nop 0
	global_load_lds_dwordx4 v[212:213], off
	v_lshl_add_u64 v[212:213], v[220:221], 0, s[18:19]
	s_mov_b32 m0, s47
	s_nop 0
	global_load_lds_dwordx4 v[212:213], off
	v_lshl_add_u64 v[212:213], v[222:223], 0, s[18:19]
	s_mov_b32 m0, s49
	s_nop 0
	global_load_lds_dwordx4 v[212:213], off
	s_waitcnt vmcnt(8)
	s_waitcnt lgkmcnt(0)
	s_setprio 1
	s_barrier
	v_mfma_f32_16x16x32_bf16 v[60:63], v[142:145], v[180:183], v[60:63]
	v_mfma_f32_16x16x32_bf16 v[56:59], v[156:159], v[180:183], v[56:59]
	v_mfma_f32_16x16x32_bf16 v[44:47], v[142:145], v[188:191], v[44:47]
	v_mfma_f32_16x16x32_bf16 v[40:43], v[156:159], v[188:191], v[40:43]
	v_mfma_f32_16x16x32_bf16 v[28:31], v[142:145], v[196:199], v[28:31]
	v_mfma_f32_16x16x32_bf16 v[24:27], v[156:159], v[196:199], v[24:27]
	v_mfma_f32_16x16x32_bf16 v[12:15], v[142:145], v[204:207], v[12:15]
	v_mfma_f32_16x16x32_bf16 v[8:11], v[156:159], v[204:207], v[8:11]
	v_mfma_f32_16x16x32_bf16 v[60:63], v[152:155], v[184:187], v[60:63]
	v_mfma_f32_16x16x32_bf16 v[56:59], v[160:163], v[184:187], v[56:59]
	v_mfma_f32_16x16x32_bf16 v[44:47], v[152:155], v[192:195], v[44:47]
	v_mfma_f32_16x16x32_bf16 v[40:43], v[160:163], v[192:195], v[40:43]
	v_mfma_f32_16x16x32_bf16 v[28:31], v[152:155], v[200:203], v[28:31]
	v_mfma_f32_16x16x32_bf16 v[24:27], v[160:163], v[200:203], v[24:27]
	v_mfma_f32_16x16x32_bf16 v[12:15], v[152:155], v[208:211], v[12:15]
	v_mfma_f32_16x16x32_bf16 v[8:11], v[160:163], v[208:211], v[8:11]
	v_mfma_f32_16x16x32_bf16 v[52:55], v[164:167], v[180:183], v[52:55]
	v_mfma_f32_16x16x32_bf16 v[48:51], v[172:175], v[180:183], v[48:51]
	v_mfma_f32_16x16x32_bf16 v[36:39], v[164:167], v[188:191], v[36:39]
	v_mfma_f32_16x16x32_bf16 v[32:35], v[172:175], v[188:191], v[32:35]
	v_mfma_f32_16x16x32_bf16 v[20:23], v[164:167], v[196:199], v[20:23]
	v_mfma_f32_16x16x32_bf16 v[16:19], v[172:175], v[196:199], v[16:19]
	v_mfma_f32_16x16x32_bf16 v[4:7], v[164:167], v[204:207], v[4:7]
	v_mfma_f32_16x16x32_bf16 v[0:3], v[172:175], v[204:207], v[0:3]
	v_mfma_f32_16x16x32_bf16 v[52:55], v[168:171], v[184:187], v[52:55]
	v_mfma_f32_16x16x32_bf16 v[48:51], v[176:179], v[184:187], v[48:51]
	v_mfma_f32_16x16x32_bf16 v[36:39], v[168:171], v[192:195], v[36:39]
	v_mfma_f32_16x16x32_bf16 v[32:35], v[176:179], v[192:195], v[32:35]
	v_mfma_f32_16x16x32_bf16 v[20:23], v[168:171], v[200:203], v[20:23]
	v_mfma_f32_16x16x32_bf16 v[16:19], v[176:179], v[200:203], v[16:19]
	v_mfma_f32_16x16x32_bf16 v[4:7], v[168:171], v[208:211], v[4:7]
	v_mfma_f32_16x16x32_bf16 v[0:3], v[176:179], v[208:211], v[0:3]
	s_barrier
	s_setprio 0
	s_add_u32 s26, s26, 0x100
	s_addc_u32 s27, s27, 0
	s_add_u32 s0, s0, 0x100
	s_addc_u32 s1, s1, 0
	s_cmp_ge_i32 s61, s50
	s_mov_b32 s28, s61
	s_cbranch_scc1 .LBB0_1180
.LBB0_1179:
	ds_read_b128 v[142:145], v149
	ds_read_b128 v[152:155], v149 offset:1024
	ds_read_b128 v[156:159], v149 offset:2048
	ds_read_b128 v[160:163], v149 offset:3072
	ds_read_b128 v[164:167], v150
	ds_read_b128 v[168:171], v150 offset:1024
	ds_read_b128 v[172:175], v150 offset:2048
	ds_read_b128 v[176:179], v150 offset:3072
	s_add_i32 s61, s28, 2
	s_add_u32 s33, s26, 0x80
	s_addc_u32 s29, s27, 0
	s_cmp_eq_u32 s53, s28
	s_cselect_b32 s28, s4, s33
	s_cselect_b32 s29, s5, s29
	s_cselect_b32 s63, s25, s1
	s_cselect_b32 s62, s24, s0
	v_lshl_add_u64 v[212:213], s[26:27], 0, v[136:137]
	s_add_i32 m0, s42, 0xc000
	ds_read_b128 v[180:183], v151
	ds_read_b128 v[184:187], v151 offset:1024
	ds_read_b128 v[188:191], v151 offset:2048
	ds_read_b128 v[192:195], v151 offset:3072
	ds_read_b128 v[196:199], v151 offset:4096
	ds_read_b128 v[200:203], v151 offset:5120
	ds_read_b128 v[204:207], v151 offset:6144
	ds_read_b128 v[208:211], v151 offset:7168
	global_load_lds_dwordx4 v[212:213], off
	v_lshl_add_u64 v[212:213], s[26:27], 0, v[138:139]
	s_add_i32 m0, s42, 0xe000
	s_nop 0
	global_load_lds_dwordx4 v[212:213], off
	s_waitcnt vmcnt(8)
	s_waitcnt lgkmcnt(0)
	s_setprio 1
	s_barrier
; #define PG8_STAGE(bufoff, gbase, voff) do { _Pragma("unroll") for (int _i = 0; _i < 2; ++_i) \
;         __builtin_amdgcn_global_load_lds((const unsigned*)((const char*)(gbase) + (voff)[_i]), (PG8_LAS unsigned*)(lds + (bufoff) + ldsw + _i * 8192), 16, 0, 0); } while (0)
; #define PG8_LDA(dst, b, h) do { _Pragma("unroll") for (int m = 0; m < 4; ++m) _Pragma("unroll") for (int k = 0; k < 2; ++k) dst[m][k] = *(const PG8_LAS bf16x8*)(lds + PG8_SA(b, h) + aoff + m * 2048 + k * 1024); } while (0)
; #define PG8_LDB(dst, b, h) do { _Pragma("unroll") for (int n = 0; n < 2; ++n) _Pragma("unroll") for (int k = 0; k < 2; ++k) dst[n][k] = *(const PG8_LAS bf16x8*)(lds + PG8_SB(b, h) + boff + n * 2048 + k * 1024); } while (0)
; #define PG8_MMA(ai, bj, At, Bt) do { __builtin_amdgcn_s_setprio(1); _Pragma("unroll") for (int m = 0; m < 4; ++m) _Pragma("unroll") for (int n = 0; n < 2; ++n) _Pragma("unroll") for (int k = 0; k < 2; ++k) \
;         acc[ai][bj][m][n] = __builtin_amdgcn_mfma_f32_16x16x32_bf16(Bt[n][k], At[m][k], acc[ai][bj][m][n], 0, 0, 0); __builtin_amdgcn_s_setprio(0); } while (0)
; #define PG8_BAR __builtin_amdgcn_s_barrier()
; template <class Epi, class Sched, bool ALIGN_EPI = false, bool SP2 = false>
; __device__ __forceinline__ void gemm_phase(PG8_LAS unsigned char* lds, const Gemm g, const Sched& S, const Epi& E, const int wid) {
;     ...
;             PG8_LDB(B0, 0, 0); PG8_LDB(B1, 0, 1); PG8_SCHED; PG8_LDA(At, 0, 0); PG8_STAGE(PG8_SA(1, 1), a1 + hstep, voffA);
;             PG8_WAIT_V(8); PG8_WAIT_L(0); PG8_BAR; PG8_MMA(0, 0, At, B0); PG8_MMA(0, 1, At, B1); PG8_BAR; PG8_SCHED;
;             PG8_LDA(At, 0, 1); PG8_STAGE(PG8_SB(0, 0), b2, voffB); PG8_STAGE(PG8_SB(0, 1), b2 + hstep, voffB); PG8_STAGE(PG8_SA(0, 0), a2, voffA);
;             PG8_WAIT_V(8); PG8_WAIT_L(0); PG8_BAR; PG8_MMA(1, 0, At, B0); PG8_MMA(1, 1, At, B1); PG8_BAR; PG8_SCHED;
;             PG8_LDB(B0, 1, 0); PG8_LDB(B1, 1, 1); PG8_SCHED; PG8_LDA(At, 1, 0); PG8_STAGE(PG8_SA(0, 1), a2 + hstep, voffA);
;             PG8_WAIT_V(8); PG8_WAIT_L(0); PG8_BAR; PG8_MMA(0, 0, At, B0); PG8_MMA(0, 1, At, B1); PG8_BAR; PG8_SCHED;
;             PG8_LDA(At, 1, 1); PG8_STAGE(PG8_SB(1, 0), b3, voffB); PG8_STAGE(PG8_SB(1, 1), b3 + hstep, voffB); PG8_STAGE(PG8_SA(1, 0), a3, voffA);
;             PG8_WAIT_V(8); PG8_WAIT_L(0); PG8_BAR; PG8_MMA(1, 0, At, B0); PG8_MMA(1, 1, At, B1); PG8_BAR; PG8_SCHED;
	v_mfma_f32_16x16x32_bf16 v[124:127], v[142:145], v[180:183], v[124:127]
	v_mfma_f32_16x16x32_bf16 v[120:123], v[156:159], v[180:183], v[120:123]
	v_mfma_f32_16x16x32_bf16 v[108:111], v[142:145], v[188:191], v[108:111]
	v_mfma_f32_16x16x32_bf16 v[104:107], v[156:159], v[188:191], v[104:107]
	v_mfma_f32_16x16x32_bf16 v[92:95], v[142:145], v[196:199], v[92:95]
	v_mfma_f32_16x16x32_bf16 v[88:91], v[156:159], v[196:199], v[88:91]
	v_mfma_f32_16x16x32_bf16 v[76:79], v[142:145], v[204:207], v[76:79]
	v_mfma_f32_16x16x32_bf16 v[72:75], v[156:159], v[204:207], v[72:75]
	v_mfma_f32_16x16x32_bf16 v[124:127], v[152:155], v[184:187], v[124:127]
	v_mfma_f32_16x16x32_bf16 v[120:123], v[160:163], v[184:187], v[120:123]
	v_mfma_f32_16x16x32_bf16 v[108:111], v[152:155], v[192:195], v[108:111]
	v_mfma_f32_16x16x32_bf16 v[104:107], v[160:163], v[192:195], v[104:107]
	v_mfma_f32_16x16x32_bf16 v[92:95], v[152:155], v[200:203], v[92:95]
	v_mfma_f32_16x16x32_bf16 v[88:91], v[160:163], v[200:203], v[88:91]
	v_mfma_f32_16x16x32_bf16 v[76:79], v[152:155], v[208:211], v[76:79]
	v_mfma_f32_16x16x32_bf16 v[72:75], v[160:163], v[208:211], v[72:75]
	v_mfma_f32_16x16x32_bf16 v[116:119], v[164:167], v[180:183], v[116:119]
	v_mfma_f32_16x16x32_bf16 v[112:115], v[172:175], v[180:183], v[112:115]
	v_mfma_f32_16x16x32_bf16 v[100:103], v[164:167], v[188:191], v[100:103]
	v_mfma_f32_16x16x32_bf16 v[96:99], v[172:175], v[188:191], v[96:99]
	v_mfma_f32_16x16x32_bf16 v[84:87], v[164:167], v[196:199], v[84:87]
	v_mfma_f32_16x16x32_bf16 v[80:83], v[172:175], v[196:199], v[80:83]
	v_mfma_f32_16x16x32_bf16 v[68:71], v[164:167], v[204:207], v[68:71]
	v_mfma_f32_16x16x32_bf16 v[64:67], v[172:175], v[204:207], v[64:67]
	v_mfma_f32_16x16x32_bf16 v[116:119], v[168:171], v[184:187], v[116:119]
	v_mfma_f32_16x16x32_bf16 v[112:115], v[176:179], v[184:187], v[112:115]
	v_mfma_f32_16x16x32_bf16 v[100:103], v[168:171], v[192:195], v[100:103]
	v_mfma_f32_16x16x32_bf16 v[96:99], v[176:179], v[192:195], v[96:99]
	v_mfma_f32_16x16x32_bf16 v[84:87], v[168:171], v[200:203], v[84:87]
	v_mfma_f32_16x16x32_bf16 v[80:83], v[176:179], v[200:203], v[80:83]
	v_mfma_f32_16x16x32_bf16 v[68:71], v[168:171], v[208:211], v[68:71]
	v_mfma_f32_16x16x32_bf16 v[64:67], v[176:179], v[208:211], v[64:67]
	s_barrier
	s_setprio 0
	s_add_i32 s33, s55, s34
	v_lshl_add_u64 v[212:213], s[62:63], 0, v[132:133]
	s_mov_b32 m0, s33
	ds_read_b128 v[180:183], v151 offset:16384
	ds_read_b128 v[184:187], v151 offset:17408
	ds_read_b128 v[188:191], v151 offset:18432
	ds_read_b128 v[192:195], v151 offset:19456
	ds_read_b128 v[196:199], v151 offset:20480
	ds_read_b128 v[200:203], v151 offset:21504
	ds_read_b128 v[204:207], v151 offset:22528
	ds_read_b128 v[208:211], v151 offset:23552
	global_load_lds_dwordx4 v[212:213], off
	s_add_i32 m0, s33, 0x2000
	v_lshl_add_u64 v[214:215], s[62:63], 0, v[128:129]
	s_add_u32 s62, s62, s8
	s_addc_u32 s63, s63, s9
	s_add_i32 s33, s56, s34
	global_load_lds_dwordx4 v[214:215], off
	v_lshl_add_u64 v[216:217], s[62:63], 0, v[132:133]
	s_mov_b32 m0, s33
	v_lshl_add_u64 v[218:219], s[62:63], 0, v[128:129]
	global_load_lds_dwordx4 v[216:217], off
	s_add_i32 m0, s33, 0x2000
	v_lshl_add_u64 v[220:221], s[28:29], 0, v[134:135]
	global_load_lds_dwordx4 v[218:219], off
	s_mov_b32 m0, s42
	v_lshl_add_u64 v[222:223], s[28:29], 0, v[130:131]
	global_load_lds_dwordx4 v[220:221], off
	s_mov_b32 m0, s43
	s_nop 0
	global_load_lds_dwordx4 v[222:223], off
	s_waitcnt vmcnt(8)
	s_waitcnt lgkmcnt(0)
	s_setprio 1
	s_barrier
	v_mfma_f32_16x16x32_bf16 v[60:63], v[142:145], v[180:183], v[60:63]
	v_mfma_f32_16x16x32_bf16 v[56:59], v[156:159], v[180:183], v[56:59]
	v_mfma_f32_16x16x32_bf16 v[44:47], v[142:145], v[188:191], v[44:47]
	v_mfma_f32_16x16x32_bf16 v[40:43], v[156:159], v[188:191], v[40:43]
	v_mfma_f32_16x16x32_bf16 v[28:31], v[142:145], v[196:199], v[28:31]
	v_mfma_f32_16x16x32_bf16 v[24:27], v[156:159], v[196:199], v[24:27]
	v_mfma_f32_16x16x32_bf16 v[12:15], v[142:145], v[204:207], v[12:15]
	v_mfma_f32_16x16x32_bf16 v[8:11], v[156:159], v[204:207], v[8:11]
	v_mfma_f32_16x16x32_bf16 v[60:63], v[152:155], v[184:187], v[60:63]
	v_mfma_f32_16x16x32_bf16 v[56:59], v[160:163], v[184:187], v[56:59]
	v_mfma_f32_16x16x32_bf16 v[44:47], v[152:155], v[192:195], v[44:47]
	v_mfma_f32_16x16x32_bf16 v[40:43], v[160:163], v[192:195], v[40:43]
	v_mfma_f32_16x16x32_bf16 v[28:31], v[152:155], v[200:203], v[28:31]
	v_mfma_f32_16x16x32_bf16 v[24:27], v[160:163], v[200:203], v[24:27]
	v_mfma_f32_16x16x32_bf16 v[12:15], v[152:155], v[208:211], v[12:15]
	v_mfma_f32_16x16x32_bf16 v[8:11], v[160:163], v[208:211], v[8:11]
	v_mfma_f32_16x16x32_bf16 v[52:55], v[164:167], v[180:183], v[52:55]
	v_mfma_f32_16x16x32_bf16 v[48:51], v[172:175], v[180:183], v[48:51]
	v_mfma_f32_16x16x32_bf16 v[36:39], v[164:167], v[188:191], v[36:39]
	v_mfma_f32_16x16x32_bf16 v[32:35], v[172:175], v[188:191], v[32:35]
	v_mfma_f32_16x16x32_bf16 v[20:23], v[164:167], v[196:199], v[20:23]
	v_mfma_f32_16x16x32_bf16 v[16:19], v[172:175], v[196:199], v[16:19]
	v_mfma_f32_16x16x32_bf16 v[4:7], v[164:167], v[204:207], v[4:7]
	v_mfma_f32_16x16x32_bf16 v[0:3], v[172:175], v[204:207], v[0:3]
	v_mfma_f32_16x16x32_bf16 v[52:55], v[168:171], v[184:187], v[52:55]
	v_mfma_f32_16x16x32_bf16 v[48:51], v[176:179], v[184:187], v[48:51]
	v_mfma_f32_16x16x32_bf16 v[36:39], v[168:171], v[192:195], v[36:39]
	v_mfma_f32_16x16x32_bf16 v[32:35], v[176:179], v[192:195], v[32:35]
	v_mfma_f32_16x16x32_bf16 v[20:23], v[168:171], v[200:203], v[20:23]
	v_mfma_f32_16x16x32_bf16 v[16:19], v[176:179], v[200:203], v[16:19]
	v_mfma_f32_16x16x32_bf16 v[4:7], v[168:171], v[208:211], v[4:7]
	v_mfma_f32_16x16x32_bf16 v[0:3], v[176:179], v[208:211], v[0:3]
	s_barrier
; #define PG8_STAGE(bufoff, gbase, voff) do { _Pragma("unroll") for (int _i = 0; _i < 2; ++_i) \
;         __builtin_amdgcn_global_load_lds((const unsigned*)((const char*)(gbase) + (voff)[_i]), (PG8_LAS unsigned*)(lds + (bufoff) + ldsw + _i * 8192), 16, 0, 0); } while (0)
; #define PG8_LDA(dst, b, h) do { _Pragma("unroll") for (int m = 0; m < 4; ++m) _Pragma("unroll") for (int k = 0; k < 2; ++k) dst[m][k] = *(const PG8_LAS bf16x8*)(lds + PG8_SA(b, h) + aoff + m * 2048 + k * 1024); } while (0)
; #define PG8_LDB(dst, b, h) do { _Pragma("unroll") for (int n = 0; n < 2; ++n) _Pragma("unroll") for (int k = 0; k < 2; ++k) dst[n][k] = *(const PG8_LAS bf16x8*)(lds + PG8_SB(b, h) + boff + n * 2048 + k * 1024); } while (0)
; template <class Epi, class Sched, bool ALIGN_EPI = false, bool SP2 = false>
; __device__ __forceinline__ void gemm_phase(PG8_LAS unsigned char* lds, const Gemm g, const Sched& S, const Epi& E, const int wid) {
;     ...
;         for (int t = 0; t < nt; t += 2) {
;             const bool last = (t == nt - 2);
;             const char* a1 = cA + (size_t)(t + 1) * kstep;
;             const char* a2 = last ? nA : cA + (size_t)(t + 2) * kstep; const char* b2 = last ? nB : cB + (size_t)(t + 2) * kstep;
;             const char* a3 = a2 + kstep; const char* b3 = b2 + kstep;
;             if (last && has_next) S.a_ready(nxt);
;     ...
;             PG8_LDB(B0, 0, 0); PG8_LDB(B1, 0, 1); PG8_SCHED; PG8_LDA(At, 0, 0); PG8_STAGE(PG8_SA(1, 1), a1 + hstep, voffA);
;             PG8_WAIT_V(8); PG8_WAIT_L(0); PG8_BAR; PG8_MMA(0, 0, At, B0); PG8_MMA(0, 1, At, B1); PG8_BAR; PG8_SCHED;
;             PG8_LDA(At, 0, 1); PG8_STAGE(PG8_SB(0, 0), b2, voffB); PG8_STAGE(PG8_SB(0, 1), b2 + hstep, voffB); PG8_STAGE(PG8_SA(0, 0), a2, voffA);
;             PG8_WAIT_V(8); PG8_WAIT_L(0); PG8_BAR; PG8_MMA(1, 0, At, B0); PG8_MMA(1, 1, At, B1); PG8_BAR; PG8_SCHED;
;             PG8_LDB(B0, 1, 0); PG8_LDB(B1, 1, 1); PG8_SCHED; PG8_LDA(At, 1, 0); PG8_STAGE(PG8_SA(0, 1), a2 + hstep, voffA);
;             PG8_WAIT_V(8); PG8_WAIT_L(0); PG8_BAR; PG8_MMA(0, 0, At, B0); PG8_MMA(0, 1, At, B1); PG8_BAR; PG8_SCHED;
;             PG8_LDA(At, 1, 1); PG8_STAGE(PG8_SB(1, 0), b3, voffB); PG8_STAGE(PG8_SB(1, 1), b3 + hstep, voffB); PG8_STAGE(PG8_SA(1, 0), a3, voffA);
;             PG8_WAIT_V(8); PG8_WAIT_L(0); PG8_BAR; PG8_MMA(1, 0, At, B0); PG8_MMA(1, 1, At, B1); PG8_BAR; PG8_SCHED;
	s_setprio 0
	s_add_i32 s33, 0, 0x18000
	s_add_i32 s62, 0, 0x1c000
	v_add_u32_e32 v160, s33, v148
	v_add_u32_e32 v176, s62, v148
	ds_read_b128 v[142:145], v160
	ds_read_b128 v[152:155], v160 offset:1024
	ds_read_b128 v[156:159], v160 offset:2048
	ds_read_b128 v[160:163], v160 offset:3072
	ds_read_b128 v[164:167], v176
	ds_read_b128 v[168:171], v176 offset:1024
	ds_read_b128 v[172:175], v176 offset:2048
	ds_read_b128 v[176:179], v176 offset:3072
	s_add_u32 s28, s28, s8
	s_addc_u32 s29, s29, s9
	s_mov_b32 m0, s44
	v_lshl_add_u64 v[224:225], s[28:29], 0, v[134:135]
	ds_read_b128 v[180:183], v151 offset:32768
	ds_read_b128 v[184:187], v151 offset:33792
	ds_read_b128 v[188:191], v151 offset:34816
	ds_read_b128 v[192:195], v151 offset:35840
	ds_read_b128 v[196:199], v151 offset:36864
	ds_read_b128 v[200:203], v151 offset:37888
	ds_read_b128 v[204:207], v151 offset:38912
	ds_read_b128 v[208:211], v151 offset:39936
	global_load_lds_dwordx4 v[224:225], off
	v_lshl_add_u64 v[224:225], s[28:29], 0, v[130:131]
	s_mov_b32 m0, s45
	s_nop 0
	global_load_lds_dwordx4 v[224:225], off
	s_waitcnt vmcnt(8)
	s_waitcnt lgkmcnt(0)
	s_setprio 1
	s_barrier
	v_mfma_f32_16x16x32_bf16 v[124:127], v[142:145], v[180:183], v[124:127]
	v_mfma_f32_16x16x32_bf16 v[120:123], v[156:159], v[180:183], v[120:123]
	v_mfma_f32_16x16x32_bf16 v[108:111], v[142:145], v[188:191], v[108:111]
	v_mfma_f32_16x16x32_bf16 v[104:107], v[156:159], v[188:191], v[104:107]
	v_mfma_f32_16x16x32_bf16 v[92:95], v[142:145], v[196:199], v[92:95]
	v_mfma_f32_16x16x32_bf16 v[88:91], v[156:159], v[196:199], v[88:91]
	v_mfma_f32_16x16x32_bf16 v[76:79], v[142:145], v[204:207], v[76:79]
	v_mfma_f32_16x16x32_bf16 v[72:75], v[156:159], v[204:207], v[72:75]
	v_mfma_f32_16x16x32_bf16 v[124:127], v[152:155], v[184:187], v[124:127]
	v_mfma_f32_16x16x32_bf16 v[120:123], v[160:163], v[184:187], v[120:123]
	v_mfma_f32_16x16x32_bf16 v[108:111], v[152:155], v[192:195], v[108:111]
	v_mfma_f32_16x16x32_bf16 v[104:107], v[160:163], v[192:195], v[104:107]
	v_mfma_f32_16x16x32_bf16 v[92:95], v[152:155], v[200:203], v[92:95]
	v_mfma_f32_16x16x32_bf16 v[88:91], v[160:163], v[200:203], v[88:91]
	v_mfma_f32_16x16x32_bf16 v[76:79], v[152:155], v[208:211], v[76:79]
	v_mfma_f32_16x16x32_bf16 v[72:75], v[160:163], v[208:211], v[72:75]
	v_mfma_f32_16x16x32_bf16 v[116:119], v[164:167], v[180:183], v[116:119]
	v_mfma_f32_16x16x32_bf16 v[112:115], v[172:175], v[180:183], v[112:115]
	v_mfma_f32_16x16x32_bf16 v[100:103], v[164:167], v[188:191], v[100:103]
	v_mfma_f32_16x16x32_bf16 v[96:99], v[172:175], v[188:191], v[96:99]
	v_mfma_f32_16x16x32_bf16 v[84:87], v[164:167], v[196:199], v[84:87]
	v_mfma_f32_16x16x32_bf16 v[80:83], v[172:175], v[196:199], v[80:83]
	v_mfma_f32_16x16x32_bf16 v[68:71], v[164:167], v[204:207], v[68:71]
	v_mfma_f32_16x16x32_bf16 v[64:67], v[172:175], v[204:207], v[64:67]
	v_mfma_f32_16x16x32_bf16 v[116:119], v[168:171], v[184:187], v[116:119]
	v_mfma_f32_16x16x32_bf16 v[112:115], v[176:179], v[184:187], v[112:115]
	v_mfma_f32_16x16x32_bf16 v[100:103], v[168:171], v[192:195], v[100:103]
	v_mfma_f32_16x16x32_bf16 v[96:99], v[176:179], v[192:195], v[96:99]
	v_mfma_f32_16x16x32_bf16 v[84:87], v[168:171], v[200:203], v[84:87]
	v_mfma_f32_16x16x32_bf16 v[80:83], v[176:179], v[200:203], v[80:83]
	v_mfma_f32_16x16x32_bf16 v[68:71], v[168:171], v[208:211], v[68:71]
	v_mfma_f32_16x16x32_bf16 v[64:67], v[176:179], v[208:211], v[64:67]
	s_barrier
	s_setprio 0
	s_add_i32 s28, s33, s34
	v_lshl_add_u64 v[212:213], v[212:213], 0, s[18:19]
	s_mov_b32 m0, s28
	ds_read_b128 v[180:183], v151 offset:49152
	ds_read_b128 v[184:187], v151 offset:50176
	ds_read_b128 v[188:191], v151 offset:51200
	ds_read_b128 v[192:195], v151 offset:52224
	ds_read_b128 v[196:199], v151 offset:53248
	ds_read_b128 v[200:203], v151 offset:54272
	ds_read_b128 v[204:207], v151 offset:55296
	ds_read_b128 v[208:211], v151 offset:56320
	global_load_lds_dwordx4 v[212:213], off
	v_lshl_add_u64 v[212:213], v[214:215], 0, s[18:19]
	s_add_i32 m0, s28, 0x2000
	s_add_i32 s28, s62, s34
	global_load_lds_dwordx4 v[212:213], off
	v_lshl_add_u64 v[212:213], v[216:217], 0, s[18:19]
	s_mov_b32 m0, s28
	s_nop 0
	global_load_lds_dwordx4 v[212:213], off
	v_lshl_add_u64 v[212:213], v[218:219], 0, s[18:19]
	s_add_i32 m0, s28, 0x2000
	s_nop 0
	global_load_lds_dwordx4 v[212:213], off
	v_lshl_add_u64 v[212:213], v[220:221], 0, s[18:19]
	s_mov_b32 m0, s47
	s_nop 0
	global_load_lds_dwordx4 v[212:213], off
	v_lshl_add_u64 v[212:213], v[222:223], 0, s[18:19]
	s_mov_b32 m0, s49
	s_nop 0
	global_load_lds_dwordx4 v[212:213], off
	s_waitcnt vmcnt(8)
	s_waitcnt lgkmcnt(0)
	s_setprio 1
	s_barrier
	v_mfma_f32_16x16x32_bf16 v[60:63], v[142:145], v[180:183], v[60:63]
	v_mfma_f32_16x16x32_bf16 v[56:59], v[156:159], v[180:183], v[56:59]
	v_mfma_f32_16x16x32_bf16 v[44:47], v[142:145], v[188:191], v[44:47]
	v_mfma_f32_16x16x32_bf16 v[40:43], v[156:159], v[188:191], v[40:43]
	v_mfma_f32_16x16x32_bf16 v[28:31], v[142:145], v[196:199], v[28:31]
	v_mfma_f32_16x16x32_bf16 v[24:27], v[156:159], v[196:199], v[24:27]
	v_mfma_f32_16x16x32_bf16 v[12:15], v[142:145], v[204:207], v[12:15]
	v_mfma_f32_16x16x32_bf16 v[8:11], v[156:159], v[204:207], v[8:11]
	v_mfma_f32_16x16x32_bf16 v[60:63], v[152:155], v[184:187], v[60:63]
	v_mfma_f32_16x16x32_bf16 v[56:59], v[160:163], v[184:187], v[56:59]
	v_mfma_f32_16x16x32_bf16 v[44:47], v[152:155], v[192:195], v[44:47]
	v_mfma_f32_16x16x32_bf16 v[40:43], v[160:163], v[192:195], v[40:43]
	v_mfma_f32_16x16x32_bf16 v[28:31], v[152:155], v[200:203], v[28:31]
	v_mfma_f32_16x16x32_bf16 v[24:27], v[160:163], v[200:203], v[24:27]
	v_mfma_f32_16x16x32_bf16 v[12:15], v[152:155], v[208:211], v[12:15]
	v_mfma_f32_16x16x32_bf16 v[8:11], v[160:163], v[208:211], v[8:11]
	v_mfma_f32_16x16x32_bf16 v[52:55], v[164:167], v[180:183], v[52:55]
	v_mfma_f32_16x16x32_bf16 v[48:51], v[172:175], v[180:183], v[48:51]
	v_mfma_f32_16x16x32_bf16 v[36:39], v[164:167], v[188:191], v[36:39]
	v_mfma_f32_16x16x32_bf16 v[32:35], v[172:175], v[188:191], v[32:35]
	v_mfma_f32_16x16x32_bf16 v[20:23], v[164:167], v[196:199], v[20:23]
	v_mfma_f32_16x16x32_bf16 v[16:19], v[172:175], v[196:199], v[16:19]
	v_mfma_f32_16x16x32_bf16 v[4:7], v[164:167], v[204:207], v[4:7]
	v_mfma_f32_16x16x32_bf16 v[0:3], v[172:175], v[204:207], v[0:3]
	v_mfma_f32_16x16x32_bf16 v[52:55], v[168:171], v[184:187], v[52:55]
	v_mfma_f32_16x16x32_bf16 v[48:51], v[176:179], v[184:187], v[48:51]
	v_mfma_f32_16x16x32_bf16 v[36:39], v[168:171], v[192:195], v[36:39]
	v_mfma_f32_16x16x32_bf16 v[32:35], v[176:179], v[192:195], v[32:35]
	v_mfma_f32_16x16x32_bf16 v[20:23], v[168:171], v[200:203], v[20:23]
	v_mfma_f32_16x16x32_bf16 v[16:19], v[176:179], v[200:203], v[16:19]
	v_mfma_f32_16x16x32_bf16 v[4:7], v[168:171], v[208:211], v[4:7]
	v_mfma_f32_16x16x32_bf16 v[0:3], v[176:179], v[208:211], v[0:3]
	s_barrier
	s_setprio 0
	s_add_u32 s26, s26, 0x100
	s_addc_u32 s27, s27, 0
	s_add_u32 s0, s0, 0x100
	s_addc_u32 s1, s1, 0
	s_cmp_ge_i32 s61, s50
	s_mov_b32 s28, s61
	s_cbranch_scc0 .LBB0_1179

; #define PG8_STAGE(bufoff, gbase, voff) do { _Pragma("unroll") for (int _i = 0; _i < 2; ++_i) \
;         __builtin_amdgcn_global_load_lds((const unsigned*)((const char*)(gbase) + (voff)[_i]), (PG8_LAS unsigned*)(lds + (bufoff) + ldsw + _i * 8192), 16, 0, 0); } while (0)
; #define PG8_LDA(dst, b, h) do { _Pragma("unroll") for (int m = 0; m < 4; ++m) _Pragma("unroll") for (int k = 0; k < 2; ++k) dst[m][k] = *(const PG8_LAS bf16x8*)(lds + PG8_SA(b, h) + aoff + m * 2048 + k * 1024); } while (0)
; template <class Epi, class Sched, bool ALIGN_EPI = false, bool SP2 = false>
; __device__ __forceinline__ void gemm_phase(PG8_LAS unsigned char* lds, const Gemm g, const Sched& S, const Epi& E, const int wid) {
;     ...
;         const bool has_next = S.next(ui + 1, nxt);
;         const char* nA = has_next ? (const char*)g.A + (size_t)nxt.pm * tstep : cA; const char* nB = has_next ? (const char*)g.Bt + (size_t)nxt.pn * tstep : cB;
;         for (int t = 0; t < nt; t += 2) {
;             const bool last = (t == nt - 2);
;             const char* a1 = cA + (size_t)(t + 1) * kstep;
;             const char* a2 = last ? nA : cA + (size_t)(t + 2) * kstep; const char* b2 = last ? nB : cB + (size_t)(t + 2) * kstep;
;             const char* a3 = a2 + kstep; const char* b3 = b2 + kstep;
;             if (last && has_next) S.a_ready(nxt);
;             if constexpr (SP2) {
;             PG8_LDB(B0, 0, 0); PG8_LDB(B1, 0, 1); PG8_SCHED; PG8_LDA(At, 0, 0); PG8_STAGE(PG8_SA(1, 1), a1 + hstep, voffA);
;             PG8_WAIT_V(8); PG8_WAIT_L(0); PG8_BAR; PG8_MMA(0, 0, At, B0); PG8_MMA(0, 1, At, B1); PG8_BAR; PG8_SCHED;
;             PG8_LDA(At, 0, 1); PG8_STAGE(PG8_SB(0, 0), b2, voffB); PG8_STAGE(PG8_SB(0, 1), b2 + hstep, voffB); PG8_STAGE(PG8_SA(0, 0), a2, voffA);
;             PG8_WAIT_V(8); PG8_WAIT_L(0); PG8_BAR; PG8_MMA(1, 0, At, B0); PG8_MMA(1, 1, At, B1); PG8_BAR; PG8_SCHED;
;             PG8_LDB(B0, 1, 0); PG8_LDB(B1, 1, 1); PG8_SCHED; PG8_LDA(At, 1, 0); PG8_STAGE(PG8_SA(0, 1), a2 + hstep, voffA);
;             PG8_WAIT_V(8); PG8_WAIT_L(0); PG8_BAR; PG8_MMA(0, 0, At, B0); PG8_MMA(0, 1, At, B1); PG8_BAR; PG8_SCHED;
;             PG8_LDA(At, 1, 1); PG8_STAGE(PG8_SB(1, 0), b3, voffB); PG8_STAGE(PG8_SB(1, 1), b3 + hstep, voffB); PG8_STAGE(PG8_SA(1, 0), a3, voffA);
;             PG8_WAIT_V(8); PG8_WAIT_L(0); PG8_BAR; PG8_MMA(1, 0, At, B0); PG8_MMA(1, 1, At, B1); PG8_BAR; PG8_SCHED;
.LBB0_1256:
	s_andn2_b64 vcc, exec, s[20:21]
	s_cbranch_vccnz .Lz_GMB
	s_add_u32 s28, s28, 0x80
	s_addc_u32 s29, s29, 0
	s_add_u32 s0, s30, 0x100
	s_addc_u32 s1, s31, 0
	s_mov_b32 s30, 0
	ds_read_b128 v[142:145], v149
	ds_read_b128 v[152:155], v149 offset:1024
	ds_read_b128 v[156:159], v149 offset:2048
	ds_read_b128 v[160:163], v149 offset:3072
	ds_read_b128 v[164:167], v150
	ds_read_b128 v[168:171], v150 offset:1024
	ds_read_b128 v[172:175], v150 offset:2048
	ds_read_b128 v[176:179], v150 offset:3072
	s_add_i32 s66, s30, 2
	s_add_u32 s33, s28, 0x80
	s_addc_u32 s31, s29, 0
	s_cmp_eq_u32 s57, s30
	s_cselect_b32 s30, s4, s33
	s_cselect_b32 s31, s5, s31
	s_cselect_b32 s69, s27, s1
	s_cselect_b32 s68, s26, s0
	v_lshl_add_u64 v[212:213], s[28:29], 0, v[136:137]
	s_add_i32 m0, s46, 0xc000
	ds_read_b128 v[180:183], v151
	ds_read_b128 v[184:187], v151 offset:1024
	ds_read_b128 v[188:191], v151 offset:2048
	ds_read_b128 v[192:195], v151 offset:3072
	ds_read_b128 v[196:199], v151 offset:4096
	ds_read_b128 v[200:203], v151 offset:5120
	ds_read_b128 v[204:207], v151 offset:6144
	ds_read_b128 v[208:211], v151 offset:7168
	global_load_lds_dwordx4 v[212:213], off
	v_lshl_add_u64 v[212:213], s[28:29], 0, v[138:139]
	s_add_i32 m0, s46, 0xe000
	s_nop 0
	global_load_lds_dwordx4 v[212:213], off
	s_waitcnt vmcnt(8)
	s_waitcnt lgkmcnt(0)
	s_setprio 1
	s_barrier
	v_mfma_f32_16x16x32_bf16 v[124:127], v[142:145], v[180:183], 0
	v_mfma_f32_16x16x32_bf16 v[120:123], v[156:159], v[180:183], 0
	v_mfma_f32_16x16x32_bf16 v[108:111], v[142:145], v[188:191], 0
	v_mfma_f32_16x16x32_bf16 v[104:107], v[156:159], v[188:191], 0
	v_mfma_f32_16x16x32_bf16 v[92:95], v[142:145], v[196:199], 0
	v_mfma_f32_16x16x32_bf16 v[88:91], v[156:159], v[196:199], 0
	v_mfma_f32_16x16x32_bf16 v[76:79], v[142:145], v[204:207], 0
	v_mfma_f32_16x16x32_bf16 v[72:75], v[156:159], v[204:207], 0
	v_mfma_f32_16x16x32_bf16 v[124:127], v[152:155], v[184:187], v[124:127]
	v_mfma_f32_16x16x32_bf16 v[120:123], v[160:163], v[184:187], v[120:123]
	v_mfma_f32_16x16x32_bf16 v[108:111], v[152:155], v[192:195], v[108:111]
	v_mfma_f32_16x16x32_bf16 v[104:107], v[160:163], v[192:195], v[104:107]
	v_mfma_f32_16x16x32_bf16 v[92:95], v[152:155], v[200:203], v[92:95]
	v_mfma_f32_16x16x32_bf16 v[88:91], v[160:163], v[200:203], v[88:91]
	v_mfma_f32_16x16x32_bf16 v[76:79], v[152:155], v[208:211], v[76:79]
	v_mfma_f32_16x16x32_bf16 v[72:75], v[160:163], v[208:211], v[72:75]
	v_mfma_f32_16x16x32_bf16 v[116:119], v[164:167], v[180:183], 0
	v_mfma_f32_16x16x32_bf16 v[112:115], v[172:175], v[180:183], 0
	v_mfma_f32_16x16x32_bf16 v[100:103], v[164:167], v[188:191], 0
	v_mfma_f32_16x16x32_bf16 v[96:99], v[172:175], v[188:191], 0
	v_mfma_f32_16x16x32_bf16 v[84:87], v[164:167], v[196:199], 0
	v_mfma_f32_16x16x32_bf16 v[80:83], v[172:175], v[196:199], 0
	v_mfma_f32_16x16x32_bf16 v[68:71], v[164:167], v[204:207], 0
	v_mfma_f32_16x16x32_bf16 v[64:67], v[172:175], v[204:207], 0
	v_mfma_f32_16x16x32_bf16 v[116:119], v[168:171], v[184:187], v[116:119]
	v_mfma_f32_16x16x32_bf16 v[112:115], v[176:179], v[184:187], v[112:115]
	v_mfma_f32_16x16x32_bf16 v[100:103], v[168:171], v[192:195], v[100:103]
	v_mfma_f32_16x16x32_bf16 v[96:99], v[176:179], v[192:195], v[96:99]
	v_mfma_f32_16x16x32_bf16 v[84:87], v[168:171], v[200:203], v[84:87]
	v_mfma_f32_16x16x32_bf16 v[80:83], v[176:179], v[200:203], v[80:83]
	v_mfma_f32_16x16x32_bf16 v[68:71], v[168:171], v[208:211], v[68:71]
	v_mfma_f32_16x16x32_bf16 v[64:67], v[176:179], v[208:211], v[64:67]
	s_barrier
	s_setprio 0
	s_add_i32 s33, s59, s38
	v_lshl_add_u64 v[212:213], s[68:69], 0, v[132:133]
	s_mov_b32 m0, s33
	ds_read_b128 v[180:183], v151 offset:16384
	ds_read_b128 v[184:187], v151 offset:17408
	ds_read_b128 v[188:191], v151 offset:18432
	ds_read_b128 v[192:195], v151 offset:19456
	ds_read_b128 v[196:199], v151 offset:20480
	ds_read_b128 v[200:203], v151 offset:21504
	ds_read_b128 v[204:207], v151 offset:22528
	ds_read_b128 v[208:211], v151 offset:23552
	global_load_lds_dwordx4 v[212:213], off
	s_add_i32 m0, s33, 0x2000
	v_lshl_add_u64 v[214:215], s[68:69], 0, v[128:129]
	s_add_u32 s68, s68, s8
	s_addc_u32 s69, s69, s9
	s_add_i32 s33, s60, s38
	global_load_lds_dwordx4 v[214:215], off
	v_lshl_add_u64 v[216:217], s[68:69], 0, v[132:133]
	s_mov_b32 m0, s33
	v_lshl_add_u64 v[218:219], s[68:69], 0, v[128:129]
	global_load_lds_dwordx4 v[216:217], off
	s_add_i32 m0, s33, 0x2000
	v_lshl_add_u64 v[220:221], s[30:31], 0, v[134:135]
	global_load_lds_dwordx4 v[218:219], off
	s_mov_b32 m0, s46
	v_lshl_add_u64 v[222:223], s[30:31], 0, v[130:131]
	global_load_lds_dwordx4 v[220:221], off
	s_mov_b32 m0, s47
	s_nop 0
	global_load_lds_dwordx4 v[222:223], off
	s_waitcnt vmcnt(8)
	s_waitcnt lgkmcnt(0)
	s_setprio 1
	s_barrier
; #define PG8_STAGE(bufoff, gbase, voff) do { _Pragma("unroll") for (int _i = 0; _i < 2; ++_i) \
;         __builtin_amdgcn_global_load_lds((const unsigned*)((const char*)(gbase) + (voff)[_i]), (PG8_LAS unsigned*)(lds + (bufoff) + ldsw + _i * 8192), 16, 0, 0); } while (0)
; #define PG8_LDA(dst, b, h) do { _Pragma("unroll") for (int m = 0; m < 4; ++m) _Pragma("unroll") for (int k = 0; k < 2; ++k) dst[m][k] = *(const PG8_LAS bf16x8*)(lds + PG8_SA(b, h) + aoff + m * 2048 + k * 1024); } while (0)
; #define PG8_LDB(dst, b, h) do { _Pragma("unroll") for (int n = 0; n < 2; ++n) _Pragma("unroll") for (int k = 0; k < 2; ++k) dst[n][k] = *(const PG8_LAS bf16x8*)(lds + PG8_SB(b, h) + boff + n * 2048 + k * 1024); } while (0)
; #define PG8_MMA(ai, bj, At, Bt) do { __builtin_amdgcn_s_setprio(1); _Pragma("unroll") for (int m = 0; m < 4; ++m) _Pragma("unroll") for (int n = 0; n < 2; ++n) _Pragma("unroll") for (int k = 0; k < 2; ++k) \
;         acc[ai][bj][m][n] = __builtin_amdgcn_mfma_f32_16x16x32_bf16(Bt[n][k], At[m][k], acc[ai][bj][m][n], 0, 0, 0); __builtin_amdgcn_s_setprio(0); } while (0)
; #define PG8_BAR __builtin_amdgcn_s_barrier()
; template <class Epi, class Sched, bool ALIGN_EPI = false, bool SP2 = false>
; __device__ __forceinline__ void gemm_phase(PG8_LAS unsigned char* lds, const Gemm g, const Sched& S, const Epi& E, const int wid) {
;     ...
;             PG8_LDB(B0, 0, 0); PG8_LDB(B1, 0, 1); PG8_SCHED; PG8_LDA(At, 0, 0); PG8_STAGE(PG8_SA(1, 1), a1 + hstep, voffA);
;             PG8_WAIT_V(8); PG8_WAIT_L(0); PG8_BAR; PG8_MMA(0, 0, At, B0); PG8_MMA(0, 1, At, B1); PG8_BAR; PG8_SCHED;
;             PG8_LDA(At, 0, 1); PG8_STAGE(PG8_SB(0, 0), b2, voffB); PG8_STAGE(PG8_SB(0, 1), b2 + hstep, voffB); PG8_STAGE(PG8_SA(0, 0), a2, voffA);
;             PG8_WAIT_V(8); PG8_WAIT_L(0); PG8_BAR; PG8_MMA(1, 0, At, B0); PG8_MMA(1, 1, At, B1); PG8_BAR; PG8_SCHED;
;             PG8_LDB(B0, 1, 0); PG8_LDB(B1, 1, 1); PG8_SCHED; PG8_LDA(At, 1, 0); PG8_STAGE(PG8_SA(0, 1), a2 + hstep, voffA);
;             PG8_WAIT_V(8); PG8_WAIT_L(0); PG8_BAR; PG8_MMA(0, 0, At, B0); PG8_MMA(0, 1, At, B1); PG8_BAR; PG8_SCHED;
;             PG8_LDA(At, 1, 1); PG8_STAGE(PG8_SB(1, 0), b3, voffB); PG8_STAGE(PG8_SB(1, 1), b3 + hstep, voffB); PG8_STAGE(PG8_SA(1, 0), a3, voffA);
;             PG8_WAIT_V(8); PG8_WAIT_L(0); PG8_BAR; PG8_MMA(1, 0, At, B0); PG8_MMA(1, 1, At, B1); PG8_BAR; PG8_SCHED;
	v_mfma_f32_16x16x32_bf16 v[60:63], v[142:145], v[180:183], 0
	v_mfma_f32_16x16x32_bf16 v[56:59], v[156:159], v[180:183], 0
	v_mfma_f32_16x16x32_bf16 v[44:47], v[142:145], v[188:191], 0
	v_mfma_f32_16x16x32_bf16 v[40:43], v[156:159], v[188:191], 0
	v_mfma_f32_16x16x32_bf16 v[28:31], v[142:145], v[196:199], 0
	v_mfma_f32_16x16x32_bf16 v[24:27], v[156:159], v[196:199], 0
	v_mfma_f32_16x16x32_bf16 v[12:15], v[142:145], v[204:207], 0
	v_mfma_f32_16x16x32_bf16 v[8:11], v[156:159], v[204:207], 0
	v_mfma_f32_16x16x32_bf16 v[60:63], v[152:155], v[184:187], v[60:63]
	v_mfma_f32_16x16x32_bf16 v[56:59], v[160:163], v[184:187], v[56:59]
	v_mfma_f32_16x16x32_bf16 v[44:47], v[152:155], v[192:195], v[44:47]
	v_mfma_f32_16x16x32_bf16 v[40:43], v[160:163], v[192:195], v[40:43]
	v_mfma_f32_16x16x32_bf16 v[28:31], v[152:155], v[200:203], v[28:31]
	v_mfma_f32_16x16x32_bf16 v[24:27], v[160:163], v[200:203], v[24:27]
	v_mfma_f32_16x16x32_bf16 v[12:15], v[152:155], v[208:211], v[12:15]
	v_mfma_f32_16x16x32_bf16 v[8:11], v[160:163], v[208:211], v[8:11]
	v_mfma_f32_16x16x32_bf16 v[52:55], v[164:167], v[180:183], 0
	v_mfma_f32_16x16x32_bf16 v[48:51], v[172:175], v[180:183], 0
	v_mfma_f32_16x16x32_bf16 v[36:39], v[164:167], v[188:191], 0
	v_mfma_f32_16x16x32_bf16 v[32:35], v[172:175], v[188:191], 0
	v_mfma_f32_16x16x32_bf16 v[20:23], v[164:167], v[196:199], 0
	v_mfma_f32_16x16x32_bf16 v[16:19], v[172:175], v[196:199], 0
	v_mfma_f32_16x16x32_bf16 v[4:7], v[164:167], v[204:207], 0
	v_mfma_f32_16x16x32_bf16 v[0:3], v[172:175], v[204:207], 0
	v_mfma_f32_16x16x32_bf16 v[52:55], v[168:171], v[184:187], v[52:55]
	v_mfma_f32_16x16x32_bf16 v[48:51], v[176:179], v[184:187], v[48:51]
	v_mfma_f32_16x16x32_bf16 v[36:39], v[168:171], v[192:195], v[36:39]
	v_mfma_f32_16x16x32_bf16 v[32:35], v[176:179], v[192:195], v[32:35]
	v_mfma_f32_16x16x32_bf16 v[20:23], v[168:171], v[200:203], v[20:23]
	v_mfma_f32_16x16x32_bf16 v[16:19], v[176:179], v[200:203], v[16:19]
	v_mfma_f32_16x16x32_bf16 v[4:7], v[168:171], v[208:211], v[4:7]
	v_mfma_f32_16x16x32_bf16 v[0:3], v[176:179], v[208:211], v[0:3]
	s_barrier
	s_setprio 0
	s_add_i32 s33, 0, 0x18000
	s_add_i32 s67, 0, 0x1c000
	v_add_u32_e32 v160, s33, v148
	v_add_u32_e32 v176, s67, v148
	ds_read_b128 v[142:145], v160
	ds_read_b128 v[152:155], v160 offset:1024
	ds_read_b128 v[156:159], v160 offset:2048
	ds_read_b128 v[160:163], v160 offset:3072
	ds_read_b128 v[164:167], v176
	ds_read_b128 v[168:171], v176 offset:1024
	ds_read_b128 v[172:175], v176 offset:2048
	ds_read_b128 v[176:179], v176 offset:3072
	s_add_u32 s30, s30, s8
	s_addc_u32 s31, s31, s9
	s_mov_b32 m0, s49
	v_lshl_add_u64 v[224:225], s[30:31], 0, v[134:135]
	ds_read_b128 v[180:183], v151 offset:32768
	ds_read_b128 v[184:187], v151 offset:33792
	ds_read_b128 v[188:191], v151 offset:34816
	ds_read_b128 v[192:195], v151 offset:35840
	ds_read_b128 v[196:199], v151 offset:36864
	ds_read_b128 v[200:203], v151 offset:37888
	ds_read_b128 v[204:207], v151 offset:38912
	ds_read_b128 v[208:211], v151 offset:39936
	global_load_lds_dwordx4 v[224:225], off
	v_lshl_add_u64 v[224:225], s[30:31], 0, v[130:131]
	s_mov_b32 m0, s50
	s_nop 0
	global_load_lds_dwordx4 v[224:225], off
	s_waitcnt vmcnt(8)
	s_waitcnt lgkmcnt(0)
	s_setprio 1
	s_barrier
	v_mfma_f32_16x16x32_bf16 v[124:127], v[142:145], v[180:183], v[124:127]
	v_mfma_f32_16x16x32_bf16 v[120:123], v[156:159], v[180:183], v[120:123]
	v_mfma_f32_16x16x32_bf16 v[108:111], v[142:145], v[188:191], v[108:111]
	v_mfma_f32_16x16x32_bf16 v[104:107], v[156:159], v[188:191], v[104:107]
	v_mfma_f32_16x16x32_bf16 v[92:95], v[142:145], v[196:199], v[92:95]
	v_mfma_f32_16x16x32_bf16 v[88:91], v[156:159], v[196:199], v[88:91]
	v_mfma_f32_16x16x32_bf16 v[76:79], v[142:145], v[204:207], v[76:79]
	v_mfma_f32_16x16x32_bf16 v[72:75], v[156:159], v[204:207], v[72:75]
	v_mfma_f32_16x16x32_bf16 v[124:127], v[152:155], v[184:187], v[124:127]
	v_mfma_f32_16x16x32_bf16 v[120:123], v[160:163], v[184:187], v[120:123]
	v_mfma_f32_16x16x32_bf16 v[108:111], v[152:155], v[192:195], v[108:111]
	v_mfma_f32_16x16x32_bf16 v[104:107], v[160:163], v[192:195], v[104:107]
	v_mfma_f32_16x16x32_bf16 v[92:95], v[152:155], v[200:203], v[92:95]
	v_mfma_f32_16x16x32_bf16 v[88:91], v[160:163], v[200:203], v[88:91]
	v_mfma_f32_16x16x32_bf16 v[76:79], v[152:155], v[208:211], v[76:79]
	v_mfma_f32_16x16x32_bf16 v[72:75], v[160:163], v[208:211], v[72:75]
	v_mfma_f32_16x16x32_bf16 v[116:119], v[164:167], v[180:183], v[116:119]
	v_mfma_f32_16x16x32_bf16 v[112:115], v[172:175], v[180:183], v[112:115]
	v_mfma_f32_16x16x32_bf16 v[100:103], v[164:167], v[188:191], v[100:103]
	v_mfma_f32_16x16x32_bf16 v[96:99], v[172:175], v[188:191], v[96:99]
	v_mfma_f32_16x16x32_bf16 v[84:87], v[164:167], v[196:199], v[84:87]
	v_mfma_f32_16x16x32_bf16 v[80:83], v[172:175], v[196:199], v[80:83]
	v_mfma_f32_16x16x32_bf16 v[68:71], v[164:167], v[204:207], v[68:71]
	v_mfma_f32_16x16x32_bf16 v[64:67], v[172:175], v[204:207], v[64:67]
	v_mfma_f32_16x16x32_bf16 v[116:119], v[168:171], v[184:187], v[116:119]
	v_mfma_f32_16x16x32_bf16 v[112:115], v[176:179], v[184:187], v[112:115]
	v_mfma_f32_16x16x32_bf16 v[100:103], v[168:171], v[192:195], v[100:103]
	v_mfma_f32_16x16x32_bf16 v[96:99], v[176:179], v[192:195], v[96:99]
	v_mfma_f32_16x16x32_bf16 v[84:87], v[168:171], v[200:203], v[84:87]
	v_mfma_f32_16x16x32_bf16 v[80:83], v[176:179], v[200:203], v[80:83]
	v_mfma_f32_16x16x32_bf16 v[68:71], v[168:171], v[208:211], v[68:71]
	v_mfma_f32_16x16x32_bf16 v[64:67], v[176:179], v[208:211], v[64:67]
	s_barrier
; #define PG8_STAGE(bufoff, gbase, voff) do { _Pragma("unroll") for (int _i = 0; _i < 2; ++_i) \
;         __builtin_amdgcn_global_load_lds((const unsigned*)((const char*)(gbase) + (voff)[_i]), (PG8_LAS unsigned*)(lds + (bufoff) + ldsw + _i * 8192), 16, 0, 0); } while (0)
; #define PG8_LDA(dst, b, h) do { _Pragma("unroll") for (int m = 0; m < 4; ++m) _Pragma("unroll") for (int k = 0; k < 2; ++k) dst[m][k] = *(const PG8_LAS bf16x8*)(lds + PG8_SA(b, h) + aoff + m * 2048 + k * 1024); } while (0)
; #define PG8_WAIT_V(n) asm volatile("s_waitcnt vmcnt(" #n ")" ::: "memory")
; #define PG8_WAIT_L(n) asm volatile("s_waitcnt lgkmcnt(" #n ")" ::: "memory")
; #define PG8_BAR __builtin_amdgcn_s_barrier()
; template <class Epi, class Sched, bool ALIGN_EPI = false, bool SP2 = false>
; __device__ __forceinline__ void gemm_phase(PG8_LAS unsigned char* lds, const Gemm g, const Sched& S, const Epi& E, const int wid) {
;     ...
;         for (int t = 0; t < nt; t += 2) {
;             const bool last = (t == nt - 2);
;             const char* a1 = cA + (size_t)(t + 1) * kstep;
;             const char* a2 = last ? nA : cA + (size_t)(t + 2) * kstep; const char* b2 = last ? nB : cB + (size_t)(t + 2) * kstep;
;             const char* a3 = a2 + kstep; const char* b3 = b2 + kstep;
;             if (last && has_next) S.a_ready(nxt);
;             if constexpr (SP2) {
;             PG8_LDB(B0, 0, 0); PG8_LDB(B1, 0, 1); PG8_SCHED; PG8_LDA(At, 0, 0); PG8_STAGE(PG8_SA(1, 1), a1 + hstep, voffA);
;             PG8_WAIT_V(8); PG8_WAIT_L(0); PG8_BAR; PG8_MMA(0, 0, At, B0); PG8_MMA(0, 1, At, B1); PG8_BAR; PG8_SCHED;
;             PG8_LDA(At, 0, 1); PG8_STAGE(PG8_SB(0, 0), b2, voffB); PG8_STAGE(PG8_SB(0, 1), b2 + hstep, voffB); PG8_STAGE(PG8_SA(0, 0), a2, voffA);
;             PG8_WAIT_V(8); PG8_WAIT_L(0); PG8_BAR; PG8_MMA(1, 0, At, B0); PG8_MMA(1, 1, At, B1); PG8_BAR; PG8_SCHED;
;             PG8_LDB(B0, 1, 0); PG8_LDB(B1, 1, 1); PG8_SCHED; PG8_LDA(At, 1, 0); PG8_STAGE(PG8_SA(0, 1), a2 + hstep, voffA);
;             PG8_WAIT_V(8); PG8_WAIT_L(0); PG8_BAR; PG8_MMA(0, 0, At, B0); PG8_MMA(0, 1, At, B1); PG8_BAR; PG8_SCHED;
;             PG8_LDA(At, 1, 1); PG8_STAGE(PG8_SB(1, 0), b3, voffB); PG8_STAGE(PG8_SB(1, 1), b3 + hstep, voffB); PG8_STAGE(PG8_SA(1, 0), a3, voffA);
;             PG8_WAIT_V(8); PG8_WAIT_L(0); PG8_BAR; PG8_MMA(1, 0, At, B0); PG8_MMA(1, 1, At, B1); PG8_BAR; PG8_SCHED;
	s_setprio 0
	s_add_i32 s30, s33, s38
	v_lshl_add_u64 v[212:213], v[212:213], 0, s[18:19]
	s_mov_b32 m0, s30
	ds_read_b128 v[180:183], v151 offset:49152
	ds_read_b128 v[184:187], v151 offset:50176
	ds_read_b128 v[188:191], v151 offset:51200
	ds_read_b128 v[192:195], v151 offset:52224
	ds_read_b128 v[196:199], v151 offset:53248
	ds_read_b128 v[200:203], v151 offset:54272
	ds_read_b128 v[204:207], v151 offset:55296
	ds_read_b128 v[208:211], v151 offset:56320
	global_load_lds_dwordx4 v[212:213], off
	v_lshl_add_u64 v[212:213], v[214:215], 0, s[18:19]
	s_add_i32 m0, s30, 0x2000
	s_add_i32 s30, s67, s38
	global_load_lds_dwordx4 v[212:213], off
	v_lshl_add_u64 v[212:213], v[216:217], 0, s[18:19]
	s_mov_b32 m0, s30
	s_nop 0
	global_load_lds_dwordx4 v[212:213], off
	v_lshl_add_u64 v[212:213], v[218:219], 0, s[18:19]
	s_add_i32 m0, s30, 0x2000
	s_nop 0
	global_load_lds_dwordx4 v[212:213], off
	v_lshl_add_u64 v[212:213], v[220:221], 0, s[18:19]
	s_mov_b32 m0, s52
	s_nop 0
	global_load_lds_dwordx4 v[212:213], off
	v_lshl_add_u64 v[212:213], v[222:223], 0, s[18:19]
	s_mov_b32 m0, s53
	s_nop 0
	global_load_lds_dwordx4 v[212:213], off
	s_waitcnt vmcnt(8)
	s_waitcnt lgkmcnt(0)
	s_setprio 1
	s_barrier
	v_mfma_f32_16x16x32_bf16 v[60:63], v[142:145], v[180:183], v[60:63]
	v_mfma_f32_16x16x32_bf16 v[56:59], v[156:159], v[180:183], v[56:59]
	v_mfma_f32_16x16x32_bf16 v[44:47], v[142:145], v[188:191], v[44:47]
	v_mfma_f32_16x16x32_bf16 v[40:43], v[156:159], v[188:191], v[40:43]
	v_mfma_f32_16x16x32_bf16 v[28:31], v[142:145], v[196:199], v[28:31]
	v_mfma_f32_16x16x32_bf16 v[24:27], v[156:159], v[196:199], v[24:27]
	v_mfma_f32_16x16x32_bf16 v[12:15], v[142:145], v[204:207], v[12:15]
	v_mfma_f32_16x16x32_bf16 v[8:11], v[156:159], v[204:207], v[8:11]
	v_mfma_f32_16x16x32_bf16 v[60:63], v[152:155], v[184:187], v[60:63]
	v_mfma_f32_16x16x32_bf16 v[56:59], v[160:163], v[184:187], v[56:59]
	v_mfma_f32_16x16x32_bf16 v[44:47], v[152:155], v[192:195], v[44:47]
	v_mfma_f32_16x16x32_bf16 v[40:43], v[160:163], v[192:195], v[40:43]
	v_mfma_f32_16x16x32_bf16 v[28:31], v[152:155], v[200:203], v[28:31]
	v_mfma_f32_16x16x32_bf16 v[24:27], v[160:163], v[200:203], v[24:27]
	v_mfma_f32_16x16x32_bf16 v[12:15], v[152:155], v[208:211], v[12:15]
	v_mfma_f32_16x16x32_bf16 v[8:11], v[160:163], v[208:211], v[8:11]
	v_mfma_f32_16x16x32_bf16 v[52:55], v[164:167], v[180:183], v[52:55]
	v_mfma_f32_16x16x32_bf16 v[48:51], v[172:175], v[180:183], v[48:51]
	v_mfma_f32_16x16x32_bf16 v[36:39], v[164:167], v[188:191], v[36:39]
	v_mfma_f32_16x16x32_bf16 v[32:35], v[172:175], v[188:191], v[32:35]
	v_mfma_f32_16x16x32_bf16 v[20:23], v[164:167], v[196:199], v[20:23]
	v_mfma_f32_16x16x32_bf16 v[16:19], v[172:175], v[196:199], v[16:19]
	v_mfma_f32_16x16x32_bf16 v[4:7], v[164:167], v[204:207], v[4:7]
	v_mfma_f32_16x16x32_bf16 v[0:3], v[172:175], v[204:207], v[0:3]
	v_mfma_f32_16x16x32_bf16 v[52:55], v[168:171], v[184:187], v[52:55]
	v_mfma_f32_16x16x32_bf16 v[48:51], v[176:179], v[184:187], v[48:51]
	v_mfma_f32_16x16x32_bf16 v[36:39], v[168:171], v[192:195], v[36:39]
	v_mfma_f32_16x16x32_bf16 v[32:35], v[176:179], v[192:195], v[32:35]
	v_mfma_f32_16x16x32_bf16 v[20:23], v[168:171], v[200:203], v[20:23]
	v_mfma_f32_16x16x32_bf16 v[16:19], v[176:179], v[200:203], v[16:19]
	v_mfma_f32_16x16x32_bf16 v[4:7], v[168:171], v[208:211], v[4:7]
	v_mfma_f32_16x16x32_bf16 v[0:3], v[176:179], v[208:211], v[0:3]
	s_barrier
	s_setprio 0
	s_add_u32 s28, s28, 0x100
	s_addc_u32 s29, s29, 0
	s_add_u32 s0, s0, 0x100
	s_addc_u32 s1, s1, 0
	s_cmp_ge_i32 s66, s54
	s_mov_b32 s30, s66
	s_cbranch_scc1 .LBB0_1259
.LBB0_1258:
	ds_read_b128 v[142:145], v149
	ds_read_b128 v[152:155], v149 offset:1024
	ds_read_b128 v[156:159], v149 offset:2048
	ds_read_b128 v[160:163], v149 offset:3072
	ds_read_b128 v[164:167], v150
	ds_read_b128 v[168:171], v150 offset:1024
	ds_read_b128 v[172:175], v150 offset:2048
	ds_read_b128 v[176:179], v150 offset:3072
	s_add_i32 s66, s30, 2
	s_add_u32 s33, s28, 0x80
	s_addc_u32 s31, s29, 0
	s_cmp_eq_u32 s57, s30
	s_cselect_b32 s30, s4, s33
	s_cselect_b32 s31, s5, s31
	s_cselect_b32 s69, s27, s1
	s_cselect_b32 s68, s26, s0
	v_lshl_add_u64 v[212:213], s[28:29], 0, v[136:137]
	s_add_i32 m0, s46, 0xc000
	ds_read_b128 v[180:183], v151
	ds_read_b128 v[184:187], v151 offset:1024
	ds_read_b128 v[188:191], v151 offset:2048
	ds_read_b128 v[192:195], v151 offset:3072
	ds_read_b128 v[196:199], v151 offset:4096
	ds_read_b128 v[200:203], v151 offset:5120
	ds_read_b128 v[204:207], v151 offset:6144
	ds_read_b128 v[208:211], v151 offset:7168
	global_load_lds_dwordx4 v[212:213], off
	v_lshl_add_u64 v[212:213], s[28:29], 0, v[138:139]
	s_add_i32 m0, s46, 0xe000
	s_nop 0
	global_load_lds_dwordx4 v[212:213], off
	s_waitcnt vmcnt(8)
	s_waitcnt lgkmcnt(0)
	s_setprio 1
	s_barrier
; #define PG8_STAGE(bufoff, gbase, voff) do { _Pragma("unroll") for (int _i = 0; _i < 2; ++_i) \
;         __builtin_amdgcn_global_load_lds((const unsigned*)((const char*)(gbase) + (voff)[_i]), (PG8_LAS unsigned*)(lds + (bufoff) + ldsw + _i * 8192), 16, 0, 0); } while (0)
; #define PG8_LDA(dst, b, h) do { _Pragma("unroll") for (int m = 0; m < 4; ++m) _Pragma("unroll") for (int k = 0; k < 2; ++k) dst[m][k] = *(const PG8_LAS bf16x8*)(lds + PG8_SA(b, h) + aoff + m * 2048 + k * 1024); } while (0)
; #define PG8_LDB(dst, b, h) do { _Pragma("unroll") for (int n = 0; n < 2; ++n) _Pragma("unroll") for (int k = 0; k < 2; ++k) dst[n][k] = *(const PG8_LAS bf16x8*)(lds + PG8_SB(b, h) + boff + n * 2048 + k * 1024); } while (0)
; #define PG8_MMA(ai, bj, At, Bt) do { __builtin_amdgcn_s_setprio(1); _Pragma("unroll") for (int m = 0; m < 4; ++m) _Pragma("unroll") for (int n = 0; n < 2; ++n) _Pragma("unroll") for (int k = 0; k < 2; ++k) \
;         acc[ai][bj][m][n] = __builtin_amdgcn_mfma_f32_16x16x32_bf16(Bt[n][k], At[m][k], acc[ai][bj][m][n], 0, 0, 0); __builtin_amdgcn_s_setprio(0); } while (0)
; #define PG8_BAR __builtin_amdgcn_s_barrier()
; template <class Epi, class Sched, bool ALIGN_EPI = false, bool SP2 = false>
; __device__ __forceinline__ void gemm_phase(PG8_LAS unsigned char* lds, const Gemm g, const Sched& S, const Epi& E, const int wid) {
;     ...
;             PG8_LDB(B0, 0, 0); PG8_LDB(B1, 0, 1); PG8_SCHED; PG8_LDA(At, 0, 0); PG8_STAGE(PG8_SA(1, 1), a1 + hstep, voffA);
;             PG8_WAIT_V(8); PG8_WAIT_L(0); PG8_BAR; PG8_MMA(0, 0, At, B0); PG8_MMA(0, 1, At, B1); PG8_BAR; PG8_SCHED;
;             PG8_LDA(At, 0, 1); PG8_STAGE(PG8_SB(0, 0), b2, voffB); PG8_STAGE(PG8_SB(0, 1), b2 + hstep, voffB); PG8_STAGE(PG8_SA(0, 0), a2, voffA);
;             PG8_WAIT_V(8); PG8_WAIT_L(0); PG8_BAR; PG8_MMA(1, 0, At, B0); PG8_MMA(1, 1, At, B1); PG8_BAR; PG8_SCHED;
;             PG8_LDB(B0, 1, 0); PG8_LDB(B1, 1, 1); PG8_SCHED; PG8_LDA(At, 1, 0); PG8_STAGE(PG8_SA(0, 1), a2 + hstep, voffA);
;             PG8_WAIT_V(8); PG8_WAIT_L(0); PG8_BAR; PG8_MMA(0, 0, At, B0); PG8_MMA(0, 1, At, B1); PG8_BAR; PG8_SCHED;
;             PG8_LDA(At, 1, 1); PG8_STAGE(PG8_SB(1, 0), b3, voffB); PG8_STAGE(PG8_SB(1, 1), b3 + hstep, voffB); PG8_STAGE(PG8_SA(1, 0), a3, voffA);
;             PG8_WAIT_V(8); PG8_WAIT_L(0); PG8_BAR; PG8_MMA(1, 0, At, B0); PG8_MMA(1, 1, At, B1); PG8_BAR; PG8_SCHED;
	v_mfma_f32_16x16x32_bf16 v[124:127], v[142:145], v[180:183], v[124:127]
	v_mfma_f32_16x16x32_bf16 v[120:123], v[156:159], v[180:183], v[120:123]
	v_mfma_f32_16x16x32_bf16 v[108:111], v[142:145], v[188:191], v[108:111]
	v_mfma_f32_16x16x32_bf16 v[104:107], v[156:159], v[188:191], v[104:107]
	v_mfma_f32_16x16x32_bf16 v[92:95], v[142:145], v[196:199], v[92:95]
	v_mfma_f32_16x16x32_bf16 v[88:91], v[156:159], v[196:199], v[88:91]
	v_mfma_f32_16x16x32_bf16 v[76:79], v[142:145], v[204:207], v[76:79]
	v_mfma_f32_16x16x32_bf16 v[72:75], v[156:159], v[204:207], v[72:75]
	v_mfma_f32_16x16x32_bf16 v[124:127], v[152:155], v[184:187], v[124:127]
	v_mfma_f32_16x16x32_bf16 v[120:123], v[160:163], v[184:187], v[120:123]
	v_mfma_f32_16x16x32_bf16 v[108:111], v[152:155], v[192:195], v[108:111]
	v_mfma_f32_16x16x32_bf16 v[104:107], v[160:163], v[192:195], v[104:107]
	v_mfma_f32_16x16x32_bf16 v[92:95], v[152:155], v[200:203], v[92:95]
	v_mfma_f32_16x16x32_bf16 v[88:91], v[160:163], v[200:203], v[88:91]
	v_mfma_f32_16x16x32_bf16 v[76:79], v[152:155], v[208:211], v[76:79]
	v_mfma_f32_16x16x32_bf16 v[72:75], v[160:163], v[208:211], v[72:75]
	v_mfma_f32_16x16x32_bf16 v[116:119], v[164:167], v[180:183], v[116:119]
	v_mfma_f32_16x16x32_bf16 v[112:115], v[172:175], v[180:183], v[112:115]
	v_mfma_f32_16x16x32_bf16 v[100:103], v[164:167], v[188:191], v[100:103]
	v_mfma_f32_16x16x32_bf16 v[96:99], v[172:175], v[188:191], v[96:99]
	v_mfma_f32_16x16x32_bf16 v[84:87], v[164:167], v[196:199], v[84:87]
	v_mfma_f32_16x16x32_bf16 v[80:83], v[172:175], v[196:199], v[80:83]
	v_mfma_f32_16x16x32_bf16 v[68:71], v[164:167], v[204:207], v[68:71]
	v_mfma_f32_16x16x32_bf16 v[64:67], v[172:175], v[204:207], v[64:67]
	v_mfma_f32_16x16x32_bf16 v[116:119], v[168:171], v[184:187], v[116:119]
	v_mfma_f32_16x16x32_bf16 v[112:115], v[176:179], v[184:187], v[112:115]
	v_mfma_f32_16x16x32_bf16 v[100:103], v[168:171], v[192:195], v[100:103]
	v_mfma_f32_16x16x32_bf16 v[96:99], v[176:179], v[192:195], v[96:99]
	v_mfma_f32_16x16x32_bf16 v[84:87], v[168:171], v[200:203], v[84:87]
	v_mfma_f32_16x16x32_bf16 v[80:83], v[176:179], v[200:203], v[80:83]
	v_mfma_f32_16x16x32_bf16 v[68:71], v[168:171], v[208:211], v[68:71]
	v_mfma_f32_16x16x32_bf16 v[64:67], v[176:179], v[208:211], v[64:67]
	s_barrier
	s_setprio 0
	s_add_i32 s33, s59, s38
	v_lshl_add_u64 v[212:213], s[68:69], 0, v[132:133]
	s_mov_b32 m0, s33
	ds_read_b128 v[180:183], v151 offset:16384
	ds_read_b128 v[184:187], v151 offset:17408
	ds_read_b128 v[188:191], v151 offset:18432
	ds_read_b128 v[192:195], v151 offset:19456
	ds_read_b128 v[196:199], v151 offset:20480
	ds_read_b128 v[200:203], v151 offset:21504
	ds_read_b128 v[204:207], v151 offset:22528
	ds_read_b128 v[208:211], v151 offset:23552
	global_load_lds_dwordx4 v[212:213], off
	s_add_i32 m0, s33, 0x2000
	v_lshl_add_u64 v[214:215], s[68:69], 0, v[128:129]
	s_add_u32 s68, s68, s8
	s_addc_u32 s69, s69, s9
	s_add_i32 s33, s60, s38
	global_load_lds_dwordx4 v[214:215], off
	v_lshl_add_u64 v[216:217], s[68:69], 0, v[132:133]
	s_mov_b32 m0, s33
	v_lshl_add_u64 v[218:219], s[68:69], 0, v[128:129]
	global_load_lds_dwordx4 v[216:217], off
	s_add_i32 m0, s33, 0x2000
	v_lshl_add_u64 v[220:221], s[30:31], 0, v[134:135]
	global_load_lds_dwordx4 v[218:219], off
	s_mov_b32 m0, s46
	v_lshl_add_u64 v[222:223], s[30:31], 0, v[130:131]
	global_load_lds_dwordx4 v[220:221], off
	s_mov_b32 m0, s47
	s_nop 0
	global_load_lds_dwordx4 v[222:223], off
	s_waitcnt vmcnt(8)
	s_waitcnt lgkmcnt(0)
	s_setprio 1
	s_barrier
	v_mfma_f32_16x16x32_bf16 v[60:63], v[142:145], v[180:183], v[60:63]
	v_mfma_f32_16x16x32_bf16 v[56:59], v[156:159], v[180:183], v[56:59]
	v_mfma_f32_16x16x32_bf16 v[44:47], v[142:145], v[188:191], v[44:47]
	v_mfma_f32_16x16x32_bf16 v[40:43], v[156:159], v[188:191], v[40:43]
	v_mfma_f32_16x16x32_bf16 v[28:31], v[142:145], v[196:199], v[28:31]
	v_mfma_f32_16x16x32_bf16 v[24:27], v[156:159], v[196:199], v[24:27]
	v_mfma_f32_16x16x32_bf16 v[12:15], v[142:145], v[204:207], v[12:15]
	v_mfma_f32_16x16x32_bf16 v[8:11], v[156:159], v[204:207], v[8:11]
	v_mfma_f32_16x16x32_bf16 v[60:63], v[152:155], v[184:187], v[60:63]
	v_mfma_f32_16x16x32_bf16 v[56:59], v[160:163], v[184:187], v[56:59]
	v_mfma_f32_16x16x32_bf16 v[44:47], v[152:155], v[192:195], v[44:47]
	v_mfma_f32_16x16x32_bf16 v[40:43], v[160:163], v[192:195], v[40:43]
	v_mfma_f32_16x16x32_bf16 v[28:31], v[152:155], v[200:203], v[28:31]
	v_mfma_f32_16x16x32_bf16 v[24:27], v[160:163], v[200:203], v[24:27]
	v_mfma_f32_16x16x32_bf16 v[12:15], v[152:155], v[208:211], v[12:15]
	v_mfma_f32_16x16x32_bf16 v[8:11], v[160:163], v[208:211], v[8:11]
	v_mfma_f32_16x16x32_bf16 v[52:55], v[164:167], v[180:183], v[52:55]
	v_mfma_f32_16x16x32_bf16 v[48:51], v[172:175], v[180:183], v[48:51]
	v_mfma_f32_16x16x32_bf16 v[36:39], v[164:167], v[188:191], v[36:39]
	v_mfma_f32_16x16x32_bf16 v[32:35], v[172:175], v[188:191], v[32:35]
	v_mfma_f32_16x16x32_bf16 v[20:23], v[164:167], v[196:199], v[20:23]
	v_mfma_f32_16x16x32_bf16 v[16:19], v[172:175], v[196:199], v[16:19]
	v_mfma_f32_16x16x32_bf16 v[4:7], v[164:167], v[204:207], v[4:7]
	v_mfma_f32_16x16x32_bf16 v[0:3], v[172:175], v[204:207], v[0:3]
	v_mfma_f32_16x16x32_bf16 v[52:55], v[168:171], v[184:187], v[52:55]
	v_mfma_f32_16x16x32_bf16 v[48:51], v[176:179], v[184:187], v[48:51]
	v_mfma_f32_16x16x32_bf16 v[36:39], v[168:171], v[192:195], v[36:39]
	v_mfma_f32_16x16x32_bf16 v[32:35], v[176:179], v[192:195], v[32:35]
	v_mfma_f32_16x16x32_bf16 v[20:23], v[168:171], v[200:203], v[20:23]
	v_mfma_f32_16x16x32_bf16 v[16:19], v[176:179], v[200:203], v[16:19]
	v_mfma_f32_16x16x32_bf16 v[4:7], v[168:171], v[208:211], v[4:7]
	v_mfma_f32_16x16x32_bf16 v[0:3], v[176:179], v[208:211], v[0:3]
	s_barrier
; #define PG8_STAGE(bufoff, gbase, voff) do { _Pragma("unroll") for (int _i = 0; _i < 2; ++_i) \
;         __builtin_amdgcn_global_load_lds((const unsigned*)((const char*)(gbase) + (voff)[_i]), (PG8_LAS unsigned*)(lds + (bufoff) + ldsw + _i * 8192), 16, 0, 0); } while (0)
; #define PG8_LDA(dst, b, h) do { _Pragma("unroll") for (int m = 0; m < 4; ++m) _Pragma("unroll") for (int k = 0; k < 2; ++k) dst[m][k] = *(const PG8_LAS bf16x8*)(lds + PG8_SA(b, h) + aoff + m * 2048 + k * 1024); } while (0)
; #define PG8_LDB(dst, b, h) do { _Pragma("unroll") for (int n = 0; n < 2; ++n) _Pragma("unroll") for (int k = 0; k < 2; ++k) dst[n][k] = *(const PG8_LAS bf16x8*)(lds + PG8_SB(b, h) + boff + n * 2048 + k * 1024); } while (0)
; template <class Epi, class Sched, bool ALIGN_EPI = false, bool SP2 = false>
; __device__ __forceinline__ void gemm_phase(PG8_LAS unsigned char* lds, const Gemm g, const Sched& S, const Epi& E, const int wid) {
;     ...
;         for (int t = 0; t < nt; t += 2) {
;             const bool last = (t == nt - 2);
;             const char* a1 = cA + (size_t)(t + 1) * kstep;
;             const char* a2 = last ? nA : cA + (size_t)(t + 2) * kstep; const char* b2 = last ? nB : cB + (size_t)(t + 2) * kstep;
;             const char* a3 = a2 + kstep; const char* b3 = b2 + kstep;
;             if (last && has_next) S.a_ready(nxt);
;     ...
;             PG8_LDB(B0, 0, 0); PG8_LDB(B1, 0, 1); PG8_SCHED; PG8_LDA(At, 0, 0); PG8_STAGE(PG8_SA(1, 1), a1 + hstep, voffA);
;             PG8_WAIT_V(8); PG8_WAIT_L(0); PG8_BAR; PG8_MMA(0, 0, At, B0); PG8_MMA(0, 1, At, B1); PG8_BAR; PG8_SCHED;
;             PG8_LDA(At, 0, 1); PG8_STAGE(PG8_SB(0, 0), b2, voffB); PG8_STAGE(PG8_SB(0, 1), b2 + hstep, voffB); PG8_STAGE(PG8_SA(0, 0), a2, voffA);
;             PG8_WAIT_V(8); PG8_WAIT_L(0); PG8_BAR; PG8_MMA(1, 0, At, B0); PG8_MMA(1, 1, At, B1); PG8_BAR; PG8_SCHED;
;             PG8_LDB(B0, 1, 0); PG8_LDB(B1, 1, 1); PG8_SCHED; PG8_LDA(At, 1, 0); PG8_STAGE(PG8_SA(0, 1), a2 + hstep, voffA);
;             PG8_WAIT_V(8); PG8_WAIT_L(0); PG8_BAR; PG8_MMA(0, 0, At, B0); PG8_MMA(0, 1, At, B1); PG8_BAR; PG8_SCHED;
;             PG8_LDA(At, 1, 1); PG8_STAGE(PG8_SB(1, 0), b3, voffB); PG8_STAGE(PG8_SB(1, 1), b3 + hstep, voffB); PG8_STAGE(PG8_SA(1, 0), a3, voffA);
;             PG8_WAIT_V(8); PG8_WAIT_L(0); PG8_BAR; PG8_MMA(1, 0, At, B0); PG8_MMA(1, 1, At, B1); PG8_BAR; PG8_SCHED;
	s_setprio 0
	s_add_i32 s33, 0, 0x18000
	s_add_i32 s67, 0, 0x1c000
	v_add_u32_e32 v160, s33, v148
	v_add_u32_e32 v176, s67, v148
	ds_read_b128 v[142:145], v160
	ds_read_b128 v[152:155], v160 offset:1024
	ds_read_b128 v[156:159], v160 offset:2048
	ds_read_b128 v[160:163], v160 offset:3072
	ds_read_b128 v[164:167], v176
	ds_read_b128 v[168:171], v176 offset:1024
	ds_read_b128 v[172:175], v176 offset:2048
	ds_read_b128 v[176:179], v176 offset:3072
	s_add_u32 s30, s30, s8
	s_addc_u32 s31, s31, s9
	s_mov_b32 m0, s49
	v_lshl_add_u64 v[224:225], s[30:31], 0, v[134:135]
	ds_read_b128 v[180:183], v151 offset:32768
	ds_read_b128 v[184:187], v151 offset:33792
	ds_read_b128 v[188:191], v151 offset:34816
	ds_read_b128 v[192:195], v151 offset:35840
	ds_read_b128 v[196:199], v151 offset:36864
	ds_read_b128 v[200:203], v151 offset:37888
	ds_read_b128 v[204:207], v151 offset:38912
	ds_read_b128 v[208:211], v151 offset:39936
	global_load_lds_dwordx4 v[224:225], off
	v_lshl_add_u64 v[224:225], s[30:31], 0, v[130:131]
	s_mov_b32 m0, s50
	s_nop 0
	global_load_lds_dwordx4 v[224:225], off
	s_waitcnt vmcnt(8)
	s_waitcnt lgkmcnt(0)
	s_setprio 1
	s_barrier
	v_mfma_f32_16x16x32_bf16 v[124:127], v[142:145], v[180:183], v[124:127]
	v_mfma_f32_16x16x32_bf16 v[120:123], v[156:159], v[180:183], v[120:123]
	v_mfma_f32_16x16x32_bf16 v[108:111], v[142:145], v[188:191], v[108:111]
	v_mfma_f32_16x16x32_bf16 v[104:107], v[156:159], v[188:191], v[104:107]
	v_mfma_f32_16x16x32_bf16 v[92:95], v[142:145], v[196:199], v[92:95]
	v_mfma_f32_16x16x32_bf16 v[88:91], v[156:159], v[196:199], v[88:91]
	v_mfma_f32_16x16x32_bf16 v[76:79], v[142:145], v[204:207], v[76:79]
	v_mfma_f32_16x16x32_bf16 v[72:75], v[156:159], v[204:207], v[72:75]
	v_mfma_f32_16x16x32_bf16 v[124:127], v[152:155], v[184:187], v[124:127]
	v_mfma_f32_16x16x32_bf16 v[120:123], v[160:163], v[184:187], v[120:123]
	v_mfma_f32_16x16x32_bf16 v[108:111], v[152:155], v[192:195], v[108:111]
	v_mfma_f32_16x16x32_bf16 v[104:107], v[160:163], v[192:195], v[104:107]
	v_mfma_f32_16x16x32_bf16 v[92:95], v[152:155], v[200:203], v[92:95]
	v_mfma_f32_16x16x32_bf16 v[88:91], v[160:163], v[200:203], v[88:91]
	v_mfma_f32_16x16x32_bf16 v[76:79], v[152:155], v[208:211], v[76:79]
	v_mfma_f32_16x16x32_bf16 v[72:75], v[160:163], v[208:211], v[72:75]
	v_mfma_f32_16x16x32_bf16 v[116:119], v[164:167], v[180:183], v[116:119]
	v_mfma_f32_16x16x32_bf16 v[112:115], v[172:175], v[180:183], v[112:115]
	v_mfma_f32_16x16x32_bf16 v[100:103], v[164:167], v[188:191], v[100:103]
	v_mfma_f32_16x16x32_bf16 v[96:99], v[172:175], v[188:191], v[96:99]
	v_mfma_f32_16x16x32_bf16 v[84:87], v[164:167], v[196:199], v[84:87]
	v_mfma_f32_16x16x32_bf16 v[80:83], v[172:175], v[196:199], v[80:83]
	v_mfma_f32_16x16x32_bf16 v[68:71], v[164:167], v[204:207], v[68:71]
	v_mfma_f32_16x16x32_bf16 v[64:67], v[172:175], v[204:207], v[64:67]
	v_mfma_f32_16x16x32_bf16 v[116:119], v[168:171], v[184:187], v[116:119]
	v_mfma_f32_16x16x32_bf16 v[112:115], v[176:179], v[184:187], v[112:115]
	v_mfma_f32_16x16x32_bf16 v[100:103], v[168:171], v[192:195], v[100:103]
	v_mfma_f32_16x16x32_bf16 v[96:99], v[176:179], v[192:195], v[96:99]
	v_mfma_f32_16x16x32_bf16 v[84:87], v[168:171], v[200:203], v[84:87]
	v_mfma_f32_16x16x32_bf16 v[80:83], v[176:179], v[200:203], v[80:83]
	v_mfma_f32_16x16x32_bf16 v[68:71], v[168:171], v[208:211], v[68:71]
	v_mfma_f32_16x16x32_bf16 v[64:67], v[176:179], v[208:211], v[64:67]
	s_barrier
	s_setprio 0
	s_add_i32 s30, s33, s38
	v_lshl_add_u64 v[212:213], v[212:213], 0, s[18:19]
	s_mov_b32 m0, s30
	ds_read_b128 v[180:183], v151 offset:49152
	ds_read_b128 v[184:187], v151 offset:50176
	ds_read_b128 v[188:191], v151 offset:51200
	ds_read_b128 v[192:195], v151 offset:52224
	ds_read_b128 v[196:199], v151 offset:53248
	ds_read_b128 v[200:203], v151 offset:54272
	ds_read_b128 v[204:207], v151 offset:55296
	ds_read_b128 v[208:211], v151 offset:56320
	global_load_lds_dwordx4 v[212:213], off
	v_lshl_add_u64 v[212:213], v[214:215], 0, s[18:19]
	s_add_i32 m0, s30, 0x2000
	s_add_i32 s30, s67, s38
	global_load_lds_dwordx4 v[212:213], off
	v_lshl_add_u64 v[212:213], v[216:217], 0, s[18:19]
	s_mov_b32 m0, s30
	s_nop 0
	global_load_lds_dwordx4 v[212:213], off
	v_lshl_add_u64 v[212:213], v[218:219], 0, s[18:19]
	s_add_i32 m0, s30, 0x2000
	s_nop 0
	global_load_lds_dwordx4 v[212:213], off
	v_lshl_add_u64 v[212:213], v[220:221], 0, s[18:19]
	s_mov_b32 m0, s52
	s_nop 0
	global_load_lds_dwordx4 v[212:213], off
	v_lshl_add_u64 v[212:213], v[222:223], 0, s[18:19]
	s_mov_b32 m0, s53
	s_nop 0
	global_load_lds_dwordx4 v[212:213], off
	s_waitcnt vmcnt(8)
	s_waitcnt lgkmcnt(0)
	s_setprio 1
	s_barrier
	v_mfma_f32_16x16x32_bf16 v[60:63], v[142:145], v[180:183], v[60:63]
	v_mfma_f32_16x16x32_bf16 v[56:59], v[156:159], v[180:183], v[56:59]
	v_mfma_f32_16x16x32_bf16 v[44:47], v[142:145], v[188:191], v[44:47]
	v_mfma_f32_16x16x32_bf16 v[40:43], v[156:159], v[188:191], v[40:43]
	v_mfma_f32_16x16x32_bf16 v[28:31], v[142:145], v[196:199], v[28:31]
	v_mfma_f32_16x16x32_bf16 v[24:27], v[156:159], v[196:199], v[24:27]
	v_mfma_f32_16x16x32_bf16 v[12:15], v[142:145], v[204:207], v[12:15]
	v_mfma_f32_16x16x32_bf16 v[8:11], v[156:159], v[204:207], v[8:11]
	v_mfma_f32_16x16x32_bf16 v[60:63], v[152:155], v[184:187], v[60:63]
	v_mfma_f32_16x16x32_bf16 v[56:59], v[160:163], v[184:187], v[56:59]
	v_mfma_f32_16x16x32_bf16 v[44:47], v[152:155], v[192:195], v[44:47]
	v_mfma_f32_16x16x32_bf16 v[40:43], v[160:163], v[192:195], v[40:43]
	v_mfma_f32_16x16x32_bf16 v[28:31], v[152:155], v[200:203], v[28:31]
	v_mfma_f32_16x16x32_bf16 v[24:27], v[160:163], v[200:203], v[24:27]
	v_mfma_f32_16x16x32_bf16 v[12:15], v[152:155], v[208:211], v[12:15]
	v_mfma_f32_16x16x32_bf16 v[8:11], v[160:163], v[208:211], v[8:11]
	v_mfma_f32_16x16x32_bf16 v[52:55], v[164:167], v[180:183], v[52:55]
	v_mfma_f32_16x16x32_bf16 v[48:51], v[172:175], v[180:183], v[48:51]
	v_mfma_f32_16x16x32_bf16 v[36:39], v[164:167], v[188:191], v[36:39]
	v_mfma_f32_16x16x32_bf16 v[32:35], v[172:175], v[188:191], v[32:35]
	v_mfma_f32_16x16x32_bf16 v[20:23], v[164:167], v[196:199], v[20:23]
	v_mfma_f32_16x16x32_bf16 v[16:19], v[172:175], v[196:199], v[16:19]
	v_mfma_f32_16x16x32_bf16 v[4:7], v[164:167], v[204:207], v[4:7]
	v_mfma_f32_16x16x32_bf16 v[0:3], v[172:175], v[204:207], v[0:3]
	v_mfma_f32_16x16x32_bf16 v[52:55], v[168:171], v[184:187], v[52:55]
	v_mfma_f32_16x16x32_bf16 v[48:51], v[176:179], v[184:187], v[48:51]
	v_mfma_f32_16x16x32_bf16 v[36:39], v[168:171], v[192:195], v[36:39]
	v_mfma_f32_16x16x32_bf16 v[32:35], v[176:179], v[192:195], v[32:35]
	v_mfma_f32_16x16x32_bf16 v[20:23], v[168:171], v[200:203], v[20:23]
	v_mfma_f32_16x16x32_bf16 v[16:19], v[176:179], v[200:203], v[16:19]
	v_mfma_f32_16x16x32_bf16 v[4:7], v[168:171], v[208:211], v[4:7]
	v_mfma_f32_16x16x32_bf16 v[0:3], v[176:179], v[208:211], v[0:3]
	s_barrier
	s_setprio 0
	s_add_u32 s28, s28, 0x100
	s_addc_u32 s29, s29, 0
	s_add_u32 s0, s0, 0x100
	s_addc_u32 s1, s1, 0
	s_cmp_ge_i32 s66, s54
	s_mov_b32 s30, s66
	s_cbranch_scc0 .LBB0_1258

; #define PG8_STAGE(bufoff, gbase, voff) do { _Pragma("unroll") for (int _i = 0; _i < 2; ++_i) \
;         __builtin_amdgcn_global_load_lds((const unsigned*)((const char*)(gbase) + (voff)[_i]), (PG8_LAS unsigned*)(lds + (bufoff) + ldsw + _i * 8192), 16, 0, 0); } while (0)
; #define PG8_LDA(dst, b, h) do { _Pragma("unroll") for (int m = 0; m < 4; ++m) _Pragma("unroll") for (int k = 0; k < 2; ++k) dst[m][k] = *(const PG8_LAS bf16x8*)(lds + PG8_SA(b, h) + aoff + m * 2048 + k * 1024); } while (0)
; template <class Epi, class Sched, bool ALIGN_EPI = false, bool SP2 = false>
; __device__ __forceinline__ void gemm_phase(PG8_LAS unsigned char* lds, const Gemm g, const Sched& S, const Epi& E, const int wid) {
;     ...
;         const bool has_next = S.next(ui + 1, nxt);
;         const char* nA = has_next ? (const char*)g.A + (size_t)nxt.pm * tstep : cA; const char* nB = has_next ? (const char*)g.Bt + (size_t)nxt.pn * tstep : cB;
;         for (int t = 0; t < nt; t += 2) {
;             const bool last = (t == nt - 2);
;             const char* a1 = cA + (size_t)(t + 1) * kstep;
;             const char* a2 = last ? nA : cA + (size_t)(t + 2) * kstep; const char* b2 = last ? nB : cB + (size_t)(t + 2) * kstep;
;             const char* a3 = a2 + kstep; const char* b3 = b2 + kstep;
;             if (last && has_next) S.a_ready(nxt);
;             if constexpr (SP2) {
;             PG8_LDB(B0, 0, 0); PG8_LDB(B1, 0, 1); PG8_SCHED; PG8_LDA(At, 0, 0); PG8_STAGE(PG8_SA(1, 1), a1 + hstep, voffA);
;             PG8_WAIT_V(8); PG8_WAIT_L(0); PG8_BAR; PG8_MMA(0, 0, At, B0); PG8_MMA(0, 1, At, B1); PG8_BAR; PG8_SCHED;
;             PG8_LDA(At, 0, 1); PG8_STAGE(PG8_SB(0, 0), b2, voffB); PG8_STAGE(PG8_SB(0, 1), b2 + hstep, voffB); PG8_STAGE(PG8_SA(0, 0), a2, voffA);
;             PG8_WAIT_V(8); PG8_WAIT_L(0); PG8_BAR; PG8_MMA(1, 0, At, B0); PG8_MMA(1, 1, At, B1); PG8_BAR; PG8_SCHED;
;             PG8_LDB(B0, 1, 0); PG8_LDB(B1, 1, 1); PG8_SCHED; PG8_LDA(At, 1, 0); PG8_STAGE(PG8_SA(0, 1), a2 + hstep, voffA);
;             PG8_WAIT_V(8); PG8_WAIT_L(0); PG8_BAR; PG8_MMA(0, 0, At, B0); PG8_MMA(0, 1, At, B1); PG8_BAR; PG8_SCHED;
;             PG8_LDA(At, 1, 1); PG8_STAGE(PG8_SB(1, 0), b3, voffB); PG8_STAGE(PG8_SB(1, 1), b3 + hstep, voffB); PG8_STAGE(PG8_SA(1, 0), a3, voffA);
;             PG8_WAIT_V(8); PG8_WAIT_L(0); PG8_BAR; PG8_MMA(1, 0, At, B0); PG8_MMA(1, 1, At, B1); PG8_BAR; PG8_SCHED;
.LBB0_1337:
	s_andn2_b64 vcc, exec, s[24:25]
	s_waitcnt lgkmcnt(0)
	s_cbranch_vccnz .Lz_GOUT
	s_add_u32 s4, s36, 0x80
	s_addc_u32 s5, s37, 0
	s_add_u32 s0, s34, 0x100
	s_addc_u32 s1, s35, 0
	s_mov_b32 s34, 0
	ds_read_b128 v[142:145], v149
	ds_read_b128 v[154:157], v149 offset:1024
	ds_read_b128 v[158:161], v149 offset:2048
	ds_read_b128 v[162:165], v149 offset:3072
	ds_read_b128 v[166:169], v150
	ds_read_b128 v[170:173], v150 offset:1024
	ds_read_b128 v[174:177], v150 offset:2048
	ds_read_b128 v[178:181], v150 offset:3072
	s_add_i32 s36, s34, 2
	s_add_u32 s33, s4, 0x80
	s_addc_u32 s35, s5, 0
	s_cmp_eq_u32 s54, s34
	s_cselect_b32 s34, s28, s33
	s_cselect_b32 s35, s29, s35
	s_cselect_b32 s69, s31, s1
	s_cselect_b32 s68, s30, s0
	v_lshl_add_u64 v[214:215], s[4:5], 0, v[136:137]
	s_add_i32 m0, s43, 0xc000
	ds_read_b128 v[182:185], v151
	ds_read_b128 v[186:189], v151 offset:1024
	ds_read_b128 v[190:193], v151 offset:2048
	ds_read_b128 v[194:197], v151 offset:3072
	ds_read_b128 v[198:201], v151 offset:4096
	ds_read_b128 v[202:205], v151 offset:5120
	ds_read_b128 v[206:209], v151 offset:6144
	ds_read_b128 v[210:213], v151 offset:7168
	global_load_lds_dwordx4 v[214:215], off
	v_lshl_add_u64 v[214:215], s[4:5], 0, v[138:139]
	s_add_i32 m0, s43, 0xe000
	s_nop 0
	global_load_lds_dwordx4 v[214:215], off
	s_waitcnt vmcnt(8)
	s_waitcnt lgkmcnt(0)
	s_setprio 1
	s_barrier
	v_mfma_f32_16x16x32_bf16 v[120:123], v[142:145], v[182:185], 0
	v_mfma_f32_16x16x32_bf16 v[124:127], v[158:161], v[182:185], 0
	v_mfma_f32_16x16x32_bf16 v[108:111], v[142:145], v[190:193], 0
	v_mfma_f32_16x16x32_bf16 v[104:107], v[158:161], v[190:193], 0
	v_mfma_f32_16x16x32_bf16 v[92:95], v[142:145], v[198:201], 0
	v_mfma_f32_16x16x32_bf16 v[88:91], v[158:161], v[198:201], 0
	v_mfma_f32_16x16x32_bf16 v[76:79], v[142:145], v[206:209], 0
	v_mfma_f32_16x16x32_bf16 v[72:75], v[158:161], v[206:209], 0
	v_mfma_f32_16x16x32_bf16 v[120:123], v[154:157], v[186:189], v[120:123]
	v_mfma_f32_16x16x32_bf16 v[124:127], v[162:165], v[186:189], v[124:127]
	v_mfma_f32_16x16x32_bf16 v[108:111], v[154:157], v[194:197], v[108:111]
	v_mfma_f32_16x16x32_bf16 v[104:107], v[162:165], v[194:197], v[104:107]
	v_mfma_f32_16x16x32_bf16 v[92:95], v[154:157], v[202:205], v[92:95]
	v_mfma_f32_16x16x32_bf16 v[88:91], v[162:165], v[202:205], v[88:91]
	v_mfma_f32_16x16x32_bf16 v[76:79], v[154:157], v[210:213], v[76:79]
	v_mfma_f32_16x16x32_bf16 v[72:75], v[162:165], v[210:213], v[72:75]
	v_mfma_f32_16x16x32_bf16 v[116:119], v[166:169], v[182:185], 0
	v_mfma_f32_16x16x32_bf16 v[112:115], v[174:177], v[182:185], 0
	v_mfma_f32_16x16x32_bf16 v[100:103], v[166:169], v[190:193], 0
	v_mfma_f32_16x16x32_bf16 v[96:99], v[174:177], v[190:193], 0
	v_mfma_f32_16x16x32_bf16 v[84:87], v[166:169], v[198:201], 0
	v_mfma_f32_16x16x32_bf16 v[80:83], v[174:177], v[198:201], 0
	v_mfma_f32_16x16x32_bf16 v[68:71], v[166:169], v[206:209], 0
	v_mfma_f32_16x16x32_bf16 v[64:67], v[174:177], v[206:209], 0
	v_mfma_f32_16x16x32_bf16 v[116:119], v[170:173], v[186:189], v[116:119]
	v_mfma_f32_16x16x32_bf16 v[112:115], v[178:181], v[186:189], v[112:115]
	v_mfma_f32_16x16x32_bf16 v[100:103], v[170:173], v[194:197], v[100:103]
	v_mfma_f32_16x16x32_bf16 v[96:99], v[178:181], v[194:197], v[96:99]
	v_mfma_f32_16x16x32_bf16 v[84:87], v[170:173], v[202:205], v[84:87]
	v_mfma_f32_16x16x32_bf16 v[80:83], v[178:181], v[202:205], v[80:83]
	v_mfma_f32_16x16x32_bf16 v[68:71], v[170:173], v[210:213], v[68:71]
	v_mfma_f32_16x16x32_bf16 v[64:67], v[178:181], v[210:213], v[64:67]
	s_barrier
	s_setprio 0
	s_add_i32 s33, s62, s42
	v_lshl_add_u64 v[214:215], s[68:69], 0, v[130:131]
	s_mov_b32 m0, s33
	ds_read_b128 v[182:185], v151 offset:16384
	ds_read_b128 v[186:189], v151 offset:17408
	ds_read_b128 v[190:193], v151 offset:18432
	ds_read_b128 v[194:197], v151 offset:19456
	ds_read_b128 v[198:201], v151 offset:20480
	ds_read_b128 v[202:205], v151 offset:21504
	ds_read_b128 v[206:209], v151 offset:22528
	ds_read_b128 v[210:213], v151 offset:23552
	global_load_lds_dwordx4 v[214:215], off
	s_add_i32 m0, s33, 0x2000
	v_lshl_add_u64 v[216:217], s[68:69], 0, v[134:135]
	s_add_u32 s68, s68, s8
	s_addc_u32 s69, s69, s9
	s_add_i32 s33, s63, s42
	global_load_lds_dwordx4 v[216:217], off
	v_lshl_add_u64 v[218:219], s[68:69], 0, v[130:131]
	s_mov_b32 m0, s33
	v_lshl_add_u64 v[220:221], s[68:69], 0, v[134:135]
	global_load_lds_dwordx4 v[218:219], off
	s_add_i32 m0, s33, 0x2000
	v_lshl_add_u64 v[222:223], s[34:35], 0, v[128:129]
	global_load_lds_dwordx4 v[220:221], off
	s_mov_b32 m0, s43
	v_lshl_add_u64 v[224:225], s[34:35], 0, v[132:133]
	global_load_lds_dwordx4 v[222:223], off
	s_mov_b32 m0, s44
	s_nop 0
	global_load_lds_dwordx4 v[224:225], off
	s_waitcnt vmcnt(8)
	s_waitcnt lgkmcnt(0)
	s_setprio 1
	s_barrier
; #define PG8_STAGE(bufoff, gbase, voff) do { _Pragma("unroll") for (int _i = 0; _i < 2; ++_i) \
;         __builtin_amdgcn_global_load_lds((const unsigned*)((const char*)(gbase) + (voff)[_i]), (PG8_LAS unsigned*)(lds + (bufoff) + ldsw + _i * 8192), 16, 0, 0); } while (0)
; #define PG8_LDA(dst, b, h) do { _Pragma("unroll") for (int m = 0; m < 4; ++m) _Pragma("unroll") for (int k = 0; k < 2; ++k) dst[m][k] = *(const PG8_LAS bf16x8*)(lds + PG8_SA(b, h) + aoff + m * 2048 + k * 1024); } while (0)
; #define PG8_LDB(dst, b, h) do { _Pragma("unroll") for (int n = 0; n < 2; ++n) _Pragma("unroll") for (int k = 0; k < 2; ++k) dst[n][k] = *(const PG8_LAS bf16x8*)(lds + PG8_SB(b, h) + boff + n * 2048 + k * 1024); } while (0)
; #define PG8_MMA(ai, bj, At, Bt) do { __builtin_amdgcn_s_setprio(1); _Pragma("unroll") for (int m = 0; m < 4; ++m) _Pragma("unroll") for (int n = 0; n < 2; ++n) _Pragma("unroll") for (int k = 0; k < 2; ++k) \
;         acc[ai][bj][m][n] = __builtin_amdgcn_mfma_f32_16x16x32_bf16(Bt[n][k], At[m][k], acc[ai][bj][m][n], 0, 0, 0); __builtin_amdgcn_s_setprio(0); } while (0)
; #define PG8_BAR __builtin_amdgcn_s_barrier()
; template <class Epi, class Sched, bool ALIGN_EPI = false, bool SP2 = false>
; __device__ __forceinline__ void gemm_phase(PG8_LAS unsigned char* lds, const Gemm g, const Sched& S, const Epi& E, const int wid) {
;     ...
;             PG8_LDB(B0, 0, 0); PG8_LDB(B1, 0, 1); PG8_SCHED; PG8_LDA(At, 0, 0); PG8_STAGE(PG8_SA(1, 1), a1 + hstep, voffA);
;             PG8_WAIT_V(8); PG8_WAIT_L(0); PG8_BAR; PG8_MMA(0, 0, At, B0); PG8_MMA(0, 1, At, B1); PG8_BAR; PG8_SCHED;
;             PG8_LDA(At, 0, 1); PG8_STAGE(PG8_SB(0, 0), b2, voffB); PG8_STAGE(PG8_SB(0, 1), b2 + hstep, voffB); PG8_STAGE(PG8_SA(0, 0), a2, voffA);
;             PG8_WAIT_V(8); PG8_WAIT_L(0); PG8_BAR; PG8_MMA(1, 0, At, B0); PG8_MMA(1, 1, At, B1); PG8_BAR; PG8_SCHED;
;             PG8_LDB(B0, 1, 0); PG8_LDB(B1, 1, 1); PG8_SCHED; PG8_LDA(At, 1, 0); PG8_STAGE(PG8_SA(0, 1), a2 + hstep, voffA);
;             PG8_WAIT_V(8); PG8_WAIT_L(0); PG8_BAR; PG8_MMA(0, 0, At, B0); PG8_MMA(0, 1, At, B1); PG8_BAR; PG8_SCHED;
;             PG8_LDA(At, 1, 1); PG8_STAGE(PG8_SB(1, 0), b3, voffB); PG8_STAGE(PG8_SB(1, 1), b3 + hstep, voffB); PG8_STAGE(PG8_SA(1, 0), a3, voffA);
;             PG8_WAIT_V(8); PG8_WAIT_L(0); PG8_BAR; PG8_MMA(1, 0, At, B0); PG8_MMA(1, 1, At, B1); PG8_BAR; PG8_SCHED;
	v_mfma_f32_16x16x32_bf16 v[60:63], v[142:145], v[182:185], 0
	v_mfma_f32_16x16x32_bf16 v[56:59], v[158:161], v[182:185], 0
	v_mfma_f32_16x16x32_bf16 v[44:47], v[142:145], v[190:193], 0
	v_mfma_f32_16x16x32_bf16 v[40:43], v[158:161], v[190:193], 0
	v_mfma_f32_16x16x32_bf16 v[28:31], v[142:145], v[198:201], 0
	v_mfma_f32_16x16x32_bf16 v[24:27], v[158:161], v[198:201], 0
	v_mfma_f32_16x16x32_bf16 v[12:15], v[142:145], v[206:209], 0
	v_mfma_f32_16x16x32_bf16 v[8:11], v[158:161], v[206:209], 0
	v_mfma_f32_16x16x32_bf16 v[60:63], v[154:157], v[186:189], v[60:63]
	v_mfma_f32_16x16x32_bf16 v[56:59], v[162:165], v[186:189], v[56:59]
	v_mfma_f32_16x16x32_bf16 v[44:47], v[154:157], v[194:197], v[44:47]
	v_mfma_f32_16x16x32_bf16 v[40:43], v[162:165], v[194:197], v[40:43]
	v_mfma_f32_16x16x32_bf16 v[28:31], v[154:157], v[202:205], v[28:31]
	v_mfma_f32_16x16x32_bf16 v[24:27], v[162:165], v[202:205], v[24:27]
	v_mfma_f32_16x16x32_bf16 v[12:15], v[154:157], v[210:213], v[12:15]
	v_mfma_f32_16x16x32_bf16 v[8:11], v[162:165], v[210:213], v[8:11]
	v_mfma_f32_16x16x32_bf16 v[52:55], v[166:169], v[182:185], 0
	v_mfma_f32_16x16x32_bf16 v[48:51], v[174:177], v[182:185], 0
	v_mfma_f32_16x16x32_bf16 v[36:39], v[166:169], v[190:193], 0
	v_mfma_f32_16x16x32_bf16 v[32:35], v[174:177], v[190:193], 0
	v_mfma_f32_16x16x32_bf16 v[20:23], v[166:169], v[198:201], 0
	v_mfma_f32_16x16x32_bf16 v[16:19], v[174:177], v[198:201], 0
	v_mfma_f32_16x16x32_bf16 v[4:7], v[166:169], v[206:209], 0
	v_mfma_f32_16x16x32_bf16 v[0:3], v[174:177], v[206:209], 0
	v_mfma_f32_16x16x32_bf16 v[52:55], v[170:173], v[186:189], v[52:55]
	v_mfma_f32_16x16x32_bf16 v[48:51], v[178:181], v[186:189], v[48:51]
	v_mfma_f32_16x16x32_bf16 v[36:39], v[170:173], v[194:197], v[36:39]
	v_mfma_f32_16x16x32_bf16 v[32:35], v[178:181], v[194:197], v[32:35]
	v_mfma_f32_16x16x32_bf16 v[20:23], v[170:173], v[202:205], v[20:23]
	v_mfma_f32_16x16x32_bf16 v[16:19], v[178:181], v[202:205], v[16:19]
	v_mfma_f32_16x16x32_bf16 v[4:7], v[170:173], v[210:213], v[4:7]
	v_mfma_f32_16x16x32_bf16 v[0:3], v[178:181], v[210:213], v[0:3]
	s_barrier
	s_setprio 0
	s_add_i32 s33, 0, 0x18000
	v_add_u32_e32 v153, s33, v148
	s_add_i32 s37, 0, 0x1c000
	ds_read_b128 v[142:145], v153
	ds_read_b128 v[154:157], v153 offset:1024
	ds_read_b128 v[158:161], v153 offset:2048
	ds_read_b128 v[162:165], v153 offset:3072
	v_add_u32_e32 v153, s37, v148
	ds_read_b128 v[166:169], v153
	ds_read_b128 v[170:173], v153 offset:1024
	ds_read_b128 v[174:177], v153 offset:2048
	ds_read_b128 v[178:181], v153 offset:3072
	s_add_u32 s34, s34, s8
	s_addc_u32 s35, s35, s9
	s_mov_b32 m0, s45
	v_lshl_add_u64 v[226:227], s[34:35], 0, v[128:129]
	ds_read_b128 v[182:185], v151 offset:32768
	ds_read_b128 v[186:189], v151 offset:33792
	ds_read_b128 v[190:193], v151 offset:34816
	ds_read_b128 v[194:197], v151 offset:35840
	ds_read_b128 v[198:201], v151 offset:36864
	ds_read_b128 v[202:205], v151 offset:37888
	ds_read_b128 v[206:209], v151 offset:38912
	ds_read_b128 v[210:213], v151 offset:39936
	global_load_lds_dwordx4 v[226:227], off
	v_lshl_add_u64 v[226:227], s[34:35], 0, v[132:133]
	s_mov_b32 m0, s46
	s_nop 0
	global_load_lds_dwordx4 v[226:227], off
	s_waitcnt vmcnt(8)
	s_waitcnt lgkmcnt(0)
	s_setprio 1
	s_barrier
	v_mfma_f32_16x16x32_bf16 v[120:123], v[142:145], v[182:185], v[120:123]
	v_mfma_f32_16x16x32_bf16 v[124:127], v[158:161], v[182:185], v[124:127]
	v_mfma_f32_16x16x32_bf16 v[108:111], v[142:145], v[190:193], v[108:111]
	v_mfma_f32_16x16x32_bf16 v[104:107], v[158:161], v[190:193], v[104:107]
	v_mfma_f32_16x16x32_bf16 v[92:95], v[142:145], v[198:201], v[92:95]
	v_mfma_f32_16x16x32_bf16 v[88:91], v[158:161], v[198:201], v[88:91]
	v_mfma_f32_16x16x32_bf16 v[76:79], v[142:145], v[206:209], v[76:79]
	v_mfma_f32_16x16x32_bf16 v[72:75], v[158:161], v[206:209], v[72:75]
	v_mfma_f32_16x16x32_bf16 v[120:123], v[154:157], v[186:189], v[120:123]
	v_mfma_f32_16x16x32_bf16 v[124:127], v[162:165], v[186:189], v[124:127]
	v_mfma_f32_16x16x32_bf16 v[108:111], v[154:157], v[194:197], v[108:111]
	v_mfma_f32_16x16x32_bf16 v[104:107], v[162:165], v[194:197], v[104:107]
	v_mfma_f32_16x16x32_bf16 v[92:95], v[154:157], v[202:205], v[92:95]
	v_mfma_f32_16x16x32_bf16 v[88:91], v[162:165], v[202:205], v[88:91]
	v_mfma_f32_16x16x32_bf16 v[76:79], v[154:157], v[210:213], v[76:79]
	v_mfma_f32_16x16x32_bf16 v[72:75], v[162:165], v[210:213], v[72:75]
	v_mfma_f32_16x16x32_bf16 v[116:119], v[166:169], v[182:185], v[116:119]
	v_mfma_f32_16x16x32_bf16 v[112:115], v[174:177], v[182:185], v[112:115]
	v_mfma_f32_16x16x32_bf16 v[100:103], v[166:169], v[190:193], v[100:103]
	v_mfma_f32_16x16x32_bf16 v[96:99], v[174:177], v[190:193], v[96:99]
	v_mfma_f32_16x16x32_bf16 v[84:87], v[166:169], v[198:201], v[84:87]
	v_mfma_f32_16x16x32_bf16 v[80:83], v[174:177], v[198:201], v[80:83]
	v_mfma_f32_16x16x32_bf16 v[68:71], v[166:169], v[206:209], v[68:71]
	v_mfma_f32_16x16x32_bf16 v[64:67], v[174:177], v[206:209], v[64:67]
	v_mfma_f32_16x16x32_bf16 v[116:119], v[170:173], v[186:189], v[116:119]
	v_mfma_f32_16x16x32_bf16 v[112:115], v[178:181], v[186:189], v[112:115]
	v_mfma_f32_16x16x32_bf16 v[100:103], v[170:173], v[194:197], v[100:103]
	v_mfma_f32_16x16x32_bf16 v[96:99], v[178:181], v[194:197], v[96:99]
	v_mfma_f32_16x16x32_bf16 v[84:87], v[170:173], v[202:205], v[84:87]
	v_mfma_f32_16x16x32_bf16 v[80:83], v[178:181], v[202:205], v[80:83]
	v_mfma_f32_16x16x32_bf16 v[68:71], v[170:173], v[210:213], v[68:71]
	v_mfma_f32_16x16x32_bf16 v[64:67], v[178:181], v[210:213], v[64:67]
	s_barrier
; #define PG8_STAGE(bufoff, gbase, voff) do { _Pragma("unroll") for (int _i = 0; _i < 2; ++_i) \
;         __builtin_amdgcn_global_load_lds((const unsigned*)((const char*)(gbase) + (voff)[_i]), (PG8_LAS unsigned*)(lds + (bufoff) + ldsw + _i * 8192), 16, 0, 0); } while (0)
; #define PG8_LDA(dst, b, h) do { _Pragma("unroll") for (int m = 0; m < 4; ++m) _Pragma("unroll") for (int k = 0; k < 2; ++k) dst[m][k] = *(const PG8_LAS bf16x8*)(lds + PG8_SA(b, h) + aoff + m * 2048 + k * 1024); } while (0)
; #define PG8_WAIT_V(n) asm volatile("s_waitcnt vmcnt(" #n ")" ::: "memory")
; #define PG8_WAIT_L(n) asm volatile("s_waitcnt lgkmcnt(" #n ")" ::: "memory")
; #define PG8_BAR __builtin_amdgcn_s_barrier()
; template <class Epi, class Sched, bool ALIGN_EPI = false, bool SP2 = false>
; __device__ __forceinline__ void gemm_phase(PG8_LAS unsigned char* lds, const Gemm g, const Sched& S, const Epi& E, const int wid) {
;     ...
;         for (int t = 0; t < nt; t += 2) {
;             const bool last = (t == nt - 2);
;             const char* a1 = cA + (size_t)(t + 1) * kstep;
;             const char* a2 = last ? nA : cA + (size_t)(t + 2) * kstep; const char* b2 = last ? nB : cB + (size_t)(t + 2) * kstep;
;             const char* a3 = a2 + kstep; const char* b3 = b2 + kstep;
;             if (last && has_next) S.a_ready(nxt);
;             if constexpr (SP2) {
;             PG8_LDB(B0, 0, 0); PG8_LDB(B1, 0, 1); PG8_SCHED; PG8_LDA(At, 0, 0); PG8_STAGE(PG8_SA(1, 1), a1 + hstep, voffA);
;             PG8_WAIT_V(8); PG8_WAIT_L(0); PG8_BAR; PG8_MMA(0, 0, At, B0); PG8_MMA(0, 1, At, B1); PG8_BAR; PG8_SCHED;
;             PG8_LDA(At, 0, 1); PG8_STAGE(PG8_SB(0, 0), b2, voffB); PG8_STAGE(PG8_SB(0, 1), b2 + hstep, voffB); PG8_STAGE(PG8_SA(0, 0), a2, voffA);
;             PG8_WAIT_V(8); PG8_WAIT_L(0); PG8_BAR; PG8_MMA(1, 0, At, B0); PG8_MMA(1, 1, At, B1); PG8_BAR; PG8_SCHED;
;             PG8_LDB(B0, 1, 0); PG8_LDB(B1, 1, 1); PG8_SCHED; PG8_LDA(At, 1, 0); PG8_STAGE(PG8_SA(0, 1), a2 + hstep, voffA);
;             PG8_WAIT_V(8); PG8_WAIT_L(0); PG8_BAR; PG8_MMA(0, 0, At, B0); PG8_MMA(0, 1, At, B1); PG8_BAR; PG8_SCHED;
;             PG8_LDA(At, 1, 1); PG8_STAGE(PG8_SB(1, 0), b3, voffB); PG8_STAGE(PG8_SB(1, 1), b3 + hstep, voffB); PG8_STAGE(PG8_SA(1, 0), a3, voffA);
;             PG8_WAIT_V(8); PG8_WAIT_L(0); PG8_BAR; PG8_MMA(1, 0, At, B0); PG8_MMA(1, 1, At, B1); PG8_BAR; PG8_SCHED;
	s_setprio 0
	s_add_i32 s33, s33, s42
	v_lshl_add_u64 v[214:215], v[214:215], 0, s[22:23]
	s_mov_b32 m0, s33
	ds_read_b128 v[182:185], v151 offset:49152
	ds_read_b128 v[186:189], v151 offset:50176
	ds_read_b128 v[190:193], v151 offset:51200
	ds_read_b128 v[194:197], v151 offset:52224
	ds_read_b128 v[198:201], v151 offset:53248
	ds_read_b128 v[202:205], v151 offset:54272
	ds_read_b128 v[206:209], v151 offset:55296
	ds_read_b128 v[210:213], v151 offset:56320
	global_load_lds_dwordx4 v[214:215], off
	v_lshl_add_u64 v[214:215], v[216:217], 0, s[22:23]
	s_add_i32 m0, s33, 0x2000
	s_add_i32 s33, s37, s42
	global_load_lds_dwordx4 v[214:215], off
	v_lshl_add_u64 v[214:215], v[218:219], 0, s[22:23]
	s_mov_b32 m0, s33
	s_nop 0
	global_load_lds_dwordx4 v[214:215], off
	v_lshl_add_u64 v[214:215], v[220:221], 0, s[22:23]
	s_add_i32 m0, s33, 0x2000
	s_nop 0
	global_load_lds_dwordx4 v[214:215], off
	v_lshl_add_u64 v[214:215], v[222:223], 0, s[22:23]
	s_mov_b32 m0, s47
	s_nop 0
	global_load_lds_dwordx4 v[214:215], off
	v_lshl_add_u64 v[214:215], v[224:225], 0, s[22:23]
	s_mov_b32 m0, s49
	s_nop 0
	global_load_lds_dwordx4 v[214:215], off
	s_waitcnt vmcnt(8)
	s_waitcnt lgkmcnt(0)
	s_setprio 1
	s_barrier
	v_mfma_f32_16x16x32_bf16 v[60:63], v[142:145], v[182:185], v[60:63]
	v_mfma_f32_16x16x32_bf16 v[56:59], v[158:161], v[182:185], v[56:59]
	v_mfma_f32_16x16x32_bf16 v[44:47], v[142:145], v[190:193], v[44:47]
	v_mfma_f32_16x16x32_bf16 v[40:43], v[158:161], v[190:193], v[40:43]
	v_mfma_f32_16x16x32_bf16 v[28:31], v[142:145], v[198:201], v[28:31]
	v_mfma_f32_16x16x32_bf16 v[24:27], v[158:161], v[198:201], v[24:27]
	v_mfma_f32_16x16x32_bf16 v[12:15], v[142:145], v[206:209], v[12:15]
	v_mfma_f32_16x16x32_bf16 v[8:11], v[158:161], v[206:209], v[8:11]
	v_mfma_f32_16x16x32_bf16 v[60:63], v[154:157], v[186:189], v[60:63]
	v_mfma_f32_16x16x32_bf16 v[56:59], v[162:165], v[186:189], v[56:59]
	v_mfma_f32_16x16x32_bf16 v[44:47], v[154:157], v[194:197], v[44:47]
	v_mfma_f32_16x16x32_bf16 v[40:43], v[162:165], v[194:197], v[40:43]
	v_mfma_f32_16x16x32_bf16 v[28:31], v[154:157], v[202:205], v[28:31]
	v_mfma_f32_16x16x32_bf16 v[24:27], v[162:165], v[202:205], v[24:27]
	v_mfma_f32_16x16x32_bf16 v[12:15], v[154:157], v[210:213], v[12:15]
	v_mfma_f32_16x16x32_bf16 v[8:11], v[162:165], v[210:213], v[8:11]
	v_mfma_f32_16x16x32_bf16 v[52:55], v[166:169], v[182:185], v[52:55]
	v_mfma_f32_16x16x32_bf16 v[48:51], v[174:177], v[182:185], v[48:51]
	v_mfma_f32_16x16x32_bf16 v[36:39], v[166:169], v[190:193], v[36:39]
	v_mfma_f32_16x16x32_bf16 v[32:35], v[174:177], v[190:193], v[32:35]
	v_mfma_f32_16x16x32_bf16 v[20:23], v[166:169], v[198:201], v[20:23]
	v_mfma_f32_16x16x32_bf16 v[16:19], v[174:177], v[198:201], v[16:19]
	v_mfma_f32_16x16x32_bf16 v[4:7], v[166:169], v[206:209], v[4:7]
	v_mfma_f32_16x16x32_bf16 v[0:3], v[174:177], v[206:209], v[0:3]
	v_mfma_f32_16x16x32_bf16 v[52:55], v[170:173], v[186:189], v[52:55]
	v_mfma_f32_16x16x32_bf16 v[48:51], v[178:181], v[186:189], v[48:51]
	v_mfma_f32_16x16x32_bf16 v[36:39], v[170:173], v[194:197], v[36:39]
	v_mfma_f32_16x16x32_bf16 v[32:35], v[178:181], v[194:197], v[32:35]
	v_mfma_f32_16x16x32_bf16 v[20:23], v[170:173], v[202:205], v[20:23]
	v_mfma_f32_16x16x32_bf16 v[16:19], v[178:181], v[202:205], v[16:19]
	v_mfma_f32_16x16x32_bf16 v[4:7], v[170:173], v[210:213], v[4:7]
	v_mfma_f32_16x16x32_bf16 v[0:3], v[178:181], v[210:213], v[0:3]
	s_barrier
	s_setprio 0
	s_add_u32 s4, s4, 0x100
	s_addc_u32 s5, s5, 0
	s_add_u32 s0, s0, 0x100
	s_addc_u32 s1, s1, 0
	s_cmp_ge_i32 s36, s51
	s_mov_b32 s34, s36
	s_cbranch_scc1 .LBB0_1340
.LBB0_1339:
	ds_read_b128 v[142:145], v149
	ds_read_b128 v[154:157], v149 offset:1024
	ds_read_b128 v[158:161], v149 offset:2048
	ds_read_b128 v[162:165], v149 offset:3072
	ds_read_b128 v[166:169], v150
	ds_read_b128 v[170:173], v150 offset:1024
	ds_read_b128 v[174:177], v150 offset:2048
	ds_read_b128 v[178:181], v150 offset:3072
	s_add_i32 s36, s34, 2
	s_add_u32 s33, s4, 0x80
	s_addc_u32 s35, s5, 0
	s_cmp_eq_u32 s54, s34
	s_cselect_b32 s34, s28, s33
	s_cselect_b32 s35, s29, s35
	s_cselect_b32 s69, s31, s1
	s_cselect_b32 s68, s30, s0
	v_lshl_add_u64 v[214:215], s[4:5], 0, v[136:137]
	s_add_i32 m0, s43, 0xc000
	ds_read_b128 v[182:185], v151
	ds_read_b128 v[186:189], v151 offset:1024
	ds_read_b128 v[190:193], v151 offset:2048
	ds_read_b128 v[194:197], v151 offset:3072
	ds_read_b128 v[198:201], v151 offset:4096
	ds_read_b128 v[202:205], v151 offset:5120
	ds_read_b128 v[206:209], v151 offset:6144
	ds_read_b128 v[210:213], v151 offset:7168
	global_load_lds_dwordx4 v[214:215], off
	v_lshl_add_u64 v[214:215], s[4:5], 0, v[138:139]
	s_add_i32 m0, s43, 0xe000
	s_nop 0
	global_load_lds_dwordx4 v[214:215], off
	s_waitcnt vmcnt(8)
	s_waitcnt lgkmcnt(0)
	s_setprio 1
	s_barrier
; #define PG8_STAGE(bufoff, gbase, voff) do { _Pragma("unroll") for (int _i = 0; _i < 2; ++_i) \
;         __builtin_amdgcn_global_load_lds((const unsigned*)((const char*)(gbase) + (voff)[_i]), (PG8_LAS unsigned*)(lds + (bufoff) + ldsw + _i * 8192), 16, 0, 0); } while (0)
; #define PG8_LDA(dst, b, h) do { _Pragma("unroll") for (int m = 0; m < 4; ++m) _Pragma("unroll") for (int k = 0; k < 2; ++k) dst[m][k] = *(const PG8_LAS bf16x8*)(lds + PG8_SA(b, h) + aoff + m * 2048 + k * 1024); } while (0)
; #define PG8_WAIT_V(n) asm volatile("s_waitcnt vmcnt(" #n ")" ::: "memory")
; #define PG8_WAIT_L(n) asm volatile("s_waitcnt lgkmcnt(" #n ")" ::: "memory")
; #define PG8_BAR __builtin_amdgcn_s_barrier()
; template <class Epi, class Sched, bool ALIGN_EPI = false, bool SP2 = false>
; __device__ __forceinline__ void gemm_phase(PG8_LAS unsigned char* lds, const Gemm g, const Sched& S, const Epi& E, const int wid) {
;     ...
;         for (int t = 0; t < nt; t += 2) {
;             const bool last = (t == nt - 2);
;             const char* a1 = cA + (size_t)(t + 1) * kstep;
;             const char* a2 = last ? nA : cA + (size_t)(t + 2) * kstep; const char* b2 = last ? nB : cB + (size_t)(t + 2) * kstep;
;             const char* a3 = a2 + kstep; const char* b3 = b2 + kstep;
;             if (last && has_next) S.a_ready(nxt);
;             if constexpr (SP2) {
;             PG8_LDB(B0, 0, 0); PG8_LDB(B1, 0, 1); PG8_SCHED; PG8_LDA(At, 0, 0); PG8_STAGE(PG8_SA(1, 1), a1 + hstep, voffA);
;             PG8_WAIT_V(8); PG8_WAIT_L(0); PG8_BAR; PG8_MMA(0, 0, At, B0); PG8_MMA(0, 1, At, B1); PG8_BAR; PG8_SCHED;
;             PG8_LDA(At, 0, 1); PG8_STAGE(PG8_SB(0, 0), b2, voffB); PG8_STAGE(PG8_SB(0, 1), b2 + hstep, voffB); PG8_STAGE(PG8_SA(0, 0), a2, voffA);
;             PG8_WAIT_V(8); PG8_WAIT_L(0); PG8_BAR; PG8_MMA(1, 0, At, B0); PG8_MMA(1, 1, At, B1); PG8_BAR; PG8_SCHED;
;             PG8_LDB(B0, 1, 0); PG8_LDB(B1, 1, 1); PG8_SCHED; PG8_LDA(At, 1, 0); PG8_STAGE(PG8_SA(0, 1), a2 + hstep, voffA);
;             PG8_WAIT_V(8); PG8_WAIT_L(0); PG8_BAR; PG8_MMA(0, 0, At, B0); PG8_MMA(0, 1, At, B1); PG8_BAR; PG8_SCHED;
;             PG8_LDA(At, 1, 1); PG8_STAGE(PG8_SB(1, 0), b3, voffB); PG8_STAGE(PG8_SB(1, 1), b3 + hstep, voffB); PG8_STAGE(PG8_SA(1, 0), a3, voffA);
;             PG8_WAIT_V(8); PG8_WAIT_L(0); PG8_BAR; PG8_MMA(1, 0, At, B0); PG8_MMA(1, 1, At, B1); PG8_BAR; PG8_SCHED;
	v_mfma_f32_16x16x32_bf16 v[120:123], v[142:145], v[182:185], v[120:123]
	v_mfma_f32_16x16x32_bf16 v[124:127], v[158:161], v[182:185], v[124:127]
	v_mfma_f32_16x16x32_bf16 v[108:111], v[142:145], v[190:193], v[108:111]
	v_mfma_f32_16x16x32_bf16 v[104:107], v[158:161], v[190:193], v[104:107]
	v_mfma_f32_16x16x32_bf16 v[92:95], v[142:145], v[198:201], v[92:95]
	v_mfma_f32_16x16x32_bf16 v[88:91], v[158:161], v[198:201], v[88:91]
	v_mfma_f32_16x16x32_bf16 v[76:79], v[142:145], v[206:209], v[76:79]
	v_mfma_f32_16x16x32_bf16 v[72:75], v[158:161], v[206:209], v[72:75]
	v_mfma_f32_16x16x32_bf16 v[120:123], v[154:157], v[186:189], v[120:123]
	v_mfma_f32_16x16x32_bf16 v[124:127], v[162:165], v[186:189], v[124:127]
	v_mfma_f32_16x16x32_bf16 v[108:111], v[154:157], v[194:197], v[108:111]
	v_mfma_f32_16x16x32_bf16 v[104:107], v[162:165], v[194:197], v[104:107]
	v_mfma_f32_16x16x32_bf16 v[92:95], v[154:157], v[202:205], v[92:95]
	v_mfma_f32_16x16x32_bf16 v[88:91], v[162:165], v[202:205], v[88:91]
	v_mfma_f32_16x16x32_bf16 v[76:79], v[154:157], v[210:213], v[76:79]
	v_mfma_f32_16x16x32_bf16 v[72:75], v[162:165], v[210:213], v[72:75]
	v_mfma_f32_16x16x32_bf16 v[116:119], v[166:169], v[182:185], v[116:119]
	v_mfma_f32_16x16x32_bf16 v[112:115], v[174:177], v[182:185], v[112:115]
	v_mfma_f32_16x16x32_bf16 v[100:103], v[166:169], v[190:193], v[100:103]
	v_mfma_f32_16x16x32_bf16 v[96:99], v[174:177], v[190:193], v[96:99]
	v_mfma_f32_16x16x32_bf16 v[84:87], v[166:169], v[198:201], v[84:87]
	v_mfma_f32_16x16x32_bf16 v[80:83], v[174:177], v[198:201], v[80:83]
	v_mfma_f32_16x16x32_bf16 v[68:71], v[166:169], v[206:209], v[68:71]
	v_mfma_f32_16x16x32_bf16 v[64:67], v[174:177], v[206:209], v[64:67]
	v_mfma_f32_16x16x32_bf16 v[116:119], v[170:173], v[186:189], v[116:119]
	v_mfma_f32_16x16x32_bf16 v[112:115], v[178:181], v[186:189], v[112:115]
	v_mfma_f32_16x16x32_bf16 v[100:103], v[170:173], v[194:197], v[100:103]
	v_mfma_f32_16x16x32_bf16 v[96:99], v[178:181], v[194:197], v[96:99]
	v_mfma_f32_16x16x32_bf16 v[84:87], v[170:173], v[202:205], v[84:87]
	v_mfma_f32_16x16x32_bf16 v[80:83], v[178:181], v[202:205], v[80:83]
	v_mfma_f32_16x16x32_bf16 v[68:71], v[170:173], v[210:213], v[68:71]
	v_mfma_f32_16x16x32_bf16 v[64:67], v[178:181], v[210:213], v[64:67]
	s_barrier
	s_setprio 0
	s_add_i32 s33, s62, s42
	v_lshl_add_u64 v[214:215], s[68:69], 0, v[130:131]
	s_mov_b32 m0, s33
	ds_read_b128 v[182:185], v151 offset:16384
	ds_read_b128 v[186:189], v151 offset:17408
	ds_read_b128 v[190:193], v151 offset:18432
	ds_read_b128 v[194:197], v151 offset:19456
	ds_read_b128 v[198:201], v151 offset:20480
	ds_read_b128 v[202:205], v151 offset:21504
	ds_read_b128 v[206:209], v151 offset:22528
	ds_read_b128 v[210:213], v151 offset:23552
	global_load_lds_dwordx4 v[214:215], off
	s_add_i32 m0, s33, 0x2000
	v_lshl_add_u64 v[216:217], s[68:69], 0, v[134:135]
	s_add_u32 s68, s68, s8
	s_addc_u32 s69, s69, s9
	s_add_i32 s33, s63, s42
	global_load_lds_dwordx4 v[216:217], off
	v_lshl_add_u64 v[218:219], s[68:69], 0, v[130:131]
	s_mov_b32 m0, s33
	v_lshl_add_u64 v[220:221], s[68:69], 0, v[134:135]
	global_load_lds_dwordx4 v[218:219], off
	s_add_i32 m0, s33, 0x2000
	v_lshl_add_u64 v[222:223], s[34:35], 0, v[128:129]
	global_load_lds_dwordx4 v[220:221], off
	s_mov_b32 m0, s43
	v_lshl_add_u64 v[224:225], s[34:35], 0, v[132:133]
	global_load_lds_dwordx4 v[222:223], off
	s_mov_b32 m0, s44
	s_nop 0
	global_load_lds_dwordx4 v[224:225], off
	s_waitcnt vmcnt(8)
	s_waitcnt lgkmcnt(0)
	s_setprio 1
	s_barrier
	v_mfma_f32_16x16x32_bf16 v[60:63], v[142:145], v[182:185], v[60:63]
	v_mfma_f32_16x16x32_bf16 v[56:59], v[158:161], v[182:185], v[56:59]
	v_mfma_f32_16x16x32_bf16 v[44:47], v[142:145], v[190:193], v[44:47]
	v_mfma_f32_16x16x32_bf16 v[40:43], v[158:161], v[190:193], v[40:43]
	v_mfma_f32_16x16x32_bf16 v[28:31], v[142:145], v[198:201], v[28:31]
	v_mfma_f32_16x16x32_bf16 v[24:27], v[158:161], v[198:201], v[24:27]
	v_mfma_f32_16x16x32_bf16 v[12:15], v[142:145], v[206:209], v[12:15]
	v_mfma_f32_16x16x32_bf16 v[8:11], v[158:161], v[206:209], v[8:11]
	v_mfma_f32_16x16x32_bf16 v[60:63], v[154:157], v[186:189], v[60:63]
	v_mfma_f32_16x16x32_bf16 v[56:59], v[162:165], v[186:189], v[56:59]
	v_mfma_f32_16x16x32_bf16 v[44:47], v[154:157], v[194:197], v[44:47]
	v_mfma_f32_16x16x32_bf16 v[40:43], v[162:165], v[194:197], v[40:43]
	v_mfma_f32_16x16x32_bf16 v[28:31], v[154:157], v[202:205], v[28:31]
	v_mfma_f32_16x16x32_bf16 v[24:27], v[162:165], v[202:205], v[24:27]
	v_mfma_f32_16x16x32_bf16 v[12:15], v[154:157], v[210:213], v[12:15]
	v_mfma_f32_16x16x32_bf16 v[8:11], v[162:165], v[210:213], v[8:11]
	v_mfma_f32_16x16x32_bf16 v[52:55], v[166:169], v[182:185], v[52:55]
	v_mfma_f32_16x16x32_bf16 v[48:51], v[174:177], v[182:185], v[48:51]
	v_mfma_f32_16x16x32_bf16 v[36:39], v[166:169], v[190:193], v[36:39]
	v_mfma_f32_16x16x32_bf16 v[32:35], v[174:177], v[190:193], v[32:35]
	v_mfma_f32_16x16x32_bf16 v[20:23], v[166:169], v[198:201], v[20:23]
	v_mfma_f32_16x16x32_bf16 v[16:19], v[174:177], v[198:201], v[16:19]
	v_mfma_f32_16x16x32_bf16 v[4:7], v[166:169], v[206:209], v[4:7]
	v_mfma_f32_16x16x32_bf16 v[0:3], v[174:177], v[206:209], v[0:3]
	v_mfma_f32_16x16x32_bf16 v[52:55], v[170:173], v[186:189], v[52:55]
	v_mfma_f32_16x16x32_bf16 v[48:51], v[178:181], v[186:189], v[48:51]
	v_mfma_f32_16x16x32_bf16 v[36:39], v[170:173], v[194:197], v[36:39]
	v_mfma_f32_16x16x32_bf16 v[32:35], v[178:181], v[194:197], v[32:35]
	v_mfma_f32_16x16x32_bf16 v[20:23], v[170:173], v[202:205], v[20:23]
	v_mfma_f32_16x16x32_bf16 v[16:19], v[178:181], v[202:205], v[16:19]
	v_mfma_f32_16x16x32_bf16 v[4:7], v[170:173], v[210:213], v[4:7]
	v_mfma_f32_16x16x32_bf16 v[0:3], v[178:181], v[210:213], v[0:3]
	s_barrier
; #define PG8_STAGE(bufoff, gbase, voff) do { _Pragma("unroll") for (int _i = 0; _i < 2; ++_i) \
;         __builtin_amdgcn_global_load_lds((const unsigned*)((const char*)(gbase) + (voff)[_i]), (PG8_LAS unsigned*)(lds + (bufoff) + ldsw + _i * 8192), 16, 0, 0); } while (0)
; #define PG8_LDA(dst, b, h) do { _Pragma("unroll") for (int m = 0; m < 4; ++m) _Pragma("unroll") for (int k = 0; k < 2; ++k) dst[m][k] = *(const PG8_LAS bf16x8*)(lds + PG8_SA(b, h) + aoff + m * 2048 + k * 1024); } while (0)
; #define PG8_WAIT_V(n) asm volatile("s_waitcnt vmcnt(" #n ")" ::: "memory")
; #define PG8_WAIT_L(n) asm volatile("s_waitcnt lgkmcnt(" #n ")" ::: "memory")
; #define PG8_BAR __builtin_amdgcn_s_barrier()
; template <class Epi, class Sched, bool ALIGN_EPI = false, bool SP2 = false>
; __device__ __forceinline__ void gemm_phase(PG8_LAS unsigned char* lds, const Gemm g, const Sched& S, const Epi& E, const int wid) {
;     ...
;         for (int t = 0; t < nt; t += 2) {
;             const bool last = (t == nt - 2);
;             const char* a1 = cA + (size_t)(t + 1) * kstep;
;             const char* a2 = last ? nA : cA + (size_t)(t + 2) * kstep; const char* b2 = last ? nB : cB + (size_t)(t + 2) * kstep;
;             const char* a3 = a2 + kstep; const char* b3 = b2 + kstep;
;             if (last && has_next) S.a_ready(nxt);
;             if constexpr (SP2) {
;             PG8_LDB(B0, 0, 0); PG8_LDB(B1, 0, 1); PG8_SCHED; PG8_LDA(At, 0, 0); PG8_STAGE(PG8_SA(1, 1), a1 + hstep, voffA);
;             PG8_WAIT_V(8); PG8_WAIT_L(0); PG8_BAR; PG8_MMA(0, 0, At, B0); PG8_MMA(0, 1, At, B1); PG8_BAR; PG8_SCHED;
;             PG8_LDA(At, 0, 1); PG8_STAGE(PG8_SB(0, 0), b2, voffB); PG8_STAGE(PG8_SB(0, 1), b2 + hstep, voffB); PG8_STAGE(PG8_SA(0, 0), a2, voffA);
;             PG8_WAIT_V(8); PG8_WAIT_L(0); PG8_BAR; PG8_MMA(1, 0, At, B0); PG8_MMA(1, 1, At, B1); PG8_BAR; PG8_SCHED;
;             PG8_LDB(B0, 1, 0); PG8_LDB(B1, 1, 1); PG8_SCHED; PG8_LDA(At, 1, 0); PG8_STAGE(PG8_SA(0, 1), a2 + hstep, voffA);
;             PG8_WAIT_V(8); PG8_WAIT_L(0); PG8_BAR; PG8_MMA(0, 0, At, B0); PG8_MMA(0, 1, At, B1); PG8_BAR; PG8_SCHED;
;             PG8_LDA(At, 1, 1); PG8_STAGE(PG8_SB(1, 0), b3, voffB); PG8_STAGE(PG8_SB(1, 1), b3 + hstep, voffB); PG8_STAGE(PG8_SA(1, 0), a3, voffA);
;             PG8_WAIT_V(8); PG8_WAIT_L(0); PG8_BAR; PG8_MMA(1, 0, At, B0); PG8_MMA(1, 1, At, B1); PG8_BAR; PG8_SCHED;
	s_setprio 0
	s_add_i32 s33, 0, 0x18000
	v_add_u32_e32 v153, s33, v148
	s_add_i32 s37, 0, 0x1c000
	ds_read_b128 v[142:145], v153
	ds_read_b128 v[154:157], v153 offset:1024
	ds_read_b128 v[158:161], v153 offset:2048
	ds_read_b128 v[162:165], v153 offset:3072
	v_add_u32_e32 v153, s37, v148
	ds_read_b128 v[166:169], v153
	ds_read_b128 v[170:173], v153 offset:1024
	ds_read_b128 v[174:177], v153 offset:2048
	ds_read_b128 v[178:181], v153 offset:3072
	s_add_u32 s34, s34, s8
	s_addc_u32 s35, s35, s9
	s_mov_b32 m0, s45
	v_lshl_add_u64 v[226:227], s[34:35], 0, v[128:129]
	ds_read_b128 v[182:185], v151 offset:32768
	ds_read_b128 v[186:189], v151 offset:33792
	ds_read_b128 v[190:193], v151 offset:34816
	ds_read_b128 v[194:197], v151 offset:35840
	ds_read_b128 v[198:201], v151 offset:36864
	ds_read_b128 v[202:205], v151 offset:37888
	ds_read_b128 v[206:209], v151 offset:38912
	ds_read_b128 v[210:213], v151 offset:39936
	global_load_lds_dwordx4 v[226:227], off
	v_lshl_add_u64 v[226:227], s[34:35], 0, v[132:133]
	s_mov_b32 m0, s46
	s_nop 0
	global_load_lds_dwordx4 v[226:227], off
	s_waitcnt vmcnt(8)
	s_waitcnt lgkmcnt(0)
	s_setprio 1
	s_barrier
	v_mfma_f32_16x16x32_bf16 v[120:123], v[142:145], v[182:185], v[120:123]
	v_mfma_f32_16x16x32_bf16 v[124:127], v[158:161], v[182:185], v[124:127]
	v_mfma_f32_16x16x32_bf16 v[108:111], v[142:145], v[190:193], v[108:111]
	v_mfma_f32_16x16x32_bf16 v[104:107], v[158:161], v[190:193], v[104:107]
	v_mfma_f32_16x16x32_bf16 v[92:95], v[142:145], v[198:201], v[92:95]
	v_mfma_f32_16x16x32_bf16 v[88:91], v[158:161], v[198:201], v[88:91]
	v_mfma_f32_16x16x32_bf16 v[76:79], v[142:145], v[206:209], v[76:79]
	v_mfma_f32_16x16x32_bf16 v[72:75], v[158:161], v[206:209], v[72:75]
	v_mfma_f32_16x16x32_bf16 v[120:123], v[154:157], v[186:189], v[120:123]
	v_mfma_f32_16x16x32_bf16 v[124:127], v[162:165], v[186:189], v[124:127]
	v_mfma_f32_16x16x32_bf16 v[108:111], v[154:157], v[194:197], v[108:111]
	v_mfma_f32_16x16x32_bf16 v[104:107], v[162:165], v[194:197], v[104:107]
	v_mfma_f32_16x16x32_bf16 v[92:95], v[154:157], v[202:205], v[92:95]
	v_mfma_f32_16x16x32_bf16 v[88:91], v[162:165], v[202:205], v[88:91]
	v_mfma_f32_16x16x32_bf16 v[76:79], v[154:157], v[210:213], v[76:79]
	v_mfma_f32_16x16x32_bf16 v[72:75], v[162:165], v[210:213], v[72:75]
	v_mfma_f32_16x16x32_bf16 v[116:119], v[166:169], v[182:185], v[116:119]
	v_mfma_f32_16x16x32_bf16 v[112:115], v[174:177], v[182:185], v[112:115]
	v_mfma_f32_16x16x32_bf16 v[100:103], v[166:169], v[190:193], v[100:103]
	v_mfma_f32_16x16x32_bf16 v[96:99], v[174:177], v[190:193], v[96:99]
	v_mfma_f32_16x16x32_bf16 v[84:87], v[166:169], v[198:201], v[84:87]
	v_mfma_f32_16x16x32_bf16 v[80:83], v[174:177], v[198:201], v[80:83]
	v_mfma_f32_16x16x32_bf16 v[68:71], v[166:169], v[206:209], v[68:71]
	v_mfma_f32_16x16x32_bf16 v[64:67], v[174:177], v[206:209], v[64:67]
	v_mfma_f32_16x16x32_bf16 v[116:119], v[170:173], v[186:189], v[116:119]
	v_mfma_f32_16x16x32_bf16 v[112:115], v[178:181], v[186:189], v[112:115]
	v_mfma_f32_16x16x32_bf16 v[100:103], v[170:173], v[194:197], v[100:103]
	v_mfma_f32_16x16x32_bf16 v[96:99], v[178:181], v[194:197], v[96:99]
	v_mfma_f32_16x16x32_bf16 v[84:87], v[170:173], v[202:205], v[84:87]
	v_mfma_f32_16x16x32_bf16 v[80:83], v[178:181], v[202:205], v[80:83]
	v_mfma_f32_16x16x32_bf16 v[68:71], v[170:173], v[210:213], v[68:71]
	v_mfma_f32_16x16x32_bf16 v[64:67], v[178:181], v[210:213], v[64:67]
	s_barrier
	s_setprio 0
	s_add_i32 s33, s33, s42
	v_lshl_add_u64 v[214:215], v[214:215], 0, s[22:23]
	s_mov_b32 m0, s33
	ds_read_b128 v[182:185], v151 offset:49152
	ds_read_b128 v[186:189], v151 offset:50176
	ds_read_b128 v[190:193], v151 offset:51200
	ds_read_b128 v[194:197], v151 offset:52224
	ds_read_b128 v[198:201], v151 offset:53248
	ds_read_b128 v[202:205], v151 offset:54272
	ds_read_b128 v[206:209], v151 offset:55296
	ds_read_b128 v[210:213], v151 offset:56320
	global_load_lds_dwordx4 v[214:215], off
	v_lshl_add_u64 v[214:215], v[216:217], 0, s[22:23]
	s_add_i32 m0, s33, 0x2000
	s_add_i32 s33, s37, s42
	global_load_lds_dwordx4 v[214:215], off
	v_lshl_add_u64 v[214:215], v[218:219], 0, s[22:23]
	s_mov_b32 m0, s33
	s_nop 0
	global_load_lds_dwordx4 v[214:215], off
	v_lshl_add_u64 v[214:215], v[220:221], 0, s[22:23]
	s_add_i32 m0, s33, 0x2000
	s_nop 0
	global_load_lds_dwordx4 v[214:215], off
	v_lshl_add_u64 v[214:215], v[222:223], 0, s[22:23]
	s_mov_b32 m0, s47
	s_nop 0
	global_load_lds_dwordx4 v[214:215], off
	v_lshl_add_u64 v[214:215], v[224:225], 0, s[22:23]
	s_mov_b32 m0, s49
	s_nop 0
	global_load_lds_dwordx4 v[214:215], off
	s_waitcnt vmcnt(8)
	s_waitcnt lgkmcnt(0)
	s_setprio 1
	s_barrier
	v_mfma_f32_16x16x32_bf16 v[60:63], v[142:145], v[182:185], v[60:63]
	v_mfma_f32_16x16x32_bf16 v[56:59], v[158:161], v[182:185], v[56:59]
	v_mfma_f32_16x16x32_bf16 v[44:47], v[142:145], v[190:193], v[44:47]
	v_mfma_f32_16x16x32_bf16 v[40:43], v[158:161], v[190:193], v[40:43]
	v_mfma_f32_16x16x32_bf16 v[28:31], v[142:145], v[198:201], v[28:31]
	v_mfma_f32_16x16x32_bf16 v[24:27], v[158:161], v[198:201], v[24:27]
	v_mfma_f32_16x16x32_bf16 v[12:15], v[142:145], v[206:209], v[12:15]
	v_mfma_f32_16x16x32_bf16 v[8:11], v[158:161], v[206:209], v[8:11]
	v_mfma_f32_16x16x32_bf16 v[60:63], v[154:157], v[186:189], v[60:63]
	v_mfma_f32_16x16x32_bf16 v[56:59], v[162:165], v[186:189], v[56:59]
	v_mfma_f32_16x16x32_bf16 v[44:47], v[154:157], v[194:197], v[44:47]
	v_mfma_f32_16x16x32_bf16 v[40:43], v[162:165], v[194:197], v[40:43]
	v_mfma_f32_16x16x32_bf16 v[28:31], v[154:157], v[202:205], v[28:31]
	v_mfma_f32_16x16x32_bf16 v[24:27], v[162:165], v[202:205], v[24:27]
	v_mfma_f32_16x16x32_bf16 v[12:15], v[154:157], v[210:213], v[12:15]
	v_mfma_f32_16x16x32_bf16 v[8:11], v[162:165], v[210:213], v[8:11]
	v_mfma_f32_16x16x32_bf16 v[52:55], v[166:169], v[182:185], v[52:55]
	v_mfma_f32_16x16x32_bf16 v[48:51], v[174:177], v[182:185], v[48:51]
	v_mfma_f32_16x16x32_bf16 v[36:39], v[166:169], v[190:193], v[36:39]
	v_mfma_f32_16x16x32_bf16 v[32:35], v[174:177], v[190:193], v[32:35]
	v_mfma_f32_16x16x32_bf16 v[20:23], v[166:169], v[198:201], v[20:23]
	v_mfma_f32_16x16x32_bf16 v[16:19], v[174:177], v[198:201], v[16:19]
	v_mfma_f32_16x16x32_bf16 v[4:7], v[166:169], v[206:209], v[4:7]
	v_mfma_f32_16x16x32_bf16 v[0:3], v[174:177], v[206:209], v[0:3]
	v_mfma_f32_16x16x32_bf16 v[52:55], v[170:173], v[186:189], v[52:55]
	v_mfma_f32_16x16x32_bf16 v[48:51], v[178:181], v[186:189], v[48:51]
	v_mfma_f32_16x16x32_bf16 v[36:39], v[170:173], v[194:197], v[36:39]
	v_mfma_f32_16x16x32_bf16 v[32:35], v[178:181], v[194:197], v[32:35]
	v_mfma_f32_16x16x32_bf16 v[20:23], v[170:173], v[202:205], v[20:23]
	v_mfma_f32_16x16x32_bf16 v[16:19], v[178:181], v[202:205], v[16:19]
	v_mfma_f32_16x16x32_bf16 v[4:7], v[170:173], v[210:213], v[4:7]
	v_mfma_f32_16x16x32_bf16 v[0:3], v[178:181], v[210:213], v[0:3]
	s_barrier
	s_setprio 0
	s_add_u32 s4, s4, 0x100
	s_addc_u32 s5, s5, 0
	s_add_u32 s0, s0, 0x100
	s_addc_u32 s1, s1, 0
	s_cmp_ge_i32 s36, s51
	s_mov_b32 s34, s36
	s_cbranch_scc0 .LBB0_1339

; #define PG8_WAIT_V(n) asm volatile("s_waitcnt vmcnt(" #n ")" ::: "memory")
; #define PG8_BAR __builtin_amdgcn_s_barrier()
; template <class Epi, class Sched, bool ALIGN_EPI = false, bool SP2 = false>
; __device__ __forceinline__ void gemm_phase(PG8_LAS unsigned char* lds, const Gemm g, const Sched& S, const Epi& E, const int wid) {
;     ...
;         const bool has_next = S.next(ui + 1, nxt);
;         const char* nA = has_next ? (const char*)g.A + (size_t)nxt.pm * tstep : cA; const char* nB = has_next ? (const char*)g.Bt + (size_t)nxt.pn * tstep : cB;
;         for (int t = 0; t < nt; t += 2) {
;             const bool last = (t == nt - 2);
;             const char* a1 = cA + (size_t)(t + 1) * kstep;
;             const char* a2 = last ? nA : cA + (size_t)(t + 2) * kstep; const char* b2 = last ? nB : cB + (size_t)(t + 2) * kstep;
;             const char* a3 = a2 + kstep; const char* b3 = b2 + kstep;
;             if (last && has_next) S.a_ready(nxt);
;             if constexpr (SP2) {
;             PG8_LDB(B0, 0, 0); PG8_LDB(B1, 0, 1); PG8_SCHED; PG8_LDA(At, 0, 0); PG8_STAGE(PG8_SA(1, 1), a1 + hstep, voffA);
;             PG8_WAIT_V(8); PG8_WAIT_L(0); PG8_BAR; PG8_MMA(0, 0, At, B0); PG8_MMA(0, 1, At, B1); PG8_BAR; PG8_SCHED;
;             PG8_LDA(At, 0, 1); PG8_STAGE(PG8_SB(0, 0), b2, voffB); PG8_STAGE(PG8_SB(0, 1), b2 + hstep, voffB); PG8_STAGE(PG8_SA(0, 0), a2, voffA);
;             PG8_WAIT_V(8); PG8_WAIT_L(0); PG8_BAR; PG8_MMA(1, 0, At, B0); PG8_MMA(1, 1, At, B1); PG8_BAR; PG8_SCHED;
;             PG8_LDB(B0, 1, 0); PG8_LDB(B1, 1, 1); PG8_SCHED; PG8_LDA(At, 1, 0); PG8_STAGE(PG8_SA(0, 1), a2 + hstep, voffA);
;             PG8_WAIT_V(8); PG8_WAIT_L(0); PG8_BAR; PG8_MMA(0, 0, At, B0); PG8_MMA(0, 1, At, B1); PG8_BAR; PG8_SCHED;
;             PG8_LDA(At, 1, 1); PG8_STAGE(PG8_SB(1, 0), b3, voffB); PG8_STAGE(PG8_SB(1, 1), b3 + hstep, voffB); PG8_STAGE(PG8_SA(1, 0), a3, voffA);
;             PG8_WAIT_V(8); PG8_WAIT_L(0); PG8_BAR; PG8_MMA(1, 0, At, B0); PG8_MMA(1, 1, At, B1); PG8_BAR; PG8_SCHED;
;             } else {
;             PG8_LDB(B0, 0, 0); PG8_SCHED; PG8_LDA(At, 0, 0); PG8_STAGE(PG8_SA(1, 1), a1 + hstep, voffA);
;             PG8_WAIT_L(8); PG8_BAR; PG8_WAIT_L(0); PG8_MMA(0, 0, At, B0); PG8_BAR; PG8_SCHED;
;             PG8_LDB(B1, 0, 1); PG8_STAGE(PG8_SB(0, 0), b2, voffB);
;             PG8_BAR; PG8_WAIT_L(0); PG8_MMA(0, 1, At, B1); PG8_BAR;
.LBB0_1493:
	s_andn2_b64 vcc, exec, s[22:23]
	s_cbranch_vccnz .Lz_FFN1
	s_add_u32 s4, s8, 0x80
	s_addc_u32 s5, s9, 0
	s_add_u32 s0, s6, 0x100
	s_addc_u32 s1, s7, 0
	s_mov_b32 s6, 0
	ds_read_b128 v[142:145], v149
	ds_read_b128 v[152:155], v149 offset:1024
	ds_read_b128 v[156:159], v149 offset:2048
	ds_read_b128 v[160:163], v149 offset:3072
	ds_read_b128 v[164:167], v150
	ds_read_b128 v[168:171], v150 offset:1024
	ds_read_b128 v[172:175], v150 offset:2048
	ds_read_b128 v[176:179], v150 offset:3072
	s_add_i32 s8, s6, 2
	s_add_u32 s9, s4, 0x80
	s_addc_u32 s7, s5, 0
	s_cmp_eq_u32 s55, s6
	s_cselect_b32 s6, s26, s9
	s_cselect_b32 s7, s27, s7
	s_cselect_b32 s65, s29, s1
	s_cselect_b32 s64, s28, s0
	v_lshl_add_u64 v[212:213], s[4:5], 0, v[136:137]
	s_add_i32 m0, s44, 0xc000
	ds_read_b128 v[180:183], v151
	ds_read_b128 v[184:187], v151 offset:1024
	ds_read_b128 v[188:191], v151 offset:2048
	ds_read_b128 v[192:195], v151 offset:3072
	ds_read_b128 v[196:199], v151 offset:4096
	ds_read_b128 v[200:203], v151 offset:5120
	ds_read_b128 v[204:207], v151 offset:6144
	ds_read_b128 v[208:211], v151 offset:7168
	global_load_lds_dwordx4 v[212:213], off
	v_lshl_add_u64 v[212:213], s[4:5], 0, v[138:139]
	s_add_i32 m0, s44, 0xe000
	s_nop 0
	global_load_lds_dwordx4 v[212:213], off
	s_waitcnt vmcnt(8)
	s_waitcnt lgkmcnt(0)
	s_setprio 1
	s_barrier
	v_mfma_f32_16x16x32_bf16 v[120:123], v[142:145], v[180:183], 0
	v_mfma_f32_16x16x32_bf16 v[112:115], v[156:159], v[180:183], 0
	v_mfma_f32_16x16x32_bf16 v[104:107], v[142:145], v[188:191], 0
	v_mfma_f32_16x16x32_bf16 v[96:99], v[156:159], v[188:191], 0
	v_mfma_f32_16x16x32_bf16 v[88:91], v[142:145], v[196:199], 0
	v_mfma_f32_16x16x32_bf16 v[80:83], v[156:159], v[196:199], 0
	v_mfma_f32_16x16x32_bf16 v[72:75], v[142:145], v[204:207], 0
	v_mfma_f32_16x16x32_bf16 v[64:67], v[156:159], v[204:207], 0
	v_mfma_f32_16x16x32_bf16 v[120:123], v[152:155], v[184:187], v[120:123]
	v_mfma_f32_16x16x32_bf16 v[112:115], v[160:163], v[184:187], v[112:115]
	v_mfma_f32_16x16x32_bf16 v[104:107], v[152:155], v[192:195], v[104:107]
	v_mfma_f32_16x16x32_bf16 v[96:99], v[160:163], v[192:195], v[96:99]
	v_mfma_f32_16x16x32_bf16 v[88:91], v[152:155], v[200:203], v[88:91]
	v_mfma_f32_16x16x32_bf16 v[80:83], v[160:163], v[200:203], v[80:83]
	v_mfma_f32_16x16x32_bf16 v[72:75], v[152:155], v[208:211], v[72:75]
	v_mfma_f32_16x16x32_bf16 v[64:67], v[160:163], v[208:211], v[64:67]
	v_mfma_f32_16x16x32_bf16 v[124:127], v[164:167], v[180:183], 0
	v_mfma_f32_16x16x32_bf16 v[116:119], v[172:175], v[180:183], 0
	v_mfma_f32_16x16x32_bf16 v[108:111], v[164:167], v[188:191], 0
	v_mfma_f32_16x16x32_bf16 v[100:103], v[172:175], v[188:191], 0
	v_mfma_f32_16x16x32_bf16 v[92:95], v[164:167], v[196:199], 0
	v_mfma_f32_16x16x32_bf16 v[84:87], v[172:175], v[196:199], 0
	v_mfma_f32_16x16x32_bf16 v[76:79], v[164:167], v[204:207], 0
	v_mfma_f32_16x16x32_bf16 v[68:71], v[172:175], v[204:207], 0
	v_mfma_f32_16x16x32_bf16 v[124:127], v[168:171], v[184:187], v[124:127]
	v_mfma_f32_16x16x32_bf16 v[116:119], v[176:179], v[184:187], v[116:119]
	v_mfma_f32_16x16x32_bf16 v[108:111], v[168:171], v[192:195], v[108:111]
	v_mfma_f32_16x16x32_bf16 v[100:103], v[176:179], v[192:195], v[100:103]
	v_mfma_f32_16x16x32_bf16 v[92:95], v[168:171], v[200:203], v[92:95]
	v_mfma_f32_16x16x32_bf16 v[84:87], v[176:179], v[200:203], v[84:87]
	v_mfma_f32_16x16x32_bf16 v[76:79], v[168:171], v[208:211], v[76:79]
	v_mfma_f32_16x16x32_bf16 v[68:71], v[176:179], v[208:211], v[68:71]
	s_barrier
	s_setprio 0
	s_add_i32 s9, s57, s36
	v_lshl_add_u64 v[212:213], s[64:65], 0, v[132:133]
	s_mov_b32 m0, s9
	ds_read_b128 v[180:183], v151 offset:16384
	ds_read_b128 v[184:187], v151 offset:17408
	ds_read_b128 v[188:191], v151 offset:18432
	ds_read_b128 v[192:195], v151 offset:19456
	ds_read_b128 v[196:199], v151 offset:20480
	ds_read_b128 v[200:203], v151 offset:21504
	ds_read_b128 v[204:207], v151 offset:22528
	ds_read_b128 v[208:211], v151 offset:23552
	global_load_lds_dwordx4 v[212:213], off
	s_add_i32 m0, s9, 0x2000
	v_lshl_add_u64 v[214:215], s[64:65], 0, v[128:129]
	s_add_u32 s64, s64, s12
	s_addc_u32 s65, s65, s13
	s_add_i32 s9, s58, s36
	global_load_lds_dwordx4 v[214:215], off
	v_lshl_add_u64 v[216:217], s[64:65], 0, v[132:133]
	s_mov_b32 m0, s9
	v_lshl_add_u64 v[218:219], s[64:65], 0, v[128:129]
	global_load_lds_dwordx4 v[216:217], off
	s_add_i32 m0, s9, 0x2000
	v_lshl_add_u64 v[220:221], s[6:7], 0, v[134:135]
	global_load_lds_dwordx4 v[218:219], off
	s_mov_b32 m0, s44
	v_lshl_add_u64 v[222:223], s[6:7], 0, v[130:131]
	global_load_lds_dwordx4 v[220:221], off
	s_mov_b32 m0, s45
	s_nop 0
	global_load_lds_dwordx4 v[222:223], off
	s_waitcnt vmcnt(8)
	s_waitcnt lgkmcnt(0)
	s_setprio 1
	s_barrier
; #define PG8_STAGE(bufoff, gbase, voff) do { _Pragma("unroll") for (int _i = 0; _i < 2; ++_i) \
;         __builtin_amdgcn_global_load_lds((const unsigned*)((const char*)(gbase) + (voff)[_i]), (PG8_LAS unsigned*)(lds + (bufoff) + ldsw + _i * 8192), 16, 0, 0); } while (0)
; #define PG8_LDA(dst, b, h) do { _Pragma("unroll") for (int m = 0; m < 4; ++m) _Pragma("unroll") for (int k = 0; k < 2; ++k) dst[m][k] = *(const PG8_LAS bf16x8*)(lds + PG8_SA(b, h) + aoff + m * 2048 + k * 1024); } while (0)
; #define PG8_LDB(dst, b, h) do { _Pragma("unroll") for (int n = 0; n < 2; ++n) _Pragma("unroll") for (int k = 0; k < 2; ++k) dst[n][k] = *(const PG8_LAS bf16x8*)(lds + PG8_SB(b, h) + boff + n * 2048 + k * 1024); } while (0)
; #define PG8_MMA(ai, bj, At, Bt) do { __builtin_amdgcn_s_setprio(1); _Pragma("unroll") for (int m = 0; m < 4; ++m) _Pragma("unroll") for (int n = 0; n < 2; ++n) _Pragma("unroll") for (int k = 0; k < 2; ++k) \
;         acc[ai][bj][m][n] = __builtin_amdgcn_mfma_f32_16x16x32_bf16(Bt[n][k], At[m][k], acc[ai][bj][m][n], 0, 0, 0); __builtin_amdgcn_s_setprio(0); } while (0)
; #define PG8_WAIT_V(n) asm volatile("s_waitcnt vmcnt(" #n ")" ::: "memory")
; #define PG8_WAIT_L(n) asm volatile("s_waitcnt lgkmcnt(" #n ")" ::: "memory")
; template <class Epi, class Sched, bool ALIGN_EPI = false, bool SP2 = false>
; __device__ __forceinline__ void gemm_phase(PG8_LAS unsigned char* lds, const Gemm g, const Sched& S, const Epi& E, const int wid) {
;     ...
;             PG8_WAIT_V(8); PG8_WAIT_L(0); PG8_BAR; PG8_MMA(0, 0, At, B0); PG8_MMA(0, 1, At, B1); PG8_BAR; PG8_SCHED;
;             PG8_LDA(At, 0, 1); PG8_STAGE(PG8_SB(0, 0), b2, voffB); PG8_STAGE(PG8_SB(0, 1), b2 + hstep, voffB); PG8_STAGE(PG8_SA(0, 0), a2, voffA);
;             PG8_WAIT_V(8); PG8_WAIT_L(0); PG8_BAR; PG8_MMA(1, 0, At, B0); PG8_MMA(1, 1, At, B1); PG8_BAR; PG8_SCHED;
;             PG8_LDB(B0, 1, 0); PG8_LDB(B1, 1, 1); PG8_SCHED; PG8_LDA(At, 1, 0); PG8_STAGE(PG8_SA(0, 1), a2 + hstep, voffA);
;             PG8_WAIT_V(8); PG8_WAIT_L(0); PG8_BAR; PG8_MMA(0, 0, At, B0); PG8_MMA(0, 1, At, B1); PG8_BAR; PG8_SCHED;
;             PG8_LDA(At, 1, 1); PG8_STAGE(PG8_SB(1, 0), b3, voffB); PG8_STAGE(PG8_SB(1, 1), b3 + hstep, voffB); PG8_STAGE(PG8_SA(1, 0), a3, voffA);
;             PG8_WAIT_V(8); PG8_WAIT_L(0); PG8_BAR; PG8_MMA(1, 0, At, B0); PG8_MMA(1, 1, At, B1); PG8_BAR; PG8_SCHED;
	v_mfma_f32_16x16x32_bf16 v[56:59], v[142:145], v[180:183], 0
	v_mfma_f32_16x16x32_bf16 v[48:51], v[156:159], v[180:183], 0
	v_mfma_f32_16x16x32_bf16 v[40:43], v[142:145], v[188:191], 0
	v_mfma_f32_16x16x32_bf16 v[32:35], v[156:159], v[188:191], 0
	v_mfma_f32_16x16x32_bf16 v[24:27], v[142:145], v[196:199], 0
	v_mfma_f32_16x16x32_bf16 v[16:19], v[156:159], v[196:199], 0
	v_mfma_f32_16x16x32_bf16 v[8:11], v[142:145], v[204:207], 0
	v_mfma_f32_16x16x32_bf16 v[4:7], v[156:159], v[204:207], 0
	v_mfma_f32_16x16x32_bf16 v[56:59], v[152:155], v[184:187], v[56:59]
	v_mfma_f32_16x16x32_bf16 v[48:51], v[160:163], v[184:187], v[48:51]
	v_mfma_f32_16x16x32_bf16 v[40:43], v[152:155], v[192:195], v[40:43]
	v_mfma_f32_16x16x32_bf16 v[32:35], v[160:163], v[192:195], v[32:35]
	v_mfma_f32_16x16x32_bf16 v[24:27], v[152:155], v[200:203], v[24:27]
	v_mfma_f32_16x16x32_bf16 v[16:19], v[160:163], v[200:203], v[16:19]
	v_mfma_f32_16x16x32_bf16 v[8:11], v[152:155], v[208:211], v[8:11]
	v_mfma_f32_16x16x32_bf16 v[4:7], v[160:163], v[208:211], v[4:7]
	v_mfma_f32_16x16x32_bf16 v[60:63], v[164:167], v[180:183], 0
	v_mfma_f32_16x16x32_bf16 v[52:55], v[172:175], v[180:183], 0
	v_mfma_f32_16x16x32_bf16 v[44:47], v[164:167], v[188:191], 0
	v_mfma_f32_16x16x32_bf16 v[36:39], v[172:175], v[188:191], 0
	v_mfma_f32_16x16x32_bf16 v[28:31], v[164:167], v[196:199], 0
	v_mfma_f32_16x16x32_bf16 v[20:23], v[172:175], v[196:199], 0
	v_mfma_f32_16x16x32_bf16 v[12:15], v[164:167], v[204:207], 0
	v_mfma_f32_16x16x32_bf16 v[0:3], v[172:175], v[204:207], 0
	v_mfma_f32_16x16x32_bf16 v[60:63], v[168:171], v[184:187], v[60:63]
	v_mfma_f32_16x16x32_bf16 v[52:55], v[176:179], v[184:187], v[52:55]
	v_mfma_f32_16x16x32_bf16 v[44:47], v[168:171], v[192:195], v[44:47]
	v_mfma_f32_16x16x32_bf16 v[36:39], v[176:179], v[192:195], v[36:39]
	v_mfma_f32_16x16x32_bf16 v[28:31], v[168:171], v[200:203], v[28:31]
	v_mfma_f32_16x16x32_bf16 v[20:23], v[176:179], v[200:203], v[20:23]
	v_mfma_f32_16x16x32_bf16 v[12:15], v[168:171], v[208:211], v[12:15]
	v_mfma_f32_16x16x32_bf16 v[0:3], v[176:179], v[208:211], v[0:3]
	s_barrier
	s_setprio 0
	s_add_i32 s9, 0, 0x18000
	s_add_i32 s33, 0, 0x1c000
	v_add_u32_e32 v160, s9, v148
	v_add_u32_e32 v176, s33, v148
	ds_read_b128 v[142:145], v160
	ds_read_b128 v[152:155], v160 offset:1024
	ds_read_b128 v[156:159], v160 offset:2048
	ds_read_b128 v[160:163], v160 offset:3072
	ds_read_b128 v[164:167], v176
	ds_read_b128 v[168:171], v176 offset:1024
	ds_read_b128 v[172:175], v176 offset:2048
	ds_read_b128 v[176:179], v176 offset:3072
	s_add_u32 s6, s6, s12
	s_addc_u32 s7, s7, s13
	s_mov_b32 m0, s46
	v_lshl_add_u64 v[224:225], s[6:7], 0, v[134:135]
	ds_read_b128 v[180:183], v151 offset:32768
	ds_read_b128 v[184:187], v151 offset:33792
	ds_read_b128 v[188:191], v151 offset:34816
	ds_read_b128 v[192:195], v151 offset:35840
	ds_read_b128 v[196:199], v151 offset:36864
	ds_read_b128 v[200:203], v151 offset:37888
	ds_read_b128 v[204:207], v151 offset:38912
	ds_read_b128 v[208:211], v151 offset:39936
	global_load_lds_dwordx4 v[224:225], off
	v_lshl_add_u64 v[224:225], s[6:7], 0, v[130:131]
	s_mov_b32 m0, s47
	s_nop 0
	global_load_lds_dwordx4 v[224:225], off
	s_waitcnt vmcnt(8)
	s_waitcnt lgkmcnt(0)
	s_setprio 1
	s_barrier
	v_mfma_f32_16x16x32_bf16 v[120:123], v[142:145], v[180:183], v[120:123]
	v_mfma_f32_16x16x32_bf16 v[112:115], v[156:159], v[180:183], v[112:115]
	v_mfma_f32_16x16x32_bf16 v[104:107], v[142:145], v[188:191], v[104:107]
	v_mfma_f32_16x16x32_bf16 v[96:99], v[156:159], v[188:191], v[96:99]
	v_mfma_f32_16x16x32_bf16 v[88:91], v[142:145], v[196:199], v[88:91]
	v_mfma_f32_16x16x32_bf16 v[80:83], v[156:159], v[196:199], v[80:83]
	v_mfma_f32_16x16x32_bf16 v[72:75], v[142:145], v[204:207], v[72:75]
	v_mfma_f32_16x16x32_bf16 v[64:67], v[156:159], v[204:207], v[64:67]
	v_mfma_f32_16x16x32_bf16 v[120:123], v[152:155], v[184:187], v[120:123]
	v_mfma_f32_16x16x32_bf16 v[112:115], v[160:163], v[184:187], v[112:115]
	v_mfma_f32_16x16x32_bf16 v[104:107], v[152:155], v[192:195], v[104:107]
	v_mfma_f32_16x16x32_bf16 v[96:99], v[160:163], v[192:195], v[96:99]
	v_mfma_f32_16x16x32_bf16 v[88:91], v[152:155], v[200:203], v[88:91]
	v_mfma_f32_16x16x32_bf16 v[80:83], v[160:163], v[200:203], v[80:83]
	v_mfma_f32_16x16x32_bf16 v[72:75], v[152:155], v[208:211], v[72:75]
	v_mfma_f32_16x16x32_bf16 v[64:67], v[160:163], v[208:211], v[64:67]
	v_mfma_f32_16x16x32_bf16 v[124:127], v[164:167], v[180:183], v[124:127]
	v_mfma_f32_16x16x32_bf16 v[116:119], v[172:175], v[180:183], v[116:119]
	v_mfma_f32_16x16x32_bf16 v[108:111], v[164:167], v[188:191], v[108:111]
	v_mfma_f32_16x16x32_bf16 v[100:103], v[172:175], v[188:191], v[100:103]
	v_mfma_f32_16x16x32_bf16 v[92:95], v[164:167], v[196:199], v[92:95]
	v_mfma_f32_16x16x32_bf16 v[84:87], v[172:175], v[196:199], v[84:87]
	v_mfma_f32_16x16x32_bf16 v[76:79], v[164:167], v[204:207], v[76:79]
	v_mfma_f32_16x16x32_bf16 v[68:71], v[172:175], v[204:207], v[68:71]
	v_mfma_f32_16x16x32_bf16 v[124:127], v[168:171], v[184:187], v[124:127]
	v_mfma_f32_16x16x32_bf16 v[116:119], v[176:179], v[184:187], v[116:119]
	v_mfma_f32_16x16x32_bf16 v[108:111], v[168:171], v[192:195], v[108:111]
	v_mfma_f32_16x16x32_bf16 v[100:103], v[176:179], v[192:195], v[100:103]
	v_mfma_f32_16x16x32_bf16 v[92:95], v[168:171], v[200:203], v[92:95]
	v_mfma_f32_16x16x32_bf16 v[84:87], v[176:179], v[200:203], v[84:87]
	v_mfma_f32_16x16x32_bf16 v[76:79], v[168:171], v[208:211], v[76:79]
	v_mfma_f32_16x16x32_bf16 v[68:71], v[176:179], v[208:211], v[68:71]
	s_barrier
; #define PG8_STAGE(bufoff, gbase, voff) do { _Pragma("unroll") for (int _i = 0; _i < 2; ++_i) \
;         __builtin_amdgcn_global_load_lds((const unsigned*)((const char*)(gbase) + (voff)[_i]), (PG8_LAS unsigned*)(lds + (bufoff) + ldsw + _i * 8192), 16, 0, 0); } while (0)
; #define PG8_LDA(dst, b, h) do { _Pragma("unroll") for (int m = 0; m < 4; ++m) _Pragma("unroll") for (int k = 0; k < 2; ++k) dst[m][k] = *(const PG8_LAS bf16x8*)(lds + PG8_SA(b, h) + aoff + m * 2048 + k * 1024); } while (0)
; #define PG8_WAIT_V(n) asm volatile("s_waitcnt vmcnt(" #n ")" ::: "memory")
; #define PG8_WAIT_L(n) asm volatile("s_waitcnt lgkmcnt(" #n ")" ::: "memory")
; #define PG8_BAR __builtin_amdgcn_s_barrier()
; template <class Epi, class Sched, bool ALIGN_EPI = false, bool SP2 = false>
; __device__ __forceinline__ void gemm_phase(PG8_LAS unsigned char* lds, const Gemm g, const Sched& S, const Epi& E, const int wid) {
;     ...
;         for (int t = 0; t < nt; t += 2) {
;             const bool last = (t == nt - 2);
;             const char* a1 = cA + (size_t)(t + 1) * kstep;
;             const char* a2 = last ? nA : cA + (size_t)(t + 2) * kstep; const char* b2 = last ? nB : cB + (size_t)(t + 2) * kstep;
;             const char* a3 = a2 + kstep; const char* b3 = b2 + kstep;
;             if (last && has_next) S.a_ready(nxt);
;             if constexpr (SP2) {
;             PG8_LDB(B0, 0, 0); PG8_LDB(B1, 0, 1); PG8_SCHED; PG8_LDA(At, 0, 0); PG8_STAGE(PG8_SA(1, 1), a1 + hstep, voffA);
;             PG8_WAIT_V(8); PG8_WAIT_L(0); PG8_BAR; PG8_MMA(0, 0, At, B0); PG8_MMA(0, 1, At, B1); PG8_BAR; PG8_SCHED;
;             PG8_LDA(At, 0, 1); PG8_STAGE(PG8_SB(0, 0), b2, voffB); PG8_STAGE(PG8_SB(0, 1), b2 + hstep, voffB); PG8_STAGE(PG8_SA(0, 0), a2, voffA);
;             PG8_WAIT_V(8); PG8_WAIT_L(0); PG8_BAR; PG8_MMA(1, 0, At, B0); PG8_MMA(1, 1, At, B1); PG8_BAR; PG8_SCHED;
;             PG8_LDB(B0, 1, 0); PG8_LDB(B1, 1, 1); PG8_SCHED; PG8_LDA(At, 1, 0); PG8_STAGE(PG8_SA(0, 1), a2 + hstep, voffA);
;             PG8_WAIT_V(8); PG8_WAIT_L(0); PG8_BAR; PG8_MMA(0, 0, At, B0); PG8_MMA(0, 1, At, B1); PG8_BAR; PG8_SCHED;
;             PG8_LDA(At, 1, 1); PG8_STAGE(PG8_SB(1, 0), b3, voffB); PG8_STAGE(PG8_SB(1, 1), b3 + hstep, voffB); PG8_STAGE(PG8_SA(1, 0), a3, voffA);
;             PG8_WAIT_V(8); PG8_WAIT_L(0); PG8_BAR; PG8_MMA(1, 0, At, B0); PG8_MMA(1, 1, At, B1); PG8_BAR; PG8_SCHED;
	s_setprio 0
	s_add_i32 s6, s9, s36
	v_lshl_add_u64 v[212:213], v[212:213], 0, s[20:21]
	s_mov_b32 m0, s6
	ds_read_b128 v[180:183], v151 offset:49152
	ds_read_b128 v[184:187], v151 offset:50176
	ds_read_b128 v[188:191], v151 offset:51200
	ds_read_b128 v[192:195], v151 offset:52224
	ds_read_b128 v[196:199], v151 offset:53248
	ds_read_b128 v[200:203], v151 offset:54272
	ds_read_b128 v[204:207], v151 offset:55296
	ds_read_b128 v[208:211], v151 offset:56320
	global_load_lds_dwordx4 v[212:213], off
	v_lshl_add_u64 v[212:213], v[214:215], 0, s[20:21]
	s_add_i32 m0, s6, 0x2000
	s_add_i32 s6, s33, s36
	global_load_lds_dwordx4 v[212:213], off
	v_lshl_add_u64 v[212:213], v[216:217], 0, s[20:21]
	s_mov_b32 m0, s6
	s_nop 0
	global_load_lds_dwordx4 v[212:213], off
	v_lshl_add_u64 v[212:213], v[218:219], 0, s[20:21]
	s_add_i32 m0, s6, 0x2000
	s_nop 0
	global_load_lds_dwordx4 v[212:213], off
	v_lshl_add_u64 v[212:213], v[220:221], 0, s[20:21]
	s_mov_b32 m0, s50
	s_nop 0
	global_load_lds_dwordx4 v[212:213], off
	v_lshl_add_u64 v[212:213], v[222:223], 0, s[20:21]
	s_mov_b32 m0, s51
	s_nop 0
	global_load_lds_dwordx4 v[212:213], off
	s_waitcnt vmcnt(8)
	s_waitcnt lgkmcnt(0)
	s_setprio 1
	s_barrier
	v_mfma_f32_16x16x32_bf16 v[56:59], v[142:145], v[180:183], v[56:59]
	v_mfma_f32_16x16x32_bf16 v[48:51], v[156:159], v[180:183], v[48:51]
	v_mfma_f32_16x16x32_bf16 v[40:43], v[142:145], v[188:191], v[40:43]
	v_mfma_f32_16x16x32_bf16 v[32:35], v[156:159], v[188:191], v[32:35]
	v_mfma_f32_16x16x32_bf16 v[24:27], v[142:145], v[196:199], v[24:27]
	v_mfma_f32_16x16x32_bf16 v[16:19], v[156:159], v[196:199], v[16:19]
	v_mfma_f32_16x16x32_bf16 v[8:11], v[142:145], v[204:207], v[8:11]
	v_mfma_f32_16x16x32_bf16 v[4:7], v[156:159], v[204:207], v[4:7]
	v_mfma_f32_16x16x32_bf16 v[56:59], v[152:155], v[184:187], v[56:59]
	v_mfma_f32_16x16x32_bf16 v[48:51], v[160:163], v[184:187], v[48:51]
	v_mfma_f32_16x16x32_bf16 v[40:43], v[152:155], v[192:195], v[40:43]
	v_mfma_f32_16x16x32_bf16 v[32:35], v[160:163], v[192:195], v[32:35]
	v_mfma_f32_16x16x32_bf16 v[24:27], v[152:155], v[200:203], v[24:27]
	v_mfma_f32_16x16x32_bf16 v[16:19], v[160:163], v[200:203], v[16:19]
	v_mfma_f32_16x16x32_bf16 v[8:11], v[152:155], v[208:211], v[8:11]
	v_mfma_f32_16x16x32_bf16 v[4:7], v[160:163], v[208:211], v[4:7]
	v_mfma_f32_16x16x32_bf16 v[60:63], v[164:167], v[180:183], v[60:63]
	v_mfma_f32_16x16x32_bf16 v[52:55], v[172:175], v[180:183], v[52:55]
	v_mfma_f32_16x16x32_bf16 v[44:47], v[164:167], v[188:191], v[44:47]
	v_mfma_f32_16x16x32_bf16 v[36:39], v[172:175], v[188:191], v[36:39]
	v_mfma_f32_16x16x32_bf16 v[28:31], v[164:167], v[196:199], v[28:31]
	v_mfma_f32_16x16x32_bf16 v[20:23], v[172:175], v[196:199], v[20:23]
	v_mfma_f32_16x16x32_bf16 v[12:15], v[164:167], v[204:207], v[12:15]
	v_mfma_f32_16x16x32_bf16 v[0:3], v[172:175], v[204:207], v[0:3]
	v_mfma_f32_16x16x32_bf16 v[60:63], v[168:171], v[184:187], v[60:63]
	v_mfma_f32_16x16x32_bf16 v[52:55], v[176:179], v[184:187], v[52:55]
	v_mfma_f32_16x16x32_bf16 v[44:47], v[168:171], v[192:195], v[44:47]
	v_mfma_f32_16x16x32_bf16 v[36:39], v[176:179], v[192:195], v[36:39]
	v_mfma_f32_16x16x32_bf16 v[28:31], v[168:171], v[200:203], v[28:31]
	v_mfma_f32_16x16x32_bf16 v[20:23], v[176:179], v[200:203], v[20:23]
	v_mfma_f32_16x16x32_bf16 v[12:15], v[168:171], v[208:211], v[12:15]
	v_mfma_f32_16x16x32_bf16 v[0:3], v[176:179], v[208:211], v[0:3]
	s_barrier
	s_setprio 0
	s_add_u32 s4, s4, 0x100
	s_addc_u32 s5, s5, 0
	s_add_u32 s0, s0, 0x100
	s_addc_u32 s1, s1, 0
	s_cmp_ge_i32 s8, s52
	s_mov_b32 s6, s8
	s_cbranch_scc1 .LBB0_1496
.LBB0_1495:
	ds_read_b128 v[142:145], v149
	ds_read_b128 v[152:155], v149 offset:1024
	ds_read_b128 v[156:159], v149 offset:2048
	ds_read_b128 v[160:163], v149 offset:3072
	ds_read_b128 v[164:167], v150
	ds_read_b128 v[168:171], v150 offset:1024
	ds_read_b128 v[172:175], v150 offset:2048
	ds_read_b128 v[176:179], v150 offset:3072
	s_add_i32 s8, s6, 2
	s_add_u32 s9, s4, 0x80
	s_addc_u32 s7, s5, 0
	s_cmp_eq_u32 s55, s6
	s_cselect_b32 s6, s26, s9
	s_cselect_b32 s7, s27, s7
	s_cselect_b32 s65, s29, s1
	s_cselect_b32 s64, s28, s0
	v_lshl_add_u64 v[212:213], s[4:5], 0, v[136:137]
	s_add_i32 m0, s44, 0xc000
	ds_read_b128 v[180:183], v151
	ds_read_b128 v[184:187], v151 offset:1024
	ds_read_b128 v[188:191], v151 offset:2048
	ds_read_b128 v[192:195], v151 offset:3072
	ds_read_b128 v[196:199], v151 offset:4096
	ds_read_b128 v[200:203], v151 offset:5120
	ds_read_b128 v[204:207], v151 offset:6144
	ds_read_b128 v[208:211], v151 offset:7168
	global_load_lds_dwordx4 v[212:213], off
	v_lshl_add_u64 v[212:213], s[4:5], 0, v[138:139]
	s_add_i32 m0, s44, 0xe000
	s_nop 0
	global_load_lds_dwordx4 v[212:213], off
	s_waitcnt vmcnt(8)
	s_waitcnt lgkmcnt(0)
	s_setprio 1
	s_barrier
; #define PG8_STAGE(bufoff, gbase, voff) do { _Pragma("unroll") for (int _i = 0; _i < 2; ++_i) \
;         __builtin_amdgcn_global_load_lds((const unsigned*)((const char*)(gbase) + (voff)[_i]), (PG8_LAS unsigned*)(lds + (bufoff) + ldsw + _i * 8192), 16, 0, 0); } while (0)
; #define PG8_LDA(dst, b, h) do { _Pragma("unroll") for (int m = 0; m < 4; ++m) _Pragma("unroll") for (int k = 0; k < 2; ++k) dst[m][k] = *(const PG8_LAS bf16x8*)(lds + PG8_SA(b, h) + aoff + m * 2048 + k * 1024); } while (0)
; #define PG8_WAIT_V(n) asm volatile("s_waitcnt vmcnt(" #n ")" ::: "memory")
; #define PG8_WAIT_L(n) asm volatile("s_waitcnt lgkmcnt(" #n ")" ::: "memory")
; #define PG8_BAR __builtin_amdgcn_s_barrier()
; template <class Epi, class Sched, bool ALIGN_EPI = false, bool SP2 = false>
; __device__ __forceinline__ void gemm_phase(PG8_LAS unsigned char* lds, const Gemm g, const Sched& S, const Epi& E, const int wid) {
;     ...
;         for (int t = 0; t < nt; t += 2) {
;             const bool last = (t == nt - 2);
;             const char* a1 = cA + (size_t)(t + 1) * kstep;
;             const char* a2 = last ? nA : cA + (size_t)(t + 2) * kstep; const char* b2 = last ? nB : cB + (size_t)(t + 2) * kstep;
;             const char* a3 = a2 + kstep; const char* b3 = b2 + kstep;
;             if (last && has_next) S.a_ready(nxt);
;             if constexpr (SP2) {
;             PG8_LDB(B0, 0, 0); PG8_LDB(B1, 0, 1); PG8_SCHED; PG8_LDA(At, 0, 0); PG8_STAGE(PG8_SA(1, 1), a1 + hstep, voffA);
;             PG8_WAIT_V(8); PG8_WAIT_L(0); PG8_BAR; PG8_MMA(0, 0, At, B0); PG8_MMA(0, 1, At, B1); PG8_BAR; PG8_SCHED;
;             PG8_LDA(At, 0, 1); PG8_STAGE(PG8_SB(0, 0), b2, voffB); PG8_STAGE(PG8_SB(0, 1), b2 + hstep, voffB); PG8_STAGE(PG8_SA(0, 0), a2, voffA);
;             PG8_WAIT_V(8); PG8_WAIT_L(0); PG8_BAR; PG8_MMA(1, 0, At, B0); PG8_MMA(1, 1, At, B1); PG8_BAR; PG8_SCHED;
;             PG8_LDB(B0, 1, 0); PG8_LDB(B1, 1, 1); PG8_SCHED; PG8_LDA(At, 1, 0); PG8_STAGE(PG8_SA(0, 1), a2 + hstep, voffA);
;             PG8_WAIT_V(8); PG8_WAIT_L(0); PG8_BAR; PG8_MMA(0, 0, At, B0); PG8_MMA(0, 1, At, B1); PG8_BAR; PG8_SCHED;
;             PG8_LDA(At, 1, 1); PG8_STAGE(PG8_SB(1, 0), b3, voffB); PG8_STAGE(PG8_SB(1, 1), b3 + hstep, voffB); PG8_STAGE(PG8_SA(1, 0), a3, voffA);
;             PG8_WAIT_V(8); PG8_WAIT_L(0); PG8_BAR; PG8_MMA(1, 0, At, B0); PG8_MMA(1, 1, At, B1); PG8_BAR; PG8_SCHED;
	v_mfma_f32_16x16x32_bf16 v[120:123], v[142:145], v[180:183], v[120:123]
	v_mfma_f32_16x16x32_bf16 v[112:115], v[156:159], v[180:183], v[112:115]
	v_mfma_f32_16x16x32_bf16 v[104:107], v[142:145], v[188:191], v[104:107]
	v_mfma_f32_16x16x32_bf16 v[96:99], v[156:159], v[188:191], v[96:99]
	v_mfma_f32_16x16x32_bf16 v[88:91], v[142:145], v[196:199], v[88:91]
	v_mfma_f32_16x16x32_bf16 v[80:83], v[156:159], v[196:199], v[80:83]
	v_mfma_f32_16x16x32_bf16 v[72:75], v[142:145], v[204:207], v[72:75]
	v_mfma_f32_16x16x32_bf16 v[64:67], v[156:159], v[204:207], v[64:67]
	v_mfma_f32_16x16x32_bf16 v[120:123], v[152:155], v[184:187], v[120:123]
	v_mfma_f32_16x16x32_bf16 v[112:115], v[160:163], v[184:187], v[112:115]
	v_mfma_f32_16x16x32_bf16 v[104:107], v[152:155], v[192:195], v[104:107]
	v_mfma_f32_16x16x32_bf16 v[96:99], v[160:163], v[192:195], v[96:99]
	v_mfma_f32_16x16x32_bf16 v[88:91], v[152:155], v[200:203], v[88:91]
	v_mfma_f32_16x16x32_bf16 v[80:83], v[160:163], v[200:203], v[80:83]
	v_mfma_f32_16x16x32_bf16 v[72:75], v[152:155], v[208:211], v[72:75]
	v_mfma_f32_16x16x32_bf16 v[64:67], v[160:163], v[208:211], v[64:67]
	v_mfma_f32_16x16x32_bf16 v[124:127], v[164:167], v[180:183], v[124:127]
	v_mfma_f32_16x16x32_bf16 v[116:119], v[172:175], v[180:183], v[116:119]
	v_mfma_f32_16x16x32_bf16 v[108:111], v[164:167], v[188:191], v[108:111]
	v_mfma_f32_16x16x32_bf16 v[100:103], v[172:175], v[188:191], v[100:103]
	v_mfma_f32_16x16x32_bf16 v[92:95], v[164:167], v[196:199], v[92:95]
	v_mfma_f32_16x16x32_bf16 v[84:87], v[172:175], v[196:199], v[84:87]
	v_mfma_f32_16x16x32_bf16 v[76:79], v[164:167], v[204:207], v[76:79]
	v_mfma_f32_16x16x32_bf16 v[68:71], v[172:175], v[204:207], v[68:71]
	v_mfma_f32_16x16x32_bf16 v[124:127], v[168:171], v[184:187], v[124:127]
	v_mfma_f32_16x16x32_bf16 v[116:119], v[176:179], v[184:187], v[116:119]
	v_mfma_f32_16x16x32_bf16 v[108:111], v[168:171], v[192:195], v[108:111]
	v_mfma_f32_16x16x32_bf16 v[100:103], v[176:179], v[192:195], v[100:103]
	v_mfma_f32_16x16x32_bf16 v[92:95], v[168:171], v[200:203], v[92:95]
	v_mfma_f32_16x16x32_bf16 v[84:87], v[176:179], v[200:203], v[84:87]
	v_mfma_f32_16x16x32_bf16 v[76:79], v[168:171], v[208:211], v[76:79]
	v_mfma_f32_16x16x32_bf16 v[68:71], v[176:179], v[208:211], v[68:71]
	s_barrier
	s_setprio 0
	s_add_i32 s9, s57, s36
	v_lshl_add_u64 v[212:213], s[64:65], 0, v[132:133]
	s_mov_b32 m0, s9
	ds_read_b128 v[180:183], v151 offset:16384
	ds_read_b128 v[184:187], v151 offset:17408
	ds_read_b128 v[188:191], v151 offset:18432
	ds_read_b128 v[192:195], v151 offset:19456
	ds_read_b128 v[196:199], v151 offset:20480
	ds_read_b128 v[200:203], v151 offset:21504
	ds_read_b128 v[204:207], v151 offset:22528
	ds_read_b128 v[208:211], v151 offset:23552
	global_load_lds_dwordx4 v[212:213], off
	s_add_i32 m0, s9, 0x2000
	v_lshl_add_u64 v[214:215], s[64:65], 0, v[128:129]
	s_add_u32 s64, s64, s12
	s_addc_u32 s65, s65, s13
	s_add_i32 s9, s58, s36
	global_load_lds_dwordx4 v[214:215], off
	v_lshl_add_u64 v[216:217], s[64:65], 0, v[132:133]
	s_mov_b32 m0, s9
	v_lshl_add_u64 v[218:219], s[64:65], 0, v[128:129]
	global_load_lds_dwordx4 v[216:217], off
	s_add_i32 m0, s9, 0x2000
	v_lshl_add_u64 v[220:221], s[6:7], 0, v[134:135]
	global_load_lds_dwordx4 v[218:219], off
	s_mov_b32 m0, s44
	v_lshl_add_u64 v[222:223], s[6:7], 0, v[130:131]
	global_load_lds_dwordx4 v[220:221], off
	s_mov_b32 m0, s45
	s_nop 0
	global_load_lds_dwordx4 v[222:223], off
	s_waitcnt vmcnt(8)
	s_waitcnt lgkmcnt(0)
	s_setprio 1
	s_barrier
	v_mfma_f32_16x16x32_bf16 v[56:59], v[142:145], v[180:183], v[56:59]
	v_mfma_f32_16x16x32_bf16 v[48:51], v[156:159], v[180:183], v[48:51]
	v_mfma_f32_16x16x32_bf16 v[40:43], v[142:145], v[188:191], v[40:43]
	v_mfma_f32_16x16x32_bf16 v[32:35], v[156:159], v[188:191], v[32:35]
	v_mfma_f32_16x16x32_bf16 v[24:27], v[142:145], v[196:199], v[24:27]
	v_mfma_f32_16x16x32_bf16 v[16:19], v[156:159], v[196:199], v[16:19]
	v_mfma_f32_16x16x32_bf16 v[8:11], v[142:145], v[204:207], v[8:11]
	v_mfma_f32_16x16x32_bf16 v[4:7], v[156:159], v[204:207], v[4:7]
	v_mfma_f32_16x16x32_bf16 v[56:59], v[152:155], v[184:187], v[56:59]
	v_mfma_f32_16x16x32_bf16 v[48:51], v[160:163], v[184:187], v[48:51]
	v_mfma_f32_16x16x32_bf16 v[40:43], v[152:155], v[192:195], v[40:43]
	v_mfma_f32_16x16x32_bf16 v[32:35], v[160:163], v[192:195], v[32:35]
	v_mfma_f32_16x16x32_bf16 v[24:27], v[152:155], v[200:203], v[24:27]
	v_mfma_f32_16x16x32_bf16 v[16:19], v[160:163], v[200:203], v[16:19]
	v_mfma_f32_16x16x32_bf16 v[8:11], v[152:155], v[208:211], v[8:11]
	v_mfma_f32_16x16x32_bf16 v[4:7], v[160:163], v[208:211], v[4:7]
	v_mfma_f32_16x16x32_bf16 v[60:63], v[164:167], v[180:183], v[60:63]
	v_mfma_f32_16x16x32_bf16 v[52:55], v[172:175], v[180:183], v[52:55]
	v_mfma_f32_16x16x32_bf16 v[44:47], v[164:167], v[188:191], v[44:47]
	v_mfma_f32_16x16x32_bf16 v[36:39], v[172:175], v[188:191], v[36:39]
	v_mfma_f32_16x16x32_bf16 v[28:31], v[164:167], v[196:199], v[28:31]
	v_mfma_f32_16x16x32_bf16 v[20:23], v[172:175], v[196:199], v[20:23]
	v_mfma_f32_16x16x32_bf16 v[12:15], v[164:167], v[204:207], v[12:15]
	v_mfma_f32_16x16x32_bf16 v[0:3], v[172:175], v[204:207], v[0:3]
	v_mfma_f32_16x16x32_bf16 v[60:63], v[168:171], v[184:187], v[60:63]
	v_mfma_f32_16x16x32_bf16 v[52:55], v[176:179], v[184:187], v[52:55]
	v_mfma_f32_16x16x32_bf16 v[44:47], v[168:171], v[192:195], v[44:47]
	v_mfma_f32_16x16x32_bf16 v[36:39], v[176:179], v[192:195], v[36:39]
	v_mfma_f32_16x16x32_bf16 v[28:31], v[168:171], v[200:203], v[28:31]
	v_mfma_f32_16x16x32_bf16 v[20:23], v[176:179], v[200:203], v[20:23]
	v_mfma_f32_16x16x32_bf16 v[12:15], v[168:171], v[208:211], v[12:15]
	v_mfma_f32_16x16x32_bf16 v[0:3], v[176:179], v[208:211], v[0:3]
	s_barrier
; #define PG8_STAGE(bufoff, gbase, voff) do { _Pragma("unroll") for (int _i = 0; _i < 2; ++_i) \
;         __builtin_amdgcn_global_load_lds((const unsigned*)((const char*)(gbase) + (voff)[_i]), (PG8_LAS unsigned*)(lds + (bufoff) + ldsw + _i * 8192), 16, 0, 0); } while (0)
; #define PG8_LDA(dst, b, h) do { _Pragma("unroll") for (int m = 0; m < 4; ++m) _Pragma("unroll") for (int k = 0; k < 2; ++k) dst[m][k] = *(const PG8_LAS bf16x8*)(lds + PG8_SA(b, h) + aoff + m * 2048 + k * 1024); } while (0)
; #define PG8_WAIT_V(n) asm volatile("s_waitcnt vmcnt(" #n ")" ::: "memory")
; #define PG8_WAIT_L(n) asm volatile("s_waitcnt lgkmcnt(" #n ")" ::: "memory")
; #define PG8_BAR __builtin_amdgcn_s_barrier()
; template <class Epi, class Sched, bool ALIGN_EPI = false, bool SP2 = false>
; __device__ __forceinline__ void gemm_phase(PG8_LAS unsigned char* lds, const Gemm g, const Sched& S, const Epi& E, const int wid) {
;     ...
;         for (int t = 0; t < nt; t += 2) {
;             const bool last = (t == nt - 2);
;             const char* a1 = cA + (size_t)(t + 1) * kstep;
;             const char* a2 = last ? nA : cA + (size_t)(t + 2) * kstep; const char* b2 = last ? nB : cB + (size_t)(t + 2) * kstep;
;             const char* a3 = a2 + kstep; const char* b3 = b2 + kstep;
;             if (last && has_next) S.a_ready(nxt);
;             if constexpr (SP2) {
;             PG8_LDB(B0, 0, 0); PG8_LDB(B1, 0, 1); PG8_SCHED; PG8_LDA(At, 0, 0); PG8_STAGE(PG8_SA(1, 1), a1 + hstep, voffA);
;             PG8_WAIT_V(8); PG8_WAIT_L(0); PG8_BAR; PG8_MMA(0, 0, At, B0); PG8_MMA(0, 1, At, B1); PG8_BAR; PG8_SCHED;
;             PG8_LDA(At, 0, 1); PG8_STAGE(PG8_SB(0, 0), b2, voffB); PG8_STAGE(PG8_SB(0, 1), b2 + hstep, voffB); PG8_STAGE(PG8_SA(0, 0), a2, voffA);
;             PG8_WAIT_V(8); PG8_WAIT_L(0); PG8_BAR; PG8_MMA(1, 0, At, B0); PG8_MMA(1, 1, At, B1); PG8_BAR; PG8_SCHED;
;             PG8_LDB(B0, 1, 0); PG8_LDB(B1, 1, 1); PG8_SCHED; PG8_LDA(At, 1, 0); PG8_STAGE(PG8_SA(0, 1), a2 + hstep, voffA);
;             PG8_WAIT_V(8); PG8_WAIT_L(0); PG8_BAR; PG8_MMA(0, 0, At, B0); PG8_MMA(0, 1, At, B1); PG8_BAR; PG8_SCHED;
;             PG8_LDA(At, 1, 1); PG8_STAGE(PG8_SB(1, 0), b3, voffB); PG8_STAGE(PG8_SB(1, 1), b3 + hstep, voffB); PG8_STAGE(PG8_SA(1, 0), a3, voffA);
;             PG8_WAIT_V(8); PG8_WAIT_L(0); PG8_BAR; PG8_MMA(1, 0, At, B0); PG8_MMA(1, 1, At, B1); PG8_BAR; PG8_SCHED;
	s_setprio 0
	s_add_i32 s9, 0, 0x18000
	s_add_i32 s33, 0, 0x1c000
	v_add_u32_e32 v160, s9, v148
	v_add_u32_e32 v176, s33, v148
	ds_read_b128 v[142:145], v160
	ds_read_b128 v[152:155], v160 offset:1024
	ds_read_b128 v[156:159], v160 offset:2048
	ds_read_b128 v[160:163], v160 offset:3072
	ds_read_b128 v[164:167], v176
	ds_read_b128 v[168:171], v176 offset:1024
	ds_read_b128 v[172:175], v176 offset:2048
	ds_read_b128 v[176:179], v176 offset:3072
	s_add_u32 s6, s6, s12
	s_addc_u32 s7, s7, s13
	s_mov_b32 m0, s46
	v_lshl_add_u64 v[224:225], s[6:7], 0, v[134:135]
	ds_read_b128 v[180:183], v151 offset:32768
	ds_read_b128 v[184:187], v151 offset:33792
	ds_read_b128 v[188:191], v151 offset:34816
	ds_read_b128 v[192:195], v151 offset:35840
	ds_read_b128 v[196:199], v151 offset:36864
	ds_read_b128 v[200:203], v151 offset:37888
	ds_read_b128 v[204:207], v151 offset:38912
	ds_read_b128 v[208:211], v151 offset:39936
	global_load_lds_dwordx4 v[224:225], off
	v_lshl_add_u64 v[224:225], s[6:7], 0, v[130:131]
	s_mov_b32 m0, s47
	s_nop 0
	global_load_lds_dwordx4 v[224:225], off
	s_waitcnt vmcnt(8)
	s_waitcnt lgkmcnt(0)
	s_setprio 1
	s_barrier
	v_mfma_f32_16x16x32_bf16 v[120:123], v[142:145], v[180:183], v[120:123]
	v_mfma_f32_16x16x32_bf16 v[112:115], v[156:159], v[180:183], v[112:115]
	v_mfma_f32_16x16x32_bf16 v[104:107], v[142:145], v[188:191], v[104:107]
	v_mfma_f32_16x16x32_bf16 v[96:99], v[156:159], v[188:191], v[96:99]
	v_mfma_f32_16x16x32_bf16 v[88:91], v[142:145], v[196:199], v[88:91]
	v_mfma_f32_16x16x32_bf16 v[80:83], v[156:159], v[196:199], v[80:83]
	v_mfma_f32_16x16x32_bf16 v[72:75], v[142:145], v[204:207], v[72:75]
	v_mfma_f32_16x16x32_bf16 v[64:67], v[156:159], v[204:207], v[64:67]
	v_mfma_f32_16x16x32_bf16 v[120:123], v[152:155], v[184:187], v[120:123]
	v_mfma_f32_16x16x32_bf16 v[112:115], v[160:163], v[184:187], v[112:115]
	v_mfma_f32_16x16x32_bf16 v[104:107], v[152:155], v[192:195], v[104:107]
	v_mfma_f32_16x16x32_bf16 v[96:99], v[160:163], v[192:195], v[96:99]
	v_mfma_f32_16x16x32_bf16 v[88:91], v[152:155], v[200:203], v[88:91]
	v_mfma_f32_16x16x32_bf16 v[80:83], v[160:163], v[200:203], v[80:83]
	v_mfma_f32_16x16x32_bf16 v[72:75], v[152:155], v[208:211], v[72:75]
	v_mfma_f32_16x16x32_bf16 v[64:67], v[160:163], v[208:211], v[64:67]
	v_mfma_f32_16x16x32_bf16 v[124:127], v[164:167], v[180:183], v[124:127]
	v_mfma_f32_16x16x32_bf16 v[116:119], v[172:175], v[180:183], v[116:119]
	v_mfma_f32_16x16x32_bf16 v[108:111], v[164:167], v[188:191], v[108:111]
	v_mfma_f32_16x16x32_bf16 v[100:103], v[172:175], v[188:191], v[100:103]
	v_mfma_f32_16x16x32_bf16 v[92:95], v[164:167], v[196:199], v[92:95]
	v_mfma_f32_16x16x32_bf16 v[84:87], v[172:175], v[196:199], v[84:87]
	v_mfma_f32_16x16x32_bf16 v[76:79], v[164:167], v[204:207], v[76:79]
	v_mfma_f32_16x16x32_bf16 v[68:71], v[172:175], v[204:207], v[68:71]
	v_mfma_f32_16x16x32_bf16 v[124:127], v[168:171], v[184:187], v[124:127]
	v_mfma_f32_16x16x32_bf16 v[116:119], v[176:179], v[184:187], v[116:119]
	v_mfma_f32_16x16x32_bf16 v[108:111], v[168:171], v[192:195], v[108:111]
	v_mfma_f32_16x16x32_bf16 v[100:103], v[176:179], v[192:195], v[100:103]
	v_mfma_f32_16x16x32_bf16 v[92:95], v[168:171], v[200:203], v[92:95]
	v_mfma_f32_16x16x32_bf16 v[84:87], v[176:179], v[200:203], v[84:87]
	v_mfma_f32_16x16x32_bf16 v[76:79], v[168:171], v[208:211], v[76:79]
	v_mfma_f32_16x16x32_bf16 v[68:71], v[176:179], v[208:211], v[68:71]
	s_barrier
	s_setprio 0
	s_add_i32 s6, s9, s36
	v_lshl_add_u64 v[212:213], v[212:213], 0, s[20:21]
	s_mov_b32 m0, s6
	ds_read_b128 v[180:183], v151 offset:49152
	ds_read_b128 v[184:187], v151 offset:50176
	ds_read_b128 v[188:191], v151 offset:51200
	ds_read_b128 v[192:195], v151 offset:52224
	ds_read_b128 v[196:199], v151 offset:53248
	ds_read_b128 v[200:203], v151 offset:54272
	ds_read_b128 v[204:207], v151 offset:55296
	ds_read_b128 v[208:211], v151 offset:56320
	global_load_lds_dwordx4 v[212:213], off
	v_lshl_add_u64 v[212:213], v[214:215], 0, s[20:21]
	s_add_i32 m0, s6, 0x2000
	s_add_i32 s6, s33, s36
	global_load_lds_dwordx4 v[212:213], off
	v_lshl_add_u64 v[212:213], v[216:217], 0, s[20:21]
	s_mov_b32 m0, s6
	s_nop 0
	global_load_lds_dwordx4 v[212:213], off
	v_lshl_add_u64 v[212:213], v[218:219], 0, s[20:21]
	s_add_i32 m0, s6, 0x2000
	s_nop 0
	global_load_lds_dwordx4 v[212:213], off
	v_lshl_add_u64 v[212:213], v[220:221], 0, s[20:21]
	s_mov_b32 m0, s50
	s_nop 0
	global_load_lds_dwordx4 v[212:213], off
	v_lshl_add_u64 v[212:213], v[222:223], 0, s[20:21]
	s_mov_b32 m0, s51
	s_nop 0
	global_load_lds_dwordx4 v[212:213], off
	s_waitcnt vmcnt(8)
	s_waitcnt lgkmcnt(0)
	s_setprio 1
	s_barrier
	v_mfma_f32_16x16x32_bf16 v[56:59], v[142:145], v[180:183], v[56:59]
	v_mfma_f32_16x16x32_bf16 v[48:51], v[156:159], v[180:183], v[48:51]
	v_mfma_f32_16x16x32_bf16 v[40:43], v[142:145], v[188:191], v[40:43]
	v_mfma_f32_16x16x32_bf16 v[32:35], v[156:159], v[188:191], v[32:35]
	v_mfma_f32_16x16x32_bf16 v[24:27], v[142:145], v[196:199], v[24:27]
	v_mfma_f32_16x16x32_bf16 v[16:19], v[156:159], v[196:199], v[16:19]
	v_mfma_f32_16x16x32_bf16 v[8:11], v[142:145], v[204:207], v[8:11]
	v_mfma_f32_16x16x32_bf16 v[4:7], v[156:159], v[204:207], v[4:7]
	v_mfma_f32_16x16x32_bf16 v[56:59], v[152:155], v[184:187], v[56:59]
	v_mfma_f32_16x16x32_bf16 v[48:51], v[160:163], v[184:187], v[48:51]
	v_mfma_f32_16x16x32_bf16 v[40:43], v[152:155], v[192:195], v[40:43]
	v_mfma_f32_16x16x32_bf16 v[32:35], v[160:163], v[192:195], v[32:35]
	v_mfma_f32_16x16x32_bf16 v[24:27], v[152:155], v[200:203], v[24:27]
	v_mfma_f32_16x16x32_bf16 v[16:19], v[160:163], v[200:203], v[16:19]
	v_mfma_f32_16x16x32_bf16 v[8:11], v[152:155], v[208:211], v[8:11]
	v_mfma_f32_16x16x32_bf16 v[4:7], v[160:163], v[208:211], v[4:7]
	v_mfma_f32_16x16x32_bf16 v[60:63], v[164:167], v[180:183], v[60:63]
	v_mfma_f32_16x16x32_bf16 v[52:55], v[172:175], v[180:183], v[52:55]
	v_mfma_f32_16x16x32_bf16 v[44:47], v[164:167], v[188:191], v[44:47]
	v_mfma_f32_16x16x32_bf16 v[36:39], v[172:175], v[188:191], v[36:39]
	v_mfma_f32_16x16x32_bf16 v[28:31], v[164:167], v[196:199], v[28:31]
	v_mfma_f32_16x16x32_bf16 v[20:23], v[172:175], v[196:199], v[20:23]
	v_mfma_f32_16x16x32_bf16 v[12:15], v[164:167], v[204:207], v[12:15]
	v_mfma_f32_16x16x32_bf16 v[0:3], v[172:175], v[204:207], v[0:3]
	v_mfma_f32_16x16x32_bf16 v[60:63], v[168:171], v[184:187], v[60:63]
	v_mfma_f32_16x16x32_bf16 v[52:55], v[176:179], v[184:187], v[52:55]
	v_mfma_f32_16x16x32_bf16 v[44:47], v[168:171], v[192:195], v[44:47]
	v_mfma_f32_16x16x32_bf16 v[36:39], v[176:179], v[192:195], v[36:39]
	v_mfma_f32_16x16x32_bf16 v[28:31], v[168:171], v[200:203], v[28:31]
	v_mfma_f32_16x16x32_bf16 v[20:23], v[176:179], v[200:203], v[20:23]
	v_mfma_f32_16x16x32_bf16 v[12:15], v[168:171], v[208:211], v[12:15]
	v_mfma_f32_16x16x32_bf16 v[0:3], v[176:179], v[208:211], v[0:3]
	s_barrier
	s_setprio 0
	s_add_u32 s4, s4, 0x100
	s_addc_u32 s5, s5, 0
	s_add_u32 s0, s0, 0x100
	s_addc_u32 s1, s1, 0
	s_cmp_ge_i32 s8, s52
	s_mov_b32 s6, s8
	s_cbranch_scc0 .LBB0_1495

; #define PG8_WAIT_V(n) asm volatile("s_waitcnt vmcnt(" #n ")" ::: "memory")
; #define PG8_BAR __builtin_amdgcn_s_barrier()
; template <class Epi, class Sched, bool ALIGN_EPI = false, bool SP2 = false>
; __device__ __forceinline__ void gemm_phase(PG8_LAS unsigned char* lds, const Gemm g, const Sched& S, const Epi& E, const int wid) {
;     ...
;         const bool has_next = S.next(ui + 1, nxt);
;         const char* nA = has_next ? (const char*)g.A + (size_t)nxt.pm * tstep : cA; const char* nB = has_next ? (const char*)g.Bt + (size_t)nxt.pn * tstep : cB;
;         for (int t = 0; t < nt; t += 2) {
;             const bool last = (t == nt - 2);
;             const char* a1 = cA + (size_t)(t + 1) * kstep;
;             const char* a2 = last ? nA : cA + (size_t)(t + 2) * kstep; const char* b2 = last ? nB : cB + (size_t)(t + 2) * kstep;
;             const char* a3 = a2 + kstep; const char* b3 = b2 + kstep;
;             if (last && has_next) S.a_ready(nxt);
;             if constexpr (SP2) {
;             PG8_LDB(B0, 0, 0); PG8_LDB(B1, 0, 1); PG8_SCHED; PG8_LDA(At, 0, 0); PG8_STAGE(PG8_SA(1, 1), a1 + hstep, voffA);
;             PG8_WAIT_V(8); PG8_WAIT_L(0); PG8_BAR; PG8_MMA(0, 0, At, B0); PG8_MMA(0, 1, At, B1); PG8_BAR; PG8_SCHED;
;             PG8_LDA(At, 0, 1); PG8_STAGE(PG8_SB(0, 0), b2, voffB); PG8_STAGE(PG8_SB(0, 1), b2 + hstep, voffB); PG8_STAGE(PG8_SA(0, 0), a2, voffA);
;             PG8_WAIT_V(8); PG8_WAIT_L(0); PG8_BAR; PG8_MMA(1, 0, At, B0); PG8_MMA(1, 1, At, B1); PG8_BAR; PG8_SCHED;
;             PG8_LDB(B0, 1, 0); PG8_LDB(B1, 1, 1); PG8_SCHED; PG8_LDA(At, 1, 0); PG8_STAGE(PG8_SA(0, 1), a2 + hstep, voffA);
;             PG8_WAIT_V(8); PG8_WAIT_L(0); PG8_BAR; PG8_MMA(0, 0, At, B0); PG8_MMA(0, 1, At, B1); PG8_BAR; PG8_SCHED;
;             PG8_LDA(At, 1, 1); PG8_STAGE(PG8_SB(1, 0), b3, voffB); PG8_STAGE(PG8_SB(1, 1), b3 + hstep, voffB); PG8_STAGE(PG8_SA(1, 0), a3, voffA);
;             PG8_WAIT_V(8); PG8_WAIT_L(0); PG8_BAR; PG8_MMA(1, 0, At, B0); PG8_MMA(1, 1, At, B1); PG8_BAR; PG8_SCHED;
;             } else {
;             PG8_LDB(B0, 0, 0); PG8_SCHED; PG8_LDA(At, 0, 0); PG8_STAGE(PG8_SA(1, 1), a1 + hstep, voffA);
;             PG8_WAIT_L(8); PG8_BAR; PG8_WAIT_L(0); PG8_MMA(0, 0, At, B0); PG8_BAR; PG8_SCHED;
;             PG8_LDB(B1, 0, 1); PG8_STAGE(PG8_SB(0, 0), b2, voffB);
;             PG8_BAR; PG8_WAIT_L(0); PG8_MMA(0, 1, At, B1); PG8_BAR;
.LBB0_1572:
	s_andn2_b64 vcc, exec, s[18:19]
	s_cbranch_vccnz .Lz_FFN2
	s_add_u32 s40, s40, 0x80
	s_addc_u32 s41, s41, 0
	s_add_u32 s73, s42, 0x100
	s_addc_u32 s74, s43, 0
	s_mov_b32 s42, 0
	ds_read_b128 v[146:149], v143
	ds_read_b128 v[150:153], v143 offset:1024
	ds_read_b128 v[154:157], v143 offset:2048
	ds_read_b128 v[158:161], v143 offset:3072
	ds_read_b128 v[162:165], v144
	ds_read_b128 v[166:169], v144 offset:1024
	ds_read_b128 v[170:173], v144 offset:2048
	ds_read_b128 v[174:177], v144 offset:3072
	s_add_i32 s75, s42, 2
	s_add_u32 s33, s40, 0x80
	s_addc_u32 s43, s41, 0
	s_cmp_eq_u32 s65, s42
	s_cselect_b32 s42, s2, s33
	s_cselect_b32 s43, s3, s43
	s_cselect_b32 s77, s39, s74
	s_cselect_b32 s76, s38, s73
	v_lshl_add_u64 v[138:139], s[40:41], 0, v[132:133]
	s_add_i32 m0, s55, 0xc000
	ds_read_b128 v[178:181], v145
	ds_read_b128 v[182:185], v145 offset:1024
	ds_read_b128 v[186:189], v145 offset:2048
	ds_read_b128 v[190:193], v145 offset:3072
	ds_read_b128 v[194:197], v145 offset:4096
	ds_read_b128 v[198:201], v145 offset:5120
	ds_read_b128 v[202:205], v145 offset:6144
	ds_read_b128 v[206:209], v145 offset:7168
	global_load_lds_dwordx4 v[138:139], off
	v_lshl_add_u64 v[138:139], s[40:41], 0, v[134:135]
	s_add_i32 m0, s55, 0xe000
	s_nop 0
	global_load_lds_dwordx4 v[138:139], off
	s_waitcnt vmcnt(8)
	s_waitcnt lgkmcnt(0)
	s_setprio 1
	s_barrier
	v_mfma_f32_16x16x32_bf16 v[124:127], v[146:149], v[178:181], 0
	v_mfma_f32_16x16x32_bf16 v[120:123], v[154:157], v[178:181], 0
	v_mfma_f32_16x16x32_bf16 v[108:111], v[146:149], v[186:189], 0
	v_mfma_f32_16x16x32_bf16 v[104:107], v[154:157], v[186:189], 0
	v_mfma_f32_16x16x32_bf16 v[92:95], v[146:149], v[194:197], 0
	v_mfma_f32_16x16x32_bf16 v[88:91], v[154:157], v[194:197], 0
	v_mfma_f32_16x16x32_bf16 v[76:79], v[146:149], v[202:205], 0
	v_mfma_f32_16x16x32_bf16 v[72:75], v[154:157], v[202:205], 0
	v_mfma_f32_16x16x32_bf16 v[124:127], v[150:153], v[182:185], v[124:127]
	v_mfma_f32_16x16x32_bf16 v[120:123], v[158:161], v[182:185], v[120:123]
	v_mfma_f32_16x16x32_bf16 v[108:111], v[150:153], v[190:193], v[108:111]
	v_mfma_f32_16x16x32_bf16 v[104:107], v[158:161], v[190:193], v[104:107]
	v_mfma_f32_16x16x32_bf16 v[92:95], v[150:153], v[198:201], v[92:95]
	v_mfma_f32_16x16x32_bf16 v[88:91], v[158:161], v[198:201], v[88:91]
	v_mfma_f32_16x16x32_bf16 v[76:79], v[150:153], v[206:209], v[76:79]
	v_mfma_f32_16x16x32_bf16 v[72:75], v[158:161], v[206:209], v[72:75]
	v_mfma_f32_16x16x32_bf16 v[116:119], v[162:165], v[178:181], 0
	v_mfma_f32_16x16x32_bf16 v[112:115], v[170:173], v[178:181], 0
	v_mfma_f32_16x16x32_bf16 v[100:103], v[162:165], v[186:189], 0
	v_mfma_f32_16x16x32_bf16 v[96:99], v[170:173], v[186:189], 0
	v_mfma_f32_16x16x32_bf16 v[84:87], v[162:165], v[194:197], 0
	v_mfma_f32_16x16x32_bf16 v[80:83], v[170:173], v[194:197], 0
	v_mfma_f32_16x16x32_bf16 v[68:71], v[162:165], v[202:205], 0
	v_mfma_f32_16x16x32_bf16 v[64:67], v[170:173], v[202:205], 0
	v_mfma_f32_16x16x32_bf16 v[116:119], v[166:169], v[182:185], v[116:119]
	v_mfma_f32_16x16x32_bf16 v[112:115], v[174:177], v[182:185], v[112:115]
	v_mfma_f32_16x16x32_bf16 v[100:103], v[166:169], v[190:193], v[100:103]
	v_mfma_f32_16x16x32_bf16 v[96:99], v[174:177], v[190:193], v[96:99]
	v_mfma_f32_16x16x32_bf16 v[84:87], v[166:169], v[198:201], v[84:87]
	v_mfma_f32_16x16x32_bf16 v[80:83], v[174:177], v[198:201], v[80:83]
	v_mfma_f32_16x16x32_bf16 v[68:71], v[166:169], v[206:209], v[68:71]
	v_mfma_f32_16x16x32_bf16 v[64:67], v[174:177], v[206:209], v[64:67]
	s_barrier
	s_setprio 0
	s_add_i32 s33, s67, s47
	v_lshl_add_u64 v[138:139], s[76:77], 0, v[130:131]
	s_mov_b32 m0, s33
	ds_read_b128 v[178:181], v145 offset:16384
	ds_read_b128 v[182:185], v145 offset:17408
	ds_read_b128 v[186:189], v145 offset:18432
	ds_read_b128 v[190:193], v145 offset:19456
	ds_read_b128 v[194:197], v145 offset:20480
	ds_read_b128 v[198:201], v145 offset:21504
	ds_read_b128 v[202:205], v145 offset:22528
	ds_read_b128 v[206:209], v145 offset:23552
	global_load_lds_dwordx4 v[138:139], off
	s_add_i32 m0, s33, 0x2000
	v_lshl_add_u64 v[210:211], s[76:77], 0, v[128:129]
	s_add_u32 s76, s76, s8
	s_addc_u32 s77, s77, s9
	s_add_i32 s33, s68, s47
	global_load_lds_dwordx4 v[210:211], off
	v_lshl_add_u64 v[212:213], s[76:77], 0, v[130:131]
	s_mov_b32 m0, s33
	v_lshl_add_u64 v[214:215], s[76:77], 0, v[128:129]
	global_load_lds_dwordx4 v[212:213], off
	s_add_i32 m0, s33, 0x2000
	v_lshl_add_u64 v[216:217], s[42:43], 0, v[130:131]
	global_load_lds_dwordx4 v[214:215], off
	s_mov_b32 m0, s55
	v_lshl_add_u64 v[218:219], s[42:43], 0, v[128:129]
	global_load_lds_dwordx4 v[216:217], off
	s_mov_b32 m0, s56
	s_nop 0
	global_load_lds_dwordx4 v[218:219], off
	s_waitcnt vmcnt(8)
	s_waitcnt lgkmcnt(0)
	s_setprio 1
	s_barrier
; #define PG8_STAGE(bufoff, gbase, voff) do { _Pragma("unroll") for (int _i = 0; _i < 2; ++_i) \
;         __builtin_amdgcn_global_load_lds((const unsigned*)((const char*)(gbase) + (voff)[_i]), (PG8_LAS unsigned*)(lds + (bufoff) + ldsw + _i * 8192), 16, 0, 0); } while (0)
; #define PG8_LDA(dst, b, h) do { _Pragma("unroll") for (int m = 0; m < 4; ++m) _Pragma("unroll") for (int k = 0; k < 2; ++k) dst[m][k] = *(const PG8_LAS bf16x8*)(lds + PG8_SA(b, h) + aoff + m * 2048 + k * 1024); } while (0)
; #define PG8_LDB(dst, b, h) do { _Pragma("unroll") for (int n = 0; n < 2; ++n) _Pragma("unroll") for (int k = 0; k < 2; ++k) dst[n][k] = *(const PG8_LAS bf16x8*)(lds + PG8_SB(b, h) + boff + n * 2048 + k * 1024); } while (0)
; #define PG8_MMA(ai, bj, At, Bt) do { __builtin_amdgcn_s_setprio(1); _Pragma("unroll") for (int m = 0; m < 4; ++m) _Pragma("unroll") for (int n = 0; n < 2; ++n) _Pragma("unroll") for (int k = 0; k < 2; ++k) \
;         acc[ai][bj][m][n] = __builtin_amdgcn_mfma_f32_16x16x32_bf16(Bt[n][k], At[m][k], acc[ai][bj][m][n], 0, 0, 0); __builtin_amdgcn_s_setprio(0); } while (0)
; #define PG8_WAIT_V(n) asm volatile("s_waitcnt vmcnt(" #n ")" ::: "memory")
; #define PG8_WAIT_L(n) asm volatile("s_waitcnt lgkmcnt(" #n ")" ::: "memory")
; template <class Epi, class Sched, bool ALIGN_EPI = false, bool SP2 = false>
; __device__ __forceinline__ void gemm_phase(PG8_LAS unsigned char* lds, const Gemm g, const Sched& S, const Epi& E, const int wid) {
;     ...
;             PG8_WAIT_V(8); PG8_WAIT_L(0); PG8_BAR; PG8_MMA(0, 0, At, B0); PG8_MMA(0, 1, At, B1); PG8_BAR; PG8_SCHED;
;             PG8_LDA(At, 0, 1); PG8_STAGE(PG8_SB(0, 0), b2, voffB); PG8_STAGE(PG8_SB(0, 1), b2 + hstep, voffB); PG8_STAGE(PG8_SA(0, 0), a2, voffA);
;             PG8_WAIT_V(8); PG8_WAIT_L(0); PG8_BAR; PG8_MMA(1, 0, At, B0); PG8_MMA(1, 1, At, B1); PG8_BAR; PG8_SCHED;
;             PG8_LDB(B0, 1, 0); PG8_LDB(B1, 1, 1); PG8_SCHED; PG8_LDA(At, 1, 0); PG8_STAGE(PG8_SA(0, 1), a2 + hstep, voffA);
;             PG8_WAIT_V(8); PG8_WAIT_L(0); PG8_BAR; PG8_MMA(0, 0, At, B0); PG8_MMA(0, 1, At, B1); PG8_BAR; PG8_SCHED;
;             PG8_LDA(At, 1, 1); PG8_STAGE(PG8_SB(1, 0), b3, voffB); PG8_STAGE(PG8_SB(1, 1), b3 + hstep, voffB); PG8_STAGE(PG8_SA(1, 0), a3, voffA);
;             PG8_WAIT_V(8); PG8_WAIT_L(0); PG8_BAR; PG8_MMA(1, 0, At, B0); PG8_MMA(1, 1, At, B1); PG8_BAR; PG8_SCHED;
	v_mfma_f32_16x16x32_bf16 v[60:63], v[146:149], v[178:181], 0
	v_mfma_f32_16x16x32_bf16 v[56:59], v[154:157], v[178:181], 0
	v_mfma_f32_16x16x32_bf16 v[44:47], v[146:149], v[186:189], 0
	v_mfma_f32_16x16x32_bf16 v[40:43], v[154:157], v[186:189], 0
	v_mfma_f32_16x16x32_bf16 v[28:31], v[146:149], v[194:197], 0
	v_mfma_f32_16x16x32_bf16 v[24:27], v[154:157], v[194:197], 0
	v_mfma_f32_16x16x32_bf16 v[12:15], v[146:149], v[202:205], 0
	v_mfma_f32_16x16x32_bf16 v[8:11], v[154:157], v[202:205], 0
	v_mfma_f32_16x16x32_bf16 v[60:63], v[150:153], v[182:185], v[60:63]
	v_mfma_f32_16x16x32_bf16 v[56:59], v[158:161], v[182:185], v[56:59]
	v_mfma_f32_16x16x32_bf16 v[44:47], v[150:153], v[190:193], v[44:47]
	v_mfma_f32_16x16x32_bf16 v[40:43], v[158:161], v[190:193], v[40:43]
	v_mfma_f32_16x16x32_bf16 v[28:31], v[150:153], v[198:201], v[28:31]
	v_mfma_f32_16x16x32_bf16 v[24:27], v[158:161], v[198:201], v[24:27]
	v_mfma_f32_16x16x32_bf16 v[12:15], v[150:153], v[206:209], v[12:15]
	v_mfma_f32_16x16x32_bf16 v[8:11], v[158:161], v[206:209], v[8:11]
	v_mfma_f32_16x16x32_bf16 v[52:55], v[162:165], v[178:181], 0
	v_mfma_f32_16x16x32_bf16 v[48:51], v[170:173], v[178:181], 0
	v_mfma_f32_16x16x32_bf16 v[36:39], v[162:165], v[186:189], 0
	v_mfma_f32_16x16x32_bf16 v[32:35], v[170:173], v[186:189], 0
	v_mfma_f32_16x16x32_bf16 v[20:23], v[162:165], v[194:197], 0
	v_mfma_f32_16x16x32_bf16 v[16:19], v[170:173], v[194:197], 0
	v_mfma_f32_16x16x32_bf16 v[4:7], v[162:165], v[202:205], 0
	v_mfma_f32_16x16x32_bf16 v[0:3], v[170:173], v[202:205], 0
	v_mfma_f32_16x16x32_bf16 v[52:55], v[166:169], v[182:185], v[52:55]
	v_mfma_f32_16x16x32_bf16 v[48:51], v[174:177], v[182:185], v[48:51]
	v_mfma_f32_16x16x32_bf16 v[36:39], v[166:169], v[190:193], v[36:39]
	v_mfma_f32_16x16x32_bf16 v[32:35], v[174:177], v[190:193], v[32:35]
	v_mfma_f32_16x16x32_bf16 v[20:23], v[166:169], v[198:201], v[20:23]
	v_mfma_f32_16x16x32_bf16 v[16:19], v[174:177], v[198:201], v[16:19]
	v_mfma_f32_16x16x32_bf16 v[4:7], v[166:169], v[206:209], v[4:7]
	v_mfma_f32_16x16x32_bf16 v[0:3], v[174:177], v[206:209], v[0:3]
	s_barrier
	s_setprio 0
	s_add_i32 s33, 0, 0x18000
	s_add_i32 s76, 0, 0x1c000
	v_add_u32_e32 v158, s33, v142
	v_add_u32_e32 v174, s76, v142
	ds_read_b128 v[146:149], v158
	ds_read_b128 v[150:153], v158 offset:1024
	ds_read_b128 v[154:157], v158 offset:2048
	ds_read_b128 v[158:161], v158 offset:3072
	ds_read_b128 v[162:165], v174
	ds_read_b128 v[166:169], v174 offset:1024
	ds_read_b128 v[170:173], v174 offset:2048
	ds_read_b128 v[174:177], v174 offset:3072
	s_add_u32 s42, s42, s8
	s_addc_u32 s43, s43, s9
	s_mov_b32 m0, s57
	v_lshl_add_u64 v[220:221], s[42:43], 0, v[130:131]
	ds_read_b128 v[178:181], v145 offset:32768
	ds_read_b128 v[182:185], v145 offset:33792
	ds_read_b128 v[186:189], v145 offset:34816
	ds_read_b128 v[190:193], v145 offset:35840
	ds_read_b128 v[194:197], v145 offset:36864
	ds_read_b128 v[198:201], v145 offset:37888
	ds_read_b128 v[202:205], v145 offset:38912
	ds_read_b128 v[206:209], v145 offset:39936
	global_load_lds_dwordx4 v[220:221], off
	v_lshl_add_u64 v[220:221], s[42:43], 0, v[128:129]
	s_mov_b32 m0, s58
	s_nop 0
	global_load_lds_dwordx4 v[220:221], off
	s_waitcnt vmcnt(8)
	s_waitcnt lgkmcnt(0)
	s_setprio 1
	s_barrier
	v_mfma_f32_16x16x32_bf16 v[124:127], v[146:149], v[178:181], v[124:127]
	v_mfma_f32_16x16x32_bf16 v[120:123], v[154:157], v[178:181], v[120:123]
	v_mfma_f32_16x16x32_bf16 v[108:111], v[146:149], v[186:189], v[108:111]
	v_mfma_f32_16x16x32_bf16 v[104:107], v[154:157], v[186:189], v[104:107]
	v_mfma_f32_16x16x32_bf16 v[92:95], v[146:149], v[194:197], v[92:95]
	v_mfma_f32_16x16x32_bf16 v[88:91], v[154:157], v[194:197], v[88:91]
	v_mfma_f32_16x16x32_bf16 v[76:79], v[146:149], v[202:205], v[76:79]
	v_mfma_f32_16x16x32_bf16 v[72:75], v[154:157], v[202:205], v[72:75]
	v_mfma_f32_16x16x32_bf16 v[124:127], v[150:153], v[182:185], v[124:127]
	v_mfma_f32_16x16x32_bf16 v[120:123], v[158:161], v[182:185], v[120:123]
	v_mfma_f32_16x16x32_bf16 v[108:111], v[150:153], v[190:193], v[108:111]
	v_mfma_f32_16x16x32_bf16 v[104:107], v[158:161], v[190:193], v[104:107]
	v_mfma_f32_16x16x32_bf16 v[92:95], v[150:153], v[198:201], v[92:95]
	v_mfma_f32_16x16x32_bf16 v[88:91], v[158:161], v[198:201], v[88:91]
	v_mfma_f32_16x16x32_bf16 v[76:79], v[150:153], v[206:209], v[76:79]
	v_mfma_f32_16x16x32_bf16 v[72:75], v[158:161], v[206:209], v[72:75]
	v_mfma_f32_16x16x32_bf16 v[116:119], v[162:165], v[178:181], v[116:119]
	v_mfma_f32_16x16x32_bf16 v[112:115], v[170:173], v[178:181], v[112:115]
	v_mfma_f32_16x16x32_bf16 v[100:103], v[162:165], v[186:189], v[100:103]
	v_mfma_f32_16x16x32_bf16 v[96:99], v[170:173], v[186:189], v[96:99]
	v_mfma_f32_16x16x32_bf16 v[84:87], v[162:165], v[194:197], v[84:87]
	v_mfma_f32_16x16x32_bf16 v[80:83], v[170:173], v[194:197], v[80:83]
	v_mfma_f32_16x16x32_bf16 v[68:71], v[162:165], v[202:205], v[68:71]
	v_mfma_f32_16x16x32_bf16 v[64:67], v[170:173], v[202:205], v[64:67]
	v_mfma_f32_16x16x32_bf16 v[116:119], v[166:169], v[182:185], v[116:119]
	v_mfma_f32_16x16x32_bf16 v[112:115], v[174:177], v[182:185], v[112:115]
	v_mfma_f32_16x16x32_bf16 v[100:103], v[166:169], v[190:193], v[100:103]
	v_mfma_f32_16x16x32_bf16 v[96:99], v[174:177], v[190:193], v[96:99]
	v_mfma_f32_16x16x32_bf16 v[84:87], v[166:169], v[198:201], v[84:87]
	v_mfma_f32_16x16x32_bf16 v[80:83], v[174:177], v[198:201], v[80:83]
	v_mfma_f32_16x16x32_bf16 v[68:71], v[166:169], v[206:209], v[68:71]
	v_mfma_f32_16x16x32_bf16 v[64:67], v[174:177], v[206:209], v[64:67]
	s_barrier
; #define PG8_STAGE(bufoff, gbase, voff) do { _Pragma("unroll") for (int _i = 0; _i < 2; ++_i) \
;         __builtin_amdgcn_global_load_lds((const unsigned*)((const char*)(gbase) + (voff)[_i]), (PG8_LAS unsigned*)(lds + (bufoff) + ldsw + _i * 8192), 16, 0, 0); } while (0)
; #define PG8_LDA(dst, b, h) do { _Pragma("unroll") for (int m = 0; m < 4; ++m) _Pragma("unroll") for (int k = 0; k < 2; ++k) dst[m][k] = *(const PG8_LAS bf16x8*)(lds + PG8_SA(b, h) + aoff + m * 2048 + k * 1024); } while (0)
; #define PG8_WAIT_V(n) asm volatile("s_waitcnt vmcnt(" #n ")" ::: "memory")
; #define PG8_WAIT_L(n) asm volatile("s_waitcnt lgkmcnt(" #n ")" ::: "memory")
; #define PG8_BAR __builtin_amdgcn_s_barrier()
; template <class Epi, class Sched, bool ALIGN_EPI = false, bool SP2 = false>
; __device__ __forceinline__ void gemm_phase(PG8_LAS unsigned char* lds, const Gemm g, const Sched& S, const Epi& E, const int wid) {
;     ...
;         for (int t = 0; t < nt; t += 2) {
;             const bool last = (t == nt - 2);
;             const char* a1 = cA + (size_t)(t + 1) * kstep;
;             const char* a2 = last ? nA : cA + (size_t)(t + 2) * kstep; const char* b2 = last ? nB : cB + (size_t)(t + 2) * kstep;
;             const char* a3 = a2 + kstep; const char* b3 = b2 + kstep;
;             if (last && has_next) S.a_ready(nxt);
;             if constexpr (SP2) {
;             PG8_LDB(B0, 0, 0); PG8_LDB(B1, 0, 1); PG8_SCHED; PG8_LDA(At, 0, 0); PG8_STAGE(PG8_SA(1, 1), a1 + hstep, voffA);
;             PG8_WAIT_V(8); PG8_WAIT_L(0); PG8_BAR; PG8_MMA(0, 0, At, B0); PG8_MMA(0, 1, At, B1); PG8_BAR; PG8_SCHED;
;             PG8_LDA(At, 0, 1); PG8_STAGE(PG8_SB(0, 0), b2, voffB); PG8_STAGE(PG8_SB(0, 1), b2 + hstep, voffB); PG8_STAGE(PG8_SA(0, 0), a2, voffA);
;             PG8_WAIT_V(8); PG8_WAIT_L(0); PG8_BAR; PG8_MMA(1, 0, At, B0); PG8_MMA(1, 1, At, B1); PG8_BAR; PG8_SCHED;
;             PG8_LDB(B0, 1, 0); PG8_LDB(B1, 1, 1); PG8_SCHED; PG8_LDA(At, 1, 0); PG8_STAGE(PG8_SA(0, 1), a2 + hstep, voffA);
;             PG8_WAIT_V(8); PG8_WAIT_L(0); PG8_BAR; PG8_MMA(0, 0, At, B0); PG8_MMA(0, 1, At, B1); PG8_BAR; PG8_SCHED;
;             PG8_LDA(At, 1, 1); PG8_STAGE(PG8_SB(1, 0), b3, voffB); PG8_STAGE(PG8_SB(1, 1), b3 + hstep, voffB); PG8_STAGE(PG8_SA(1, 0), a3, voffA);
;             PG8_WAIT_V(8); PG8_WAIT_L(0); PG8_BAR; PG8_MMA(1, 0, At, B0); PG8_MMA(1, 1, At, B1); PG8_BAR; PG8_SCHED;
	s_setprio 0
	s_add_i32 s33, s33, s47
	v_lshl_add_u64 v[138:139], v[138:139], 0, s[16:17]
	s_mov_b32 m0, s33
	ds_read_b128 v[178:181], v145 offset:49152
	ds_read_b128 v[182:185], v145 offset:50176
	ds_read_b128 v[186:189], v145 offset:51200
	ds_read_b128 v[190:193], v145 offset:52224
	ds_read_b128 v[194:197], v145 offset:53248
	ds_read_b128 v[198:201], v145 offset:54272
	ds_read_b128 v[202:205], v145 offset:55296
	ds_read_b128 v[206:209], v145 offset:56320
	global_load_lds_dwordx4 v[138:139], off
	v_lshl_add_u64 v[138:139], v[210:211], 0, s[16:17]
	s_add_i32 m0, s33, 0x2000
	s_add_i32 s33, s76, s47
	global_load_lds_dwordx4 v[138:139], off
	v_lshl_add_u64 v[138:139], v[212:213], 0, s[16:17]
	s_mov_b32 m0, s33
	s_nop 0
	global_load_lds_dwordx4 v[138:139], off
	v_lshl_add_u64 v[138:139], v[214:215], 0, s[16:17]
	s_add_i32 m0, s33, 0x2000
	s_nop 0
	global_load_lds_dwordx4 v[138:139], off
	v_lshl_add_u64 v[138:139], v[216:217], 0, s[16:17]
	s_mov_b32 m0, s60
	s_nop 0
	global_load_lds_dwordx4 v[138:139], off
	v_lshl_add_u64 v[138:139], v[218:219], 0, s[16:17]
	s_mov_b32 m0, s61
	s_nop 0
	global_load_lds_dwordx4 v[138:139], off
	s_waitcnt vmcnt(8)
	s_waitcnt lgkmcnt(0)
	s_setprio 1
	s_barrier
	v_mfma_f32_16x16x32_bf16 v[60:63], v[146:149], v[178:181], v[60:63]
	v_mfma_f32_16x16x32_bf16 v[56:59], v[154:157], v[178:181], v[56:59]
	v_mfma_f32_16x16x32_bf16 v[44:47], v[146:149], v[186:189], v[44:47]
	v_mfma_f32_16x16x32_bf16 v[40:43], v[154:157], v[186:189], v[40:43]
	v_mfma_f32_16x16x32_bf16 v[28:31], v[146:149], v[194:197], v[28:31]
	v_mfma_f32_16x16x32_bf16 v[24:27], v[154:157], v[194:197], v[24:27]
	v_mfma_f32_16x16x32_bf16 v[12:15], v[146:149], v[202:205], v[12:15]
	v_mfma_f32_16x16x32_bf16 v[8:11], v[154:157], v[202:205], v[8:11]
	v_mfma_f32_16x16x32_bf16 v[60:63], v[150:153], v[182:185], v[60:63]
	v_mfma_f32_16x16x32_bf16 v[56:59], v[158:161], v[182:185], v[56:59]
	v_mfma_f32_16x16x32_bf16 v[44:47], v[150:153], v[190:193], v[44:47]
	v_mfma_f32_16x16x32_bf16 v[40:43], v[158:161], v[190:193], v[40:43]
	v_mfma_f32_16x16x32_bf16 v[28:31], v[150:153], v[198:201], v[28:31]
	v_mfma_f32_16x16x32_bf16 v[24:27], v[158:161], v[198:201], v[24:27]
	v_mfma_f32_16x16x32_bf16 v[12:15], v[150:153], v[206:209], v[12:15]
	v_mfma_f32_16x16x32_bf16 v[8:11], v[158:161], v[206:209], v[8:11]
	v_mfma_f32_16x16x32_bf16 v[52:55], v[162:165], v[178:181], v[52:55]
	v_mfma_f32_16x16x32_bf16 v[48:51], v[170:173], v[178:181], v[48:51]
	v_mfma_f32_16x16x32_bf16 v[36:39], v[162:165], v[186:189], v[36:39]
	v_mfma_f32_16x16x32_bf16 v[32:35], v[170:173], v[186:189], v[32:35]
	v_mfma_f32_16x16x32_bf16 v[20:23], v[162:165], v[194:197], v[20:23]
	v_mfma_f32_16x16x32_bf16 v[16:19], v[170:173], v[194:197], v[16:19]
	v_mfma_f32_16x16x32_bf16 v[4:7], v[162:165], v[202:205], v[4:7]
	v_mfma_f32_16x16x32_bf16 v[0:3], v[170:173], v[202:205], v[0:3]
	v_mfma_f32_16x16x32_bf16 v[52:55], v[166:169], v[182:185], v[52:55]
	v_mfma_f32_16x16x32_bf16 v[48:51], v[174:177], v[182:185], v[48:51]
	v_mfma_f32_16x16x32_bf16 v[36:39], v[166:169], v[190:193], v[36:39]
	v_mfma_f32_16x16x32_bf16 v[32:35], v[174:177], v[190:193], v[32:35]
	v_mfma_f32_16x16x32_bf16 v[20:23], v[166:169], v[198:201], v[20:23]
	v_mfma_f32_16x16x32_bf16 v[16:19], v[174:177], v[198:201], v[16:19]
	v_mfma_f32_16x16x32_bf16 v[4:7], v[166:169], v[206:209], v[4:7]
	v_mfma_f32_16x16x32_bf16 v[0:3], v[174:177], v[206:209], v[0:3]
	s_barrier
	s_setprio 0
	s_add_u32 s40, s40, 0x100
	s_addc_u32 s41, s41, 0
	s_add_u32 s73, s73, 0x100
	s_addc_u32 s74, s74, 0
	s_cmp_ge_i32 s75, s62
	s_mov_b32 s42, s75
	s_cbranch_scc1 .LBB0_1575
.LBB0_1574:
	ds_read_b128 v[146:149], v143
	ds_read_b128 v[150:153], v143 offset:1024
	ds_read_b128 v[154:157], v143 offset:2048
	ds_read_b128 v[158:161], v143 offset:3072
	ds_read_b128 v[162:165], v144
	ds_read_b128 v[166:169], v144 offset:1024
	ds_read_b128 v[170:173], v144 offset:2048
	ds_read_b128 v[174:177], v144 offset:3072
	s_add_i32 s75, s42, 2
	s_add_u32 s33, s40, 0x80
	s_addc_u32 s43, s41, 0
	s_cmp_eq_u32 s65, s42
	s_cselect_b32 s42, s2, s33
	s_cselect_b32 s43, s3, s43
	s_cselect_b32 s77, s39, s74
	s_cselect_b32 s76, s38, s73
	v_lshl_add_u64 v[138:139], s[40:41], 0, v[132:133]
	s_add_i32 m0, s55, 0xc000
	ds_read_b128 v[178:181], v145
	ds_read_b128 v[182:185], v145 offset:1024
	ds_read_b128 v[186:189], v145 offset:2048
	ds_read_b128 v[190:193], v145 offset:3072
	ds_read_b128 v[194:197], v145 offset:4096
	ds_read_b128 v[198:201], v145 offset:5120
	ds_read_b128 v[202:205], v145 offset:6144
	ds_read_b128 v[206:209], v145 offset:7168
	global_load_lds_dwordx4 v[138:139], off
	v_lshl_add_u64 v[138:139], s[40:41], 0, v[134:135]
	s_add_i32 m0, s55, 0xe000
	s_nop 0
	global_load_lds_dwordx4 v[138:139], off
	s_waitcnt vmcnt(8)
	s_waitcnt lgkmcnt(0)
	s_setprio 1
	s_barrier
; #define PG8_STAGE(bufoff, gbase, voff) do { _Pragma("unroll") for (int _i = 0; _i < 2; ++_i) \
;         __builtin_amdgcn_global_load_lds((const unsigned*)((const char*)(gbase) + (voff)[_i]), (PG8_LAS unsigned*)(lds + (bufoff) + ldsw + _i * 8192), 16, 0, 0); } while (0)
; #define PG8_LDA(dst, b, h) do { _Pragma("unroll") for (int m = 0; m < 4; ++m) _Pragma("unroll") for (int k = 0; k < 2; ++k) dst[m][k] = *(const PG8_LAS bf16x8*)(lds + PG8_SA(b, h) + aoff + m * 2048 + k * 1024); } while (0)
; #define PG8_WAIT_V(n) asm volatile("s_waitcnt vmcnt(" #n ")" ::: "memory")
; #define PG8_WAIT_L(n) asm volatile("s_waitcnt lgkmcnt(" #n ")" ::: "memory")
; #define PG8_BAR __builtin_amdgcn_s_barrier()
; template <class Epi, class Sched, bool ALIGN_EPI = false, bool SP2 = false>
; __device__ __forceinline__ void gemm_phase(PG8_LAS unsigned char* lds, const Gemm g, const Sched& S, const Epi& E, const int wid) {
;     ...
;         for (int t = 0; t < nt; t += 2) {
;             const bool last = (t == nt - 2);
;             const char* a1 = cA + (size_t)(t + 1) * kstep;
;             const char* a2 = last ? nA : cA + (size_t)(t + 2) * kstep; const char* b2 = last ? nB : cB + (size_t)(t + 2) * kstep;
;             const char* a3 = a2 + kstep; const char* b3 = b2 + kstep;
;             if (last && has_next) S.a_ready(nxt);
;             if constexpr (SP2) {
;             PG8_LDB(B0, 0, 0); PG8_LDB(B1, 0, 1); PG8_SCHED; PG8_LDA(At, 0, 0); PG8_STAGE(PG8_SA(1, 1), a1 + hstep, voffA);
;             PG8_WAIT_V(8); PG8_WAIT_L(0); PG8_BAR; PG8_MMA(0, 0, At, B0); PG8_MMA(0, 1, At, B1); PG8_BAR; PG8_SCHED;
;             PG8_LDA(At, 0, 1); PG8_STAGE(PG8_SB(0, 0), b2, voffB); PG8_STAGE(PG8_SB(0, 1), b2 + hstep, voffB); PG8_STAGE(PG8_SA(0, 0), a2, voffA);
;             PG8_WAIT_V(8); PG8_WAIT_L(0); PG8_BAR; PG8_MMA(1, 0, At, B0); PG8_MMA(1, 1, At, B1); PG8_BAR; PG8_SCHED;
;             PG8_LDB(B0, 1, 0); PG8_LDB(B1, 1, 1); PG8_SCHED; PG8_LDA(At, 1, 0); PG8_STAGE(PG8_SA(0, 1), a2 + hstep, voffA);
;             PG8_WAIT_V(8); PG8_WAIT_L(0); PG8_BAR; PG8_MMA(0, 0, At, B0); PG8_MMA(0, 1, At, B1); PG8_BAR; PG8_SCHED;
;             PG8_LDA(At, 1, 1); PG8_STAGE(PG8_SB(1, 0), b3, voffB); PG8_STAGE(PG8_SB(1, 1), b3 + hstep, voffB); PG8_STAGE(PG8_SA(1, 0), a3, voffA);
;             PG8_WAIT_V(8); PG8_WAIT_L(0); PG8_BAR; PG8_MMA(1, 0, At, B0); PG8_MMA(1, 1, At, B1); PG8_BAR; PG8_SCHED;
	v_mfma_f32_16x16x32_bf16 v[124:127], v[146:149], v[178:181], v[124:127]
	v_mfma_f32_16x16x32_bf16 v[120:123], v[154:157], v[178:181], v[120:123]
	v_mfma_f32_16x16x32_bf16 v[108:111], v[146:149], v[186:189], v[108:111]
	v_mfma_f32_16x16x32_bf16 v[104:107], v[154:157], v[186:189], v[104:107]
	v_mfma_f32_16x16x32_bf16 v[92:95], v[146:149], v[194:197], v[92:95]
	v_mfma_f32_16x16x32_bf16 v[88:91], v[154:157], v[194:197], v[88:91]
	v_mfma_f32_16x16x32_bf16 v[76:79], v[146:149], v[202:205], v[76:79]
	v_mfma_f32_16x16x32_bf16 v[72:75], v[154:157], v[202:205], v[72:75]
	v_mfma_f32_16x16x32_bf16 v[124:127], v[150:153], v[182:185], v[124:127]
	v_mfma_f32_16x16x32_bf16 v[120:123], v[158:161], v[182:185], v[120:123]
	v_mfma_f32_16x16x32_bf16 v[108:111], v[150:153], v[190:193], v[108:111]
	v_mfma_f32_16x16x32_bf16 v[104:107], v[158:161], v[190:193], v[104:107]
	v_mfma_f32_16x16x32_bf16 v[92:95], v[150:153], v[198:201], v[92:95]
	v_mfma_f32_16x16x32_bf16 v[88:91], v[158:161], v[198:201], v[88:91]
	v_mfma_f32_16x16x32_bf16 v[76:79], v[150:153], v[206:209], v[76:79]
	v_mfma_f32_16x16x32_bf16 v[72:75], v[158:161], v[206:209], v[72:75]
	v_mfma_f32_16x16x32_bf16 v[116:119], v[162:165], v[178:181], v[116:119]
	v_mfma_f32_16x16x32_bf16 v[112:115], v[170:173], v[178:181], v[112:115]
	v_mfma_f32_16x16x32_bf16 v[100:103], v[162:165], v[186:189], v[100:103]
	v_mfma_f32_16x16x32_bf16 v[96:99], v[170:173], v[186:189], v[96:99]
	v_mfma_f32_16x16x32_bf16 v[84:87], v[162:165], v[194:197], v[84:87]
	v_mfma_f32_16x16x32_bf16 v[80:83], v[170:173], v[194:197], v[80:83]
	v_mfma_f32_16x16x32_bf16 v[68:71], v[162:165], v[202:205], v[68:71]
	v_mfma_f32_16x16x32_bf16 v[64:67], v[170:173], v[202:205], v[64:67]
	v_mfma_f32_16x16x32_bf16 v[116:119], v[166:169], v[182:185], v[116:119]
	v_mfma_f32_16x16x32_bf16 v[112:115], v[174:177], v[182:185], v[112:115]
	v_mfma_f32_16x16x32_bf16 v[100:103], v[166:169], v[190:193], v[100:103]
	v_mfma_f32_16x16x32_bf16 v[96:99], v[174:177], v[190:193], v[96:99]
	v_mfma_f32_16x16x32_bf16 v[84:87], v[166:169], v[198:201], v[84:87]
	v_mfma_f32_16x16x32_bf16 v[80:83], v[174:177], v[198:201], v[80:83]
	v_mfma_f32_16x16x32_bf16 v[68:71], v[166:169], v[206:209], v[68:71]
	v_mfma_f32_16x16x32_bf16 v[64:67], v[174:177], v[206:209], v[64:67]
	s_barrier
	s_setprio 0
	s_add_i32 s33, s67, s47
	v_lshl_add_u64 v[138:139], s[76:77], 0, v[130:131]
	s_mov_b32 m0, s33
	ds_read_b128 v[178:181], v145 offset:16384
	ds_read_b128 v[182:185], v145 offset:17408
	ds_read_b128 v[186:189], v145 offset:18432
	ds_read_b128 v[190:193], v145 offset:19456
	ds_read_b128 v[194:197], v145 offset:20480
	ds_read_b128 v[198:201], v145 offset:21504
	ds_read_b128 v[202:205], v145 offset:22528
	ds_read_b128 v[206:209], v145 offset:23552
	global_load_lds_dwordx4 v[138:139], off
	s_add_i32 m0, s33, 0x2000
	v_lshl_add_u64 v[210:211], s[76:77], 0, v[128:129]
	s_add_u32 s76, s76, s8
	s_addc_u32 s77, s77, s9
	s_add_i32 s33, s68, s47
	global_load_lds_dwordx4 v[210:211], off
	v_lshl_add_u64 v[212:213], s[76:77], 0, v[130:131]
	s_mov_b32 m0, s33
	v_lshl_add_u64 v[214:215], s[76:77], 0, v[128:129]
	global_load_lds_dwordx4 v[212:213], off
	s_add_i32 m0, s33, 0x2000
	v_lshl_add_u64 v[216:217], s[42:43], 0, v[130:131]
	global_load_lds_dwordx4 v[214:215], off
	s_mov_b32 m0, s55
	v_lshl_add_u64 v[218:219], s[42:43], 0, v[128:129]
	global_load_lds_dwordx4 v[216:217], off
	s_mov_b32 m0, s56
	s_nop 0
	global_load_lds_dwordx4 v[218:219], off
	s_waitcnt vmcnt(8)
	s_waitcnt lgkmcnt(0)
	s_setprio 1
	s_barrier
	v_mfma_f32_16x16x32_bf16 v[60:63], v[146:149], v[178:181], v[60:63]
	v_mfma_f32_16x16x32_bf16 v[56:59], v[154:157], v[178:181], v[56:59]
	v_mfma_f32_16x16x32_bf16 v[44:47], v[146:149], v[186:189], v[44:47]
	v_mfma_f32_16x16x32_bf16 v[40:43], v[154:157], v[186:189], v[40:43]
	v_mfma_f32_16x16x32_bf16 v[28:31], v[146:149], v[194:197], v[28:31]
	v_mfma_f32_16x16x32_bf16 v[24:27], v[154:157], v[194:197], v[24:27]
	v_mfma_f32_16x16x32_bf16 v[12:15], v[146:149], v[202:205], v[12:15]
	v_mfma_f32_16x16x32_bf16 v[8:11], v[154:157], v[202:205], v[8:11]
	v_mfma_f32_16x16x32_bf16 v[60:63], v[150:153], v[182:185], v[60:63]
	v_mfma_f32_16x16x32_bf16 v[56:59], v[158:161], v[182:185], v[56:59]
	v_mfma_f32_16x16x32_bf16 v[44:47], v[150:153], v[190:193], v[44:47]
	v_mfma_f32_16x16x32_bf16 v[40:43], v[158:161], v[190:193], v[40:43]
	v_mfma_f32_16x16x32_bf16 v[28:31], v[150:153], v[198:201], v[28:31]
	v_mfma_f32_16x16x32_bf16 v[24:27], v[158:161], v[198:201], v[24:27]
	v_mfma_f32_16x16x32_bf16 v[12:15], v[150:153], v[206:209], v[12:15]
	v_mfma_f32_16x16x32_bf16 v[8:11], v[158:161], v[206:209], v[8:11]
	v_mfma_f32_16x16x32_bf16 v[52:55], v[162:165], v[178:181], v[52:55]
	v_mfma_f32_16x16x32_bf16 v[48:51], v[170:173], v[178:181], v[48:51]
	v_mfma_f32_16x16x32_bf16 v[36:39], v[162:165], v[186:189], v[36:39]
	v_mfma_f32_16x16x32_bf16 v[32:35], v[170:173], v[186:189], v[32:35]
	v_mfma_f32_16x16x32_bf16 v[20:23], v[162:165], v[194:197], v[20:23]
	v_mfma_f32_16x16x32_bf16 v[16:19], v[170:173], v[194:197], v[16:19]
	v_mfma_f32_16x16x32_bf16 v[4:7], v[162:165], v[202:205], v[4:7]
	v_mfma_f32_16x16x32_bf16 v[0:3], v[170:173], v[202:205], v[0:3]
	v_mfma_f32_16x16x32_bf16 v[52:55], v[166:169], v[182:185], v[52:55]
	v_mfma_f32_16x16x32_bf16 v[48:51], v[174:177], v[182:185], v[48:51]
	v_mfma_f32_16x16x32_bf16 v[36:39], v[166:169], v[190:193], v[36:39]
	v_mfma_f32_16x16x32_bf16 v[32:35], v[174:177], v[190:193], v[32:35]
	v_mfma_f32_16x16x32_bf16 v[20:23], v[166:169], v[198:201], v[20:23]
	v_mfma_f32_16x16x32_bf16 v[16:19], v[174:177], v[198:201], v[16:19]
	v_mfma_f32_16x16x32_bf16 v[4:7], v[166:169], v[206:209], v[4:7]
	v_mfma_f32_16x16x32_bf16 v[0:3], v[174:177], v[206:209], v[0:3]
	s_barrier
; #define PG8_STAGE(bufoff, gbase, voff) do { _Pragma("unroll") for (int _i = 0; _i < 2; ++_i) \
;         __builtin_amdgcn_global_load_lds((const unsigned*)((const char*)(gbase) + (voff)[_i]), (PG8_LAS unsigned*)(lds + (bufoff) + ldsw + _i * 8192), 16, 0, 0); } while (0)
; #define PG8_LDA(dst, b, h) do { _Pragma("unroll") for (int m = 0; m < 4; ++m) _Pragma("unroll") for (int k = 0; k < 2; ++k) dst[m][k] = *(const PG8_LAS bf16x8*)(lds + PG8_SA(b, h) + aoff + m * 2048 + k * 1024); } while (0)
; #define PG8_WAIT_V(n) asm volatile("s_waitcnt vmcnt(" #n ")" ::: "memory")
; #define PG8_WAIT_L(n) asm volatile("s_waitcnt lgkmcnt(" #n ")" ::: "memory")
; #define PG8_BAR __builtin_amdgcn_s_barrier()
; template <class Epi, class Sched, bool ALIGN_EPI = false, bool SP2 = false>
; __device__ __forceinline__ void gemm_phase(PG8_LAS unsigned char* lds, const Gemm g, const Sched& S, const Epi& E, const int wid) {
;     ...
;         for (int t = 0; t < nt; t += 2) {
;             const bool last = (t == nt - 2);
;             const char* a1 = cA + (size_t)(t + 1) * kstep;
;             const char* a2 = last ? nA : cA + (size_t)(t + 2) * kstep; const char* b2 = last ? nB : cB + (size_t)(t + 2) * kstep;
;             const char* a3 = a2 + kstep; const char* b3 = b2 + kstep;
;             if (last && has_next) S.a_ready(nxt);
;             if constexpr (SP2) {
;             PG8_LDB(B0, 0, 0); PG8_LDB(B1, 0, 1); PG8_SCHED; PG8_LDA(At, 0, 0); PG8_STAGE(PG8_SA(1, 1), a1 + hstep, voffA);
;             PG8_WAIT_V(8); PG8_WAIT_L(0); PG8_BAR; PG8_MMA(0, 0, At, B0); PG8_MMA(0, 1, At, B1); PG8_BAR; PG8_SCHED;
;             PG8_LDA(At, 0, 1); PG8_STAGE(PG8_SB(0, 0), b2, voffB); PG8_STAGE(PG8_SB(0, 1), b2 + hstep, voffB); PG8_STAGE(PG8_SA(0, 0), a2, voffA);
;             PG8_WAIT_V(8); PG8_WAIT_L(0); PG8_BAR; PG8_MMA(1, 0, At, B0); PG8_MMA(1, 1, At, B1); PG8_BAR; PG8_SCHED;
;             PG8_LDB(B0, 1, 0); PG8_LDB(B1, 1, 1); PG8_SCHED; PG8_LDA(At, 1, 0); PG8_STAGE(PG8_SA(0, 1), a2 + hstep, voffA);
;             PG8_WAIT_V(8); PG8_WAIT_L(0); PG8_BAR; PG8_MMA(0, 0, At, B0); PG8_MMA(0, 1, At, B1); PG8_BAR; PG8_SCHED;
;             PG8_LDA(At, 1, 1); PG8_STAGE(PG8_SB(1, 0), b3, voffB); PG8_STAGE(PG8_SB(1, 1), b3 + hstep, voffB); PG8_STAGE(PG8_SA(1, 0), a3, voffA);
;             PG8_WAIT_V(8); PG8_WAIT_L(0); PG8_BAR; PG8_MMA(1, 0, At, B0); PG8_MMA(1, 1, At, B1); PG8_BAR; PG8_SCHED;
	s_setprio 0
	s_add_i32 s33, 0, 0x18000
	s_add_i32 s76, 0, 0x1c000
	v_add_u32_e32 v158, s33, v142
	v_add_u32_e32 v174, s76, v142
	ds_read_b128 v[146:149], v158
	ds_read_b128 v[150:153], v158 offset:1024
	ds_read_b128 v[154:157], v158 offset:2048
	ds_read_b128 v[158:161], v158 offset:3072
	ds_read_b128 v[162:165], v174
	ds_read_b128 v[166:169], v174 offset:1024
	ds_read_b128 v[170:173], v174 offset:2048
	ds_read_b128 v[174:177], v174 offset:3072
	s_add_u32 s42, s42, s8
	s_addc_u32 s43, s43, s9
	s_mov_b32 m0, s57
	v_lshl_add_u64 v[220:221], s[42:43], 0, v[130:131]
	ds_read_b128 v[178:181], v145 offset:32768
	ds_read_b128 v[182:185], v145 offset:33792
	ds_read_b128 v[186:189], v145 offset:34816
	ds_read_b128 v[190:193], v145 offset:35840
	ds_read_b128 v[194:197], v145 offset:36864
	ds_read_b128 v[198:201], v145 offset:37888
	ds_read_b128 v[202:205], v145 offset:38912
	ds_read_b128 v[206:209], v145 offset:39936
	global_load_lds_dwordx4 v[220:221], off
	v_lshl_add_u64 v[220:221], s[42:43], 0, v[128:129]
	s_mov_b32 m0, s58
	s_nop 0
	global_load_lds_dwordx4 v[220:221], off
	s_waitcnt vmcnt(8)
	s_waitcnt lgkmcnt(0)
	s_setprio 1
	s_barrier
	v_mfma_f32_16x16x32_bf16 v[124:127], v[146:149], v[178:181], v[124:127]
	v_mfma_f32_16x16x32_bf16 v[120:123], v[154:157], v[178:181], v[120:123]
	v_mfma_f32_16x16x32_bf16 v[108:111], v[146:149], v[186:189], v[108:111]
	v_mfma_f32_16x16x32_bf16 v[104:107], v[154:157], v[186:189], v[104:107]
	v_mfma_f32_16x16x32_bf16 v[92:95], v[146:149], v[194:197], v[92:95]
	v_mfma_f32_16x16x32_bf16 v[88:91], v[154:157], v[194:197], v[88:91]
	v_mfma_f32_16x16x32_bf16 v[76:79], v[146:149], v[202:205], v[76:79]
	v_mfma_f32_16x16x32_bf16 v[72:75], v[154:157], v[202:205], v[72:75]
	v_mfma_f32_16x16x32_bf16 v[124:127], v[150:153], v[182:185], v[124:127]
	v_mfma_f32_16x16x32_bf16 v[120:123], v[158:161], v[182:185], v[120:123]
	v_mfma_f32_16x16x32_bf16 v[108:111], v[150:153], v[190:193], v[108:111]
	v_mfma_f32_16x16x32_bf16 v[104:107], v[158:161], v[190:193], v[104:107]
	v_mfma_f32_16x16x32_bf16 v[92:95], v[150:153], v[198:201], v[92:95]
	v_mfma_f32_16x16x32_bf16 v[88:91], v[158:161], v[198:201], v[88:91]
	v_mfma_f32_16x16x32_bf16 v[76:79], v[150:153], v[206:209], v[76:79]
	v_mfma_f32_16x16x32_bf16 v[72:75], v[158:161], v[206:209], v[72:75]
	v_mfma_f32_16x16x32_bf16 v[116:119], v[162:165], v[178:181], v[116:119]
	v_mfma_f32_16x16x32_bf16 v[112:115], v[170:173], v[178:181], v[112:115]
	v_mfma_f32_16x16x32_bf16 v[100:103], v[162:165], v[186:189], v[100:103]
	v_mfma_f32_16x16x32_bf16 v[96:99], v[170:173], v[186:189], v[96:99]
	v_mfma_f32_16x16x32_bf16 v[84:87], v[162:165], v[194:197], v[84:87]
	v_mfma_f32_16x16x32_bf16 v[80:83], v[170:173], v[194:197], v[80:83]
	v_mfma_f32_16x16x32_bf16 v[68:71], v[162:165], v[202:205], v[68:71]
	v_mfma_f32_16x16x32_bf16 v[64:67], v[170:173], v[202:205], v[64:67]
	v_mfma_f32_16x16x32_bf16 v[116:119], v[166:169], v[182:185], v[116:119]
	v_mfma_f32_16x16x32_bf16 v[112:115], v[174:177], v[182:185], v[112:115]
	v_mfma_f32_16x16x32_bf16 v[100:103], v[166:169], v[190:193], v[100:103]
	v_mfma_f32_16x16x32_bf16 v[96:99], v[174:177], v[190:193], v[96:99]
	v_mfma_f32_16x16x32_bf16 v[84:87], v[166:169], v[198:201], v[84:87]
	v_mfma_f32_16x16x32_bf16 v[80:83], v[174:177], v[198:201], v[80:83]
	v_mfma_f32_16x16x32_bf16 v[68:71], v[166:169], v[206:209], v[68:71]
	v_mfma_f32_16x16x32_bf16 v[64:67], v[174:177], v[206:209], v[64:67]
	s_barrier
	s_setprio 0
	s_add_i32 s33, s33, s47
	v_lshl_add_u64 v[138:139], v[138:139], 0, s[16:17]
	s_mov_b32 m0, s33
	ds_read_b128 v[178:181], v145 offset:49152
	ds_read_b128 v[182:185], v145 offset:50176
	ds_read_b128 v[186:189], v145 offset:51200
	ds_read_b128 v[190:193], v145 offset:52224
	ds_read_b128 v[194:197], v145 offset:53248
	ds_read_b128 v[198:201], v145 offset:54272
	ds_read_b128 v[202:205], v145 offset:55296
	ds_read_b128 v[206:209], v145 offset:56320
	global_load_lds_dwordx4 v[138:139], off
	v_lshl_add_u64 v[138:139], v[210:211], 0, s[16:17]
	s_add_i32 m0, s33, 0x2000
	s_add_i32 s33, s76, s47
	global_load_lds_dwordx4 v[138:139], off
	v_lshl_add_u64 v[138:139], v[212:213], 0, s[16:17]
	s_mov_b32 m0, s33
	s_nop 0
	global_load_lds_dwordx4 v[138:139], off
	v_lshl_add_u64 v[138:139], v[214:215], 0, s[16:17]
	s_add_i32 m0, s33, 0x2000
	s_nop 0
	global_load_lds_dwordx4 v[138:139], off
	v_lshl_add_u64 v[138:139], v[216:217], 0, s[16:17]
	s_mov_b32 m0, s60
	s_nop 0
	global_load_lds_dwordx4 v[138:139], off
	v_lshl_add_u64 v[138:139], v[218:219], 0, s[16:17]
	s_mov_b32 m0, s61
	s_nop 0
	global_load_lds_dwordx4 v[138:139], off
	s_waitcnt vmcnt(8)
	s_waitcnt lgkmcnt(0)
	s_setprio 1
	s_barrier
	v_mfma_f32_16x16x32_bf16 v[60:63], v[146:149], v[178:181], v[60:63]
	v_mfma_f32_16x16x32_bf16 v[56:59], v[154:157], v[178:181], v[56:59]
	v_mfma_f32_16x16x32_bf16 v[44:47], v[146:149], v[186:189], v[44:47]
	v_mfma_f32_16x16x32_bf16 v[40:43], v[154:157], v[186:189], v[40:43]
	v_mfma_f32_16x16x32_bf16 v[28:31], v[146:149], v[194:197], v[28:31]
	v_mfma_f32_16x16x32_bf16 v[24:27], v[154:157], v[194:197], v[24:27]
	v_mfma_f32_16x16x32_bf16 v[12:15], v[146:149], v[202:205], v[12:15]
	v_mfma_f32_16x16x32_bf16 v[8:11], v[154:157], v[202:205], v[8:11]
	v_mfma_f32_16x16x32_bf16 v[60:63], v[150:153], v[182:185], v[60:63]
	v_mfma_f32_16x16x32_bf16 v[56:59], v[158:161], v[182:185], v[56:59]
	v_mfma_f32_16x16x32_bf16 v[44:47], v[150:153], v[190:193], v[44:47]
	v_mfma_f32_16x16x32_bf16 v[40:43], v[158:161], v[190:193], v[40:43]
	v_mfma_f32_16x16x32_bf16 v[28:31], v[150:153], v[198:201], v[28:31]
	v_mfma_f32_16x16x32_bf16 v[24:27], v[158:161], v[198:201], v[24:27]
	v_mfma_f32_16x16x32_bf16 v[12:15], v[150:153], v[206:209], v[12:15]
	v_mfma_f32_16x16x32_bf16 v[8:11], v[158:161], v[206:209], v[8:11]
	v_mfma_f32_16x16x32_bf16 v[52:55], v[162:165], v[178:181], v[52:55]
	v_mfma_f32_16x16x32_bf16 v[48:51], v[170:173], v[178:181], v[48:51]
	v_mfma_f32_16x16x32_bf16 v[36:39], v[162:165], v[186:189], v[36:39]
	v_mfma_f32_16x16x32_bf16 v[32:35], v[170:173], v[186:189], v[32:35]
	v_mfma_f32_16x16x32_bf16 v[20:23], v[162:165], v[194:197], v[20:23]
	v_mfma_f32_16x16x32_bf16 v[16:19], v[170:173], v[194:197], v[16:19]
	v_mfma_f32_16x16x32_bf16 v[4:7], v[162:165], v[202:205], v[4:7]
	v_mfma_f32_16x16x32_bf16 v[0:3], v[170:173], v[202:205], v[0:3]
	v_mfma_f32_16x16x32_bf16 v[52:55], v[166:169], v[182:185], v[52:55]
	v_mfma_f32_16x16x32_bf16 v[48:51], v[174:177], v[182:185], v[48:51]
	v_mfma_f32_16x16x32_bf16 v[36:39], v[166:169], v[190:193], v[36:39]
	v_mfma_f32_16x16x32_bf16 v[32:35], v[174:177], v[190:193], v[32:35]
	v_mfma_f32_16x16x32_bf16 v[20:23], v[166:169], v[198:201], v[20:23]
	v_mfma_f32_16x16x32_bf16 v[16:19], v[174:177], v[198:201], v[16:19]
	v_mfma_f32_16x16x32_bf16 v[4:7], v[166:169], v[206:209], v[4:7]
	v_mfma_f32_16x16x32_bf16 v[0:3], v[174:177], v[206:209], v[0:3]
	s_barrier
	s_setprio 0
	s_add_u32 s40, s40, 0x100
	s_addc_u32 s41, s41, 0
	s_add_u32 s73, s73, 0x100
	s_addc_u32 s74, s74, 0
	s_cmp_ge_i32 s75, s62
	s_mov_b32 s42, s75
	s_cbranch_scc0 .LBB0_1574
